# weight rows permuted in the prologue so a wave owns 64 adjacent output columns; residual epilogues rewritten: lane-pair exchange, every load/store covers 8 rows x 128 B
# speedup vs baseline: 1.0315x; 1.0200x over previous
.LBB0_45:
	s_movk_i32 s20, 0x7ff
	v_cmp_lt_i32_e32 vcc, s20, v26
	s_and_saveexec_b64 s[20:21], vcc
	s_xor_b64 s[20:21], exec, s[20:21]
	s_cbranch_execz .LBB0_67
	s_movk_i32 s22, 0xbff
	v_cmp_lt_u32_e32 vcc, s22, v26
	s_and_saveexec_b64 s[22:23], vcc
	s_xor_b64 s[22:23], exec, s[22:23]
	s_cbranch_execz .LBB0_64
	s_movk_i32 s24, 0xcff
	v_cmp_lt_u32_e32 vcc, s24, v26
	s_and_saveexec_b64 s[24:25], vcc
	s_xor_b64 s[24:25], exec, s[24:25]
	s_cbranch_execz .LBB0_61
	s_movk_i32 s26, 0x1cff
	v_cmp_lt_u32_e32 vcc, s26, v26
	s_and_saveexec_b64 s[26:27], vcc
	s_xor_b64 s[26:27], exec, s[26:27]
	s_cbranch_execz .LBB0_58
	s_movk_i32 s28, 0x20ff
	v_cmp_lt_u32_e32 vcc, s28, v26
	s_and_saveexec_b64 s[28:29], vcc
	s_xor_b64 s[28:29], exec, s[28:29]
	s_cbranch_execz .LBB0_55
	s_movk_i32 s30, 0x40ff
	v_cmp_lt_u32_e32 vcc, s30, v26
	s_and_saveexec_b64 s[30:31], vcc
	s_xor_b64 s[30:31], exec, s[30:31]
	s_cbranch_execz .LBB0_52
	v_add_u32_e32 v15, 0xffffbf00, v26
	v_lshrrev_b32_e32 v20, 11, v15
	v_mov_b32_e32 v21, v3
	v_readlane_b32 s72, v246, 42
	v_lshlrev_b64 v[22:23], 24, v[20:21]
	v_readlane_b32 s82, v246, 52
	v_readlane_b32 s83, v246, 53
	v_add_u32_e32 v15, 0xffff7e00, v32
	v_and_b32_e32 v17, 0x3e0, v33
	v_lshl_add_u64 v[22:23], s[82:83], 0, v[22:23]
	v_and_b32_e32 v15, 0xfc0, v15
	v_and_b32_e32 v24, 0x60, v17
	v_and_b32_e32 v25, 0x80, v17
	v_lshlrev_b32_e32 v24, 1, v24
	v_lshrrev_b32_e32 v25, 2, v25
	v_or_b32_e32 v24, v24, v25
	v_and_b32_e32 v25, 0xffffff1f, v17
	v_or_b32_e32 v24, v24, v25
	v_lshlrev_b32_e32 v24, 2, v24
	v_mov_b32_e32 v25, v3
	v_or_b32_e32 v19, v15, v27
	v_lshl_add_u64 v[22:23], v[22:23], 0, v[24:25]
	v_lshl_add_u64 v[22:23], v[22:23], 0, v[2:3]
	v_lshlrev_b32_e32 v24, 12, v19
	v_lshl_add_u64 v[22:23], v[22:23], 0, v[24:25]
	v_add_co_u32_e32 v24, vcc, s38, v22
	v_lshlrev_b64 v[20:21], 23, v[20:21]
	s_nop 0
	v_addc_co_u32_e32 v25, vcc, 0, v23, vcc
	v_add_co_u32_e32 v46, vcc, s39, v22
	v_lshl_add_u64 v[20:21], s[4:5], 0, v[20:21]
	s_nop 0
	v_addc_co_u32_e32 v47, vcc, 0, v23, vcc
	v_add_co_u32_e32 v48, vcc, s40, v22
	v_readlane_b32 s73, v246, 43
	s_nop 0
	v_addc_co_u32_e32 v49, vcc, 0, v23, vcc
	v_add_co_u32_e32 v50, vcc, s41, v22
	v_readlane_b32 s74, v246, 44
	s_nop 0
	v_addc_co_u32_e32 v51, vcc, 0, v23, vcc
	v_add_co_u32_e32 v52, vcc, s42, v22
	v_readlane_b32 s75, v246, 45
	s_nop 0
	v_addc_co_u32_e32 v53, vcc, 0, v23, vcc
	v_add_co_u32_e32 v54, vcc, s43, v22
	v_readlane_b32 s76, v246, 46
	s_nop 0
	v_addc_co_u32_e32 v55, vcc, 0, v23, vcc
	v_add_co_u32_e32 v56, vcc, s44, v22
	v_readlane_b32 s77, v246, 47
	s_nop 0
	v_addc_co_u32_e32 v57, vcc, 0, v23, vcc
	global_load_dword v19, v[22:23], off
	global_load_dword v45, v[24:25], off
	global_load_dword v60, v[46:47], off
	global_load_dword v61, v[48:49], off
	global_load_dword v62, v[50:51], off
	global_load_dword v63, v[52:53], off
	global_load_dword v64, v[54:55], off
	global_load_dword v65, v[56:57], off
	v_add_co_u32_e32 v24, vcc, s45, v22
	v_readlane_b32 s78, v246, 48
	s_nop 0
	v_addc_co_u32_e32 v25, vcc, 0, v23, vcc
	v_add_co_u32_e32 v46, vcc, s46, v22
	v_readlane_b32 s79, v246, 49
	s_nop 0
	v_addc_co_u32_e32 v47, vcc, 0, v23, vcc
	v_add_co_u32_e32 v48, vcc, s47, v22
	v_readlane_b32 s80, v246, 50
	s_nop 0
	v_addc_co_u32_e32 v49, vcc, 0, v23, vcc
	v_add_co_u32_e32 v50, vcc, s48, v22
	v_readlane_b32 s81, v246, 51
	s_nop 0
	v_addc_co_u32_e32 v51, vcc, 0, v23, vcc
	v_add_co_u32_e32 v52, vcc, s49, v22
	v_readlane_b32 s84, v246, 54
	s_nop 0
	v_addc_co_u32_e32 v53, vcc, 0, v23, vcc
	v_add_co_u32_e32 v54, vcc, s50, v22
	v_readlane_b32 s85, v246, 55
	s_nop 0
	v_addc_co_u32_e32 v55, vcc, 0, v23, vcc
	v_add_co_u32_e32 v56, vcc, s51, v22
	v_readlane_b32 s86, v246, 56
	s_nop 0
	v_addc_co_u32_e32 v57, vcc, 0, v23, vcc
	v_add_co_u32_e32 v58, vcc, s53, v22
	v_readlane_b32 s87, v246, 57
	s_nop 0
	v_addc_co_u32_e32 v59, vcc, 0, v23, vcc
	global_load_dword v66, v[24:25], off
	global_load_dword v67, v[46:47], off
	global_load_dword v68, v[48:49], off
	global_load_dword v69, v[50:51], off
	global_load_dword v70, v[52:53], off
	global_load_dword v71, v[54:55], off
	global_load_dword v72, v[56:57], off
	global_load_dword v73, v[58:59], off
	v_add_co_u32_e32 v24, vcc, s54, v22
	v_readlane_b32 s72, v246, 58
	s_nop 0
	v_addc_co_u32_e32 v25, vcc, 0, v23, vcc
	v_add_co_u32_e32 v46, vcc, s55, v22
	s_nop 1
	v_addc_co_u32_e32 v47, vcc, 0, v23, vcc
	v_add_co_u32_e32 v48, vcc, s56, v22
	s_nop 1
	v_addc_co_u32_e32 v49, vcc, 0, v23, vcc
	v_add_co_u32_e32 v50, vcc, s57, v22
	s_nop 1
	v_addc_co_u32_e32 v51, vcc, 0, v23, vcc
	v_add_co_u32_e32 v52, vcc, s58, v22
	s_nop 1
	v_addc_co_u32_e32 v53, vcc, 0, v23, vcc
	v_add_co_u32_e32 v54, vcc, s59, v22
	s_nop 1
	v_addc_co_u32_e32 v55, vcc, 0, v23, vcc
	v_add_co_u32_e32 v56, vcc, s60, v22
	s_nop 1
	v_addc_co_u32_e32 v57, vcc, 0, v23, vcc
	v_add_co_u32_e32 v58, vcc, s61, v22
	s_nop 1
	v_addc_co_u32_e32 v59, vcc, 0, v23, vcc
	global_load_dword v74, v[24:25], off
	global_load_dword v75, v[46:47], off
	global_load_dword v76, v[48:49], off
	global_load_dword v77, v[50:51], off
	global_load_dword v78, v[52:53], off
	global_load_dword v79, v[54:55], off
	global_load_dword v81, v[56:57], off
	s_nop 0
	global_load_dword v58, v[58:59], off
	v_add_co_u32_e32 v24, vcc, s62, v22
	s_nop 1
	v_addc_co_u32_e32 v25, vcc, 0, v23, vcc
	v_add_co_u32_e32 v46, vcc, s63, v22
	s_nop 1
	v_addc_co_u32_e32 v47, vcc, 0, v23, vcc
	v_add_co_u32_e32 v48, vcc, s64, v22
	s_nop 1
	v_addc_co_u32_e32 v49, vcc, 0, v23, vcc
	v_add_co_u32_e32 v50, vcc, s65, v22
	s_nop 1
	v_addc_co_u32_e32 v51, vcc, 0, v23, vcc
	v_add_co_u32_e32 v52, vcc, s66, v22
	s_nop 1
	v_addc_co_u32_e32 v53, vcc, 0, v23, vcc
	v_add_co_u32_e32 v54, vcc, s67, v22
	s_nop 1
	v_addc_co_u32_e32 v55, vcc, 0, v23, vcc
	v_add_co_u32_e32 v56, vcc, s68, v22
	s_nop 1
	v_addc_co_u32_e32 v57, vcc, 0, v23, vcc
	v_add_co_u32_e32 v22, vcc, s69, v22
	s_nop 1
	v_addc_co_u32_e32 v23, vcc, 0, v23, vcc
	global_load_dword v24, v[24:25], off
	s_nop 0
	global_load_dword v25, v[46:47], off
	s_nop 0
	global_load_dword v46, v[48:49], off
	global_load_dword v47, v[50:51], off
	s_nop 0
	global_load_dword v48, v[52:53], off
	global_load_dword v49, v[54:55], off
	global_load_dword v50, v[56:57], off
	s_nop 0
	global_load_dword v22, v[22:23], off
	s_waitcnt vmcnt(30)
	ds_write2_b32 v34, v19, v45 offset1:66
	s_waitcnt vmcnt(28)
	ds_write2_b32 v34, v60, v61 offset0:132 offset1:198
	s_waitcnt vmcnt(26)
	ds_write2_b32 v35, v62, v63 offset0:8 offset1:74
	s_waitcnt vmcnt(24)
	ds_write2_b32 v35, v64, v65 offset0:140 offset1:206
	s_waitcnt vmcnt(22)
	ds_write2_b32 v36, v66, v67 offset0:16 offset1:82
	s_waitcnt vmcnt(20)
	ds_write2_b32 v36, v68, v69 offset0:148 offset1:214
	s_waitcnt vmcnt(18)
	ds_write2_b32 v37, v70, v71 offset0:24 offset1:90
	s_waitcnt vmcnt(16)
	ds_write2_b32 v37, v72, v73 offset0:156 offset1:222
	s_waitcnt vmcnt(14)
	ds_write2_b32 v38, v74, v75 offset0:32 offset1:98
	s_waitcnt vmcnt(12)
	ds_write2_b32 v38, v76, v77 offset0:164 offset1:230
	s_waitcnt vmcnt(10)
	ds_write2_b32 v39, v78, v79 offset0:40 offset1:106
	s_waitcnt vmcnt(8)
	ds_write2_b32 v39, v81, v58 offset0:172 offset1:238
	s_waitcnt vmcnt(6)
	ds_write2_b32 v40, v24, v25 offset0:48 offset1:114
	s_waitcnt vmcnt(4)
	ds_write2_b32 v40, v46, v47 offset0:180 offset1:246
	s_waitcnt vmcnt(2)
	ds_write2_b32 v41, v48, v49 offset0:56 offset1:122
	s_waitcnt vmcnt(0)
	ds_write2_b32 v41, v50, v22 offset0:188 offset1:254
	s_waitcnt lgkmcnt(0)
	ds_read2_b32 v[24:25], v42 offset1:8
	ds_read2_b32 v[48:49], v42 offset0:33 offset1:41
	ds_read2_b32 v[50:51], v42 offset0:66 offset1:74
	v_lshlrev_b32_e32 v22, 1, v15
	v_mov_b32_e32 v23, v3
	ds_read2_b32 v[52:53], v42 offset0:99 offset1:107
	v_lshl_add_u64 v[20:21], v[20:21], 0, v[22:23]
	v_mov_b32_e32 v19, v3
	s_waitcnt lgkmcnt(3)
	v_bfe_u32 v15, v24, 16, 1
	v_lshl_add_u64 v[46:47], v[20:21], 0, v[18:19]
	v_add3_u32 v15, v24, v15, s70
	s_waitcnt lgkmcnt(2)
	v_bfe_u32 v19, v48, 16, 1
	ds_read2_b32 v[54:55], v42 offset0:132 offset1:140
	v_lshrrev_b32_e32 v15, 16, v15
	v_add3_u32 v19, v48, v19, s70
	ds_read2_b32 v[56:57], v42 offset0:165 offset1:173
	v_and_or_b32 v20, v19, s71, v15
	s_waitcnt lgkmcnt(3)
	v_bfe_u32 v15, v50, 16, 1
	v_add3_u32 v15, v50, v15, s70
	s_waitcnt lgkmcnt(2)
	v_bfe_u32 v19, v52, 16, 1
	ds_read2_b32 v[58:59], v42 offset0:198 offset1:206
	v_lshrrev_b32_e32 v15, 16, v15
	v_add3_u32 v19, v52, v19, s70
	ds_read2_b32 v[60:61], v42 offset0:231 offset1:239
	v_and_or_b32 v21, v19, s71, v15
	s_waitcnt lgkmcnt(3)
	v_bfe_u32 v15, v54, 16, 1
	v_add3_u32 v15, v54, v15, s70
	s_waitcnt lgkmcnt(2)
	v_bfe_u32 v19, v56, 16, 1
	v_lshrrev_b32_e32 v15, 16, v15
	v_add3_u32 v19, v56, v19, s70
	v_and_or_b32 v22, v19, s71, v15
	s_waitcnt lgkmcnt(1)
	v_bfe_u32 v15, v58, 16, 1
	v_add3_u32 v15, v58, v15, s70
	s_waitcnt lgkmcnt(0)
	v_bfe_u32 v19, v60, 16, 1
	v_lshrrev_b32_e32 v15, 16, v15
	v_add3_u32 v19, v60, v19, s70
	v_and_or_b32 v23, v19, s71, v15
	v_or_b32_e32 v15, v17, v28
	v_lshlrev_b32_e32 v62, 13, v15
	v_bfe_u32 v15, v25, 16, 1
	v_mov_b32_e32 v63, v3
	v_add3_u32 v15, v25, v15, s70
	v_bfe_u32 v19, v49, 16, 1
	v_lshl_add_u64 v[62:63], v[46:47], 0, v[62:63]
	v_lshrrev_b32_e32 v15, 16, v15
	v_add3_u32 v19, v49, v19, s70
	global_store_dwordx4 v[62:63], v[20:23], off
	v_mov_b32_e32 v25, v3
	ds_read2_b32 v[48:49], v42 offset0:16 offset1:24
	v_and_or_b32 v20, v19, s71, v15
	v_bfe_u32 v15, v51, 16, 1
	v_add3_u32 v15, v51, v15, s70
	v_bfe_u32 v19, v53, 16, 1
	v_lshrrev_b32_e32 v15, 16, v15
	v_add3_u32 v19, v53, v19, s70
	v_and_or_b32 v21, v19, s71, v15
	v_bfe_u32 v15, v55, 16, 1
	v_add3_u32 v15, v55, v15, s70
	v_bfe_u32 v19, v57, 16, 1
	v_lshrrev_b32_e32 v15, 16, v15
	v_add3_u32 v19, v57, v19, s70
	v_and_or_b32 v22, v19, s71, v15
	v_bfe_u32 v15, v59, 16, 1
	v_add3_u32 v15, v59, v15, s70
	v_bfe_u32 v19, v61, 16, 1
	v_lshrrev_b32_e32 v15, 16, v15
	v_add3_u32 v19, v61, v19, s70
	v_and_or_b32 v23, v19, s71, v15
	v_or_b32_e32 v15, v17, v29
	v_lshlrev_b32_e32 v24, 13, v15
	v_lshl_add_u64 v[24:25], v[46:47], 0, v[24:25]
	global_store_dwordx4 v[24:25], v[20:23], off
	ds_read2_b32 v[24:25], v42 offset0:49 offset1:57
	ds_read2_b32 v[50:51], v42 offset0:82 offset1:90
	ds_read2_b32 v[52:53], v42 offset0:115 offset1:123
	s_waitcnt lgkmcnt(3)
	v_bfe_u32 v15, v48, 16, 1
	v_add3_u32 v15, v48, v15, s70
	s_waitcnt lgkmcnt(2)
	v_bfe_u32 v19, v24, 16, 1
	ds_read2_b32 v[54:55], v42 offset0:148 offset1:156
	v_lshrrev_b32_e32 v15, 16, v15
	v_add3_u32 v19, v24, v19, s70
	ds_read2_b32 v[56:57], v42 offset0:181 offset1:189
	v_and_or_b32 v20, v19, s71, v15
	s_waitcnt lgkmcnt(3)
	v_bfe_u32 v15, v50, 16, 1
	v_add3_u32 v15, v50, v15, s70
	s_waitcnt lgkmcnt(2)
	v_bfe_u32 v19, v52, 16, 1
	ds_read2_b32 v[58:59], v42 offset0:214 offset1:222
	v_lshrrev_b32_e32 v15, 16, v15
	v_add3_u32 v19, v52, v19, s70
	ds_read2_b32 v[60:61], v42 offset0:247 offset1:255
	v_and_or_b32 v21, v19, s71, v15
	s_waitcnt lgkmcnt(3)
	v_bfe_u32 v15, v54, 16, 1
	v_add3_u32 v15, v54, v15, s70
	s_waitcnt lgkmcnt(2)
	v_bfe_u32 v19, v56, 16, 1
	v_lshrrev_b32_e32 v15, 16, v15
	v_add3_u32 v19, v56, v19, s70
	v_and_or_b32 v22, v19, s71, v15
	s_waitcnt lgkmcnt(1)
	v_bfe_u32 v15, v58, 16, 1
	v_add3_u32 v15, v58, v15, s70
	s_waitcnt lgkmcnt(0)
	v_bfe_u32 v19, v60, 16, 1
	v_lshrrev_b32_e32 v15, 16, v15
	v_add3_u32 v19, v60, v19, s70
	v_and_or_b32 v23, v19, s71, v15
	v_or_b32_e32 v15, v17, v30
	v_lshlrev_b32_e32 v62, 13, v15
	v_bfe_u32 v15, v49, 16, 1
	v_mov_b32_e32 v63, v3
	v_add3_u32 v15, v49, v15, s70
	v_bfe_u32 v19, v25, 16, 1
	v_lshl_add_u64 v[62:63], v[46:47], 0, v[62:63]
	v_lshrrev_b32_e32 v15, 16, v15
	v_add3_u32 v19, v25, v19, s70
	global_store_dwordx4 v[62:63], v[20:23], off
	v_mov_b32_e32 v25, v3
	s_nop 0
	v_and_or_b32 v20, v19, s71, v15
	v_bfe_u32 v15, v51, 16, 1
	v_add3_u32 v15, v51, v15, s70
	v_bfe_u32 v19, v53, 16, 1
	v_lshrrev_b32_e32 v15, 16, v15
	v_add3_u32 v19, v53, v19, s70
	v_and_or_b32 v21, v19, s71, v15
	v_bfe_u32 v15, v55, 16, 1
	v_add3_u32 v15, v55, v15, s70
	v_bfe_u32 v19, v57, 16, 1
	v_lshrrev_b32_e32 v15, 16, v15
	v_add3_u32 v19, v57, v19, s70
	v_and_or_b32 v22, v19, s71, v15
	v_bfe_u32 v15, v59, 16, 1
	v_add3_u32 v15, v59, v15, s70
	v_bfe_u32 v19, v61, 16, 1
	v_lshrrev_b32_e32 v15, 16, v15
	v_add3_u32 v19, v61, v19, s70
	v_and_or_b32 v23, v19, s71, v15
	v_or_b32_e32 v15, v17, v31
	v_lshlrev_b32_e32 v24, 13, v15
	v_lshl_add_u64 v[24:25], v[46:47], 0, v[24:25]
	global_store_dwordx4 v[24:25], v[20:23], off
	s_waitcnt lgkmcnt(0)
.LBB0_52:
	s_andn2_saveexec_b64 s[30:31], s[30:31]
	s_cbranch_execz .LBB0_54
	v_add_u32_e32 v15, 0xffffdf00, v26
	v_lshrrev_b32_e32 v20, 11, v15
	v_mov_b32_e32 v21, v3
	v_readlane_b32 s72, v246, 42
	v_lshlrev_b64 v[22:23], 24, v[20:21]
	v_readlane_b32 s80, v246, 50
	v_readlane_b32 s81, v246, 51
	v_lshrrev_b32_e32 v15, 1, v15
	v_and_b32_e32 v17, 0xfe0, v33
	v_lshl_add_u64 v[22:23], s[80:81], 0, v[22:23]
	v_and_b32_e32 v15, 0x3c0, v15
	v_and_b32_e32 v24, 0x60, v17
	v_and_b32_e32 v25, 0x80, v17
	v_lshlrev_b32_e32 v24, 1, v24
	v_lshrrev_b32_e32 v25, 2, v25
	v_or_b32_e32 v24, v24, v25
	v_and_b32_e32 v25, 0xffffff1f, v17
	v_or_b32_e32 v24, v24, v25
	v_lshlrev_b32_e32 v24, 2, v24
	v_mov_b32_e32 v25, v3
	v_or_b32_e32 v19, v15, v27
	v_lshl_add_u64 v[22:23], v[22:23], 0, v[24:25]
	v_lshl_add_u64 v[22:23], v[22:23], 0, v[2:3]
	v_lshlrev_b32_e32 v24, 14, v19
	v_lshl_add_u64 v[22:23], v[22:23], 0, v[24:25]
	v_add_co_u32_e32 v24, vcc, s41, v22
	v_readlane_b32 s73, v246, 43
	s_nop 0
	v_addc_co_u32_e32 v25, vcc, 0, v23, vcc
	v_add_co_u32_e32 v46, vcc, s45, v22
	s_mov_b32 s73, 0x40000
	s_nop 0
	v_addc_co_u32_e32 v47, vcc, 0, v23, vcc
	v_add_co_u32_e32 v48, vcc, s49, v22
	v_lshlrev_b64 v[20:21], 23, v[20:21]
	s_nop 0
	v_addc_co_u32_e32 v49, vcc, 0, v23, vcc
	v_add_co_u32_e32 v50, vcc, s54, v22
	v_lshl_add_u64 v[20:21], s[6:7], 0, v[20:21]
	s_nop 0
	v_addc_co_u32_e32 v51, vcc, 0, v23, vcc
	v_add_co_u32_e32 v52, vcc, s58, v22
	v_readlane_b32 s72, v246, 58
	s_nop 0
	v_addc_co_u32_e32 v53, vcc, 0, v23, vcc
	v_add_co_u32_e32 v54, vcc, s62, v22
	v_readlane_b32 s74, v246, 44
	s_nop 0
	v_addc_co_u32_e32 v55, vcc, 0, v23, vcc
	v_add_co_u32_e32 v56, vcc, s66, v22
	v_readlane_b32 s75, v246, 45
	s_nop 0
	v_addc_co_u32_e32 v57, vcc, 0, v23, vcc
	global_load_dword v19, v[22:23], off
	global_load_dword v45, v[24:25], off
	global_load_dword v60, v[46:47], off
	global_load_dword v61, v[48:49], off
	global_load_dword v62, v[50:51], off
	global_load_dword v63, v[52:53], off
	global_load_dword v64, v[54:55], off
	global_load_dword v65, v[56:57], off
	v_add_co_u32_e32 v24, vcc, s73, v22
	s_mov_b32 s73, 0x48000
	s_nop 0
	v_addc_co_u32_e32 v25, vcc, 0, v23, vcc
	v_add_co_u32_e32 v46, vcc, s73, v22
	s_mov_b32 s73, 0x50000
	s_nop 0
	v_addc_co_u32_e32 v47, vcc, 0, v23, vcc
	v_add_co_u32_e32 v48, vcc, s73, v22
	s_mov_b32 s73, 0x58000
	s_nop 0
	v_addc_co_u32_e32 v49, vcc, 0, v23, vcc
	v_add_co_u32_e32 v50, vcc, s73, v22
	s_mov_b32 s73, 0x60000
	s_nop 0
	v_addc_co_u32_e32 v51, vcc, 0, v23, vcc
	v_add_co_u32_e32 v52, vcc, s73, v22
	s_mov_b32 s73, 0x68000
	s_nop 0
	v_addc_co_u32_e32 v53, vcc, 0, v23, vcc
	v_add_co_u32_e32 v54, vcc, s73, v22
	s_mov_b32 s73, 0x70000
	s_nop 0
	v_addc_co_u32_e32 v55, vcc, 0, v23, vcc
	v_add_co_u32_e32 v56, vcc, s73, v22
	s_mov_b32 s73, 0x78000
	s_nop 0
	v_addc_co_u32_e32 v57, vcc, 0, v23, vcc
	v_add_co_u32_e32 v58, vcc, s73, v22
	s_mov_b32 s73, 0x80000
	s_nop 0
	v_addc_co_u32_e32 v59, vcc, 0, v23, vcc
	global_load_dword v66, v[24:25], off
	global_load_dword v67, v[46:47], off
	global_load_dword v68, v[48:49], off
	global_load_dword v69, v[50:51], off
	global_load_dword v70, v[52:53], off
	global_load_dword v71, v[54:55], off
	global_load_dword v72, v[56:57], off
	global_load_dword v73, v[58:59], off
	v_add_co_u32_e32 v24, vcc, s73, v22
	s_mov_b32 s73, 0x90000
	s_nop 0
	v_addc_co_u32_e32 v25, vcc, 0, v23, vcc
	v_add_co_u32_e32 v46, vcc, s94, v22
	v_readlane_b32 s76, v246, 46
	s_nop 0
	v_addc_co_u32_e32 v47, vcc, 0, v23, vcc
	v_add_co_u32_e32 v48, vcc, s73, v22
	s_mov_b32 s73, 0x98000
	s_nop 0
	v_addc_co_u32_e32 v49, vcc, 0, v23, vcc
	v_add_co_u32_e32 v50, vcc, s73, v22
	s_mov_b32 s73, 0xa0000
	s_nop 0
	v_addc_co_u32_e32 v51, vcc, 0, v23, vcc
	v_add_co_u32_e32 v52, vcc, s73, v22
	s_mov_b32 s73, 0xa8000
	s_nop 0
	v_addc_co_u32_e32 v53, vcc, 0, v23, vcc
	v_add_co_u32_e32 v54, vcc, s73, v22
	s_mov_b32 s73, 0xb0000
	s_nop 0
	v_addc_co_u32_e32 v55, vcc, 0, v23, vcc
	v_add_co_u32_e32 v56, vcc, s73, v22
	s_mov_b32 s73, 0xb8000
	s_nop 0
	v_addc_co_u32_e32 v57, vcc, 0, v23, vcc
	v_add_co_u32_e32 v58, vcc, s73, v22
	s_mov_b32 s73, 0xc0000
	s_nop 0
	v_addc_co_u32_e32 v59, vcc, 0, v23, vcc
	global_load_dword v74, v[24:25], off
	global_load_dword v75, v[46:47], off
	global_load_dword v76, v[48:49], off
	global_load_dword v77, v[50:51], off
	global_load_dword v78, v[52:53], off
	global_load_dword v79, v[54:55], off
	global_load_dword v81, v[56:57], off
	s_nop 0
	global_load_dword v58, v[58:59], off
	v_add_co_u32_e32 v24, vcc, s73, v22
	v_readlane_b32 s77, v246, 47
	s_nop 0
	v_addc_co_u32_e32 v25, vcc, 0, v23, vcc
	v_add_co_u32_e32 v46, vcc, s95, v22
	v_readlane_b32 s78, v246, 48
	s_nop 0
	v_addc_co_u32_e32 v47, vcc, 0, v23, vcc
	v_add_co_u32_e32 v48, vcc, s93, v22
	v_readlane_b32 s79, v246, 49
	s_nop 0
	v_addc_co_u32_e32 v49, vcc, 0, v23, vcc
	v_add_co_u32_e32 v50, vcc, s2, v22
	v_readlane_b32 s82, v246, 52
	s_nop 0
	v_addc_co_u32_e32 v51, vcc, 0, v23, vcc
	v_add_co_u32_e32 v52, vcc, s35, v22
	v_readlane_b32 s83, v246, 53
	s_nop 0
	v_addc_co_u32_e32 v53, vcc, 0, v23, vcc
	v_add_co_u32_e32 v54, vcc, s96, v22
	v_readlane_b32 s84, v246, 54
	s_nop 0
	v_addc_co_u32_e32 v55, vcc, 0, v23, vcc
	v_add_co_u32_e32 v56, vcc, s97, v22
	v_readlane_b32 s85, v246, 55
	s_nop 0
	v_addc_co_u32_e32 v57, vcc, 0, v23, vcc
	v_add_co_u32_e32 v22, vcc, s34, v22
	v_readlane_b32 s86, v246, 56
	s_nop 0
	v_addc_co_u32_e32 v23, vcc, 0, v23, vcc
	global_load_dword v24, v[24:25], off
	s_nop 0
	global_load_dword v25, v[46:47], off
	s_nop 0
	global_load_dword v46, v[48:49], off
	global_load_dword v47, v[50:51], off
	s_nop 0
	global_load_dword v48, v[52:53], off
	global_load_dword v49, v[54:55], off
	global_load_dword v50, v[56:57], off
	s_nop 0
	global_load_dword v22, v[22:23], off
	s_waitcnt vmcnt(30)
	ds_write2_b32 v34, v19, v45 offset1:66
	s_waitcnt vmcnt(28)
	ds_write2_b32 v34, v60, v61 offset0:132 offset1:198
	s_waitcnt vmcnt(26)
	ds_write2_b32 v35, v62, v63 offset0:8 offset1:74
	s_waitcnt vmcnt(24)
	ds_write2_b32 v35, v64, v65 offset0:140 offset1:206
	s_waitcnt vmcnt(22)
	ds_write2_b32 v36, v66, v67 offset0:16 offset1:82
	s_waitcnt vmcnt(20)
	ds_write2_b32 v36, v68, v69 offset0:148 offset1:214
	s_waitcnt vmcnt(18)
	ds_write2_b32 v37, v70, v71 offset0:24 offset1:90
	s_waitcnt vmcnt(16)
	ds_write2_b32 v37, v72, v73 offset0:156 offset1:222
	s_waitcnt vmcnt(14)
	ds_write2_b32 v38, v74, v75 offset0:32 offset1:98
	s_waitcnt vmcnt(12)
	ds_write2_b32 v38, v76, v77 offset0:164 offset1:230
	s_waitcnt vmcnt(10)
	ds_write2_b32 v39, v78, v79 offset0:40 offset1:106
	s_waitcnt vmcnt(8)
	ds_write2_b32 v39, v81, v58 offset0:172 offset1:238
	s_waitcnt vmcnt(6)
	ds_write2_b32 v40, v24, v25 offset0:48 offset1:114
	s_waitcnt vmcnt(4)
	ds_write2_b32 v40, v46, v47 offset0:180 offset1:246
	s_waitcnt vmcnt(2)
	ds_write2_b32 v41, v48, v49 offset0:56 offset1:122
	s_waitcnt vmcnt(0)
	ds_write2_b32 v41, v50, v22 offset0:188 offset1:254
	s_waitcnt lgkmcnt(0)
	ds_read2_b32 v[24:25], v42 offset1:8
	ds_read2_b32 v[48:49], v42 offset0:33 offset1:41
	ds_read2_b32 v[50:51], v42 offset0:66 offset1:74
	v_lshlrev_b32_e32 v22, 1, v15
	v_mov_b32_e32 v23, v3
	ds_read2_b32 v[52:53], v42 offset0:99 offset1:107
	v_lshl_add_u64 v[20:21], v[20:21], 0, v[22:23]
	v_mov_b32_e32 v19, v3
	s_waitcnt lgkmcnt(3)
	v_bfe_u32 v15, v24, 16, 1
	v_lshl_add_u64 v[46:47], v[20:21], 0, v[18:19]
	v_add3_u32 v15, v24, v15, s70
	s_waitcnt lgkmcnt(2)
	v_bfe_u32 v19, v48, 16, 1
	ds_read2_b32 v[54:55], v42 offset0:132 offset1:140
	v_lshrrev_b32_e32 v15, 16, v15
	v_add3_u32 v19, v48, v19, s70
	ds_read2_b32 v[56:57], v42 offset0:165 offset1:173
	v_and_or_b32 v20, v19, s71, v15
	s_waitcnt lgkmcnt(3)
	v_bfe_u32 v15, v50, 16, 1
	v_add3_u32 v15, v50, v15, s70
	s_waitcnt lgkmcnt(2)
	v_bfe_u32 v19, v52, 16, 1
	ds_read2_b32 v[58:59], v42 offset0:198 offset1:206
	v_lshrrev_b32_e32 v15, 16, v15
	v_add3_u32 v19, v52, v19, s70
	ds_read2_b32 v[60:61], v42 offset0:231 offset1:239
	v_and_or_b32 v21, v19, s71, v15
	s_waitcnt lgkmcnt(3)
	v_bfe_u32 v15, v54, 16, 1
	v_add3_u32 v15, v54, v15, s70
	s_waitcnt lgkmcnt(2)
	v_bfe_u32 v19, v56, 16, 1
	v_lshrrev_b32_e32 v15, 16, v15
	v_add3_u32 v19, v56, v19, s70
	v_and_or_b32 v22, v19, s71, v15
	s_waitcnt lgkmcnt(1)
	v_bfe_u32 v15, v58, 16, 1
	v_add3_u32 v15, v58, v15, s70
	s_waitcnt lgkmcnt(0)
	v_bfe_u32 v19, v60, 16, 1
	v_lshrrev_b32_e32 v15, 16, v15
	v_add3_u32 v19, v60, v19, s70
	v_and_or_b32 v23, v19, s71, v15
	v_or_b32_e32 v15, v17, v28
	v_lshlrev_b32_e32 v62, 11, v15
	v_bfe_u32 v15, v25, 16, 1
	v_mov_b32_e32 v63, v3
	v_add3_u32 v15, v25, v15, s70
	v_bfe_u32 v19, v49, 16, 1
	v_lshl_add_u64 v[62:63], v[46:47], 0, v[62:63]
	v_lshrrev_b32_e32 v15, 16, v15
	v_add3_u32 v19, v49, v19, s70
	global_store_dwordx4 v[62:63], v[20:23], off
	v_mov_b32_e32 v25, v3
	ds_read2_b32 v[48:49], v42 offset0:16 offset1:24
	v_and_or_b32 v20, v19, s71, v15
	v_bfe_u32 v15, v51, 16, 1
	v_add3_u32 v15, v51, v15, s70
	v_bfe_u32 v19, v53, 16, 1
	v_lshrrev_b32_e32 v15, 16, v15
	v_add3_u32 v19, v53, v19, s70
	v_and_or_b32 v21, v19, s71, v15
	v_bfe_u32 v15, v55, 16, 1
	v_add3_u32 v15, v55, v15, s70
	v_bfe_u32 v19, v57, 16, 1
	v_lshrrev_b32_e32 v15, 16, v15
	v_add3_u32 v19, v57, v19, s70
	v_and_or_b32 v22, v19, s71, v15
	v_bfe_u32 v15, v59, 16, 1
	v_add3_u32 v15, v59, v15, s70
	v_bfe_u32 v19, v61, 16, 1
	v_lshrrev_b32_e32 v15, 16, v15
	v_add3_u32 v19, v61, v19, s70
	v_and_or_b32 v23, v19, s71, v15
	v_or_b32_e32 v15, v17, v29
	v_lshlrev_b32_e32 v24, 11, v15
	v_lshl_add_u64 v[24:25], v[46:47], 0, v[24:25]
	global_store_dwordx4 v[24:25], v[20:23], off
	ds_read2_b32 v[24:25], v42 offset0:49 offset1:57
	ds_read2_b32 v[50:51], v42 offset0:82 offset1:90
	ds_read2_b32 v[52:53], v42 offset0:115 offset1:123
	s_waitcnt lgkmcnt(3)
	v_bfe_u32 v15, v48, 16, 1
	v_add3_u32 v15, v48, v15, s70
	s_waitcnt lgkmcnt(2)
	v_bfe_u32 v19, v24, 16, 1
	ds_read2_b32 v[54:55], v42 offset0:148 offset1:156
	v_lshrrev_b32_e32 v15, 16, v15
	v_add3_u32 v19, v24, v19, s70
	ds_read2_b32 v[56:57], v42 offset0:181 offset1:189
	v_and_or_b32 v20, v19, s71, v15
	s_waitcnt lgkmcnt(3)
	v_bfe_u32 v15, v50, 16, 1
	v_add3_u32 v15, v50, v15, s70
	s_waitcnt lgkmcnt(2)
	v_bfe_u32 v19, v52, 16, 1
	ds_read2_b32 v[58:59], v42 offset0:214 offset1:222
	v_lshrrev_b32_e32 v15, 16, v15
	v_add3_u32 v19, v52, v19, s70
	ds_read2_b32 v[60:61], v42 offset0:247 offset1:255
	v_and_or_b32 v21, v19, s71, v15
	s_waitcnt lgkmcnt(3)
	v_bfe_u32 v15, v54, 16, 1
	v_add3_u32 v15, v54, v15, s70
	s_waitcnt lgkmcnt(2)
	v_bfe_u32 v19, v56, 16, 1
	v_lshrrev_b32_e32 v15, 16, v15
	v_add3_u32 v19, v56, v19, s70
	v_and_or_b32 v22, v19, s71, v15
	s_waitcnt lgkmcnt(1)
	v_bfe_u32 v15, v58, 16, 1
	v_add3_u32 v15, v58, v15, s70
	s_waitcnt lgkmcnt(0)
	v_bfe_u32 v19, v60, 16, 1
	v_lshrrev_b32_e32 v15, 16, v15
	v_add3_u32 v19, v60, v19, s70
	v_and_or_b32 v23, v19, s71, v15
	v_or_b32_e32 v15, v17, v30
	v_lshlrev_b32_e32 v62, 11, v15
	v_bfe_u32 v15, v49, 16, 1
	v_mov_b32_e32 v63, v3
	v_add3_u32 v15, v49, v15, s70
	v_bfe_u32 v19, v25, 16, 1
	v_lshl_add_u64 v[62:63], v[46:47], 0, v[62:63]
	v_lshrrev_b32_e32 v15, 16, v15
	v_add3_u32 v19, v25, v19, s70
	global_store_dwordx4 v[62:63], v[20:23], off
	v_mov_b32_e32 v25, v3
	v_readlane_b32 s87, v246, 57
	v_and_or_b32 v20, v19, s71, v15
	v_bfe_u32 v15, v51, 16, 1
	v_add3_u32 v15, v51, v15, s70
	v_bfe_u32 v19, v53, 16, 1
	v_lshrrev_b32_e32 v15, 16, v15
	v_add3_u32 v19, v53, v19, s70
	v_and_or_b32 v21, v19, s71, v15
	v_bfe_u32 v15, v55, 16, 1
	v_add3_u32 v15, v55, v15, s70
	v_bfe_u32 v19, v57, 16, 1
	v_lshrrev_b32_e32 v15, 16, v15
	v_add3_u32 v19, v57, v19, s70
	v_and_or_b32 v22, v19, s71, v15
	v_bfe_u32 v15, v59, 16, 1
	v_add3_u32 v15, v59, v15, s70
	v_bfe_u32 v19, v61, 16, 1
	v_lshrrev_b32_e32 v15, 16, v15
	v_add3_u32 v19, v61, v19, s70
	v_and_or_b32 v23, v19, s71, v15
	v_or_b32_e32 v15, v17, v31
	v_lshlrev_b32_e32 v24, 11, v15
	v_lshl_add_u64 v[24:25], v[46:47], 0, v[24:25]
	global_store_dwordx4 v[24:25], v[20:23], off
	s_waitcnt lgkmcnt(0)

.LBB0_55:
	s_andn2_saveexec_b64 s[28:29], s[28:29]
	s_cbranch_execz .LBB0_57
	v_add_u32_e32 v15, 0xffffe300, v26
	v_lshrrev_b32_e32 v20, 9, v15
	v_mov_b32_e32 v21, v3
	v_readlane_b32 s72, v246, 42
	v_lshlrev_b64 v[22:23], 22, v[20:21]
	v_readlane_b32 s78, v246, 48
	v_readlane_b32 s79, v246, 49
	v_add_u32_e32 v15, 0xffffc600, v32
	v_and_b32_e32 v17, 0x3e0, v33
	v_lshl_add_u64 v[22:23], s[78:79], 0, v[22:23]
	v_and_b32_e32 v15, 0x3c0, v15
	v_and_b32_e32 v24, 0x60, v17
	v_and_b32_e32 v25, 0x80, v17
	v_lshlrev_b32_e32 v24, 1, v24
	v_lshrrev_b32_e32 v25, 2, v25
	v_or_b32_e32 v24, v24, v25
	v_and_b32_e32 v25, 0xffffff1f, v17
	v_or_b32_e32 v24, v24, v25
	v_lshlrev_b32_e32 v24, 2, v24
	v_mov_b32_e32 v25, v3
	v_or_b32_e32 v19, v15, v27
	v_lshl_add_u64 v[22:23], v[22:23], 0, v[24:25]
	v_lshl_add_u64 v[22:23], v[22:23], 0, v[2:3]
	v_lshlrev_b32_e32 v24, 12, v19
	v_lshl_add_u64 v[22:23], v[22:23], 0, v[24:25]
	v_add_co_u32_e32 v24, vcc, s38, v22
	v_lshlrev_b64 v[20:21], 21, v[20:21]
	s_nop 0
	v_addc_co_u32_e32 v25, vcc, 0, v23, vcc
	v_add_co_u32_e32 v46, vcc, s39, v22
	v_lshl_add_u64 v[20:21], s[10:11], 0, v[20:21]
	s_nop 0
	v_addc_co_u32_e32 v47, vcc, 0, v23, vcc
	v_add_co_u32_e32 v48, vcc, s40, v22
	v_readlane_b32 s72, v246, 58
	s_nop 0
	v_addc_co_u32_e32 v49, vcc, 0, v23, vcc
	v_add_co_u32_e32 v50, vcc, s41, v22
	v_readlane_b32 s73, v246, 43
	s_nop 0
	v_addc_co_u32_e32 v51, vcc, 0, v23, vcc
	v_add_co_u32_e32 v52, vcc, s42, v22
	v_readlane_b32 s74, v246, 44
	s_nop 0
	v_addc_co_u32_e32 v53, vcc, 0, v23, vcc
	v_add_co_u32_e32 v54, vcc, s43, v22
	v_readlane_b32 s75, v246, 45
	s_nop 0
	v_addc_co_u32_e32 v55, vcc, 0, v23, vcc
	v_add_co_u32_e32 v56, vcc, s44, v22
	v_readlane_b32 s76, v246, 46
	s_nop 0
	v_addc_co_u32_e32 v57, vcc, 0, v23, vcc
	global_load_dword v19, v[22:23], off
	global_load_dword v45, v[24:25], off
	global_load_dword v60, v[46:47], off
	global_load_dword v61, v[48:49], off
	global_load_dword v62, v[50:51], off
	global_load_dword v63, v[52:53], off
	global_load_dword v64, v[54:55], off
	global_load_dword v65, v[56:57], off
	v_add_co_u32_e32 v24, vcc, s45, v22
	v_readlane_b32 s77, v246, 47
	s_nop 0
	v_addc_co_u32_e32 v25, vcc, 0, v23, vcc
	v_add_co_u32_e32 v46, vcc, s46, v22
	v_readlane_b32 s80, v246, 50
	s_nop 0
	v_addc_co_u32_e32 v47, vcc, 0, v23, vcc
	v_add_co_u32_e32 v48, vcc, s47, v22
	v_readlane_b32 s81, v246, 51
	s_nop 0
	v_addc_co_u32_e32 v49, vcc, 0, v23, vcc
	v_add_co_u32_e32 v50, vcc, s48, v22
	v_readlane_b32 s82, v246, 52
	s_nop 0
	v_addc_co_u32_e32 v51, vcc, 0, v23, vcc
	v_add_co_u32_e32 v52, vcc, s49, v22
	v_readlane_b32 s83, v246, 53
	s_nop 0
	v_addc_co_u32_e32 v53, vcc, 0, v23, vcc
	v_add_co_u32_e32 v54, vcc, s50, v22
	v_readlane_b32 s84, v246, 54
	s_nop 0
	v_addc_co_u32_e32 v55, vcc, 0, v23, vcc
	v_add_co_u32_e32 v56, vcc, s51, v22
	v_readlane_b32 s85, v246, 55
	s_nop 0
	v_addc_co_u32_e32 v57, vcc, 0, v23, vcc
	v_add_co_u32_e32 v58, vcc, s53, v22
	v_readlane_b32 s86, v246, 56
	s_nop 0
	v_addc_co_u32_e32 v59, vcc, 0, v23, vcc
	global_load_dword v66, v[24:25], off
	global_load_dword v67, v[46:47], off
	global_load_dword v68, v[48:49], off
	global_load_dword v69, v[50:51], off
	global_load_dword v70, v[52:53], off
	global_load_dword v71, v[54:55], off
	global_load_dword v72, v[56:57], off
	global_load_dword v73, v[58:59], off
	v_add_co_u32_e32 v24, vcc, s54, v22
	v_readlane_b32 s87, v246, 57
	s_nop 0
	v_addc_co_u32_e32 v25, vcc, 0, v23, vcc
	v_add_co_u32_e32 v46, vcc, s55, v22
	s_nop 1
	v_addc_co_u32_e32 v47, vcc, 0, v23, vcc
	v_add_co_u32_e32 v48, vcc, s56, v22
	s_nop 1
	v_addc_co_u32_e32 v49, vcc, 0, v23, vcc
	v_add_co_u32_e32 v50, vcc, s57, v22
	s_nop 1
	v_addc_co_u32_e32 v51, vcc, 0, v23, vcc
	v_add_co_u32_e32 v52, vcc, s58, v22
	s_nop 1
	v_addc_co_u32_e32 v53, vcc, 0, v23, vcc
	v_add_co_u32_e32 v54, vcc, s59, v22
	s_nop 1
	v_addc_co_u32_e32 v55, vcc, 0, v23, vcc
	v_add_co_u32_e32 v56, vcc, s60, v22
	s_nop 1
	v_addc_co_u32_e32 v57, vcc, 0, v23, vcc
	v_add_co_u32_e32 v58, vcc, s61, v22
	s_nop 1
	v_addc_co_u32_e32 v59, vcc, 0, v23, vcc
	global_load_dword v74, v[24:25], off
	global_load_dword v75, v[46:47], off
	global_load_dword v76, v[48:49], off
	global_load_dword v77, v[50:51], off
	global_load_dword v78, v[52:53], off
	global_load_dword v79, v[54:55], off
	global_load_dword v81, v[56:57], off
	s_nop 0
	global_load_dword v58, v[58:59], off
	v_add_co_u32_e32 v24, vcc, s62, v22
	s_nop 1
	v_addc_co_u32_e32 v25, vcc, 0, v23, vcc
	v_add_co_u32_e32 v46, vcc, s63, v22
	s_nop 1
	v_addc_co_u32_e32 v47, vcc, 0, v23, vcc
	v_add_co_u32_e32 v48, vcc, s64, v22
	s_nop 1
	v_addc_co_u32_e32 v49, vcc, 0, v23, vcc
	v_add_co_u32_e32 v50, vcc, s65, v22
	s_nop 1
	v_addc_co_u32_e32 v51, vcc, 0, v23, vcc
	v_add_co_u32_e32 v52, vcc, s66, v22
	s_nop 1
	v_addc_co_u32_e32 v53, vcc, 0, v23, vcc
	v_add_co_u32_e32 v54, vcc, s67, v22
	s_nop 1
	v_addc_co_u32_e32 v55, vcc, 0, v23, vcc
	v_add_co_u32_e32 v56, vcc, s68, v22
	s_nop 1
	v_addc_co_u32_e32 v57, vcc, 0, v23, vcc
	v_add_co_u32_e32 v22, vcc, s69, v22
	s_nop 1
	v_addc_co_u32_e32 v23, vcc, 0, v23, vcc
	global_load_dword v24, v[24:25], off
	s_nop 0
	global_load_dword v25, v[46:47], off
	s_nop 0
	global_load_dword v46, v[48:49], off
	global_load_dword v47, v[50:51], off
	s_nop 0
	global_load_dword v48, v[52:53], off
	global_load_dword v49, v[54:55], off
	global_load_dword v50, v[56:57], off
	s_nop 0
	global_load_dword v22, v[22:23], off
	s_waitcnt vmcnt(30)
	ds_write2_b32 v34, v19, v45 offset1:66
	s_waitcnt vmcnt(28)
	ds_write2_b32 v34, v60, v61 offset0:132 offset1:198
	s_waitcnt vmcnt(26)
	ds_write2_b32 v35, v62, v63 offset0:8 offset1:74
	s_waitcnt vmcnt(24)
	ds_write2_b32 v35, v64, v65 offset0:140 offset1:206
	s_waitcnt vmcnt(22)
	ds_write2_b32 v36, v66, v67 offset0:16 offset1:82
	s_waitcnt vmcnt(20)
	ds_write2_b32 v36, v68, v69 offset0:148 offset1:214
	s_waitcnt vmcnt(18)
	ds_write2_b32 v37, v70, v71 offset0:24 offset1:90
	s_waitcnt vmcnt(16)
	ds_write2_b32 v37, v72, v73 offset0:156 offset1:222
	s_waitcnt vmcnt(14)
	ds_write2_b32 v38, v74, v75 offset0:32 offset1:98
	s_waitcnt vmcnt(12)
	ds_write2_b32 v38, v76, v77 offset0:164 offset1:230
	s_waitcnt vmcnt(10)
	ds_write2_b32 v39, v78, v79 offset0:40 offset1:106
	s_waitcnt vmcnt(8)
	ds_write2_b32 v39, v81, v58 offset0:172 offset1:238
	s_waitcnt vmcnt(6)
	ds_write2_b32 v40, v24, v25 offset0:48 offset1:114
	s_waitcnt vmcnt(4)
	ds_write2_b32 v40, v46, v47 offset0:180 offset1:246
	s_waitcnt vmcnt(2)
	ds_write2_b32 v41, v48, v49 offset0:56 offset1:122
	s_waitcnt vmcnt(0)
	ds_write2_b32 v41, v50, v22 offset0:188 offset1:254
	s_waitcnt lgkmcnt(0)
	ds_read2_b32 v[24:25], v42 offset1:8
	ds_read2_b32 v[48:49], v42 offset0:33 offset1:41
	ds_read2_b32 v[50:51], v42 offset0:66 offset1:74
	v_lshlrev_b32_e32 v22, 1, v15
	v_mov_b32_e32 v23, v3
	ds_read2_b32 v[52:53], v42 offset0:99 offset1:107
	v_lshl_add_u64 v[20:21], v[20:21], 0, v[22:23]
	v_mov_b32_e32 v19, v3
	s_waitcnt lgkmcnt(3)
	v_bfe_u32 v15, v24, 16, 1
	v_lshl_add_u64 v[46:47], v[20:21], 0, v[18:19]
	v_add3_u32 v15, v24, v15, s70
	s_waitcnt lgkmcnt(2)
	v_bfe_u32 v19, v48, 16, 1
	ds_read2_b32 v[54:55], v42 offset0:132 offset1:140
	v_lshrrev_b32_e32 v15, 16, v15
	v_add3_u32 v19, v48, v19, s70
	ds_read2_b32 v[56:57], v42 offset0:165 offset1:173
	v_and_or_b32 v20, v19, s71, v15
	s_waitcnt lgkmcnt(3)
	v_bfe_u32 v15, v50, 16, 1
	v_add3_u32 v15, v50, v15, s70
	s_waitcnt lgkmcnt(2)
	v_bfe_u32 v19, v52, 16, 1
	ds_read2_b32 v[58:59], v42 offset0:198 offset1:206
	v_lshrrev_b32_e32 v15, 16, v15
	v_add3_u32 v19, v52, v19, s70
	ds_read2_b32 v[60:61], v42 offset0:231 offset1:239
	v_and_or_b32 v21, v19, s71, v15
	s_waitcnt lgkmcnt(3)
	v_bfe_u32 v15, v54, 16, 1
	v_add3_u32 v15, v54, v15, s70
	s_waitcnt lgkmcnt(2)
	v_bfe_u32 v19, v56, 16, 1
	v_lshrrev_b32_e32 v15, 16, v15
	v_add3_u32 v19, v56, v19, s70
	v_and_or_b32 v22, v19, s71, v15
	s_waitcnt lgkmcnt(1)
	v_bfe_u32 v15, v58, 16, 1
	v_add3_u32 v15, v58, v15, s70
	s_waitcnt lgkmcnt(0)
	v_bfe_u32 v19, v60, 16, 1
	v_lshrrev_b32_e32 v15, 16, v15
	v_add3_u32 v19, v60, v19, s70
	v_and_or_b32 v23, v19, s71, v15
	v_or_b32_e32 v15, v17, v28
	v_lshlrev_b32_e32 v62, 11, v15
	v_bfe_u32 v15, v25, 16, 1
	v_mov_b32_e32 v63, v3
	v_add3_u32 v15, v25, v15, s70
	v_bfe_u32 v19, v49, 16, 1
	v_lshl_add_u64 v[62:63], v[46:47], 0, v[62:63]
	v_lshrrev_b32_e32 v15, 16, v15
	v_add3_u32 v19, v49, v19, s70
	global_store_dwordx4 v[62:63], v[20:23], off
	v_mov_b32_e32 v25, v3
	ds_read2_b32 v[48:49], v42 offset0:16 offset1:24
	v_and_or_b32 v20, v19, s71, v15
	v_bfe_u32 v15, v51, 16, 1
	v_add3_u32 v15, v51, v15, s70
	v_bfe_u32 v19, v53, 16, 1
	v_lshrrev_b32_e32 v15, 16, v15
	v_add3_u32 v19, v53, v19, s70
	v_and_or_b32 v21, v19, s71, v15
	v_bfe_u32 v15, v55, 16, 1
	v_add3_u32 v15, v55, v15, s70
	v_bfe_u32 v19, v57, 16, 1
	v_lshrrev_b32_e32 v15, 16, v15
	v_add3_u32 v19, v57, v19, s70
	v_and_or_b32 v22, v19, s71, v15
	v_bfe_u32 v15, v59, 16, 1
	v_add3_u32 v15, v59, v15, s70
	v_bfe_u32 v19, v61, 16, 1
	v_lshrrev_b32_e32 v15, 16, v15
	v_add3_u32 v19, v61, v19, s70
	v_and_or_b32 v23, v19, s71, v15
	v_or_b32_e32 v15, v17, v29
	v_lshlrev_b32_e32 v24, 11, v15
	v_lshl_add_u64 v[24:25], v[46:47], 0, v[24:25]
	global_store_dwordx4 v[24:25], v[20:23], off
	ds_read2_b32 v[24:25], v42 offset0:49 offset1:57
	ds_read2_b32 v[50:51], v42 offset0:82 offset1:90
	ds_read2_b32 v[52:53], v42 offset0:115 offset1:123
	s_waitcnt lgkmcnt(3)
	v_bfe_u32 v15, v48, 16, 1
	v_add3_u32 v15, v48, v15, s70
	s_waitcnt lgkmcnt(2)
	v_bfe_u32 v19, v24, 16, 1
	ds_read2_b32 v[54:55], v42 offset0:148 offset1:156
	v_lshrrev_b32_e32 v15, 16, v15
	v_add3_u32 v19, v24, v19, s70
	ds_read2_b32 v[56:57], v42 offset0:181 offset1:189
	v_and_or_b32 v20, v19, s71, v15
	s_waitcnt lgkmcnt(3)
	v_bfe_u32 v15, v50, 16, 1
	v_add3_u32 v15, v50, v15, s70
	s_waitcnt lgkmcnt(2)
	v_bfe_u32 v19, v52, 16, 1
	ds_read2_b32 v[58:59], v42 offset0:214 offset1:222
	v_lshrrev_b32_e32 v15, 16, v15
	v_add3_u32 v19, v52, v19, s70
	ds_read2_b32 v[60:61], v42 offset0:247 offset1:255
	v_and_or_b32 v21, v19, s71, v15
	s_waitcnt lgkmcnt(3)
	v_bfe_u32 v15, v54, 16, 1
	v_add3_u32 v15, v54, v15, s70
	s_waitcnt lgkmcnt(2)
	v_bfe_u32 v19, v56, 16, 1
	v_lshrrev_b32_e32 v15, 16, v15
	v_add3_u32 v19, v56, v19, s70
	v_and_or_b32 v22, v19, s71, v15
	s_waitcnt lgkmcnt(1)
	v_bfe_u32 v15, v58, 16, 1
	v_add3_u32 v15, v58, v15, s70
	s_waitcnt lgkmcnt(0)
	v_bfe_u32 v19, v60, 16, 1
	v_lshrrev_b32_e32 v15, 16, v15
	v_add3_u32 v19, v60, v19, s70
	v_and_or_b32 v23, v19, s71, v15
	v_or_b32_e32 v15, v17, v30
	v_lshlrev_b32_e32 v62, 11, v15
	v_bfe_u32 v15, v49, 16, 1
	v_mov_b32_e32 v63, v3
	v_add3_u32 v15, v49, v15, s70
	v_bfe_u32 v19, v25, 16, 1
	v_lshl_add_u64 v[62:63], v[46:47], 0, v[62:63]
	v_lshrrev_b32_e32 v15, 16, v15
	v_add3_u32 v19, v25, v19, s70
	global_store_dwordx4 v[62:63], v[20:23], off
	v_mov_b32_e32 v25, v3
	s_nop 0
	v_and_or_b32 v20, v19, s71, v15
	v_bfe_u32 v15, v51, 16, 1
	v_add3_u32 v15, v51, v15, s70
	v_bfe_u32 v19, v53, 16, 1
	v_lshrrev_b32_e32 v15, 16, v15
	v_add3_u32 v19, v53, v19, s70
	v_and_or_b32 v21, v19, s71, v15
	v_bfe_u32 v15, v55, 16, 1
	v_add3_u32 v15, v55, v15, s70
	v_bfe_u32 v19, v57, 16, 1
	v_lshrrev_b32_e32 v15, 16, v15
	v_add3_u32 v19, v57, v19, s70
	v_and_or_b32 v22, v19, s71, v15
	v_bfe_u32 v15, v59, 16, 1
	v_add3_u32 v15, v59, v15, s70
	v_bfe_u32 v19, v61, 16, 1
	v_lshrrev_b32_e32 v15, 16, v15
	v_add3_u32 v19, v61, v19, s70
	v_and_or_b32 v23, v19, s71, v15
	v_or_b32_e32 v15, v17, v31
	v_lshlrev_b32_e32 v24, 11, v15
	v_lshl_add_u64 v[24:25], v[46:47], 0, v[24:25]
	global_store_dwordx4 v[24:25], v[20:23], off
	s_waitcnt lgkmcnt(0)

.LBB0_58:
	s_andn2_saveexec_b64 s[26:27], s[26:27]
	s_cbranch_execz .LBB0_60
	v_add_u32_e32 v15, 0xfffff300, v26
	v_lshrrev_b32_e32 v20, 11, v15
	v_mov_b32_e32 v21, v3
	v_readlane_b32 s72, v246, 42
	v_lshlrev_b64 v[22:23], 24, v[20:21]
	v_readlane_b32 s73, v246, 43
	v_lshrrev_b32_e32 v15, 1, v15
	v_and_b32_e32 v17, 0xfe0, v33
	v_lshl_add_u64 v[22:23], s[72:73], 0, v[22:23]
	v_and_b32_e32 v15, 0x3c0, v15
	v_and_b32_e32 v24, 0x60, v17
	v_and_b32_e32 v25, 0x80, v17
	v_lshlrev_b32_e32 v24, 1, v24
	v_lshrrev_b32_e32 v25, 2, v25
	v_or_b32_e32 v24, v24, v25
	v_and_b32_e32 v25, 0xffffff1f, v17
	v_or_b32_e32 v24, v24, v25
	v_lshlrev_b32_e32 v24, 2, v24
	v_mov_b32_e32 v25, v3
	v_or_b32_e32 v19, v15, v27
	v_lshl_add_u64 v[22:23], v[22:23], 0, v[24:25]
	v_lshl_add_u64 v[22:23], v[22:23], 0, v[2:3]
	v_lshlrev_b32_e32 v24, 14, v19
	v_lshl_add_u64 v[22:23], v[22:23], 0, v[24:25]
	v_add_co_u32_e32 v24, vcc, s41, v22
	s_mov_b32 s28, 0x40000
	s_nop 0
	v_addc_co_u32_e32 v25, vcc, 0, v23, vcc
	v_add_co_u32_e32 v46, vcc, s45, v22
	v_lshlrev_b64 v[20:21], 23, v[20:21]
	s_nop 0
	v_addc_co_u32_e32 v47, vcc, 0, v23, vcc
	v_add_co_u32_e32 v48, vcc, s49, v22
	v_lshl_add_u64 v[20:21], s[12:13], 0, v[20:21]
	s_nop 0
	v_addc_co_u32_e32 v49, vcc, 0, v23, vcc
	v_add_co_u32_e32 v50, vcc, s54, v22
	v_readlane_b32 s72, v246, 58
	s_nop 0
	v_addc_co_u32_e32 v51, vcc, 0, v23, vcc
	v_add_co_u32_e32 v52, vcc, s58, v22
	v_readlane_b32 s74, v246, 44
	s_nop 0
	v_addc_co_u32_e32 v53, vcc, 0, v23, vcc
	v_add_co_u32_e32 v54, vcc, s62, v22
	v_readlane_b32 s75, v246, 45
	s_nop 0
	v_addc_co_u32_e32 v55, vcc, 0, v23, vcc
	v_add_co_u32_e32 v56, vcc, s66, v22
	v_readlane_b32 s76, v246, 46
	s_nop 0
	v_addc_co_u32_e32 v57, vcc, 0, v23, vcc
	global_load_dword v19, v[22:23], off
	global_load_dword v45, v[24:25], off
	global_load_dword v60, v[46:47], off
	global_load_dword v61, v[48:49], off
	global_load_dword v62, v[50:51], off
	global_load_dword v63, v[52:53], off
	global_load_dword v64, v[54:55], off
	global_load_dword v65, v[56:57], off
	v_add_co_u32_e32 v24, vcc, s28, v22
	s_mov_b32 s28, 0x48000
	s_nop 0
	v_addc_co_u32_e32 v25, vcc, 0, v23, vcc
	v_add_co_u32_e32 v46, vcc, s28, v22
	s_mov_b32 s28, 0x50000
	s_nop 0
	v_addc_co_u32_e32 v47, vcc, 0, v23, vcc
	v_add_co_u32_e32 v48, vcc, s28, v22
	s_mov_b32 s28, 0x58000
	s_nop 0
	v_addc_co_u32_e32 v49, vcc, 0, v23, vcc
	v_add_co_u32_e32 v50, vcc, s28, v22
	s_mov_b32 s28, 0x60000
	s_nop 0
	v_addc_co_u32_e32 v51, vcc, 0, v23, vcc
	v_add_co_u32_e32 v52, vcc, s28, v22
	s_mov_b32 s28, 0x68000
	s_nop 0
	v_addc_co_u32_e32 v53, vcc, 0, v23, vcc
	v_add_co_u32_e32 v54, vcc, s28, v22
	s_mov_b32 s28, 0x70000
	s_nop 0
	v_addc_co_u32_e32 v55, vcc, 0, v23, vcc
	v_add_co_u32_e32 v56, vcc, s28, v22
	s_mov_b32 s28, 0x78000
	s_nop 0
	v_addc_co_u32_e32 v57, vcc, 0, v23, vcc
	v_add_co_u32_e32 v58, vcc, s28, v22
	s_mov_b32 s28, 0x80000
	s_nop 0
	v_addc_co_u32_e32 v59, vcc, 0, v23, vcc
	global_load_dword v66, v[24:25], off
	global_load_dword v67, v[46:47], off
	global_load_dword v68, v[48:49], off
	global_load_dword v69, v[50:51], off
	global_load_dword v70, v[52:53], off
	global_load_dword v71, v[54:55], off
	global_load_dword v72, v[56:57], off
	global_load_dword v73, v[58:59], off
	v_add_co_u32_e32 v24, vcc, s28, v22
	s_mov_b32 s28, 0x90000
	s_nop 0
	v_addc_co_u32_e32 v25, vcc, 0, v23, vcc
	v_add_co_u32_e32 v46, vcc, s94, v22
	v_readlane_b32 s77, v246, 47
	s_nop 0
	v_addc_co_u32_e32 v47, vcc, 0, v23, vcc
	v_add_co_u32_e32 v48, vcc, s28, v22
	s_mov_b32 s28, 0x98000
	s_nop 0
	v_addc_co_u32_e32 v49, vcc, 0, v23, vcc
	v_add_co_u32_e32 v50, vcc, s28, v22
	s_mov_b32 s28, 0xa0000
	s_nop 0
	v_addc_co_u32_e32 v51, vcc, 0, v23, vcc
	v_add_co_u32_e32 v52, vcc, s28, v22
	s_mov_b32 s28, 0xa8000
	s_nop 0
	v_addc_co_u32_e32 v53, vcc, 0, v23, vcc
	v_add_co_u32_e32 v54, vcc, s28, v22
	s_mov_b32 s28, 0xb0000
	s_nop 0
	v_addc_co_u32_e32 v55, vcc, 0, v23, vcc
	v_add_co_u32_e32 v56, vcc, s28, v22
	s_mov_b32 s28, 0xb8000
	s_nop 0
	v_addc_co_u32_e32 v57, vcc, 0, v23, vcc
	v_add_co_u32_e32 v58, vcc, s28, v22
	s_mov_b32 s28, 0xc0000
	s_nop 0
	v_addc_co_u32_e32 v59, vcc, 0, v23, vcc
	global_load_dword v74, v[24:25], off
	global_load_dword v75, v[46:47], off
	global_load_dword v76, v[48:49], off
	global_load_dword v77, v[50:51], off
	global_load_dword v78, v[52:53], off
	global_load_dword v79, v[54:55], off
	global_load_dword v81, v[56:57], off
	s_nop 0
	global_load_dword v58, v[58:59], off
	v_add_co_u32_e32 v24, vcc, s28, v22
	v_readlane_b32 s78, v246, 48
	s_nop 0
	v_addc_co_u32_e32 v25, vcc, 0, v23, vcc
	v_add_co_u32_e32 v46, vcc, s95, v22
	v_readlane_b32 s79, v246, 49
	s_nop 0
	v_addc_co_u32_e32 v47, vcc, 0, v23, vcc
	v_add_co_u32_e32 v48, vcc, s93, v22
	v_readlane_b32 s80, v246, 50
	s_nop 0
	v_addc_co_u32_e32 v49, vcc, 0, v23, vcc
	v_add_co_u32_e32 v50, vcc, s2, v22
	v_readlane_b32 s81, v246, 51
	s_nop 0
	v_addc_co_u32_e32 v51, vcc, 0, v23, vcc
	v_add_co_u32_e32 v52, vcc, s35, v22
	v_readlane_b32 s82, v246, 52
	s_nop 0
	v_addc_co_u32_e32 v53, vcc, 0, v23, vcc
	v_add_co_u32_e32 v54, vcc, s96, v22
	v_readlane_b32 s83, v246, 53
	s_nop 0
	v_addc_co_u32_e32 v55, vcc, 0, v23, vcc
	v_add_co_u32_e32 v56, vcc, s97, v22
	v_readlane_b32 s84, v246, 54
	s_nop 0
	v_addc_co_u32_e32 v57, vcc, 0, v23, vcc
	v_add_co_u32_e32 v22, vcc, s34, v22
	v_readlane_b32 s85, v246, 55
	s_nop 0
	v_addc_co_u32_e32 v23, vcc, 0, v23, vcc
	global_load_dword v24, v[24:25], off
	s_nop 0
	global_load_dword v25, v[46:47], off
	s_nop 0
	global_load_dword v46, v[48:49], off
	global_load_dword v47, v[50:51], off
	s_nop 0
	global_load_dword v48, v[52:53], off
	global_load_dword v49, v[54:55], off
	global_load_dword v50, v[56:57], off
	s_nop 0
	global_load_dword v22, v[22:23], off
	s_waitcnt vmcnt(30)
	ds_write2_b32 v34, v19, v45 offset1:66
	s_waitcnt vmcnt(28)
	ds_write2_b32 v34, v60, v61 offset0:132 offset1:198
	s_waitcnt vmcnt(26)
	ds_write2_b32 v35, v62, v63 offset0:8 offset1:74
	s_waitcnt vmcnt(24)
	ds_write2_b32 v35, v64, v65 offset0:140 offset1:206
	s_waitcnt vmcnt(22)
	ds_write2_b32 v36, v66, v67 offset0:16 offset1:82
	s_waitcnt vmcnt(20)
	ds_write2_b32 v36, v68, v69 offset0:148 offset1:214
	s_waitcnt vmcnt(18)
	ds_write2_b32 v37, v70, v71 offset0:24 offset1:90
	s_waitcnt vmcnt(16)
	ds_write2_b32 v37, v72, v73 offset0:156 offset1:222
	s_waitcnt vmcnt(14)
	ds_write2_b32 v38, v74, v75 offset0:32 offset1:98
	s_waitcnt vmcnt(12)
	ds_write2_b32 v38, v76, v77 offset0:164 offset1:230
	s_waitcnt vmcnt(10)
	ds_write2_b32 v39, v78, v79 offset0:40 offset1:106
	s_waitcnt vmcnt(8)
	ds_write2_b32 v39, v81, v58 offset0:172 offset1:238
	s_waitcnt vmcnt(6)
	ds_write2_b32 v40, v24, v25 offset0:48 offset1:114
	s_waitcnt vmcnt(4)
	ds_write2_b32 v40, v46, v47 offset0:180 offset1:246
	s_waitcnt vmcnt(2)
	ds_write2_b32 v41, v48, v49 offset0:56 offset1:122
	s_waitcnt vmcnt(0)
	ds_write2_b32 v41, v50, v22 offset0:188 offset1:254
	s_waitcnt lgkmcnt(0)
	ds_read2_b32 v[24:25], v42 offset1:8
	ds_read2_b32 v[48:49], v42 offset0:33 offset1:41
	ds_read2_b32 v[50:51], v42 offset0:66 offset1:74
	v_lshlrev_b32_e32 v22, 1, v15
	v_mov_b32_e32 v23, v3
	ds_read2_b32 v[52:53], v42 offset0:99 offset1:107
	v_lshl_add_u64 v[20:21], v[20:21], 0, v[22:23]
	v_mov_b32_e32 v19, v3
	s_waitcnt lgkmcnt(3)
	v_bfe_u32 v15, v24, 16, 1
	v_lshl_add_u64 v[46:47], v[20:21], 0, v[18:19]
	v_add3_u32 v15, v24, v15, s70
	s_waitcnt lgkmcnt(2)
	v_bfe_u32 v19, v48, 16, 1
	ds_read2_b32 v[54:55], v42 offset0:132 offset1:140
	v_lshrrev_b32_e32 v15, 16, v15
	v_add3_u32 v19, v48, v19, s70
	ds_read2_b32 v[56:57], v42 offset0:165 offset1:173
	v_and_or_b32 v20, v19, s71, v15
	s_waitcnt lgkmcnt(3)
	v_bfe_u32 v15, v50, 16, 1
	v_add3_u32 v15, v50, v15, s70
	s_waitcnt lgkmcnt(2)
	v_bfe_u32 v19, v52, 16, 1
	ds_read2_b32 v[58:59], v42 offset0:198 offset1:206
	v_lshrrev_b32_e32 v15, 16, v15
	v_add3_u32 v19, v52, v19, s70
	ds_read2_b32 v[60:61], v42 offset0:231 offset1:239
	v_and_or_b32 v21, v19, s71, v15
	s_waitcnt lgkmcnt(3)
	v_bfe_u32 v15, v54, 16, 1
	v_add3_u32 v15, v54, v15, s70
	s_waitcnt lgkmcnt(2)
	v_bfe_u32 v19, v56, 16, 1
	v_lshrrev_b32_e32 v15, 16, v15
	v_add3_u32 v19, v56, v19, s70
	v_and_or_b32 v22, v19, s71, v15
	s_waitcnt lgkmcnt(1)
	v_bfe_u32 v15, v58, 16, 1
	v_add3_u32 v15, v58, v15, s70
	s_waitcnt lgkmcnt(0)
	v_bfe_u32 v19, v60, 16, 1
	v_lshrrev_b32_e32 v15, 16, v15
	v_add3_u32 v19, v60, v19, s70
	v_and_or_b32 v23, v19, s71, v15
	v_or_b32_e32 v15, v17, v28
	v_lshlrev_b32_e32 v62, 11, v15
	v_bfe_u32 v15, v25, 16, 1
	v_mov_b32_e32 v63, v3
	v_add3_u32 v15, v25, v15, s70
	v_bfe_u32 v19, v49, 16, 1
	v_lshl_add_u64 v[62:63], v[46:47], 0, v[62:63]
	v_lshrrev_b32_e32 v15, 16, v15
	v_add3_u32 v19, v49, v19, s70
	global_store_dwordx4 v[62:63], v[20:23], off
	v_mov_b32_e32 v25, v3
	ds_read2_b32 v[48:49], v42 offset0:16 offset1:24
	v_and_or_b32 v20, v19, s71, v15
	v_bfe_u32 v15, v51, 16, 1
	v_add3_u32 v15, v51, v15, s70
	v_bfe_u32 v19, v53, 16, 1
	v_lshrrev_b32_e32 v15, 16, v15
	v_add3_u32 v19, v53, v19, s70
	v_and_or_b32 v21, v19, s71, v15
	v_bfe_u32 v15, v55, 16, 1
	v_add3_u32 v15, v55, v15, s70
	v_bfe_u32 v19, v57, 16, 1
	v_lshrrev_b32_e32 v15, 16, v15
	v_add3_u32 v19, v57, v19, s70
	v_and_or_b32 v22, v19, s71, v15
	v_bfe_u32 v15, v59, 16, 1
	v_add3_u32 v15, v59, v15, s70
	v_bfe_u32 v19, v61, 16, 1
	v_lshrrev_b32_e32 v15, 16, v15
	v_add3_u32 v19, v61, v19, s70
	v_and_or_b32 v23, v19, s71, v15
	v_or_b32_e32 v15, v17, v29
	v_lshlrev_b32_e32 v24, 11, v15
	v_lshl_add_u64 v[24:25], v[46:47], 0, v[24:25]
	global_store_dwordx4 v[24:25], v[20:23], off
	ds_read2_b32 v[24:25], v42 offset0:49 offset1:57
	ds_read2_b32 v[50:51], v42 offset0:82 offset1:90
	ds_read2_b32 v[52:53], v42 offset0:115 offset1:123
	s_waitcnt lgkmcnt(3)
	v_bfe_u32 v15, v48, 16, 1
	v_add3_u32 v15, v48, v15, s70
	s_waitcnt lgkmcnt(2)
	v_bfe_u32 v19, v24, 16, 1
	ds_read2_b32 v[54:55], v42 offset0:148 offset1:156
	v_lshrrev_b32_e32 v15, 16, v15
	v_add3_u32 v19, v24, v19, s70
	ds_read2_b32 v[56:57], v42 offset0:181 offset1:189
	v_and_or_b32 v20, v19, s71, v15
	s_waitcnt lgkmcnt(3)
	v_bfe_u32 v15, v50, 16, 1
	v_add3_u32 v15, v50, v15, s70
	s_waitcnt lgkmcnt(2)
	v_bfe_u32 v19, v52, 16, 1
	ds_read2_b32 v[58:59], v42 offset0:214 offset1:222
	v_lshrrev_b32_e32 v15, 16, v15
	v_add3_u32 v19, v52, v19, s70
	ds_read2_b32 v[60:61], v42 offset0:247 offset1:255
	v_and_or_b32 v21, v19, s71, v15
	s_waitcnt lgkmcnt(3)
	v_bfe_u32 v15, v54, 16, 1
	v_add3_u32 v15, v54, v15, s70
	s_waitcnt lgkmcnt(2)
	v_bfe_u32 v19, v56, 16, 1
	v_lshrrev_b32_e32 v15, 16, v15
	v_add3_u32 v19, v56, v19, s70
	v_and_or_b32 v22, v19, s71, v15
	s_waitcnt lgkmcnt(1)
	v_bfe_u32 v15, v58, 16, 1
	v_add3_u32 v15, v58, v15, s70
	s_waitcnt lgkmcnt(0)
	v_bfe_u32 v19, v60, 16, 1
	v_lshrrev_b32_e32 v15, 16, v15
	v_add3_u32 v19, v60, v19, s70
	v_and_or_b32 v23, v19, s71, v15
	v_or_b32_e32 v15, v17, v30
	v_lshlrev_b32_e32 v62, 11, v15
	v_bfe_u32 v15, v49, 16, 1
	v_mov_b32_e32 v63, v3
	v_add3_u32 v15, v49, v15, s70
	v_bfe_u32 v19, v25, 16, 1
	v_lshl_add_u64 v[62:63], v[46:47], 0, v[62:63]
	v_lshrrev_b32_e32 v15, 16, v15
	v_add3_u32 v19, v25, v19, s70
	global_store_dwordx4 v[62:63], v[20:23], off
	v_mov_b32_e32 v25, v3
	v_readlane_b32 s86, v246, 56
	v_and_or_b32 v20, v19, s71, v15
	v_bfe_u32 v15, v51, 16, 1
	v_add3_u32 v15, v51, v15, s70
	v_bfe_u32 v19, v53, 16, 1
	v_lshrrev_b32_e32 v15, 16, v15
	v_add3_u32 v19, v53, v19, s70
	v_and_or_b32 v21, v19, s71, v15
	v_bfe_u32 v15, v55, 16, 1
	v_add3_u32 v15, v55, v15, s70
	v_bfe_u32 v19, v57, 16, 1
	v_lshrrev_b32_e32 v15, 16, v15
	v_add3_u32 v19, v57, v19, s70
	v_and_or_b32 v22, v19, s71, v15
	v_bfe_u32 v15, v59, 16, 1
	v_add3_u32 v15, v59, v15, s70
	v_bfe_u32 v19, v61, 16, 1
	v_lshrrev_b32_e32 v15, 16, v15
	v_add3_u32 v19, v61, v19, s70
	v_and_or_b32 v23, v19, s71, v15
	v_or_b32_e32 v15, v17, v31
	v_lshlrev_b32_e32 v24, 11, v15
	v_lshl_add_u64 v[24:25], v[46:47], 0, v[24:25]
	global_store_dwordx4 v[24:25], v[20:23], off
	s_waitcnt lgkmcnt(0)
	v_readlane_b32 s87, v246, 57

.LBB0_64:
	s_andn2_saveexec_b64 s[22:23], s[22:23]
	s_cbranch_execz .LBB0_66
	v_add_u32_e32 v15, 0xfffff800, v26
	v_lshrrev_b32_e32 v20, 9, v15
	v_mov_b32_e32 v21, v3
	v_readlane_b32 s76, v246, 26
	v_lshlrev_b64 v[22:23], 22, v[20:21]
	v_readlane_b32 s90, v246, 40
	v_readlane_b32 s91, v246, 41
	v_and_b32_e32 v17, 0x3e0, v33
	v_and_b32_e32 v15, 0x3c0, v32
	v_lshl_add_u64 v[22:23], s[90:91], 0, v[22:23]
	v_and_b32_e32 v24, 0x60, v17
	v_and_b32_e32 v25, 0x80, v17
	v_lshlrev_b32_e32 v24, 1, v24
	v_lshrrev_b32_e32 v25, 2, v25
	v_or_b32_e32 v24, v24, v25
	v_and_b32_e32 v25, 0xffffff1f, v17
	v_or_b32_e32 v24, v24, v25
	v_cmp_eq_u32_e32 vcc, 1, v20
	s_nop 1
	v_cndmask_b32_e32 v24, v17, v24, vcc
	v_lshlrev_b32_e32 v24, 2, v24
	v_mov_b32_e32 v25, v3
	v_or_b32_e32 v19, v15, v27
	v_lshl_add_u64 v[22:23], v[22:23], 0, v[24:25]
	v_lshl_add_u64 v[22:23], v[22:23], 0, v[2:3]
	v_lshlrev_b32_e32 v24, 12, v19
	v_lshl_add_u64 v[22:23], v[22:23], 0, v[24:25]
	v_add_co_u32_e32 v24, vcc, s38, v22
	v_lshlrev_b64 v[20:21], 21, v[20:21]
	s_nop 0
	v_addc_co_u32_e32 v25, vcc, 0, v23, vcc
	v_add_co_u32_e32 v46, vcc, s39, v22
	v_lshl_add_u64 v[20:21], s[14:15], 0, v[20:21]
	s_nop 0
	v_addc_co_u32_e32 v47, vcc, 0, v23, vcc
	v_add_co_u32_e32 v48, vcc, s40, v22
	v_readlane_b32 s77, v246, 27
	s_nop 0
	v_addc_co_u32_e32 v49, vcc, 0, v23, vcc
	v_add_co_u32_e32 v50, vcc, s41, v22
	v_readlane_b32 s78, v246, 28
	s_nop 0
	v_addc_co_u32_e32 v51, vcc, 0, v23, vcc
	v_add_co_u32_e32 v52, vcc, s42, v22
	v_readlane_b32 s79, v246, 29
	s_nop 0
	v_addc_co_u32_e32 v53, vcc, 0, v23, vcc
	v_add_co_u32_e32 v54, vcc, s43, v22
	v_readlane_b32 s80, v246, 30
	s_nop 0
	v_addc_co_u32_e32 v55, vcc, 0, v23, vcc
	v_add_co_u32_e32 v56, vcc, s44, v22
	v_readlane_b32 s81, v246, 31
	s_nop 0
	v_addc_co_u32_e32 v57, vcc, 0, v23, vcc
	global_load_dword v19, v[22:23], off
	global_load_dword v45, v[24:25], off
	global_load_dword v60, v[46:47], off
	global_load_dword v61, v[48:49], off
	global_load_dword v62, v[50:51], off
	global_load_dword v63, v[52:53], off
	global_load_dword v64, v[54:55], off
	global_load_dword v65, v[56:57], off
	v_add_co_u32_e32 v24, vcc, s45, v22
	v_readlane_b32 s82, v246, 32
	s_nop 0
	v_addc_co_u32_e32 v25, vcc, 0, v23, vcc
	v_add_co_u32_e32 v46, vcc, s46, v22
	v_readlane_b32 s83, v246, 33
	s_nop 0
	v_addc_co_u32_e32 v47, vcc, 0, v23, vcc
	v_add_co_u32_e32 v48, vcc, s47, v22
	v_readlane_b32 s84, v246, 34
	s_nop 0
	v_addc_co_u32_e32 v49, vcc, 0, v23, vcc
	v_add_co_u32_e32 v50, vcc, s48, v22
	v_readlane_b32 s85, v246, 35
	s_nop 0
	v_addc_co_u32_e32 v51, vcc, 0, v23, vcc
	v_add_co_u32_e32 v52, vcc, s49, v22
	v_readlane_b32 s86, v246, 36
	s_nop 0
	v_addc_co_u32_e32 v53, vcc, 0, v23, vcc
	v_add_co_u32_e32 v54, vcc, s50, v22
	v_readlane_b32 s87, v246, 37
	s_nop 0
	v_addc_co_u32_e32 v55, vcc, 0, v23, vcc
	v_add_co_u32_e32 v56, vcc, s51, v22
	v_readlane_b32 s88, v246, 38
	s_nop 0
	v_addc_co_u32_e32 v57, vcc, 0, v23, vcc
	v_add_co_u32_e32 v58, vcc, s53, v22
	v_readlane_b32 s89, v246, 39
	s_nop 0
	v_addc_co_u32_e32 v59, vcc, 0, v23, vcc
	global_load_dword v66, v[24:25], off
	global_load_dword v67, v[46:47], off
	global_load_dword v68, v[48:49], off
	global_load_dword v69, v[50:51], off
	global_load_dword v70, v[52:53], off
	global_load_dword v71, v[54:55], off
	global_load_dword v72, v[56:57], off
	global_load_dword v73, v[58:59], off
	v_add_co_u32_e32 v24, vcc, s54, v22
	s_nop 1
	v_addc_co_u32_e32 v25, vcc, 0, v23, vcc
	v_add_co_u32_e32 v46, vcc, s55, v22
	s_nop 1
	v_addc_co_u32_e32 v47, vcc, 0, v23, vcc
	v_add_co_u32_e32 v48, vcc, s56, v22
	s_nop 1
	v_addc_co_u32_e32 v49, vcc, 0, v23, vcc
	v_add_co_u32_e32 v50, vcc, s57, v22
	s_nop 1
	v_addc_co_u32_e32 v51, vcc, 0, v23, vcc
	v_add_co_u32_e32 v52, vcc, s58, v22
	s_nop 1
	v_addc_co_u32_e32 v53, vcc, 0, v23, vcc
	v_add_co_u32_e32 v54, vcc, s59, v22
	s_nop 1
	v_addc_co_u32_e32 v55, vcc, 0, v23, vcc
	v_add_co_u32_e32 v56, vcc, s60, v22
	s_nop 1
	v_addc_co_u32_e32 v57, vcc, 0, v23, vcc
	v_add_co_u32_e32 v58, vcc, s61, v22
	s_nop 1
	v_addc_co_u32_e32 v59, vcc, 0, v23, vcc
	global_load_dword v74, v[24:25], off
	global_load_dword v75, v[46:47], off
	global_load_dword v76, v[48:49], off
	global_load_dword v77, v[50:51], off
	global_load_dword v78, v[52:53], off
	global_load_dword v79, v[54:55], off
	global_load_dword v81, v[56:57], off
	s_nop 0
	global_load_dword v58, v[58:59], off
	v_add_co_u32_e32 v24, vcc, s62, v22
	s_nop 1
	v_addc_co_u32_e32 v25, vcc, 0, v23, vcc
	v_add_co_u32_e32 v46, vcc, s63, v22
	s_nop 1
	v_addc_co_u32_e32 v47, vcc, 0, v23, vcc
	v_add_co_u32_e32 v48, vcc, s64, v22
	s_nop 1
	v_addc_co_u32_e32 v49, vcc, 0, v23, vcc
	v_add_co_u32_e32 v50, vcc, s65, v22
	s_nop 1
	v_addc_co_u32_e32 v51, vcc, 0, v23, vcc
	v_add_co_u32_e32 v52, vcc, s66, v22
	s_nop 1
	v_addc_co_u32_e32 v53, vcc, 0, v23, vcc
	v_add_co_u32_e32 v54, vcc, s67, v22
	s_nop 1
	v_addc_co_u32_e32 v55, vcc, 0, v23, vcc
	v_add_co_u32_e32 v56, vcc, s68, v22
	s_nop 1
	v_addc_co_u32_e32 v57, vcc, 0, v23, vcc
	v_add_co_u32_e32 v22, vcc, s69, v22
	s_nop 1
	v_addc_co_u32_e32 v23, vcc, 0, v23, vcc
	global_load_dword v24, v[24:25], off
	s_nop 0
	global_load_dword v25, v[46:47], off
	s_nop 0
	global_load_dword v46, v[48:49], off
	global_load_dword v47, v[50:51], off
	s_nop 0
	global_load_dword v48, v[52:53], off
	global_load_dword v49, v[54:55], off
	global_load_dword v50, v[56:57], off
	s_nop 0
	global_load_dword v22, v[22:23], off
	s_waitcnt vmcnt(30)
	ds_write2_b32 v34, v19, v45 offset1:66
	s_waitcnt vmcnt(28)
	ds_write2_b32 v34, v60, v61 offset0:132 offset1:198
	s_waitcnt vmcnt(26)
	ds_write2_b32 v35, v62, v63 offset0:8 offset1:74
	s_waitcnt vmcnt(24)
	ds_write2_b32 v35, v64, v65 offset0:140 offset1:206
	s_waitcnt vmcnt(22)
	ds_write2_b32 v36, v66, v67 offset0:16 offset1:82
	s_waitcnt vmcnt(20)
	ds_write2_b32 v36, v68, v69 offset0:148 offset1:214
	s_waitcnt vmcnt(18)
	ds_write2_b32 v37, v70, v71 offset0:24 offset1:90
	s_waitcnt vmcnt(16)
	ds_write2_b32 v37, v72, v73 offset0:156 offset1:222
	s_waitcnt vmcnt(14)
	ds_write2_b32 v38, v74, v75 offset0:32 offset1:98
	s_waitcnt vmcnt(12)
	ds_write2_b32 v38, v76, v77 offset0:164 offset1:230
	s_waitcnt vmcnt(10)
	ds_write2_b32 v39, v78, v79 offset0:40 offset1:106
	s_waitcnt vmcnt(8)
	ds_write2_b32 v39, v81, v58 offset0:172 offset1:238
	s_waitcnt vmcnt(6)
	ds_write2_b32 v40, v24, v25 offset0:48 offset1:114
	s_waitcnt vmcnt(4)
	ds_write2_b32 v40, v46, v47 offset0:180 offset1:246
	s_waitcnt vmcnt(2)
	ds_write2_b32 v41, v48, v49 offset0:56 offset1:122
	s_waitcnt vmcnt(0)
	ds_write2_b32 v41, v50, v22 offset0:188 offset1:254
	s_waitcnt lgkmcnt(0)
	ds_read2_b32 v[24:25], v42 offset1:8
	ds_read2_b32 v[48:49], v42 offset0:33 offset1:41
	ds_read2_b32 v[50:51], v42 offset0:66 offset1:74
	v_lshlrev_b32_e32 v22, 1, v15
	v_mov_b32_e32 v23, v3
	ds_read2_b32 v[52:53], v42 offset0:99 offset1:107
	v_lshl_add_u64 v[20:21], v[20:21], 0, v[22:23]
	v_mov_b32_e32 v19, v3
	s_waitcnt lgkmcnt(3)
	v_bfe_u32 v15, v24, 16, 1
	v_lshl_add_u64 v[46:47], v[20:21], 0, v[18:19]
	v_add3_u32 v15, v24, v15, s70
	s_waitcnt lgkmcnt(2)
	v_bfe_u32 v19, v48, 16, 1
	ds_read2_b32 v[54:55], v42 offset0:132 offset1:140
	v_lshrrev_b32_e32 v15, 16, v15
	v_add3_u32 v19, v48, v19, s70
	ds_read2_b32 v[56:57], v42 offset0:165 offset1:173
	v_and_or_b32 v20, v19, s71, v15
	s_waitcnt lgkmcnt(3)
	v_bfe_u32 v15, v50, 16, 1
	v_add3_u32 v15, v50, v15, s70
	s_waitcnt lgkmcnt(2)
	v_bfe_u32 v19, v52, 16, 1
	ds_read2_b32 v[58:59], v42 offset0:198 offset1:206
	v_lshrrev_b32_e32 v15, 16, v15
	v_add3_u32 v19, v52, v19, s70
	ds_read2_b32 v[60:61], v42 offset0:231 offset1:239
	v_and_or_b32 v21, v19, s71, v15
	s_waitcnt lgkmcnt(3)
	v_bfe_u32 v15, v54, 16, 1
	v_add3_u32 v15, v54, v15, s70
	s_waitcnt lgkmcnt(2)
	v_bfe_u32 v19, v56, 16, 1
	v_lshrrev_b32_e32 v15, 16, v15
	v_add3_u32 v19, v56, v19, s70
	v_and_or_b32 v22, v19, s71, v15
	s_waitcnt lgkmcnt(1)
	v_bfe_u32 v15, v58, 16, 1
	v_add3_u32 v15, v58, v15, s70
	s_waitcnt lgkmcnt(0)
	v_bfe_u32 v19, v60, 16, 1
	v_lshrrev_b32_e32 v15, 16, v15
	v_add3_u32 v19, v60, v19, s70
	v_and_or_b32 v23, v19, s71, v15
	v_or_b32_e32 v15, v17, v28
	v_lshlrev_b32_e32 v62, 11, v15
	v_bfe_u32 v15, v25, 16, 1
	v_mov_b32_e32 v63, v3
	v_add3_u32 v15, v25, v15, s70
	v_bfe_u32 v19, v49, 16, 1
	v_lshl_add_u64 v[62:63], v[46:47], 0, v[62:63]
	v_lshrrev_b32_e32 v15, 16, v15
	v_add3_u32 v19, v49, v19, s70
	global_store_dwordx4 v[62:63], v[20:23], off
	v_mov_b32_e32 v25, v3
	ds_read2_b32 v[48:49], v42 offset0:16 offset1:24
	v_and_or_b32 v20, v19, s71, v15
	v_bfe_u32 v15, v51, 16, 1
	v_add3_u32 v15, v51, v15, s70
	v_bfe_u32 v19, v53, 16, 1
	v_lshrrev_b32_e32 v15, 16, v15
	v_add3_u32 v19, v53, v19, s70
	v_and_or_b32 v21, v19, s71, v15
	v_bfe_u32 v15, v55, 16, 1
	v_add3_u32 v15, v55, v15, s70
	v_bfe_u32 v19, v57, 16, 1
	v_lshrrev_b32_e32 v15, 16, v15
	v_add3_u32 v19, v57, v19, s70
	v_and_or_b32 v22, v19, s71, v15
	v_bfe_u32 v15, v59, 16, 1
	v_add3_u32 v15, v59, v15, s70
	v_bfe_u32 v19, v61, 16, 1
	v_lshrrev_b32_e32 v15, 16, v15
	v_add3_u32 v19, v61, v19, s70
	v_and_or_b32 v23, v19, s71, v15
	v_or_b32_e32 v15, v17, v29
	v_lshlrev_b32_e32 v24, 11, v15
	v_lshl_add_u64 v[24:25], v[46:47], 0, v[24:25]
	global_store_dwordx4 v[24:25], v[20:23], off
	ds_read2_b32 v[24:25], v42 offset0:49 offset1:57
	ds_read2_b32 v[50:51], v42 offset0:82 offset1:90
	ds_read2_b32 v[52:53], v42 offset0:115 offset1:123
	s_waitcnt lgkmcnt(3)
	v_bfe_u32 v15, v48, 16, 1
	v_add3_u32 v15, v48, v15, s70
	s_waitcnt lgkmcnt(2)
	v_bfe_u32 v19, v24, 16, 1
	ds_read2_b32 v[54:55], v42 offset0:148 offset1:156
	v_lshrrev_b32_e32 v15, 16, v15
	v_add3_u32 v19, v24, v19, s70
	ds_read2_b32 v[56:57], v42 offset0:181 offset1:189
	v_and_or_b32 v20, v19, s71, v15
	s_waitcnt lgkmcnt(3)
	v_bfe_u32 v15, v50, 16, 1
	v_add3_u32 v15, v50, v15, s70
	s_waitcnt lgkmcnt(2)
	v_bfe_u32 v19, v52, 16, 1
	ds_read2_b32 v[58:59], v42 offset0:214 offset1:222
	v_lshrrev_b32_e32 v15, 16, v15
	v_add3_u32 v19, v52, v19, s70
	ds_read2_b32 v[60:61], v42 offset0:247 offset1:255
	v_and_or_b32 v21, v19, s71, v15
	s_waitcnt lgkmcnt(3)
	v_bfe_u32 v15, v54, 16, 1
	v_add3_u32 v15, v54, v15, s70
	s_waitcnt lgkmcnt(2)
	v_bfe_u32 v19, v56, 16, 1
	v_lshrrev_b32_e32 v15, 16, v15
	v_add3_u32 v19, v56, v19, s70
	v_and_or_b32 v22, v19, s71, v15
	s_waitcnt lgkmcnt(1)
	v_bfe_u32 v15, v58, 16, 1
	v_add3_u32 v15, v58, v15, s70
	s_waitcnt lgkmcnt(0)
	v_bfe_u32 v19, v60, 16, 1
	v_lshrrev_b32_e32 v15, 16, v15
	v_add3_u32 v19, v60, v19, s70
	v_and_or_b32 v23, v19, s71, v15
	v_or_b32_e32 v15, v17, v30
	v_lshlrev_b32_e32 v62, 11, v15
	v_bfe_u32 v15, v49, 16, 1
	v_mov_b32_e32 v63, v3
	v_add3_u32 v15, v49, v15, s70
	v_bfe_u32 v19, v25, 16, 1
	v_lshl_add_u64 v[62:63], v[46:47], 0, v[62:63]
	v_lshrrev_b32_e32 v15, 16, v15
	v_add3_u32 v19, v25, v19, s70
	global_store_dwordx4 v[62:63], v[20:23], off
	v_mov_b32_e32 v25, v3
	s_nop 0
	v_and_or_b32 v20, v19, s71, v15
	v_bfe_u32 v15, v51, 16, 1
	v_add3_u32 v15, v51, v15, s70
	v_bfe_u32 v19, v53, 16, 1
	v_lshrrev_b32_e32 v15, 16, v15
	v_add3_u32 v19, v53, v19, s70
	v_and_or_b32 v21, v19, s71, v15
	v_bfe_u32 v15, v55, 16, 1
	v_add3_u32 v15, v55, v15, s70
	v_bfe_u32 v19, v57, 16, 1
	v_lshrrev_b32_e32 v15, 16, v15
	v_add3_u32 v19, v57, v19, s70
	v_and_or_b32 v22, v19, s71, v15
	v_bfe_u32 v15, v59, 16, 1
	v_add3_u32 v15, v59, v15, s70
	v_bfe_u32 v19, v61, 16, 1
	v_lshrrev_b32_e32 v15, 16, v15
	v_add3_u32 v19, v61, v19, s70
	v_and_or_b32 v23, v19, s71, v15
	v_or_b32_e32 v15, v17, v31
	v_lshlrev_b32_e32 v24, 11, v15
	v_lshl_add_u64 v[24:25], v[46:47], 0, v[24:25]
	global_store_dwordx4 v[24:25], v[20:23], off
	s_waitcnt lgkmcnt(0)

.LBB0_261:
	s_lshl_b32 s4, s66, 10
	s_lshl_b64 s[18:19], s[4:5], 2
	v_readlane_b32 s4, v245, 0
	s_add_u32 s18, s4, s18
	v_readlane_b32 s4, v245, 1
	v_lshrrev_b32_e32 v17, 1, v16
	s_addc_u32 s19, s4, s19
	v_and_b32_e32 v211, 24, v17
	s_lshl_b32 s15, s15, 5
	v_and_b32_e32 v209, 15, v16
	v_lshlrev_b32_e32 v17, 1, v211
	v_lshlrev_b32_e32 v16, 2, v16
	s_and_b32 s43, s15, 0x60
	s_add_i32 m0, s39, 0x18000
	v_lshl_add_u64 v[8:9], v[8:9], 0, s[6:7]
	s_lshl_b32 s4, s20, 6
	v_lshl_or_b32 v17, v209, 6, v17
	s_lshl_b32 s20, s20, 13
	v_and_b32_e32 v16, 32, v16
	s_lshl_b32 s15, s43, 7
	s_waitcnt vmcnt(2)
	s_barrier
	global_load_lds_dwordx4 v[8:9], off
	v_lshl_add_u64 v[6:7], v[6:7], 0, s[6:7]
	s_add_i32 m0, s39, 0x1a000
	s_add_i32 s44, s39, 0x8000
	s_add_i32 s45, s39, 0xa000
	v_bitop3_b32 v18, v17, s20, v16 bitop3:0xde
	global_load_lds_dwordx4 v[6:7], off
	v_lshl_add_u64 v[2:3], v[2:3], 0, s[6:7]
	s_mov_b32 m0, s44
	s_add_u32 s20, s12, 0x40080
	global_load_lds_dwordx4 v[2:3], off
	v_lshl_add_u64 v[2:3], v[4:5], 0, s[6:7]
	s_mov_b32 m0, s45
	s_addc_u32 s21, s13, 0
	global_load_lds_dwordx4 v[2:3], off
	s_add_i32 m0, s39, 0x1c000
	v_lshl_add_u64 v[2:3], s[20:21], 0, v[0:1]
	global_load_lds_dwordx4 v[2:3], off
	v_lshl_add_u64 v[2:3], s[20:21], 0, v[146:147]
	s_add_i32 m0, s39, 0x1e000
	v_bitop3_b32 v212, v17, s15, v16 bitop3:0xde
	global_load_lds_dwordx4 v[2:3], off
	v_lshlrev_b32_e32 v2, 14, v14
	v_and_b32_e32 v2, 0xffff8000, v2
	v_lshl_add_u32 v2, v13, 11, v2
	v_and_b32_e32 v3, 1, v14
	v_lshl_or_b32 v2, v3, 6, v2
	v_lshl_add_u32 v152, v15, 1, v2
	v_lshlrev_b32_e32 v2, 14, v10
	s_cmpk_lt_u32 s14, 0x100
	v_and_b32_e32 v2, 0xffff8000, v2
	v_readlane_b32 s14, v245, 18
	s_waitcnt vmcnt(6)
	v_lshl_add_u32 v2, v11, 11, v2
	v_and_b32_e32 v3, 1, v10
	v_readlane_b32 s15, v245, 19
	v_lshl_or_b32 v2, v3, 6, v2
	s_mov_b32 s34, s14
	v_readlane_b32 s14, v245, 35
	v_or_b32_e32 v210, s4, v209
	s_cselect_b64 s[20:21], -1, 0
	v_lshl_or_b32 v213, s43, 1, v211
	v_mov_b32_e32 v153, v1
	v_lshl_add_u32 v166, v12, 1, v2
	v_mov_b32_e32 v167, v1
	s_mov_b32 s35, 0
	v_add_u32_e32 v214, 0, v18
	s_mov_b32 s48, s14
	s_mov_b32 s46, 0
	s_barrier
	v_readlane_b32 s15, v245, 36
	s_branch .LBB0_264

.LBB0_278:
	v_readlane_b32 s56, v246, 3
	v_mov_b32_e32 v215, 0
	s_and_b64 vcc, exec, s[0:1]
	v_mov_b32_e32 v220, 0
	v_mov_b32_e32 v221, 0
	v_mov_b32_e32 v222, 0
	v_mov_b32_e32 v216, 0
	v_readlane_b32 s57, v246, 4
	s_cbranch_vccnz .LBB0_280
	global_load_dwordx4 v[188:191], v[186:187], off offset:-3968
	s_waitcnt vmcnt(0)
	v_sub_f32_e32 v220, 1.0, v188
	v_sub_f32_e32 v221, 1.0, v189
	v_sub_f32_e32 v222, 1.0, v190
	v_sub_f32_e32 v216, 1.0, v191
.LBB0_280:
	s_and_b64 vcc, exec, s[0:1]
	v_mov_b32_e32 v217, 0
	v_mov_b32_e32 v218, 0
	v_mov_b32_e32 v219, 0
	s_cbranch_vccnz .LBB0_282
	global_load_dwordx4 v[186:189], v[186:187], off offset:-3952
	s_waitcnt vmcnt(0)
	v_sub_f32_e32 v215, 1.0, v186
	v_sub_f32_e32 v217, 1.0, v187
	v_sub_f32_e32 v218, 1.0, v188
	v_sub_f32_e32 v219, 1.0, v189

.LBB0_294:
	global_store_dwordx4 v[144:145], v[130:133], off offset:64
	s_mov_b64 s[30:31], -1
	s_mov_b64 s[0:1], 0
	v_pk_fma_f32 v[130:131], v[128:129], v[182:183], v[48:49] op_sel_hi:[1,0,1]
	v_pk_fma_f32 v[132:133], v[126:127], v[182:183], v[46:47] op_sel_hi:[1,0,1]
	v_pk_fma_f32 v[126:127], v[124:125], v[182:183], v[44:45] op_sel_hi:[1,0,1]
	v_pk_fma_f32 v[128:129], v[122:123], v[182:183], v[42:43] op_sel_hi:[1,0,1]
	s_cmp_lt_i32 s23, 2
	s_mov_b64 s[12:13], 0
	s_mov_b64 s[34:35], 0
	s_cbranch_scc1 .LBB0_386
	s_cmp_lg_u32 s23, 2
	s_mov_b64 s[12:13], -1
	s_cselect_b64 s[34:35], -1, 0
	v_mov_b32_e32 v135, v127
	v_mov_b32_e32 v134, v126
	v_mov_b32_e32 v139, v129
	v_mov_b32_e32 v138, v128
	v_mov_b32_e32 v137, v131
	v_mov_b32_e32 v136, v130
	v_mov_b32_e32 v141, v133
	v_mov_b32_e32 v140, v132
	s_cbranch_execz .LBB0_387

.LBB0_306:
	global_store_dwordx4 v[126:127], v[114:117], off offset:64
	s_mov_b64 s[30:31], -1
	s_mov_b64 s[0:1], 0
	v_pk_fma_f32 v[114:115], v[112:113], v[180:181], v[48:49] op_sel_hi:[1,0,1]
	v_pk_fma_f32 v[116:117], v[110:111], v[180:181], v[46:47] op_sel_hi:[1,0,1]
	v_pk_fma_f32 v[110:111], v[108:109], v[180:181], v[44:45] op_sel_hi:[1,0,1]
	v_pk_fma_f32 v[112:113], v[106:107], v[180:181], v[42:43] op_sel_hi:[1,0,1]
	s_cmp_lt_i32 s23, 2
	s_mov_b64 s[12:13], 0
	s_mov_b64 s[34:35], 0
	s_cbranch_scc1 .LBB0_394
	s_cmp_lg_u32 s23, 2
	s_mov_b64 s[12:13], -1
	s_cselect_b64 s[34:35], -1, 0
	v_mov_b32_e32 v119, v111
	v_mov_b32_e32 v118, v110
	v_mov_b32_e32 v123, v113
	v_mov_b32_e32 v122, v112
	v_mov_b32_e32 v121, v115
	v_mov_b32_e32 v120, v114
	v_mov_b32_e32 v125, v117
	v_mov_b32_e32 v124, v116
	s_cbranch_execz .LBB0_395

.LBB0_318:
	global_store_dwordx4 v[110:111], v[98:101], off offset:64
	s_mov_b64 s[30:31], -1
	s_mov_b64 s[0:1], 0
	v_pk_fma_f32 v[98:99], v[96:97], v[178:179], v[48:49] op_sel_hi:[1,0,1]
	v_pk_fma_f32 v[100:101], v[94:95], v[178:179], v[46:47] op_sel_hi:[1,0,1]
	v_pk_fma_f32 v[94:95], v[92:93], v[178:179], v[44:45] op_sel_hi:[1,0,1]
	v_pk_fma_f32 v[96:97], v[90:91], v[178:179], v[42:43] op_sel_hi:[1,0,1]
	s_cmp_lt_i32 s23, 2
	s_mov_b64 s[12:13], 0
	s_mov_b64 s[34:35], 0
	s_cbranch_scc1 .LBB0_402
	s_cmp_lg_u32 s23, 2
	s_mov_b64 s[12:13], -1
	s_cselect_b64 s[34:35], -1, 0
	v_mov_b32_e32 v103, v95
	v_mov_b32_e32 v102, v94
	v_mov_b32_e32 v107, v97
	v_mov_b32_e32 v106, v96
	v_mov_b32_e32 v105, v99
	v_mov_b32_e32 v104, v98
	v_mov_b32_e32 v109, v101
	v_mov_b32_e32 v108, v100
	s_cbranch_execz .LBB0_403

.LBB0_330:
	global_store_dwordx4 v[94:95], v[82:85], off offset:64
	s_mov_b64 s[30:31], -1
	s_mov_b64 s[0:1], 0
	v_pk_fma_f32 v[82:83], v[80:81], v[176:177], v[48:49] op_sel_hi:[1,0,1]
	v_pk_fma_f32 v[84:85], v[78:79], v[176:177], v[46:47] op_sel_hi:[1,0,1]
	v_pk_fma_f32 v[78:79], v[76:77], v[176:177], v[44:45] op_sel_hi:[1,0,1]
	v_pk_fma_f32 v[80:81], v[74:75], v[176:177], v[42:43] op_sel_hi:[1,0,1]
	s_cmp_lt_i32 s23, 2
	s_mov_b64 s[12:13], 0
	s_mov_b64 s[34:35], 0
	s_cbranch_scc1 .LBB0_410
	s_cmp_lg_u32 s23, 2
	s_mov_b64 s[12:13], -1
	s_cselect_b64 s[34:35], -1, 0
	v_mov_b32_e32 v87, v79
	v_mov_b32_e32 v86, v78
	v_mov_b32_e32 v91, v81
	v_mov_b32_e32 v90, v80
	v_mov_b32_e32 v89, v83
	v_mov_b32_e32 v88, v82
	v_mov_b32_e32 v93, v85
	v_mov_b32_e32 v92, v84
	s_cbranch_execz .LBB0_411

.LBB0_342:
	global_store_dwordx4 v[78:79], v[66:69], off offset:64
	s_mov_b64 s[30:31], -1
	s_mov_b64 s[0:1], 0
	v_pk_fma_f32 v[66:67], v[64:65], v[174:175], v[48:49] op_sel_hi:[1,0,1]
	v_pk_fma_f32 v[68:69], v[62:63], v[174:175], v[46:47] op_sel_hi:[1,0,1]
	v_pk_fma_f32 v[62:63], v[60:61], v[174:175], v[44:45] op_sel_hi:[1,0,1]
	v_pk_fma_f32 v[64:65], v[58:59], v[174:175], v[42:43] op_sel_hi:[1,0,1]
	s_cmp_lt_i32 s23, 2
	s_mov_b64 s[12:13], 0
	s_mov_b64 s[34:35], 0
	s_cbranch_scc1 .LBB0_418
	s_cmp_lg_u32 s23, 2
	s_mov_b64 s[12:13], -1
	s_cselect_b64 s[34:35], -1, 0
	v_mov_b32_e32 v71, v63
	v_mov_b32_e32 v70, v62
	v_mov_b32_e32 v75, v65
	v_mov_b32_e32 v74, v64
	v_mov_b32_e32 v73, v67
	v_mov_b32_e32 v72, v66
	v_mov_b32_e32 v77, v69
	v_mov_b32_e32 v76, v68
	s_cbranch_execz .LBB0_419

.LBB0_354:
	global_store_dwordx4 v[62:63], v[50:53], off offset:64
	s_mov_b64 s[30:31], -1
	s_mov_b64 s[0:1], 0
	v_pk_fma_f32 v[50:51], v[40:41], v[172:173], v[48:49] op_sel_hi:[1,0,1]
	v_pk_fma_f32 v[52:53], v[38:39], v[172:173], v[46:47] op_sel_hi:[1,0,1]
	v_pk_fma_f32 v[38:39], v[36:37], v[172:173], v[44:45] op_sel_hi:[1,0,1]
	v_pk_fma_f32 v[40:41], v[34:35], v[172:173], v[42:43] op_sel_hi:[1,0,1]
	s_cmp_lt_i32 s23, 2
	s_mov_b64 s[12:13], 0
	s_mov_b64 s[34:35], 0
	s_cbranch_scc1 .LBB0_426
	s_cmp_lg_u32 s23, 2
	s_mov_b64 s[12:13], -1
	s_cselect_b64 s[34:35], -1, 0
	v_mov_b32_e32 v55, v39
	v_mov_b32_e32 v54, v38
	v_mov_b32_e32 v59, v41
	v_mov_b32_e32 v58, v40
	v_mov_b32_e32 v57, v51
	v_mov_b32_e32 v56, v50
	v_mov_b32_e32 v61, v53
	v_mov_b32_e32 v60, v52
	s_cbranch_execz .LBB0_427

.LBB0_366:
	global_store_dwordx4 v[38:39], v[18:21], off offset:64
	s_mov_b64 s[30:31], -1
	s_mov_b64 s[0:1], 0
	v_pk_fma_f32 v[18:19], v[16:17], v[168:169], v[48:49] op_sel_hi:[1,0,1]
	v_pk_fma_f32 v[20:21], v[14:15], v[168:169], v[46:47] op_sel_hi:[1,0,1]
	v_pk_fma_f32 v[14:15], v[12:13], v[168:169], v[44:45] op_sel_hi:[1,0,1]
	v_pk_fma_f32 v[16:17], v[10:11], v[168:169], v[42:43] op_sel_hi:[1,0,1]
	s_cmp_lt_i32 s23, 2
	s_mov_b64 s[12:13], 0
	s_mov_b64 s[34:35], 0
	s_cbranch_scc1 .LBB0_434
	s_cmp_lg_u32 s23, 2
	s_mov_b64 s[12:13], -1
	s_cselect_b64 s[34:35], -1, 0
	v_mov_b32_e32 v23, v15
	v_mov_b32_e32 v22, v14
	v_mov_b32_e32 v35, v17
	v_mov_b32_e32 v34, v16
	v_mov_b32_e32 v25, v19
	v_mov_b32_e32 v24, v18
	v_mov_b32_e32 v37, v21
	v_mov_b32_e32 v36, v20
	s_cbranch_execz .LBB0_435

.LBB0_377:
	v_mul_f32_e32 v2, 0x3fb8aa3b, v12
	v_mul_f32_e32 v3, 0x3fb8aa3b, v13
	v_mul_f32_e32 v4, 0x3fb8aa3b, v10
	v_mul_f32_e32 v5, 0x3fb8aa3b, v11
	v_mul_f32_e32 v8, 0x3fb8aa3b, v8
	v_mul_f32_e32 v9, 0x3fb8aa3b, v9
	v_mul_f32_e32 v6, 0x3fb8aa3b, v6
	v_mul_f32_e32 v7, 0x3fb8aa3b, v7
	v_exp_f32_e32 v2, v2
	v_exp_f32_e32 v3, v3
	v_exp_f32_e32 v4, v4
	v_exp_f32_e32 v5, v5
	v_exp_f32_e32 v8, v8
	v_exp_f32_e32 v9, v9
	v_exp_f32_e32 v6, v6
	v_exp_f32_e32 v7, v7
	v_add_f32_e32 v2, 1.0, v2
	v_add_f32_e32 v3, 1.0, v3
	v_add_f32_e32 v4, 1.0, v4
	v_add_f32_e32 v5, 1.0, v5
	v_add_f32_e32 v8, 1.0, v8
	v_add_f32_e32 v9, 1.0, v9
	v_add_f32_e32 v6, 1.0, v6
	v_add_f32_e32 v7, 1.0, v7
	v_rcp_f32_e32 v2, v2
	v_rcp_f32_e32 v3, v3
	v_rcp_f32_e32 v4, v4
	v_rcp_f32_e32 v5, v5
	v_rcp_f32_e32 v8, v8
	v_rcp_f32_e32 v9, v9
	v_rcp_f32_e32 v6, v6
	v_rcp_f32_e32 v7, v7
	v_mul_f32_e32 v2, v2, v220
	v_mul_f32_e32 v3, v3, v221
	v_mul_f32_e32 v4, v4, v222
	v_mul_f32_e32 v5, v5, v216
	v_mul_f32_e32 v8, v8, v215
	v_mul_f32_e32 v9, v9, v217
	v_mul_f32_e32 v6, v6, v218
	v_mul_f32_e32 v7, v7, v219
	v_cvt_pk_f16_f32 v2, v2, v3
	v_cvt_pk_f16_f32 v3, v4, v5
	v_cvt_pk_f16_f32 v4, v8, v9
	v_cvt_pk_f16_f32 v5, v6, v7
	s_andn2_b64 vcc, exec, s[14:15]
	s_mov_b64 s[0:1], -1
	global_store_dwordx4 v[14:15], v[2:5], off offset:64
	s_cbranch_vccnz .LBB0_263
	s_branch .LBB0_443

.LBB0_442:
	s_andn2_b64 vcc, exec, s[14:15]
	s_mov_b64 s[0:1], -1
	global_store_dwordx4 v[14:15], v[2:5], off offset:64
	s_cbranch_vccnz .LBB0_263

.LBB0_1191:
	s_ashr_i32 s12, s55, 31
	s_lshr_b32 s12, s12, 29
	s_add_i32 s12, s55, s12
	s_ashr_i32 s12, s12, 3
	s_mul_i32 s27, s12, 0x6000
	s_mul_hi_i32 s25, s12, 0x6000
	s_add_u32 s80, s40, s27
	s_addc_u32 s81, s41, s25
	s_add_u32 s82, s47, s27
	s_addc_u32 s83, s48, s25
	s_mov_b32 s62, 0xaaaaaaaa
	s_mov_b32 s63, 0xaaaaaaaa
	s_mov_b32 s66, 0x55555555
	s_mov_b32 s67, 0x55555555
	v_mbcnt_lo_u32_b32 v150, -1, 0
	v_mbcnt_hi_u32_b32 v150, -1, v150
	v_and_b32_e32 v150, 1, v150
	v_and_b32_e32 v149, 0x60, v194
	v_add_u32_e32 v149, v149, v194
	v_lshl_or_b32 v149, s4, 8, v149
	v_lshlrev_b32_e32 v28, 2, v149
	v_lshl_add_u32 v149, v150, 5, v149
	v_lshl_add_u32 v148, s55, 8, v192
	v_sub_u32_e32 v148, v148, v150
	v_lshl_add_u32 v148, v148, 10, v149
	v_lshlrev_b32_e32 v149, 1, v148
	global_load_dwordx4 v[176:179], v28, s[80:81] offset:0
	global_load_dwordx4 v[180:183], v28, s[80:81] offset:16
	global_load_dwordx4 v[210:213], v28, s[20:21] offset:0
	global_load_dwordx4 v[214:217], v28, s[20:21] offset:16
	global_load_dwordx4 v[184:187], v28, s[80:81] offset:128
	global_load_dwordx4 v[188:191], v28, s[80:81] offset:144
	global_load_dwordx4 v[218:221], v28, s[20:21] offset:128
	global_load_dwordx4 v[222:225], v28, s[20:21] offset:144
	global_load_dwordx4 v[226:229], v28, s[82:83] offset:0
	global_load_dwordx4 v[230:233], v28, s[82:83] offset:16
	s_waitcnt vmcnt(0)
	v_pk_add_f32 v[226:227], v[226:227], 1.0 op_sel_hi:[1,0]
	v_pk_add_f32 v[228:229], v[228:229], 1.0 op_sel_hi:[1,0]
	v_pk_add_f32 v[230:231], v[230:231], 1.0 op_sel_hi:[1,0]
	v_pk_add_f32 v[232:233], v[232:233], 1.0 op_sel_hi:[1,0]
	v_pk_mul_f32 v[210:211], v[210:211], v[226:227]
	v_pk_mul_f32 v[212:213], v[212:213], v[228:229]
	v_pk_mul_f32 v[214:215], v[214:215], v[230:231]
	v_pk_mul_f32 v[216:217], v[216:217], v[232:233]
	s_nop 1
	global_load_dwordx4 v[226:229], v28, s[82:83] offset:128
	global_load_dwordx4 v[230:233], v28, s[82:83] offset:144
	s_waitcnt vmcnt(0)
	v_pk_add_f32 v[226:227], v[226:227], 1.0 op_sel_hi:[1,0]
	v_pk_add_f32 v[228:229], v[228:229], 1.0 op_sel_hi:[1,0]
	v_pk_add_f32 v[230:231], v[230:231], 1.0 op_sel_hi:[1,0]
	v_pk_add_f32 v[232:233], v[232:233], 1.0 op_sel_hi:[1,0]
	v_pk_mul_f32 v[218:219], v[218:219], v[226:227]
	v_pk_mul_f32 v[220:221], v[220:221], v[228:229]
	v_pk_mul_f32 v[222:223], v[222:223], v[230:231]
	v_pk_mul_f32 v[224:225], v[224:225], v[232:233]
	s_add_u32 s84, s58, 0x0
	s_addc_u32 s85, s59, 0
	s_add_u32 s86, s74, 0x0
	s_addc_u32 s87, s75, 0
	global_load_dwordx4 v[226:229], v149, s[84:85]
	global_load_dwordx2 v[152:153], v148, s[86:87]
	global_load_dwordx4 v[230:233], v149, s[84:85] offset:2048
	global_load_dwordx2 v[196:197], v148, s[86:87] offset:1024
	s_waitcnt vmcnt(0)
	v_mov_b32_dpp v32, v226 quad_perm:[1,0,3,2] row_mask:0xf bank_mask:0xf
	v_mov_b32_dpp v33, v227 quad_perm:[1,0,3,2] row_mask:0xf bank_mask:0xf
	v_mov_b32_dpp v34, v228 quad_perm:[1,0,3,2] row_mask:0xf bank_mask:0xf
	v_mov_b32_dpp v35, v229 quad_perm:[1,0,3,2] row_mask:0xf bank_mask:0xf
	v_mov_b32_dpp v36, v230 quad_perm:[1,0,3,2] row_mask:0xf bank_mask:0xf
	v_mov_b32_dpp v37, v231 quad_perm:[1,0,3,2] row_mask:0xf bank_mask:0xf
	v_mov_b32_dpp v38, v232 quad_perm:[1,0,3,2] row_mask:0xf bank_mask:0xf
	v_mov_b32_dpp v39, v233 quad_perm:[1,0,3,2] row_mask:0xf bank_mask:0xf
	s_mov_b64 exec, s[62:63]
	v_mov_b32_e32 v226, v36
	v_mov_b32_e32 v227, v37
	v_mov_b32_e32 v228, v38
	v_mov_b32_e32 v229, v39
	s_mov_b64 exec, s[66:67]
	v_mov_b32_e32 v230, v32
	v_mov_b32_e32 v231, v33
	v_mov_b32_e32 v232, v34
	v_mov_b32_e32 v233, v35
	s_mov_b64 exec, -1
	v_mov_b32_dpp v32, v152 quad_perm:[1,0,3,2] row_mask:0xf bank_mask:0xf
	v_mov_b32_dpp v33, v153 quad_perm:[1,0,3,2] row_mask:0xf bank_mask:0xf
	v_mov_b32_dpp v36, v196 quad_perm:[1,0,3,2] row_mask:0xf bank_mask:0xf
	v_mov_b32_dpp v37, v197 quad_perm:[1,0,3,2] row_mask:0xf bank_mask:0xf
	s_mov_b64 exec, s[62:63]
	v_mov_b32_e32 v152, v36
	v_mov_b32_e32 v153, v37
	s_mov_b64 exec, s[66:67]
	v_mov_b32_e32 v196, v32
	v_mov_b32_e32 v197, v33
	s_mov_b64 exec, -1
	v_lshlrev_b32_e32 v28, 8, v152
	v_perm_b32 v29, v226, v152, s8
	v_lshrrev_b32_e32 v30, 8, v152
	v_lshrrev_b32_e32 v31, 16, v152
	v_perm_b32 v28, v226, v28, s33
	v_perm_b32 v30, v227, v30, s33
	v_perm_b32 v31, v227, v31, s8
	v_pk_fma_f32 v[142:143], v[142:143], v[176:177], v[28:29]
	v_pk_fma_f32 v[144:145], v[144:145], v[178:179], v[30:31]
	v_lshlrev_b32_e32 v28, 8, v153
	v_perm_b32 v29, v228, v153, s8
	v_lshrrev_b32_e32 v30, 8, v153
	v_lshrrev_b32_e32 v31, 16, v153
	v_perm_b32 v28, v228, v28, s33
	v_perm_b32 v30, v229, v30, s33
	v_perm_b32 v31, v229, v31, s8
	v_pk_fma_f32 v[138:139], v[138:139], v[180:181], v[28:29]
	v_pk_fma_f32 v[140:141], v[140:141], v[182:183], v[30:31]
	v_lshlrev_b32_e32 v28, 8, v196
	v_perm_b32 v29, v230, v196, s8
	v_lshrrev_b32_e32 v30, 8, v196
	v_lshrrev_b32_e32 v31, 16, v196
	v_perm_b32 v28, v230, v28, s33
	v_perm_b32 v30, v231, v30, s33
	v_perm_b32 v31, v231, v31, s8
	v_pk_fma_f32 v[134:135], v[134:135], v[184:185], v[28:29]
	v_pk_fma_f32 v[136:137], v[136:137], v[186:187], v[30:31]
	v_lshlrev_b32_e32 v28, 8, v197
	v_perm_b32 v29, v232, v197, s8
	v_lshrrev_b32_e32 v30, 8, v197
	v_lshrrev_b32_e32 v31, 16, v197
	v_perm_b32 v28, v232, v28, s33
	v_perm_b32 v30, v233, v30, s33
	v_perm_b32 v31, v233, v31, s8
	v_pk_fma_f32 v[130:131], v[130:131], v[188:189], v[28:29]
	v_pk_fma_f32 v[132:133], v[132:133], v[190:191], v[30:31]
	v_mul_f32_e32 v28, v143, v143
	v_mul_f32_e32 v29, v145, v145
	v_mul_f32_e32 v30, v139, v139
	v_mul_f32_e32 v31, v141, v141
	v_fmac_f32_e32 v28, v142, v142
	v_fmac_f32_e32 v29, v144, v144
	v_fmac_f32_e32 v30, v138, v138
	v_fmac_f32_e32 v31, v140, v140
	v_add_f32_e32 v28, v28, v29
	v_add_f32_e32 v30, v30, v31
	v_add_f32_e32 v151, v28, v30
	v_add_u32_e32 v28, 0x80, v142
	v_add_u32_e32 v29, 0x80, v143
	v_add_u32_e32 v30, 0x80, v144
	v_add_u32_e32 v31, 0x80, v145
	v_perm_b32 v32, v29, v28, s78
	v_perm_b32 v33, v31, v30, s78
	v_perm_b32 v26, v29, v28, s79
	v_perm_b32 v27, v31, v30, s79
	v_perm_b32 v40, v27, v26, s60
	v_add_u32_e32 v28, 0x80, v138
	v_add_u32_e32 v29, 0x80, v139
	v_add_u32_e32 v30, 0x80, v140
	v_add_u32_e32 v31, 0x80, v141
	v_perm_b32 v34, v29, v28, s78
	v_perm_b32 v35, v31, v30, s78
	v_perm_b32 v26, v29, v28, s79
	v_perm_b32 v27, v31, v30, s79
	v_perm_b32 v41, v27, v26, s60
	v_mul_f32_e32 v28, v135, v135
	v_mul_f32_e32 v29, v137, v137
	v_mul_f32_e32 v30, v131, v131
	v_mul_f32_e32 v31, v133, v133
	v_fmac_f32_e32 v28, v134, v134
	v_fmac_f32_e32 v29, v136, v136
	v_fmac_f32_e32 v30, v130, v130
	v_fmac_f32_e32 v31, v132, v132
	v_add_f32_e32 v28, v28, v29
	v_add_f32_e32 v30, v30, v31
	v_add_f32_e32 v28, v28, v30
	v_add_f32_e32 v151, v151, v28
	v_add_u32_e32 v28, 0x80, v134
	v_add_u32_e32 v29, 0x80, v135
	v_add_u32_e32 v30, 0x80, v136
	v_add_u32_e32 v31, 0x80, v137
	v_perm_b32 v36, v29, v28, s78
	v_perm_b32 v37, v31, v30, s78
	v_perm_b32 v26, v29, v28, s79
	v_perm_b32 v27, v31, v30, s79
	v_perm_b32 v146, v27, v26, s60
	v_add_u32_e32 v28, 0x80, v130
	v_add_u32_e32 v29, 0x80, v131
	v_add_u32_e32 v30, 0x80, v132
	v_add_u32_e32 v31, 0x80, v133
	v_perm_b32 v38, v29, v28, s78
	v_perm_b32 v39, v31, v30, s78
	v_perm_b32 v26, v29, v28, s79
	v_perm_b32 v27, v31, v30, s79
	v_perm_b32 v147, v27, v26, s60
	v_mov_b32_dpp v226, v32 quad_perm:[1,0,3,2] row_mask:0xf bank_mask:0xf
	v_mov_b32_dpp v227, v33 quad_perm:[1,0,3,2] row_mask:0xf bank_mask:0xf
	v_mov_b32_dpp v228, v34 quad_perm:[1,0,3,2] row_mask:0xf bank_mask:0xf
	v_mov_b32_dpp v229, v35 quad_perm:[1,0,3,2] row_mask:0xf bank_mask:0xf
	v_mov_b32_dpp v230, v36 quad_perm:[1,0,3,2] row_mask:0xf bank_mask:0xf
	v_mov_b32_dpp v231, v37 quad_perm:[1,0,3,2] row_mask:0xf bank_mask:0xf
	v_mov_b32_dpp v232, v38 quad_perm:[1,0,3,2] row_mask:0xf bank_mask:0xf
	v_mov_b32_dpp v233, v39 quad_perm:[1,0,3,2] row_mask:0xf bank_mask:0xf
	s_mov_b64 exec, s[62:63]
	v_mov_b32_e32 v32, v230
	v_mov_b32_e32 v33, v231
	v_mov_b32_e32 v34, v232
	v_mov_b32_e32 v35, v233
	s_mov_b64 exec, s[66:67]
	v_mov_b32_e32 v36, v226
	v_mov_b32_e32 v37, v227
	v_mov_b32_e32 v38, v228
	v_mov_b32_e32 v39, v229
	s_mov_b64 exec, -1
	v_mov_b32_dpp v226, v40 quad_perm:[1,0,3,2] row_mask:0xf bank_mask:0xf
	v_mov_b32_dpp v227, v41 quad_perm:[1,0,3,2] row_mask:0xf bank_mask:0xf
	v_mov_b32_dpp v230, v146 quad_perm:[1,0,3,2] row_mask:0xf bank_mask:0xf
	v_mov_b32_dpp v231, v147 quad_perm:[1,0,3,2] row_mask:0xf bank_mask:0xf
	s_mov_b64 exec, s[62:63]
	v_mov_b32_e32 v40, v230
	v_mov_b32_e32 v41, v231
	s_mov_b64 exec, s[66:67]
	v_mov_b32_e32 v146, v226
	v_mov_b32_e32 v147, v227
	s_mov_b64 exec, -1
	s_add_u32 s88, s58, 0x0
	s_addc_u32 s89, s59, 0
	s_add_u32 s90, s74, 0x0
	s_addc_u32 s91, s75, 0
	global_store_dwordx4 v149, v[32:35], s[88:89]
	global_store_dwordx4 v149, v[36:39], s[88:89] offset:2048
	global_store_dwordx2 v148, v[40:41], s[90:91]
	global_store_dwordx2 v148, v[146:147], s[90:91] offset:1024
	s_add_u32 s92, s96, 0x0
	s_addc_u32 s93, s97, 0
	v_pk_mul_f32 v[142:143], v[210:211], v[142:143]
	v_pk_mul_f32 v[144:145], v[212:213], v[144:145]
	v_pk_mul_f32 v[138:139], v[214:215], v[138:139]
	v_pk_mul_f32 v[140:141], v[216:217], v[140:141]
	v_cvt_pk_bf16_f32 v32, v142, v143
	v_cvt_pk_bf16_f32 v33, v144, v145
	v_cvt_pk_bf16_f32 v34, v138, v139
	v_cvt_pk_bf16_f32 v35, v140, v141
	v_pk_mul_f32 v[134:135], v[218:219], v[134:135]
	v_pk_mul_f32 v[136:137], v[220:221], v[136:137]
	v_pk_mul_f32 v[130:131], v[222:223], v[130:131]
	v_pk_mul_f32 v[132:133], v[224:225], v[132:133]
	v_cvt_pk_bf16_f32 v36, v134, v135
	v_cvt_pk_bf16_f32 v37, v136, v137
	v_cvt_pk_bf16_f32 v38, v130, v131
	v_cvt_pk_bf16_f32 v39, v132, v133
	v_mov_b32_dpp v226, v32 quad_perm:[1,0,3,2] row_mask:0xf bank_mask:0xf
	v_mov_b32_dpp v227, v33 quad_perm:[1,0,3,2] row_mask:0xf bank_mask:0xf
	v_mov_b32_dpp v228, v34 quad_perm:[1,0,3,2] row_mask:0xf bank_mask:0xf
	v_mov_b32_dpp v229, v35 quad_perm:[1,0,3,2] row_mask:0xf bank_mask:0xf
	v_mov_b32_dpp v230, v36 quad_perm:[1,0,3,2] row_mask:0xf bank_mask:0xf
	v_mov_b32_dpp v231, v37 quad_perm:[1,0,3,2] row_mask:0xf bank_mask:0xf
	v_mov_b32_dpp v232, v38 quad_perm:[1,0,3,2] row_mask:0xf bank_mask:0xf
	v_mov_b32_dpp v233, v39 quad_perm:[1,0,3,2] row_mask:0xf bank_mask:0xf
	s_mov_b64 exec, s[62:63]
	v_mov_b32_e32 v32, v230
	v_mov_b32_e32 v33, v231
	v_mov_b32_e32 v34, v232
	v_mov_b32_e32 v35, v233
	s_mov_b64 exec, s[66:67]
	v_mov_b32_e32 v36, v226
	v_mov_b32_e32 v37, v227
	v_mov_b32_e32 v38, v228
	v_mov_b32_e32 v39, v229
	s_mov_b64 exec, -1
	global_store_dwordx4 v149, v[32:35], s[92:93]
	global_store_dwordx4 v149, v[36:39], s[92:93] offset:2048
	v_mov_b32_e32 v130, v151
	s_add_u32 s84, s58, 0x8000
	s_addc_u32 s85, s59, 0
	s_add_u32 s86, s74, 0x4000
	s_addc_u32 s87, s75, 0
	global_load_dwordx4 v[132:135], v149, s[84:85]
	global_load_dwordx2 v[136:137], v148, s[86:87]
	global_load_dwordx4 v[138:141], v149, s[84:85] offset:2048
	global_load_dwordx2 v[142:143], v148, s[86:87] offset:1024
	s_add_u32 s84, s58, 0x10000
	s_addc_u32 s85, s59, 0
	s_add_u32 s86, s74, 0x8000
	s_addc_u32 s87, s75, 0
	global_load_dwordx4 v[226:229], v149, s[84:85]
	global_load_dwordx2 v[144:145], v148, s[86:87]
	global_load_dwordx4 v[230:233], v149, s[84:85] offset:2048
	global_load_dwordx2 v[152:153], v148, s[86:87] offset:1024
	s_waitcnt vmcnt(4)
	v_mov_b32_dpp v32, v132 quad_perm:[1,0,3,2] row_mask:0xf bank_mask:0xf
	v_mov_b32_dpp v33, v133 quad_perm:[1,0,3,2] row_mask:0xf bank_mask:0xf
	v_mov_b32_dpp v34, v134 quad_perm:[1,0,3,2] row_mask:0xf bank_mask:0xf
	v_mov_b32_dpp v35, v135 quad_perm:[1,0,3,2] row_mask:0xf bank_mask:0xf
	v_mov_b32_dpp v36, v138 quad_perm:[1,0,3,2] row_mask:0xf bank_mask:0xf
	v_mov_b32_dpp v37, v139 quad_perm:[1,0,3,2] row_mask:0xf bank_mask:0xf
	v_mov_b32_dpp v38, v140 quad_perm:[1,0,3,2] row_mask:0xf bank_mask:0xf
	v_mov_b32_dpp v39, v141 quad_perm:[1,0,3,2] row_mask:0xf bank_mask:0xf
	s_mov_b64 exec, s[62:63]
	v_mov_b32_e32 v132, v36
	v_mov_b32_e32 v133, v37
	v_mov_b32_e32 v134, v38
	v_mov_b32_e32 v135, v39
	s_mov_b64 exec, s[66:67]
	v_mov_b32_e32 v138, v32
	v_mov_b32_e32 v139, v33
	v_mov_b32_e32 v140, v34
	v_mov_b32_e32 v141, v35
	s_mov_b64 exec, -1
	v_mov_b32_dpp v32, v136 quad_perm:[1,0,3,2] row_mask:0xf bank_mask:0xf
	v_mov_b32_dpp v33, v137 quad_perm:[1,0,3,2] row_mask:0xf bank_mask:0xf
	v_mov_b32_dpp v36, v142 quad_perm:[1,0,3,2] row_mask:0xf bank_mask:0xf
	v_mov_b32_dpp v37, v143 quad_perm:[1,0,3,2] row_mask:0xf bank_mask:0xf
	s_mov_b64 exec, s[62:63]
	v_mov_b32_e32 v136, v36
	v_mov_b32_e32 v137, v37
	s_mov_b64 exec, s[66:67]
	v_mov_b32_e32 v142, v32
	v_mov_b32_e32 v143, v33
	s_mov_b64 exec, -1
	v_lshlrev_b32_e32 v28, 8, v136
	v_perm_b32 v29, v132, v136, s8
	v_lshrrev_b32_e32 v30, 8, v136
	v_lshrrev_b32_e32 v31, 16, v136
	v_perm_b32 v28, v132, v28, s33
	v_perm_b32 v30, v133, v30, s33
	v_perm_b32 v31, v133, v31, s8
	v_pk_fma_f32 v[126:127], v[126:127], v[176:177], v[28:29]
	v_pk_fma_f32 v[128:129], v[128:129], v[178:179], v[30:31]
	v_lshlrev_b32_e32 v28, 8, v137
	v_perm_b32 v29, v134, v137, s8
	v_lshrrev_b32_e32 v30, 8, v137
	v_lshrrev_b32_e32 v31, 16, v137
	v_perm_b32 v28, v134, v28, s33
	v_perm_b32 v30, v135, v30, s33
	v_perm_b32 v31, v135, v31, s8
	v_pk_fma_f32 v[122:123], v[122:123], v[180:181], v[28:29]
	v_pk_fma_f32 v[124:125], v[124:125], v[182:183], v[30:31]
	v_lshlrev_b32_e32 v28, 8, v142
	v_perm_b32 v29, v138, v142, s8
	v_lshrrev_b32_e32 v30, 8, v142
	v_lshrrev_b32_e32 v31, 16, v142
	v_perm_b32 v28, v138, v28, s33
	v_perm_b32 v30, v139, v30, s33
	v_perm_b32 v31, v139, v31, s8
	v_pk_fma_f32 v[118:119], v[118:119], v[184:185], v[28:29]
	v_pk_fma_f32 v[120:121], v[120:121], v[186:187], v[30:31]
	v_lshlrev_b32_e32 v28, 8, v143
	v_perm_b32 v29, v140, v143, s8
	v_lshrrev_b32_e32 v30, 8, v143
	v_lshrrev_b32_e32 v31, 16, v143
	v_perm_b32 v28, v140, v28, s33
	v_perm_b32 v30, v141, v30, s33
	v_perm_b32 v31, v141, v31, s8
	v_pk_fma_f32 v[114:115], v[114:115], v[188:189], v[28:29]
	v_pk_fma_f32 v[116:117], v[116:117], v[190:191], v[30:31]
	v_mul_f32_e32 v28, v127, v127
	v_mul_f32_e32 v29, v129, v129
	v_mul_f32_e32 v30, v123, v123
	v_mul_f32_e32 v31, v125, v125
	v_fmac_f32_e32 v28, v126, v126
	v_fmac_f32_e32 v29, v128, v128
	v_fmac_f32_e32 v30, v122, v122
	v_fmac_f32_e32 v31, v124, v124
	v_add_f32_e32 v28, v28, v29
	v_add_f32_e32 v30, v30, v31
	v_add_f32_e32 v151, v28, v30
	v_add_u32_e32 v28, 0x80, v126
	v_add_u32_e32 v29, 0x80, v127
	v_add_u32_e32 v30, 0x80, v128
	v_add_u32_e32 v31, 0x80, v129
	v_perm_b32 v32, v29, v28, s78
	v_perm_b32 v33, v31, v30, s78
	v_perm_b32 v26, v29, v28, s79
	v_perm_b32 v27, v31, v30, s79
	v_perm_b32 v40, v27, v26, s60
	v_add_u32_e32 v28, 0x80, v122
	v_add_u32_e32 v29, 0x80, v123
	v_add_u32_e32 v30, 0x80, v124
	v_add_u32_e32 v31, 0x80, v125
	v_perm_b32 v34, v29, v28, s78
	v_perm_b32 v35, v31, v30, s78
	v_perm_b32 v26, v29, v28, s79
	v_perm_b32 v27, v31, v30, s79
	v_perm_b32 v41, v27, v26, s60
	v_mul_f32_e32 v28, v119, v119
	v_mul_f32_e32 v29, v121, v121
	v_mul_f32_e32 v30, v115, v115
	v_mul_f32_e32 v31, v117, v117
	v_fmac_f32_e32 v28, v118, v118
	v_fmac_f32_e32 v29, v120, v120
	v_fmac_f32_e32 v30, v114, v114
	v_fmac_f32_e32 v31, v116, v116
	v_add_f32_e32 v28, v28, v29
	v_add_f32_e32 v30, v30, v31
	v_add_f32_e32 v28, v28, v30
	v_add_f32_e32 v151, v151, v28
	v_add_u32_e32 v28, 0x80, v118
	v_add_u32_e32 v29, 0x80, v119
	v_add_u32_e32 v30, 0x80, v120
	v_add_u32_e32 v31, 0x80, v121
	v_perm_b32 v36, v29, v28, s78
	v_perm_b32 v37, v31, v30, s78
	v_perm_b32 v26, v29, v28, s79
	v_perm_b32 v27, v31, v30, s79
	v_perm_b32 v146, v27, v26, s60
	v_add_u32_e32 v28, 0x80, v114
	v_add_u32_e32 v29, 0x80, v115
	v_add_u32_e32 v30, 0x80, v116
	v_add_u32_e32 v31, 0x80, v117
	v_perm_b32 v38, v29, v28, s78
	v_perm_b32 v39, v31, v30, s78
	v_perm_b32 v26, v29, v28, s79
	v_perm_b32 v27, v31, v30, s79
	v_perm_b32 v147, v27, v26, s60
	v_mov_b32_dpp v132, v32 quad_perm:[1,0,3,2] row_mask:0xf bank_mask:0xf
	v_mov_b32_dpp v133, v33 quad_perm:[1,0,3,2] row_mask:0xf bank_mask:0xf
	v_mov_b32_dpp v134, v34 quad_perm:[1,0,3,2] row_mask:0xf bank_mask:0xf
	v_mov_b32_dpp v135, v35 quad_perm:[1,0,3,2] row_mask:0xf bank_mask:0xf
	v_mov_b32_dpp v138, v36 quad_perm:[1,0,3,2] row_mask:0xf bank_mask:0xf
	v_mov_b32_dpp v139, v37 quad_perm:[1,0,3,2] row_mask:0xf bank_mask:0xf
	v_mov_b32_dpp v140, v38 quad_perm:[1,0,3,2] row_mask:0xf bank_mask:0xf
	v_mov_b32_dpp v141, v39 quad_perm:[1,0,3,2] row_mask:0xf bank_mask:0xf
	s_mov_b64 exec, s[62:63]
	v_mov_b32_e32 v32, v138
	v_mov_b32_e32 v33, v139
	v_mov_b32_e32 v34, v140
	v_mov_b32_e32 v35, v141
	s_mov_b64 exec, s[66:67]
	v_mov_b32_e32 v36, v132
	v_mov_b32_e32 v37, v133
	v_mov_b32_e32 v38, v134
	v_mov_b32_e32 v39, v135
	s_mov_b64 exec, -1
	v_mov_b32_dpp v132, v40 quad_perm:[1,0,3,2] row_mask:0xf bank_mask:0xf
	v_mov_b32_dpp v133, v41 quad_perm:[1,0,3,2] row_mask:0xf bank_mask:0xf
	v_mov_b32_dpp v138, v146 quad_perm:[1,0,3,2] row_mask:0xf bank_mask:0xf
	v_mov_b32_dpp v139, v147 quad_perm:[1,0,3,2] row_mask:0xf bank_mask:0xf
	s_mov_b64 exec, s[62:63]
	v_mov_b32_e32 v40, v138
	v_mov_b32_e32 v41, v139
	s_mov_b64 exec, s[66:67]
	v_mov_b32_e32 v146, v132
	v_mov_b32_e32 v147, v133
	s_mov_b64 exec, -1
	s_add_u32 s88, s58, 0x8000
	s_addc_u32 s89, s59, 0
	s_add_u32 s90, s74, 0x4000
	s_addc_u32 s91, s75, 0
	global_store_dwordx4 v149, v[32:35], s[88:89]
	global_store_dwordx4 v149, v[36:39], s[88:89] offset:2048
	global_store_dwordx2 v148, v[40:41], s[90:91]
	global_store_dwordx2 v148, v[146:147], s[90:91] offset:1024
	s_add_u32 s92, s96, 0x8000
	s_addc_u32 s93, s97, 0
	v_pk_mul_f32 v[126:127], v[210:211], v[126:127]
	v_pk_mul_f32 v[128:129], v[212:213], v[128:129]
	v_pk_mul_f32 v[122:123], v[214:215], v[122:123]
	v_pk_mul_f32 v[124:125], v[216:217], v[124:125]
	v_cvt_pk_bf16_f32 v32, v126, v127
	v_cvt_pk_bf16_f32 v33, v128, v129
	v_cvt_pk_bf16_f32 v34, v122, v123
	v_cvt_pk_bf16_f32 v35, v124, v125
	v_pk_mul_f32 v[118:119], v[218:219], v[118:119]
	v_pk_mul_f32 v[120:121], v[220:221], v[120:121]
	v_pk_mul_f32 v[114:115], v[222:223], v[114:115]
	v_pk_mul_f32 v[116:117], v[224:225], v[116:117]
	v_cvt_pk_bf16_f32 v36, v118, v119
	v_cvt_pk_bf16_f32 v37, v120, v121
	v_cvt_pk_bf16_f32 v38, v114, v115
	v_cvt_pk_bf16_f32 v39, v116, v117
	v_mov_b32_dpp v132, v32 quad_perm:[1,0,3,2] row_mask:0xf bank_mask:0xf
	v_mov_b32_dpp v133, v33 quad_perm:[1,0,3,2] row_mask:0xf bank_mask:0xf
	v_mov_b32_dpp v134, v34 quad_perm:[1,0,3,2] row_mask:0xf bank_mask:0xf
	v_mov_b32_dpp v135, v35 quad_perm:[1,0,3,2] row_mask:0xf bank_mask:0xf
	v_mov_b32_dpp v138, v36 quad_perm:[1,0,3,2] row_mask:0xf bank_mask:0xf
	v_mov_b32_dpp v139, v37 quad_perm:[1,0,3,2] row_mask:0xf bank_mask:0xf
	v_mov_b32_dpp v140, v38 quad_perm:[1,0,3,2] row_mask:0xf bank_mask:0xf
	v_mov_b32_dpp v141, v39 quad_perm:[1,0,3,2] row_mask:0xf bank_mask:0xf
	s_mov_b64 exec, s[62:63]
	v_mov_b32_e32 v32, v138
	v_mov_b32_e32 v33, v139
	v_mov_b32_e32 v34, v140
	v_mov_b32_e32 v35, v141
	s_mov_b64 exec, s[66:67]
	v_mov_b32_e32 v36, v132
	v_mov_b32_e32 v37, v133
	v_mov_b32_e32 v38, v134
	v_mov_b32_e32 v39, v135
	s_mov_b64 exec, -1
	global_store_dwordx4 v149, v[32:35], s[92:93]
	global_store_dwordx4 v149, v[36:39], s[92:93] offset:2048
	v_mov_b32_e32 v114, v151
	s_add_u32 s84, s58, 0x18000
	s_addc_u32 s85, s59, 0
	s_add_u32 s86, s74, 0xc000
	s_addc_u32 s87, s75, 0
	global_load_dwordx4 v[116:119], v149, s[84:85]
	global_load_dwordx2 v[120:121], v148, s[86:87]
	global_load_dwordx4 v[122:125], v149, s[84:85] offset:2048
	global_load_dwordx2 v[126:127], v148, s[86:87] offset:1024
	s_waitcnt vmcnt(10)
	v_mov_b32_dpp v32, v226 quad_perm:[1,0,3,2] row_mask:0xf bank_mask:0xf
	v_mov_b32_dpp v33, v227 quad_perm:[1,0,3,2] row_mask:0xf bank_mask:0xf
	v_mov_b32_dpp v34, v228 quad_perm:[1,0,3,2] row_mask:0xf bank_mask:0xf
	v_mov_b32_dpp v35, v229 quad_perm:[1,0,3,2] row_mask:0xf bank_mask:0xf
	v_mov_b32_dpp v36, v230 quad_perm:[1,0,3,2] row_mask:0xf bank_mask:0xf
	v_mov_b32_dpp v37, v231 quad_perm:[1,0,3,2] row_mask:0xf bank_mask:0xf
	v_mov_b32_dpp v38, v232 quad_perm:[1,0,3,2] row_mask:0xf bank_mask:0xf
	v_mov_b32_dpp v39, v233 quad_perm:[1,0,3,2] row_mask:0xf bank_mask:0xf
	s_mov_b64 exec, s[62:63]
	v_mov_b32_e32 v226, v36
	v_mov_b32_e32 v227, v37
	v_mov_b32_e32 v228, v38
	v_mov_b32_e32 v229, v39
	s_mov_b64 exec, s[66:67]
	v_mov_b32_e32 v230, v32
	v_mov_b32_e32 v231, v33
	v_mov_b32_e32 v232, v34
	v_mov_b32_e32 v233, v35
	s_mov_b64 exec, -1
	v_mov_b32_dpp v32, v144 quad_perm:[1,0,3,2] row_mask:0xf bank_mask:0xf
	v_mov_b32_dpp v33, v145 quad_perm:[1,0,3,2] row_mask:0xf bank_mask:0xf
	v_mov_b32_dpp v36, v152 quad_perm:[1,0,3,2] row_mask:0xf bank_mask:0xf
	v_mov_b32_dpp v37, v153 quad_perm:[1,0,3,2] row_mask:0xf bank_mask:0xf
	s_mov_b64 exec, s[62:63]
	v_mov_b32_e32 v144, v36
	v_mov_b32_e32 v145, v37
	s_mov_b64 exec, s[66:67]
	v_mov_b32_e32 v152, v32
	v_mov_b32_e32 v153, v33
	s_mov_b64 exec, -1
	v_lshlrev_b32_e32 v28, 8, v144
	v_perm_b32 v29, v226, v144, s8
	v_lshrrev_b32_e32 v30, 8, v144
	v_lshrrev_b32_e32 v31, 16, v144
	v_perm_b32 v28, v226, v28, s33
	v_perm_b32 v30, v227, v30, s33
	v_perm_b32 v31, v227, v31, s8
	v_pk_fma_f32 v[110:111], v[110:111], v[176:177], v[28:29]
	v_pk_fma_f32 v[112:113], v[112:113], v[178:179], v[30:31]
	v_lshlrev_b32_e32 v28, 8, v145
	v_perm_b32 v29, v228, v145, s8
	v_lshrrev_b32_e32 v30, 8, v145
	v_lshrrev_b32_e32 v31, 16, v145
	v_perm_b32 v28, v228, v28, s33
	v_perm_b32 v30, v229, v30, s33
	v_perm_b32 v31, v229, v31, s8
	v_pk_fma_f32 v[106:107], v[106:107], v[180:181], v[28:29]
	v_pk_fma_f32 v[108:109], v[108:109], v[182:183], v[30:31]
	v_lshlrev_b32_e32 v28, 8, v152
	v_perm_b32 v29, v230, v152, s8
	v_lshrrev_b32_e32 v30, 8, v152
	v_lshrrev_b32_e32 v31, 16, v152
	v_perm_b32 v28, v230, v28, s33
	v_perm_b32 v30, v231, v30, s33
	v_perm_b32 v31, v231, v31, s8
	v_pk_fma_f32 v[102:103], v[102:103], v[184:185], v[28:29]
	v_pk_fma_f32 v[104:105], v[104:105], v[186:187], v[30:31]
	v_lshlrev_b32_e32 v28, 8, v153
	v_perm_b32 v29, v232, v153, s8
	v_lshrrev_b32_e32 v30, 8, v153
	v_lshrrev_b32_e32 v31, 16, v153
	v_perm_b32 v28, v232, v28, s33
	v_perm_b32 v30, v233, v30, s33
	v_perm_b32 v31, v233, v31, s8
	v_pk_fma_f32 v[98:99], v[98:99], v[188:189], v[28:29]
	v_pk_fma_f32 v[100:101], v[100:101], v[190:191], v[30:31]
	v_mul_f32_e32 v28, v111, v111
	v_mul_f32_e32 v29, v113, v113
	v_mul_f32_e32 v30, v107, v107
	v_mul_f32_e32 v31, v109, v109
	v_fmac_f32_e32 v28, v110, v110
	v_fmac_f32_e32 v29, v112, v112
	v_fmac_f32_e32 v30, v106, v106
	v_fmac_f32_e32 v31, v108, v108
	v_add_f32_e32 v28, v28, v29
	v_add_f32_e32 v30, v30, v31
	v_add_f32_e32 v151, v28, v30
	v_add_u32_e32 v28, 0x80, v110
	v_add_u32_e32 v29, 0x80, v111
	v_add_u32_e32 v30, 0x80, v112
	v_add_u32_e32 v31, 0x80, v113
	v_perm_b32 v32, v29, v28, s78
	v_perm_b32 v33, v31, v30, s78
	v_perm_b32 v26, v29, v28, s79
	v_perm_b32 v27, v31, v30, s79
	v_perm_b32 v40, v27, v26, s60
	v_add_u32_e32 v28, 0x80, v106
	v_add_u32_e32 v29, 0x80, v107
	v_add_u32_e32 v30, 0x80, v108
	v_add_u32_e32 v31, 0x80, v109
	v_perm_b32 v34, v29, v28, s78
	v_perm_b32 v35, v31, v30, s78
	v_perm_b32 v26, v29, v28, s79
	v_perm_b32 v27, v31, v30, s79
	v_perm_b32 v41, v27, v26, s60
	v_mul_f32_e32 v28, v103, v103
	v_mul_f32_e32 v29, v105, v105
	v_mul_f32_e32 v30, v99, v99
	v_mul_f32_e32 v31, v101, v101
	v_fmac_f32_e32 v28, v102, v102
	v_fmac_f32_e32 v29, v104, v104
	v_fmac_f32_e32 v30, v98, v98
	v_fmac_f32_e32 v31, v100, v100
	v_add_f32_e32 v28, v28, v29
	v_add_f32_e32 v30, v30, v31
	v_add_f32_e32 v28, v28, v30
	v_add_f32_e32 v151, v151, v28
	v_add_u32_e32 v28, 0x80, v102
	v_add_u32_e32 v29, 0x80, v103
	v_add_u32_e32 v30, 0x80, v104
	v_add_u32_e32 v31, 0x80, v105
	v_perm_b32 v36, v29, v28, s78
	v_perm_b32 v37, v31, v30, s78
	v_perm_b32 v26, v29, v28, s79
	v_perm_b32 v27, v31, v30, s79
	v_perm_b32 v146, v27, v26, s60
	v_add_u32_e32 v28, 0x80, v98
	v_add_u32_e32 v29, 0x80, v99
	v_add_u32_e32 v30, 0x80, v100
	v_add_u32_e32 v31, 0x80, v101
	v_perm_b32 v38, v29, v28, s78
	v_perm_b32 v39, v31, v30, s78
	v_perm_b32 v26, v29, v28, s79
	v_perm_b32 v27, v31, v30, s79
	v_perm_b32 v147, v27, v26, s60
	v_mov_b32_dpp v226, v32 quad_perm:[1,0,3,2] row_mask:0xf bank_mask:0xf
	v_mov_b32_dpp v227, v33 quad_perm:[1,0,3,2] row_mask:0xf bank_mask:0xf
	v_mov_b32_dpp v228, v34 quad_perm:[1,0,3,2] row_mask:0xf bank_mask:0xf
	v_mov_b32_dpp v229, v35 quad_perm:[1,0,3,2] row_mask:0xf bank_mask:0xf
	v_mov_b32_dpp v230, v36 quad_perm:[1,0,3,2] row_mask:0xf bank_mask:0xf
	v_mov_b32_dpp v231, v37 quad_perm:[1,0,3,2] row_mask:0xf bank_mask:0xf
	v_mov_b32_dpp v232, v38 quad_perm:[1,0,3,2] row_mask:0xf bank_mask:0xf
	v_mov_b32_dpp v233, v39 quad_perm:[1,0,3,2] row_mask:0xf bank_mask:0xf
	s_mov_b64 exec, s[62:63]
	v_mov_b32_e32 v32, v230
	v_mov_b32_e32 v33, v231
	v_mov_b32_e32 v34, v232
	v_mov_b32_e32 v35, v233
	s_mov_b64 exec, s[66:67]
	v_mov_b32_e32 v36, v226
	v_mov_b32_e32 v37, v227
	v_mov_b32_e32 v38, v228
	v_mov_b32_e32 v39, v229
	s_mov_b64 exec, -1
	v_mov_b32_dpp v226, v40 quad_perm:[1,0,3,2] row_mask:0xf bank_mask:0xf
	v_mov_b32_dpp v227, v41 quad_perm:[1,0,3,2] row_mask:0xf bank_mask:0xf
	v_mov_b32_dpp v230, v146 quad_perm:[1,0,3,2] row_mask:0xf bank_mask:0xf
	v_mov_b32_dpp v231, v147 quad_perm:[1,0,3,2] row_mask:0xf bank_mask:0xf
	s_mov_b64 exec, s[62:63]
	v_mov_b32_e32 v40, v230
	v_mov_b32_e32 v41, v231
	s_mov_b64 exec, s[66:67]
	v_mov_b32_e32 v146, v226
	v_mov_b32_e32 v147, v227
	s_mov_b64 exec, -1
	s_add_u32 s88, s58, 0x10000
	s_addc_u32 s89, s59, 0
	s_add_u32 s90, s74, 0x8000
	s_addc_u32 s91, s75, 0
	global_store_dwordx4 v149, v[32:35], s[88:89]
	global_store_dwordx4 v149, v[36:39], s[88:89] offset:2048
	global_store_dwordx2 v148, v[40:41], s[90:91]
	global_store_dwordx2 v148, v[146:147], s[90:91] offset:1024
	s_add_u32 s92, s96, 0x10000
	s_addc_u32 s93, s97, 0
	v_pk_mul_f32 v[110:111], v[210:211], v[110:111]
	v_pk_mul_f32 v[112:113], v[212:213], v[112:113]
	v_pk_mul_f32 v[106:107], v[214:215], v[106:107]
	v_pk_mul_f32 v[108:109], v[216:217], v[108:109]
	v_cvt_pk_bf16_f32 v32, v110, v111
	v_cvt_pk_bf16_f32 v33, v112, v113
	v_cvt_pk_bf16_f32 v34, v106, v107
	v_cvt_pk_bf16_f32 v35, v108, v109
	v_pk_mul_f32 v[102:103], v[218:219], v[102:103]
	v_pk_mul_f32 v[104:105], v[220:221], v[104:105]
	v_pk_mul_f32 v[98:99], v[222:223], v[98:99]
	v_pk_mul_f32 v[100:101], v[224:225], v[100:101]
	v_cvt_pk_bf16_f32 v36, v102, v103
	v_cvt_pk_bf16_f32 v37, v104, v105
	v_cvt_pk_bf16_f32 v38, v98, v99
	v_cvt_pk_bf16_f32 v39, v100, v101
	v_mov_b32_dpp v226, v32 quad_perm:[1,0,3,2] row_mask:0xf bank_mask:0xf
	v_mov_b32_dpp v227, v33 quad_perm:[1,0,3,2] row_mask:0xf bank_mask:0xf
	v_mov_b32_dpp v228, v34 quad_perm:[1,0,3,2] row_mask:0xf bank_mask:0xf
	v_mov_b32_dpp v229, v35 quad_perm:[1,0,3,2] row_mask:0xf bank_mask:0xf
	v_mov_b32_dpp v230, v36 quad_perm:[1,0,3,2] row_mask:0xf bank_mask:0xf
	v_mov_b32_dpp v231, v37 quad_perm:[1,0,3,2] row_mask:0xf bank_mask:0xf
	v_mov_b32_dpp v232, v38 quad_perm:[1,0,3,2] row_mask:0xf bank_mask:0xf
	v_mov_b32_dpp v233, v39 quad_perm:[1,0,3,2] row_mask:0xf bank_mask:0xf
	s_mov_b64 exec, s[62:63]
	v_mov_b32_e32 v32, v230
	v_mov_b32_e32 v33, v231
	v_mov_b32_e32 v34, v232
	v_mov_b32_e32 v35, v233
	s_mov_b64 exec, s[66:67]
	v_mov_b32_e32 v36, v226
	v_mov_b32_e32 v37, v227
	v_mov_b32_e32 v38, v228
	v_mov_b32_e32 v39, v229
	s_mov_b64 exec, -1
	global_store_dwordx4 v149, v[32:35], s[92:93]
	global_store_dwordx4 v149, v[36:39], s[92:93] offset:2048
	v_mov_b32_e32 v98, v151
	s_add_u32 s84, s58, 0x40000
	s_addc_u32 s85, s59, 0
	s_add_u32 s86, s74, 0x20000
	s_addc_u32 s87, s75, 0
	global_load_dwordx4 v[100:103], v149, s[84:85]
	global_load_dwordx2 v[104:105], v148, s[86:87]
	global_load_dwordx4 v[106:109], v149, s[84:85] offset:2048
	global_load_dwordx2 v[110:111], v148, s[86:87] offset:1024
	s_waitcnt vmcnt(10)
	v_mov_b32_dpp v32, v116 quad_perm:[1,0,3,2] row_mask:0xf bank_mask:0xf
	v_mov_b32_dpp v33, v117 quad_perm:[1,0,3,2] row_mask:0xf bank_mask:0xf
	v_mov_b32_dpp v34, v118 quad_perm:[1,0,3,2] row_mask:0xf bank_mask:0xf
	v_mov_b32_dpp v35, v119 quad_perm:[1,0,3,2] row_mask:0xf bank_mask:0xf
	v_mov_b32_dpp v36, v122 quad_perm:[1,0,3,2] row_mask:0xf bank_mask:0xf
	v_mov_b32_dpp v37, v123 quad_perm:[1,0,3,2] row_mask:0xf bank_mask:0xf
	v_mov_b32_dpp v38, v124 quad_perm:[1,0,3,2] row_mask:0xf bank_mask:0xf
	v_mov_b32_dpp v39, v125 quad_perm:[1,0,3,2] row_mask:0xf bank_mask:0xf
	s_mov_b64 exec, s[62:63]
	v_mov_b32_e32 v116, v36
	v_mov_b32_e32 v117, v37
	v_mov_b32_e32 v118, v38
	v_mov_b32_e32 v119, v39
	s_mov_b64 exec, s[66:67]
	v_mov_b32_e32 v122, v32
	v_mov_b32_e32 v123, v33
	v_mov_b32_e32 v124, v34
	v_mov_b32_e32 v125, v35
	s_mov_b64 exec, -1
	v_mov_b32_dpp v32, v120 quad_perm:[1,0,3,2] row_mask:0xf bank_mask:0xf
	v_mov_b32_dpp v33, v121 quad_perm:[1,0,3,2] row_mask:0xf bank_mask:0xf
	v_mov_b32_dpp v36, v126 quad_perm:[1,0,3,2] row_mask:0xf bank_mask:0xf
	v_mov_b32_dpp v37, v127 quad_perm:[1,0,3,2] row_mask:0xf bank_mask:0xf
	s_mov_b64 exec, s[62:63]
	v_mov_b32_e32 v120, v36
	v_mov_b32_e32 v121, v37
	s_mov_b64 exec, s[66:67]
	v_mov_b32_e32 v126, v32
	v_mov_b32_e32 v127, v33
	s_mov_b64 exec, -1
	v_lshlrev_b32_e32 v28, 8, v120
	v_perm_b32 v29, v116, v120, s8
	v_lshrrev_b32_e32 v30, 8, v120
	v_lshrrev_b32_e32 v31, 16, v120
	v_perm_b32 v28, v116, v28, s33
	v_perm_b32 v30, v117, v30, s33
	v_perm_b32 v31, v117, v31, s8
	v_pk_fma_f32 v[94:95], v[94:95], v[176:177], v[28:29]
	v_pk_fma_f32 v[96:97], v[96:97], v[178:179], v[30:31]
	v_lshlrev_b32_e32 v28, 8, v121
	v_perm_b32 v29, v118, v121, s8
	v_lshrrev_b32_e32 v30, 8, v121
	v_lshrrev_b32_e32 v31, 16, v121
	v_perm_b32 v28, v118, v28, s33
	v_perm_b32 v30, v119, v30, s33
	v_perm_b32 v31, v119, v31, s8
	v_pk_fma_f32 v[90:91], v[90:91], v[180:181], v[28:29]
	v_pk_fma_f32 v[92:93], v[92:93], v[182:183], v[30:31]
	v_lshlrev_b32_e32 v28, 8, v126
	v_perm_b32 v29, v122, v126, s8
	v_lshrrev_b32_e32 v30, 8, v126
	v_lshrrev_b32_e32 v31, 16, v126
	v_perm_b32 v28, v122, v28, s33
	v_perm_b32 v30, v123, v30, s33
	v_perm_b32 v31, v123, v31, s8
	v_pk_fma_f32 v[86:87], v[86:87], v[184:185], v[28:29]
	v_pk_fma_f32 v[88:89], v[88:89], v[186:187], v[30:31]
	v_lshlrev_b32_e32 v28, 8, v127
	v_perm_b32 v29, v124, v127, s8
	v_lshrrev_b32_e32 v30, 8, v127
	v_lshrrev_b32_e32 v31, 16, v127
	v_perm_b32 v28, v124, v28, s33
	v_perm_b32 v30, v125, v30, s33
	v_perm_b32 v31, v125, v31, s8
	v_pk_fma_f32 v[82:83], v[82:83], v[188:189], v[28:29]
	v_pk_fma_f32 v[84:85], v[84:85], v[190:191], v[30:31]
	v_mul_f32_e32 v28, v95, v95
	v_mul_f32_e32 v29, v97, v97
	v_mul_f32_e32 v30, v91, v91
	v_mul_f32_e32 v31, v93, v93
	v_fmac_f32_e32 v28, v94, v94
	v_fmac_f32_e32 v29, v96, v96
	v_fmac_f32_e32 v30, v90, v90
	v_fmac_f32_e32 v31, v92, v92
	v_add_f32_e32 v28, v28, v29
	v_add_f32_e32 v30, v30, v31
	v_add_f32_e32 v151, v28, v30
	v_add_u32_e32 v28, 0x80, v94
	v_add_u32_e32 v29, 0x80, v95
	v_add_u32_e32 v30, 0x80, v96
	v_add_u32_e32 v31, 0x80, v97
	v_perm_b32 v32, v29, v28, s78
	v_perm_b32 v33, v31, v30, s78
	v_perm_b32 v26, v29, v28, s79
	v_perm_b32 v27, v31, v30, s79
	v_perm_b32 v40, v27, v26, s60
	v_add_u32_e32 v28, 0x80, v90
	v_add_u32_e32 v29, 0x80, v91
	v_add_u32_e32 v30, 0x80, v92
	v_add_u32_e32 v31, 0x80, v93
	v_perm_b32 v34, v29, v28, s78
	v_perm_b32 v35, v31, v30, s78
	v_perm_b32 v26, v29, v28, s79
	v_perm_b32 v27, v31, v30, s79
	v_perm_b32 v41, v27, v26, s60
	v_mul_f32_e32 v28, v87, v87
	v_mul_f32_e32 v29, v89, v89
	v_mul_f32_e32 v30, v83, v83
	v_mul_f32_e32 v31, v85, v85
	v_fmac_f32_e32 v28, v86, v86
	v_fmac_f32_e32 v29, v88, v88
	v_fmac_f32_e32 v30, v82, v82
	v_fmac_f32_e32 v31, v84, v84
	v_add_f32_e32 v28, v28, v29
	v_add_f32_e32 v30, v30, v31
	v_add_f32_e32 v28, v28, v30
	v_add_f32_e32 v151, v151, v28
	v_add_u32_e32 v28, 0x80, v86
	v_add_u32_e32 v29, 0x80, v87
	v_add_u32_e32 v30, 0x80, v88
	v_add_u32_e32 v31, 0x80, v89
	v_perm_b32 v36, v29, v28, s78
	v_perm_b32 v37, v31, v30, s78
	v_perm_b32 v26, v29, v28, s79
	v_perm_b32 v27, v31, v30, s79
	v_perm_b32 v146, v27, v26, s60
	v_add_u32_e32 v28, 0x80, v82
	v_add_u32_e32 v29, 0x80, v83
	v_add_u32_e32 v30, 0x80, v84
	v_add_u32_e32 v31, 0x80, v85
	v_perm_b32 v38, v29, v28, s78
	v_perm_b32 v39, v31, v30, s78
	v_perm_b32 v26, v29, v28, s79
	v_perm_b32 v27, v31, v30, s79
	v_perm_b32 v147, v27, v26, s60
	v_mov_b32_dpp v116, v32 quad_perm:[1,0,3,2] row_mask:0xf bank_mask:0xf
	v_mov_b32_dpp v117, v33 quad_perm:[1,0,3,2] row_mask:0xf bank_mask:0xf
	v_mov_b32_dpp v118, v34 quad_perm:[1,0,3,2] row_mask:0xf bank_mask:0xf
	v_mov_b32_dpp v119, v35 quad_perm:[1,0,3,2] row_mask:0xf bank_mask:0xf
	v_mov_b32_dpp v122, v36 quad_perm:[1,0,3,2] row_mask:0xf bank_mask:0xf
	v_mov_b32_dpp v123, v37 quad_perm:[1,0,3,2] row_mask:0xf bank_mask:0xf
	v_mov_b32_dpp v124, v38 quad_perm:[1,0,3,2] row_mask:0xf bank_mask:0xf
	v_mov_b32_dpp v125, v39 quad_perm:[1,0,3,2] row_mask:0xf bank_mask:0xf
	s_mov_b64 exec, s[62:63]
	v_mov_b32_e32 v32, v122
	v_mov_b32_e32 v33, v123
	v_mov_b32_e32 v34, v124
	v_mov_b32_e32 v35, v125
	s_mov_b64 exec, s[66:67]
	v_mov_b32_e32 v36, v116
	v_mov_b32_e32 v37, v117
	v_mov_b32_e32 v38, v118
	v_mov_b32_e32 v39, v119
	s_mov_b64 exec, -1
	v_mov_b32_dpp v116, v40 quad_perm:[1,0,3,2] row_mask:0xf bank_mask:0xf
	v_mov_b32_dpp v117, v41 quad_perm:[1,0,3,2] row_mask:0xf bank_mask:0xf
	v_mov_b32_dpp v122, v146 quad_perm:[1,0,3,2] row_mask:0xf bank_mask:0xf
	v_mov_b32_dpp v123, v147 quad_perm:[1,0,3,2] row_mask:0xf bank_mask:0xf
	s_mov_b64 exec, s[62:63]
	v_mov_b32_e32 v40, v122
	v_mov_b32_e32 v41, v123
	s_mov_b64 exec, s[66:67]
	v_mov_b32_e32 v146, v116
	v_mov_b32_e32 v147, v117
	s_mov_b64 exec, -1
	s_add_u32 s88, s58, 0x18000
	s_addc_u32 s89, s59, 0
	s_add_u32 s90, s74, 0xc000
	s_addc_u32 s91, s75, 0
	global_store_dwordx4 v149, v[32:35], s[88:89]
	global_store_dwordx4 v149, v[36:39], s[88:89] offset:2048
	global_store_dwordx2 v148, v[40:41], s[90:91]
	global_store_dwordx2 v148, v[146:147], s[90:91] offset:1024
	s_add_u32 s92, s96, 0x18000
	s_addc_u32 s93, s97, 0
	v_pk_mul_f32 v[94:95], v[210:211], v[94:95]
	v_pk_mul_f32 v[96:97], v[212:213], v[96:97]
	v_pk_mul_f32 v[90:91], v[214:215], v[90:91]
	v_pk_mul_f32 v[92:93], v[216:217], v[92:93]
	v_cvt_pk_bf16_f32 v32, v94, v95
	v_cvt_pk_bf16_f32 v33, v96, v97
	v_cvt_pk_bf16_f32 v34, v90, v91
	v_cvt_pk_bf16_f32 v35, v92, v93
	v_pk_mul_f32 v[86:87], v[218:219], v[86:87]
	v_pk_mul_f32 v[88:89], v[220:221], v[88:89]
	v_pk_mul_f32 v[82:83], v[222:223], v[82:83]
	v_pk_mul_f32 v[84:85], v[224:225], v[84:85]
	v_cvt_pk_bf16_f32 v36, v86, v87
	v_cvt_pk_bf16_f32 v37, v88, v89
	v_cvt_pk_bf16_f32 v38, v82, v83
	v_cvt_pk_bf16_f32 v39, v84, v85
	v_mov_b32_dpp v116, v32 quad_perm:[1,0,3,2] row_mask:0xf bank_mask:0xf
	v_mov_b32_dpp v117, v33 quad_perm:[1,0,3,2] row_mask:0xf bank_mask:0xf
	v_mov_b32_dpp v118, v34 quad_perm:[1,0,3,2] row_mask:0xf bank_mask:0xf
	v_mov_b32_dpp v119, v35 quad_perm:[1,0,3,2] row_mask:0xf bank_mask:0xf
	v_mov_b32_dpp v122, v36 quad_perm:[1,0,3,2] row_mask:0xf bank_mask:0xf
	v_mov_b32_dpp v123, v37 quad_perm:[1,0,3,2] row_mask:0xf bank_mask:0xf
	v_mov_b32_dpp v124, v38 quad_perm:[1,0,3,2] row_mask:0xf bank_mask:0xf
	v_mov_b32_dpp v125, v39 quad_perm:[1,0,3,2] row_mask:0xf bank_mask:0xf
	s_mov_b64 exec, s[62:63]
	v_mov_b32_e32 v32, v122
	v_mov_b32_e32 v33, v123
	v_mov_b32_e32 v34, v124
	v_mov_b32_e32 v35, v125
	s_mov_b64 exec, s[66:67]
	v_mov_b32_e32 v36, v116
	v_mov_b32_e32 v37, v117
	v_mov_b32_e32 v38, v118
	v_mov_b32_e32 v39, v119
	s_mov_b64 exec, -1
	global_store_dwordx4 v149, v[32:35], s[92:93]
	global_store_dwordx4 v149, v[36:39], s[92:93] offset:2048
	v_mov_b32_e32 v82, v151
	s_add_u32 s84, s58, 0x48000
	s_addc_u32 s85, s59, 0
	s_add_u32 s86, s74, 0x24000
	s_addc_u32 s87, s75, 0
	global_load_dwordx4 v[84:87], v149, s[84:85]
	global_load_dwordx2 v[88:89], v148, s[86:87]
	global_load_dwordx4 v[90:93], v149, s[84:85] offset:2048
	global_load_dwordx2 v[94:95], v148, s[86:87] offset:1024
	s_waitcnt vmcnt(10)
	v_mov_b32_dpp v32, v100 quad_perm:[1,0,3,2] row_mask:0xf bank_mask:0xf
	v_mov_b32_dpp v33, v101 quad_perm:[1,0,3,2] row_mask:0xf bank_mask:0xf
	v_mov_b32_dpp v34, v102 quad_perm:[1,0,3,2] row_mask:0xf bank_mask:0xf
	v_mov_b32_dpp v35, v103 quad_perm:[1,0,3,2] row_mask:0xf bank_mask:0xf
	v_mov_b32_dpp v36, v106 quad_perm:[1,0,3,2] row_mask:0xf bank_mask:0xf
	v_mov_b32_dpp v37, v107 quad_perm:[1,0,3,2] row_mask:0xf bank_mask:0xf
	v_mov_b32_dpp v38, v108 quad_perm:[1,0,3,2] row_mask:0xf bank_mask:0xf
	v_mov_b32_dpp v39, v109 quad_perm:[1,0,3,2] row_mask:0xf bank_mask:0xf
	s_mov_b64 exec, s[62:63]
	v_mov_b32_e32 v100, v36
	v_mov_b32_e32 v101, v37
	v_mov_b32_e32 v102, v38
	v_mov_b32_e32 v103, v39
	s_mov_b64 exec, s[66:67]
	v_mov_b32_e32 v106, v32
	v_mov_b32_e32 v107, v33
	v_mov_b32_e32 v108, v34
	v_mov_b32_e32 v109, v35
	s_mov_b64 exec, -1
	v_mov_b32_dpp v32, v104 quad_perm:[1,0,3,2] row_mask:0xf bank_mask:0xf
	v_mov_b32_dpp v33, v105 quad_perm:[1,0,3,2] row_mask:0xf bank_mask:0xf
	v_mov_b32_dpp v36, v110 quad_perm:[1,0,3,2] row_mask:0xf bank_mask:0xf
	v_mov_b32_dpp v37, v111 quad_perm:[1,0,3,2] row_mask:0xf bank_mask:0xf
	s_mov_b64 exec, s[62:63]
	v_mov_b32_e32 v104, v36
	v_mov_b32_e32 v105, v37
	s_mov_b64 exec, s[66:67]
	v_mov_b32_e32 v110, v32
	v_mov_b32_e32 v111, v33
	s_mov_b64 exec, -1
	v_lshlrev_b32_e32 v28, 8, v104
	v_perm_b32 v29, v100, v104, s8
	v_lshrrev_b32_e32 v30, 8, v104
	v_lshrrev_b32_e32 v31, 16, v104
	v_perm_b32 v28, v100, v28, s33
	v_perm_b32 v30, v101, v30, s33
	v_perm_b32 v31, v101, v31, s8
	v_pk_fma_f32 v[78:79], v[78:79], v[176:177], v[28:29]
	v_pk_fma_f32 v[80:81], v[80:81], v[178:179], v[30:31]
	v_lshlrev_b32_e32 v28, 8, v105
	v_perm_b32 v29, v102, v105, s8
	v_lshrrev_b32_e32 v30, 8, v105
	v_lshrrev_b32_e32 v31, 16, v105
	v_perm_b32 v28, v102, v28, s33
	v_perm_b32 v30, v103, v30, s33
	v_perm_b32 v31, v103, v31, s8
	v_pk_fma_f32 v[74:75], v[74:75], v[180:181], v[28:29]
	v_pk_fma_f32 v[76:77], v[76:77], v[182:183], v[30:31]
	v_lshlrev_b32_e32 v28, 8, v110
	v_perm_b32 v29, v106, v110, s8
	v_lshrrev_b32_e32 v30, 8, v110
	v_lshrrev_b32_e32 v31, 16, v110
	v_perm_b32 v28, v106, v28, s33
	v_perm_b32 v30, v107, v30, s33
	v_perm_b32 v31, v107, v31, s8
	v_pk_fma_f32 v[70:71], v[70:71], v[184:185], v[28:29]
	v_pk_fma_f32 v[72:73], v[72:73], v[186:187], v[30:31]
	v_lshlrev_b32_e32 v28, 8, v111
	v_perm_b32 v29, v108, v111, s8
	v_lshrrev_b32_e32 v30, 8, v111
	v_lshrrev_b32_e32 v31, 16, v111
	v_perm_b32 v28, v108, v28, s33
	v_perm_b32 v30, v109, v30, s33
	v_perm_b32 v31, v109, v31, s8
	v_pk_fma_f32 v[66:67], v[66:67], v[188:189], v[28:29]
	v_pk_fma_f32 v[68:69], v[68:69], v[190:191], v[30:31]
	v_mul_f32_e32 v28, v79, v79
	v_mul_f32_e32 v29, v81, v81
	v_mul_f32_e32 v30, v75, v75
	v_mul_f32_e32 v31, v77, v77
	v_fmac_f32_e32 v28, v78, v78
	v_fmac_f32_e32 v29, v80, v80
	v_fmac_f32_e32 v30, v74, v74
	v_fmac_f32_e32 v31, v76, v76
	v_add_f32_e32 v28, v28, v29
	v_add_f32_e32 v30, v30, v31
	v_add_f32_e32 v151, v28, v30
	v_add_u32_e32 v28, 0x80, v78
	v_add_u32_e32 v29, 0x80, v79
	v_add_u32_e32 v30, 0x80, v80
	v_add_u32_e32 v31, 0x80, v81
	v_perm_b32 v32, v29, v28, s78
	v_perm_b32 v33, v31, v30, s78
	v_perm_b32 v26, v29, v28, s79
	v_perm_b32 v27, v31, v30, s79
	v_perm_b32 v40, v27, v26, s60
	v_add_u32_e32 v28, 0x80, v74
	v_add_u32_e32 v29, 0x80, v75
	v_add_u32_e32 v30, 0x80, v76
	v_add_u32_e32 v31, 0x80, v77
	v_perm_b32 v34, v29, v28, s78
	v_perm_b32 v35, v31, v30, s78
	v_perm_b32 v26, v29, v28, s79
	v_perm_b32 v27, v31, v30, s79
	v_perm_b32 v41, v27, v26, s60
	v_mul_f32_e32 v28, v71, v71
	v_mul_f32_e32 v29, v73, v73
	v_mul_f32_e32 v30, v67, v67
	v_mul_f32_e32 v31, v69, v69
	v_fmac_f32_e32 v28, v70, v70
	v_fmac_f32_e32 v29, v72, v72
	v_fmac_f32_e32 v30, v66, v66
	v_fmac_f32_e32 v31, v68, v68
	v_add_f32_e32 v28, v28, v29
	v_add_f32_e32 v30, v30, v31
	v_add_f32_e32 v28, v28, v30
	v_add_f32_e32 v151, v151, v28
	v_add_u32_e32 v28, 0x80, v70
	v_add_u32_e32 v29, 0x80, v71
	v_add_u32_e32 v30, 0x80, v72
	v_add_u32_e32 v31, 0x80, v73
	v_perm_b32 v36, v29, v28, s78
	v_perm_b32 v37, v31, v30, s78
	v_perm_b32 v26, v29, v28, s79
	v_perm_b32 v27, v31, v30, s79
	v_perm_b32 v146, v27, v26, s60
	v_add_u32_e32 v28, 0x80, v66
	v_add_u32_e32 v29, 0x80, v67
	v_add_u32_e32 v30, 0x80, v68
	v_add_u32_e32 v31, 0x80, v69
	v_perm_b32 v38, v29, v28, s78
	v_perm_b32 v39, v31, v30, s78
	v_perm_b32 v26, v29, v28, s79
	v_perm_b32 v27, v31, v30, s79
	v_perm_b32 v147, v27, v26, s60
	v_mov_b32_dpp v100, v32 quad_perm:[1,0,3,2] row_mask:0xf bank_mask:0xf
	v_mov_b32_dpp v101, v33 quad_perm:[1,0,3,2] row_mask:0xf bank_mask:0xf
	v_mov_b32_dpp v102, v34 quad_perm:[1,0,3,2] row_mask:0xf bank_mask:0xf
	v_mov_b32_dpp v103, v35 quad_perm:[1,0,3,2] row_mask:0xf bank_mask:0xf
	v_mov_b32_dpp v106, v36 quad_perm:[1,0,3,2] row_mask:0xf bank_mask:0xf
	v_mov_b32_dpp v107, v37 quad_perm:[1,0,3,2] row_mask:0xf bank_mask:0xf
	v_mov_b32_dpp v108, v38 quad_perm:[1,0,3,2] row_mask:0xf bank_mask:0xf
	v_mov_b32_dpp v109, v39 quad_perm:[1,0,3,2] row_mask:0xf bank_mask:0xf
	s_mov_b64 exec, s[62:63]
	v_mov_b32_e32 v32, v106
	v_mov_b32_e32 v33, v107
	v_mov_b32_e32 v34, v108
	v_mov_b32_e32 v35, v109
	s_mov_b64 exec, s[66:67]
	v_mov_b32_e32 v36, v100
	v_mov_b32_e32 v37, v101
	v_mov_b32_e32 v38, v102
	v_mov_b32_e32 v39, v103
	s_mov_b64 exec, -1
	v_mov_b32_dpp v100, v40 quad_perm:[1,0,3,2] row_mask:0xf bank_mask:0xf
	v_mov_b32_dpp v101, v41 quad_perm:[1,0,3,2] row_mask:0xf bank_mask:0xf
	v_mov_b32_dpp v106, v146 quad_perm:[1,0,3,2] row_mask:0xf bank_mask:0xf
	v_mov_b32_dpp v107, v147 quad_perm:[1,0,3,2] row_mask:0xf bank_mask:0xf
	s_mov_b64 exec, s[62:63]
	v_mov_b32_e32 v40, v106
	v_mov_b32_e32 v41, v107
	s_mov_b64 exec, s[66:67]
	v_mov_b32_e32 v146, v100
	v_mov_b32_e32 v147, v101
	s_mov_b64 exec, -1
	s_add_u32 s88, s58, 0x40000
	s_addc_u32 s89, s59, 0
	s_add_u32 s90, s74, 0x20000
	s_addc_u32 s91, s75, 0
	global_store_dwordx4 v149, v[32:35], s[88:89]
	global_store_dwordx4 v149, v[36:39], s[88:89] offset:2048
	global_store_dwordx2 v148, v[40:41], s[90:91]
	global_store_dwordx2 v148, v[146:147], s[90:91] offset:1024
	s_add_u32 s92, s96, 0x40000
	s_addc_u32 s93, s97, 0
	v_pk_mul_f32 v[78:79], v[210:211], v[78:79]
	v_pk_mul_f32 v[80:81], v[212:213], v[80:81]
	v_pk_mul_f32 v[74:75], v[214:215], v[74:75]
	v_pk_mul_f32 v[76:77], v[216:217], v[76:77]
	v_cvt_pk_bf16_f32 v32, v78, v79
	v_cvt_pk_bf16_f32 v33, v80, v81
	v_cvt_pk_bf16_f32 v34, v74, v75
	v_cvt_pk_bf16_f32 v35, v76, v77
	v_pk_mul_f32 v[70:71], v[218:219], v[70:71]
	v_pk_mul_f32 v[72:73], v[220:221], v[72:73]
	v_pk_mul_f32 v[66:67], v[222:223], v[66:67]
	v_pk_mul_f32 v[68:69], v[224:225], v[68:69]
	v_cvt_pk_bf16_f32 v36, v70, v71
	v_cvt_pk_bf16_f32 v37, v72, v73
	v_cvt_pk_bf16_f32 v38, v66, v67
	v_cvt_pk_bf16_f32 v39, v68, v69
	v_mov_b32_dpp v100, v32 quad_perm:[1,0,3,2] row_mask:0xf bank_mask:0xf
	v_mov_b32_dpp v101, v33 quad_perm:[1,0,3,2] row_mask:0xf bank_mask:0xf
	v_mov_b32_dpp v102, v34 quad_perm:[1,0,3,2] row_mask:0xf bank_mask:0xf
	v_mov_b32_dpp v103, v35 quad_perm:[1,0,3,2] row_mask:0xf bank_mask:0xf
	v_mov_b32_dpp v106, v36 quad_perm:[1,0,3,2] row_mask:0xf bank_mask:0xf
	v_mov_b32_dpp v107, v37 quad_perm:[1,0,3,2] row_mask:0xf bank_mask:0xf
	v_mov_b32_dpp v108, v38 quad_perm:[1,0,3,2] row_mask:0xf bank_mask:0xf
	v_mov_b32_dpp v109, v39 quad_perm:[1,0,3,2] row_mask:0xf bank_mask:0xf
	s_mov_b64 exec, s[62:63]
	v_mov_b32_e32 v32, v106
	v_mov_b32_e32 v33, v107
	v_mov_b32_e32 v34, v108
	v_mov_b32_e32 v35, v109
	s_mov_b64 exec, s[66:67]
	v_mov_b32_e32 v36, v100
	v_mov_b32_e32 v37, v101
	v_mov_b32_e32 v38, v102
	v_mov_b32_e32 v39, v103
	s_mov_b64 exec, -1
	global_store_dwordx4 v149, v[32:35], s[92:93]
	global_store_dwordx4 v149, v[36:39], s[92:93] offset:2048
	v_mov_b32_e32 v66, v151
	s_add_u32 s84, s58, 0x50000
	s_addc_u32 s85, s59, 0
	s_add_u32 s86, s74, 0x28000
	s_addc_u32 s87, s75, 0
	global_load_dwordx4 v[68:71], v149, s[84:85]
	global_load_dwordx2 v[72:73], v148, s[86:87]
	global_load_dwordx4 v[74:77], v149, s[84:85] offset:2048
	global_load_dwordx2 v[78:79], v148, s[86:87] offset:1024
	s_waitcnt vmcnt(10)
	v_mov_b32_dpp v32, v84 quad_perm:[1,0,3,2] row_mask:0xf bank_mask:0xf
	v_mov_b32_dpp v33, v85 quad_perm:[1,0,3,2] row_mask:0xf bank_mask:0xf
	v_mov_b32_dpp v34, v86 quad_perm:[1,0,3,2] row_mask:0xf bank_mask:0xf
	v_mov_b32_dpp v35, v87 quad_perm:[1,0,3,2] row_mask:0xf bank_mask:0xf
	v_mov_b32_dpp v36, v90 quad_perm:[1,0,3,2] row_mask:0xf bank_mask:0xf
	v_mov_b32_dpp v37, v91 quad_perm:[1,0,3,2] row_mask:0xf bank_mask:0xf
	v_mov_b32_dpp v38, v92 quad_perm:[1,0,3,2] row_mask:0xf bank_mask:0xf
	v_mov_b32_dpp v39, v93 quad_perm:[1,0,3,2] row_mask:0xf bank_mask:0xf
	s_mov_b64 exec, s[62:63]
	v_mov_b32_e32 v84, v36
	v_mov_b32_e32 v85, v37
	v_mov_b32_e32 v86, v38
	v_mov_b32_e32 v87, v39
	s_mov_b64 exec, s[66:67]
	v_mov_b32_e32 v90, v32
	v_mov_b32_e32 v91, v33
	v_mov_b32_e32 v92, v34
	v_mov_b32_e32 v93, v35
	s_mov_b64 exec, -1
	v_mov_b32_dpp v32, v88 quad_perm:[1,0,3,2] row_mask:0xf bank_mask:0xf
	v_mov_b32_dpp v33, v89 quad_perm:[1,0,3,2] row_mask:0xf bank_mask:0xf
	v_mov_b32_dpp v36, v94 quad_perm:[1,0,3,2] row_mask:0xf bank_mask:0xf
	v_mov_b32_dpp v37, v95 quad_perm:[1,0,3,2] row_mask:0xf bank_mask:0xf
	s_mov_b64 exec, s[62:63]
	v_mov_b32_e32 v88, v36
	v_mov_b32_e32 v89, v37
	s_mov_b64 exec, s[66:67]
	v_mov_b32_e32 v94, v32
	v_mov_b32_e32 v95, v33
	s_mov_b64 exec, -1
	v_lshlrev_b32_e32 v28, 8, v88
	v_perm_b32 v29, v84, v88, s8
	v_lshrrev_b32_e32 v30, 8, v88
	v_lshrrev_b32_e32 v31, 16, v88
	v_perm_b32 v28, v84, v28, s33
	v_perm_b32 v30, v85, v30, s33
	v_perm_b32 v31, v85, v31, s8
	v_pk_fma_f32 v[62:63], v[62:63], v[176:177], v[28:29]
	v_pk_fma_f32 v[64:65], v[64:65], v[178:179], v[30:31]
	v_lshlrev_b32_e32 v28, 8, v89
	v_perm_b32 v29, v86, v89, s8
	v_lshrrev_b32_e32 v30, 8, v89
	v_lshrrev_b32_e32 v31, 16, v89
	v_perm_b32 v28, v86, v28, s33
	v_perm_b32 v30, v87, v30, s33
	v_perm_b32 v31, v87, v31, s8
	v_pk_fma_f32 v[58:59], v[58:59], v[180:181], v[28:29]
	v_pk_fma_f32 v[60:61], v[60:61], v[182:183], v[30:31]
	v_lshlrev_b32_e32 v28, 8, v94
	v_perm_b32 v29, v90, v94, s8
	v_lshrrev_b32_e32 v30, 8, v94
	v_lshrrev_b32_e32 v31, 16, v94
	v_perm_b32 v28, v90, v28, s33
	v_perm_b32 v30, v91, v30, s33
	v_perm_b32 v31, v91, v31, s8
	v_pk_fma_f32 v[54:55], v[54:55], v[184:185], v[28:29]
	v_pk_fma_f32 v[56:57], v[56:57], v[186:187], v[30:31]
	v_lshlrev_b32_e32 v28, 8, v95
	v_perm_b32 v29, v92, v95, s8
	v_lshrrev_b32_e32 v30, 8, v95
	v_lshrrev_b32_e32 v31, 16, v95
	v_perm_b32 v28, v92, v28, s33
	v_perm_b32 v30, v93, v30, s33
	v_perm_b32 v31, v93, v31, s8
	v_pk_fma_f32 v[50:51], v[50:51], v[188:189], v[28:29]
	v_pk_fma_f32 v[52:53], v[52:53], v[190:191], v[30:31]
	v_mul_f32_e32 v28, v63, v63
	v_mul_f32_e32 v29, v65, v65
	v_mul_f32_e32 v30, v59, v59
	v_mul_f32_e32 v31, v61, v61
	v_fmac_f32_e32 v28, v62, v62
	v_fmac_f32_e32 v29, v64, v64
	v_fmac_f32_e32 v30, v58, v58
	v_fmac_f32_e32 v31, v60, v60
	v_add_f32_e32 v28, v28, v29
	v_add_f32_e32 v30, v30, v31
	v_add_f32_e32 v151, v28, v30
	v_add_u32_e32 v28, 0x80, v62
	v_add_u32_e32 v29, 0x80, v63
	v_add_u32_e32 v30, 0x80, v64
	v_add_u32_e32 v31, 0x80, v65
	v_perm_b32 v32, v29, v28, s78
	v_perm_b32 v33, v31, v30, s78
	v_perm_b32 v26, v29, v28, s79
	v_perm_b32 v27, v31, v30, s79
	v_perm_b32 v40, v27, v26, s60
	v_add_u32_e32 v28, 0x80, v58
	v_add_u32_e32 v29, 0x80, v59
	v_add_u32_e32 v30, 0x80, v60
	v_add_u32_e32 v31, 0x80, v61
	v_perm_b32 v34, v29, v28, s78
	v_perm_b32 v35, v31, v30, s78
	v_perm_b32 v26, v29, v28, s79
	v_perm_b32 v27, v31, v30, s79
	v_perm_b32 v41, v27, v26, s60
	v_mul_f32_e32 v28, v55, v55
	v_mul_f32_e32 v29, v57, v57
	v_mul_f32_e32 v30, v51, v51
	v_mul_f32_e32 v31, v53, v53
	v_fmac_f32_e32 v28, v54, v54
	v_fmac_f32_e32 v29, v56, v56
	v_fmac_f32_e32 v30, v50, v50
	v_fmac_f32_e32 v31, v52, v52
	v_add_f32_e32 v28, v28, v29
	v_add_f32_e32 v30, v30, v31
	v_add_f32_e32 v28, v28, v30
	v_add_f32_e32 v151, v151, v28
	v_add_u32_e32 v28, 0x80, v54
	v_add_u32_e32 v29, 0x80, v55
	v_add_u32_e32 v30, 0x80, v56
	v_add_u32_e32 v31, 0x80, v57
	v_perm_b32 v36, v29, v28, s78
	v_perm_b32 v37, v31, v30, s78
	v_perm_b32 v26, v29, v28, s79
	v_perm_b32 v27, v31, v30, s79
	v_perm_b32 v146, v27, v26, s60
	v_add_u32_e32 v28, 0x80, v50
	v_add_u32_e32 v29, 0x80, v51
	v_add_u32_e32 v30, 0x80, v52
	v_add_u32_e32 v31, 0x80, v53
	v_perm_b32 v38, v29, v28, s78
	v_perm_b32 v39, v31, v30, s78
	v_perm_b32 v26, v29, v28, s79
	v_perm_b32 v27, v31, v30, s79
	v_perm_b32 v147, v27, v26, s60
	v_mov_b32_dpp v84, v32 quad_perm:[1,0,3,2] row_mask:0xf bank_mask:0xf
	v_mov_b32_dpp v85, v33 quad_perm:[1,0,3,2] row_mask:0xf bank_mask:0xf
	v_mov_b32_dpp v86, v34 quad_perm:[1,0,3,2] row_mask:0xf bank_mask:0xf
	v_mov_b32_dpp v87, v35 quad_perm:[1,0,3,2] row_mask:0xf bank_mask:0xf
	v_mov_b32_dpp v90, v36 quad_perm:[1,0,3,2] row_mask:0xf bank_mask:0xf
	v_mov_b32_dpp v91, v37 quad_perm:[1,0,3,2] row_mask:0xf bank_mask:0xf
	v_mov_b32_dpp v92, v38 quad_perm:[1,0,3,2] row_mask:0xf bank_mask:0xf
	v_mov_b32_dpp v93, v39 quad_perm:[1,0,3,2] row_mask:0xf bank_mask:0xf
	s_mov_b64 exec, s[62:63]
	v_mov_b32_e32 v32, v90
	v_mov_b32_e32 v33, v91
	v_mov_b32_e32 v34, v92
	v_mov_b32_e32 v35, v93
	s_mov_b64 exec, s[66:67]
	v_mov_b32_e32 v36, v84
	v_mov_b32_e32 v37, v85
	v_mov_b32_e32 v38, v86
	v_mov_b32_e32 v39, v87
	s_mov_b64 exec, -1
	v_mov_b32_dpp v84, v40 quad_perm:[1,0,3,2] row_mask:0xf bank_mask:0xf
	v_mov_b32_dpp v85, v41 quad_perm:[1,0,3,2] row_mask:0xf bank_mask:0xf
	v_mov_b32_dpp v90, v146 quad_perm:[1,0,3,2] row_mask:0xf bank_mask:0xf
	v_mov_b32_dpp v91, v147 quad_perm:[1,0,3,2] row_mask:0xf bank_mask:0xf
	s_mov_b64 exec, s[62:63]
	v_mov_b32_e32 v40, v90
	v_mov_b32_e32 v41, v91
	s_mov_b64 exec, s[66:67]
	v_mov_b32_e32 v146, v84
	v_mov_b32_e32 v147, v85
	s_mov_b64 exec, -1
	s_add_u32 s88, s58, 0x48000
	s_addc_u32 s89, s59, 0
	s_add_u32 s90, s74, 0x24000
	s_addc_u32 s91, s75, 0
	global_store_dwordx4 v149, v[32:35], s[88:89]
	global_store_dwordx4 v149, v[36:39], s[88:89] offset:2048
	global_store_dwordx2 v148, v[40:41], s[90:91]
	global_store_dwordx2 v148, v[146:147], s[90:91] offset:1024
	s_add_u32 s92, s96, 0x48000
	s_addc_u32 s93, s97, 0
	v_pk_mul_f32 v[62:63], v[210:211], v[62:63]
	v_pk_mul_f32 v[64:65], v[212:213], v[64:65]
	v_pk_mul_f32 v[58:59], v[214:215], v[58:59]
	v_pk_mul_f32 v[60:61], v[216:217], v[60:61]
	v_cvt_pk_bf16_f32 v32, v62, v63
	v_cvt_pk_bf16_f32 v33, v64, v65
	v_cvt_pk_bf16_f32 v34, v58, v59
	v_cvt_pk_bf16_f32 v35, v60, v61
	v_pk_mul_f32 v[54:55], v[218:219], v[54:55]
	v_pk_mul_f32 v[56:57], v[220:221], v[56:57]
	v_pk_mul_f32 v[50:51], v[222:223], v[50:51]
	v_pk_mul_f32 v[52:53], v[224:225], v[52:53]
	v_cvt_pk_bf16_f32 v36, v54, v55
	v_cvt_pk_bf16_f32 v37, v56, v57
	v_cvt_pk_bf16_f32 v38, v50, v51
	v_cvt_pk_bf16_f32 v39, v52, v53
	v_mov_b32_dpp v84, v32 quad_perm:[1,0,3,2] row_mask:0xf bank_mask:0xf
	v_mov_b32_dpp v85, v33 quad_perm:[1,0,3,2] row_mask:0xf bank_mask:0xf
	v_mov_b32_dpp v86, v34 quad_perm:[1,0,3,2] row_mask:0xf bank_mask:0xf
	v_mov_b32_dpp v87, v35 quad_perm:[1,0,3,2] row_mask:0xf bank_mask:0xf
	v_mov_b32_dpp v90, v36 quad_perm:[1,0,3,2] row_mask:0xf bank_mask:0xf
	v_mov_b32_dpp v91, v37 quad_perm:[1,0,3,2] row_mask:0xf bank_mask:0xf
	v_mov_b32_dpp v92, v38 quad_perm:[1,0,3,2] row_mask:0xf bank_mask:0xf
	v_mov_b32_dpp v93, v39 quad_perm:[1,0,3,2] row_mask:0xf bank_mask:0xf
	s_mov_b64 exec, s[62:63]
	v_mov_b32_e32 v32, v90
	v_mov_b32_e32 v33, v91
	v_mov_b32_e32 v34, v92
	v_mov_b32_e32 v35, v93
	s_mov_b64 exec, s[66:67]
	v_mov_b32_e32 v36, v84
	v_mov_b32_e32 v37, v85
	v_mov_b32_e32 v38, v86
	v_mov_b32_e32 v39, v87
	s_mov_b64 exec, -1
	global_store_dwordx4 v149, v[32:35], s[92:93]
	global_store_dwordx4 v149, v[36:39], s[92:93] offset:2048
	v_mov_b32_e32 v50, v151
	s_add_u32 s84, s58, 0x58000
	s_addc_u32 s85, s59, 0
	s_add_u32 s86, s74, 0x2c000
	s_addc_u32 s87, s75, 0
	global_load_dwordx4 v[52:55], v149, s[84:85]
	global_load_dwordx2 v[56:57], v148, s[86:87]
	global_load_dwordx4 v[58:61], v149, s[84:85] offset:2048
	global_load_dwordx2 v[62:63], v148, s[86:87] offset:1024
	s_waitcnt vmcnt(10)
	v_mov_b32_dpp v32, v68 quad_perm:[1,0,3,2] row_mask:0xf bank_mask:0xf
	v_mov_b32_dpp v33, v69 quad_perm:[1,0,3,2] row_mask:0xf bank_mask:0xf
	v_mov_b32_dpp v34, v70 quad_perm:[1,0,3,2] row_mask:0xf bank_mask:0xf
	v_mov_b32_dpp v35, v71 quad_perm:[1,0,3,2] row_mask:0xf bank_mask:0xf
	v_mov_b32_dpp v36, v74 quad_perm:[1,0,3,2] row_mask:0xf bank_mask:0xf
	v_mov_b32_dpp v37, v75 quad_perm:[1,0,3,2] row_mask:0xf bank_mask:0xf
	v_mov_b32_dpp v38, v76 quad_perm:[1,0,3,2] row_mask:0xf bank_mask:0xf
	v_mov_b32_dpp v39, v77 quad_perm:[1,0,3,2] row_mask:0xf bank_mask:0xf
	s_mov_b64 exec, s[62:63]
	v_mov_b32_e32 v68, v36
	v_mov_b32_e32 v69, v37
	v_mov_b32_e32 v70, v38
	v_mov_b32_e32 v71, v39
	s_mov_b64 exec, s[66:67]
	v_mov_b32_e32 v74, v32
	v_mov_b32_e32 v75, v33
	v_mov_b32_e32 v76, v34
	v_mov_b32_e32 v77, v35
	s_mov_b64 exec, -1
	v_mov_b32_dpp v32, v72 quad_perm:[1,0,3,2] row_mask:0xf bank_mask:0xf
	v_mov_b32_dpp v33, v73 quad_perm:[1,0,3,2] row_mask:0xf bank_mask:0xf
	v_mov_b32_dpp v36, v78 quad_perm:[1,0,3,2] row_mask:0xf bank_mask:0xf
	v_mov_b32_dpp v37, v79 quad_perm:[1,0,3,2] row_mask:0xf bank_mask:0xf
	s_mov_b64 exec, s[62:63]
	v_mov_b32_e32 v72, v36
	v_mov_b32_e32 v73, v37
	s_mov_b64 exec, s[66:67]
	v_mov_b32_e32 v78, v32
	v_mov_b32_e32 v79, v33
	s_mov_b64 exec, -1
	v_lshlrev_b32_e32 v28, 8, v72
	v_perm_b32 v29, v68, v72, s8
	v_lshrrev_b32_e32 v30, 8, v72
	v_lshrrev_b32_e32 v31, 16, v72
	v_perm_b32 v28, v68, v28, s33
	v_perm_b32 v30, v69, v30, s33
	v_perm_b32 v31, v69, v31, s8
	v_pk_fma_f32 v[46:47], v[46:47], v[176:177], v[28:29]
	v_pk_fma_f32 v[48:49], v[48:49], v[178:179], v[30:31]
	v_lshlrev_b32_e32 v28, 8, v73
	v_perm_b32 v29, v70, v73, s8
	v_lshrrev_b32_e32 v30, 8, v73
	v_lshrrev_b32_e32 v31, 16, v73
	v_perm_b32 v28, v70, v28, s33
	v_perm_b32 v30, v71, v30, s33
	v_perm_b32 v31, v71, v31, s8
	v_pk_fma_f32 v[42:43], v[42:43], v[180:181], v[28:29]
	v_pk_fma_f32 v[44:45], v[44:45], v[182:183], v[30:31]
	v_lshlrev_b32_e32 v28, 8, v78
	v_perm_b32 v29, v74, v78, s8
	v_lshrrev_b32_e32 v30, 8, v78
	v_lshrrev_b32_e32 v31, 16, v78
	v_perm_b32 v28, v74, v28, s33
	v_perm_b32 v30, v75, v30, s33
	v_perm_b32 v31, v75, v31, s8
	v_pk_fma_f32 v[22:23], v[22:23], v[184:185], v[28:29]
	v_pk_fma_f32 v[24:25], v[24:25], v[186:187], v[30:31]
	v_lshlrev_b32_e32 v28, 8, v79
	v_perm_b32 v29, v76, v79, s8
	v_lshrrev_b32_e32 v30, 8, v79
	v_lshrrev_b32_e32 v31, 16, v79
	v_perm_b32 v28, v76, v28, s33
	v_perm_b32 v30, v77, v30, s33
	v_perm_b32 v31, v77, v31, s8
	v_pk_fma_f32 v[18:19], v[18:19], v[188:189], v[28:29]
	v_pk_fma_f32 v[20:21], v[20:21], v[190:191], v[30:31]
	v_mul_f32_e32 v28, v47, v47
	v_mul_f32_e32 v29, v49, v49
	v_mul_f32_e32 v30, v43, v43
	v_mul_f32_e32 v31, v45, v45
	v_fmac_f32_e32 v28, v46, v46
	v_fmac_f32_e32 v29, v48, v48
	v_fmac_f32_e32 v30, v42, v42
	v_fmac_f32_e32 v31, v44, v44
	v_add_f32_e32 v28, v28, v29
	v_add_f32_e32 v30, v30, v31
	v_add_f32_e32 v151, v28, v30
	v_add_u32_e32 v28, 0x80, v46
	v_add_u32_e32 v29, 0x80, v47
	v_add_u32_e32 v30, 0x80, v48
	v_add_u32_e32 v31, 0x80, v49
	v_perm_b32 v32, v29, v28, s78
	v_perm_b32 v33, v31, v30, s78
	v_perm_b32 v26, v29, v28, s79
	v_perm_b32 v27, v31, v30, s79
	v_perm_b32 v40, v27, v26, s60
	v_add_u32_e32 v28, 0x80, v42
	v_add_u32_e32 v29, 0x80, v43
	v_add_u32_e32 v30, 0x80, v44
	v_add_u32_e32 v31, 0x80, v45
	v_perm_b32 v34, v29, v28, s78
	v_perm_b32 v35, v31, v30, s78
	v_perm_b32 v26, v29, v28, s79
	v_perm_b32 v27, v31, v30, s79
	v_perm_b32 v41, v27, v26, s60
	v_mul_f32_e32 v28, v23, v23
	v_mul_f32_e32 v29, v25, v25
	v_mul_f32_e32 v30, v19, v19
	v_mul_f32_e32 v31, v21, v21
	v_fmac_f32_e32 v28, v22, v22
	v_fmac_f32_e32 v29, v24, v24
	v_fmac_f32_e32 v30, v18, v18
	v_fmac_f32_e32 v31, v20, v20
	v_add_f32_e32 v28, v28, v29
	v_add_f32_e32 v30, v30, v31
	v_add_f32_e32 v28, v28, v30
	v_add_f32_e32 v151, v151, v28
	v_add_u32_e32 v28, 0x80, v22
	v_add_u32_e32 v29, 0x80, v23
	v_add_u32_e32 v30, 0x80, v24
	v_add_u32_e32 v31, 0x80, v25
	v_perm_b32 v36, v29, v28, s78
	v_perm_b32 v37, v31, v30, s78
	v_perm_b32 v26, v29, v28, s79
	v_perm_b32 v27, v31, v30, s79
	v_perm_b32 v146, v27, v26, s60
	v_add_u32_e32 v28, 0x80, v18
	v_add_u32_e32 v29, 0x80, v19
	v_add_u32_e32 v30, 0x80, v20
	v_add_u32_e32 v31, 0x80, v21
	v_perm_b32 v38, v29, v28, s78
	v_perm_b32 v39, v31, v30, s78
	v_perm_b32 v26, v29, v28, s79
	v_perm_b32 v27, v31, v30, s79
	v_perm_b32 v147, v27, v26, s60
	v_mov_b32_dpp v68, v32 quad_perm:[1,0,3,2] row_mask:0xf bank_mask:0xf
	v_mov_b32_dpp v69, v33 quad_perm:[1,0,3,2] row_mask:0xf bank_mask:0xf
	v_mov_b32_dpp v70, v34 quad_perm:[1,0,3,2] row_mask:0xf bank_mask:0xf
	v_mov_b32_dpp v71, v35 quad_perm:[1,0,3,2] row_mask:0xf bank_mask:0xf
	v_mov_b32_dpp v74, v36 quad_perm:[1,0,3,2] row_mask:0xf bank_mask:0xf
	v_mov_b32_dpp v75, v37 quad_perm:[1,0,3,2] row_mask:0xf bank_mask:0xf
	v_mov_b32_dpp v76, v38 quad_perm:[1,0,3,2] row_mask:0xf bank_mask:0xf
	v_mov_b32_dpp v77, v39 quad_perm:[1,0,3,2] row_mask:0xf bank_mask:0xf
	s_mov_b64 exec, s[62:63]
	v_mov_b32_e32 v32, v74
	v_mov_b32_e32 v33, v75
	v_mov_b32_e32 v34, v76
	v_mov_b32_e32 v35, v77
	s_mov_b64 exec, s[66:67]
	v_mov_b32_e32 v36, v68
	v_mov_b32_e32 v37, v69
	v_mov_b32_e32 v38, v70
	v_mov_b32_e32 v39, v71
	s_mov_b64 exec, -1
	v_mov_b32_dpp v68, v40 quad_perm:[1,0,3,2] row_mask:0xf bank_mask:0xf
	v_mov_b32_dpp v69, v41 quad_perm:[1,0,3,2] row_mask:0xf bank_mask:0xf
	v_mov_b32_dpp v74, v146 quad_perm:[1,0,3,2] row_mask:0xf bank_mask:0xf
	v_mov_b32_dpp v75, v147 quad_perm:[1,0,3,2] row_mask:0xf bank_mask:0xf
	s_mov_b64 exec, s[62:63]
	v_mov_b32_e32 v40, v74
	v_mov_b32_e32 v41, v75
	s_mov_b64 exec, s[66:67]
	v_mov_b32_e32 v146, v68
	v_mov_b32_e32 v147, v69
	s_mov_b64 exec, -1
	s_add_u32 s88, s58, 0x50000
	s_addc_u32 s89, s59, 0
	s_add_u32 s90, s74, 0x28000
	s_addc_u32 s91, s75, 0
	global_store_dwordx4 v149, v[32:35], s[88:89]
	global_store_dwordx4 v149, v[36:39], s[88:89] offset:2048
	global_store_dwordx2 v148, v[40:41], s[90:91]
	global_store_dwordx2 v148, v[146:147], s[90:91] offset:1024
	s_add_u32 s92, s96, 0x50000
	s_addc_u32 s93, s97, 0
	v_pk_mul_f32 v[46:47], v[210:211], v[46:47]
	v_pk_mul_f32 v[48:49], v[212:213], v[48:49]
	v_pk_mul_f32 v[42:43], v[214:215], v[42:43]
	v_pk_mul_f32 v[44:45], v[216:217], v[44:45]
	v_cvt_pk_bf16_f32 v32, v46, v47
	v_cvt_pk_bf16_f32 v33, v48, v49
	v_cvt_pk_bf16_f32 v34, v42, v43
	v_cvt_pk_bf16_f32 v35, v44, v45
	v_pk_mul_f32 v[22:23], v[218:219], v[22:23]
	v_pk_mul_f32 v[24:25], v[220:221], v[24:25]
	v_pk_mul_f32 v[18:19], v[222:223], v[18:19]
	v_pk_mul_f32 v[20:21], v[224:225], v[20:21]
	v_cvt_pk_bf16_f32 v36, v22, v23
	v_cvt_pk_bf16_f32 v37, v24, v25
	v_cvt_pk_bf16_f32 v38, v18, v19
	v_cvt_pk_bf16_f32 v39, v20, v21
	v_mov_b32_dpp v68, v32 quad_perm:[1,0,3,2] row_mask:0xf bank_mask:0xf
	v_mov_b32_dpp v69, v33 quad_perm:[1,0,3,2] row_mask:0xf bank_mask:0xf
	v_mov_b32_dpp v70, v34 quad_perm:[1,0,3,2] row_mask:0xf bank_mask:0xf
	v_mov_b32_dpp v71, v35 quad_perm:[1,0,3,2] row_mask:0xf bank_mask:0xf
	v_mov_b32_dpp v74, v36 quad_perm:[1,0,3,2] row_mask:0xf bank_mask:0xf
	v_mov_b32_dpp v75, v37 quad_perm:[1,0,3,2] row_mask:0xf bank_mask:0xf
	v_mov_b32_dpp v76, v38 quad_perm:[1,0,3,2] row_mask:0xf bank_mask:0xf
	v_mov_b32_dpp v77, v39 quad_perm:[1,0,3,2] row_mask:0xf bank_mask:0xf
	s_mov_b64 exec, s[62:63]
	v_mov_b32_e32 v32, v74
	v_mov_b32_e32 v33, v75
	v_mov_b32_e32 v34, v76
	v_mov_b32_e32 v35, v77
	s_mov_b64 exec, s[66:67]
	v_mov_b32_e32 v36, v68
	v_mov_b32_e32 v37, v69
	v_mov_b32_e32 v38, v70
	v_mov_b32_e32 v39, v71
	s_mov_b64 exec, -1
	global_store_dwordx4 v149, v[32:35], s[92:93]
	global_store_dwordx4 v149, v[36:39], s[92:93] offset:2048
	v_mov_b32_e32 v18, v151
	s_waitcnt vmcnt(6)
	v_mov_b32_dpp v32, v52 quad_perm:[1,0,3,2] row_mask:0xf bank_mask:0xf
	v_mov_b32_dpp v33, v53 quad_perm:[1,0,3,2] row_mask:0xf bank_mask:0xf
	v_mov_b32_dpp v34, v54 quad_perm:[1,0,3,2] row_mask:0xf bank_mask:0xf
	v_mov_b32_dpp v35, v55 quad_perm:[1,0,3,2] row_mask:0xf bank_mask:0xf
	v_mov_b32_dpp v36, v58 quad_perm:[1,0,3,2] row_mask:0xf bank_mask:0xf
	v_mov_b32_dpp v37, v59 quad_perm:[1,0,3,2] row_mask:0xf bank_mask:0xf
	v_mov_b32_dpp v38, v60 quad_perm:[1,0,3,2] row_mask:0xf bank_mask:0xf
	v_mov_b32_dpp v39, v61 quad_perm:[1,0,3,2] row_mask:0xf bank_mask:0xf
	s_mov_b64 exec, s[62:63]
	v_mov_b32_e32 v52, v36
	v_mov_b32_e32 v53, v37
	v_mov_b32_e32 v54, v38
	v_mov_b32_e32 v55, v39
	s_mov_b64 exec, s[66:67]
	v_mov_b32_e32 v58, v32
	v_mov_b32_e32 v59, v33
	v_mov_b32_e32 v60, v34
	v_mov_b32_e32 v61, v35
	s_mov_b64 exec, -1
	v_mov_b32_dpp v32, v56 quad_perm:[1,0,3,2] row_mask:0xf bank_mask:0xf
	v_mov_b32_dpp v33, v57 quad_perm:[1,0,3,2] row_mask:0xf bank_mask:0xf
	v_mov_b32_dpp v36, v62 quad_perm:[1,0,3,2] row_mask:0xf bank_mask:0xf
	v_mov_b32_dpp v37, v63 quad_perm:[1,0,3,2] row_mask:0xf bank_mask:0xf
	s_mov_b64 exec, s[62:63]
	v_mov_b32_e32 v56, v36
	v_mov_b32_e32 v57, v37
	s_mov_b64 exec, s[66:67]
	v_mov_b32_e32 v62, v32
	v_mov_b32_e32 v63, v33
	s_mov_b64 exec, -1
	v_lshlrev_b32_e32 v28, 8, v56
	v_perm_b32 v29, v52, v56, s8
	v_lshrrev_b32_e32 v30, 8, v56
	v_lshrrev_b32_e32 v31, 16, v56
	v_perm_b32 v28, v52, v28, s33
	v_perm_b32 v30, v53, v30, s33
	v_perm_b32 v31, v53, v31, s8
	v_pk_fma_f32 v[14:15], v[14:15], v[176:177], v[28:29]
	v_pk_fma_f32 v[16:17], v[16:17], v[178:179], v[30:31]
	v_lshlrev_b32_e32 v28, 8, v57
	v_perm_b32 v29, v54, v57, s8
	v_lshrrev_b32_e32 v30, 8, v57
	v_lshrrev_b32_e32 v31, 16, v57
	v_perm_b32 v28, v54, v28, s33
	v_perm_b32 v30, v55, v30, s33
	v_perm_b32 v31, v55, v31, s8
	v_pk_fma_f32 v[10:11], v[10:11], v[180:181], v[28:29]
	v_pk_fma_f32 v[12:13], v[12:13], v[182:183], v[30:31]
	v_lshlrev_b32_e32 v28, 8, v62
	v_perm_b32 v29, v58, v62, s8
	v_lshrrev_b32_e32 v30, 8, v62
	v_lshrrev_b32_e32 v31, 16, v62
	v_perm_b32 v28, v58, v28, s33
	v_perm_b32 v30, v59, v30, s33
	v_perm_b32 v31, v59, v31, s8
	v_pk_fma_f32 v[6:7], v[6:7], v[184:185], v[28:29]
	v_pk_fma_f32 v[8:9], v[8:9], v[186:187], v[30:31]
	v_lshlrev_b32_e32 v28, 8, v63
	v_perm_b32 v29, v60, v63, s8
	v_lshrrev_b32_e32 v30, 8, v63
	v_lshrrev_b32_e32 v31, 16, v63
	v_perm_b32 v28, v60, v28, s33
	v_perm_b32 v30, v61, v30, s33
	v_perm_b32 v31, v61, v31, s8
	v_pk_fma_f32 v[2:3], v[2:3], v[188:189], v[28:29]
	v_pk_fma_f32 v[4:5], v[4:5], v[190:191], v[30:31]
	v_mul_f32_e32 v28, v15, v15
	v_mul_f32_e32 v29, v17, v17
	v_mul_f32_e32 v30, v11, v11
	v_mul_f32_e32 v31, v13, v13
	v_fmac_f32_e32 v28, v14, v14
	v_fmac_f32_e32 v29, v16, v16
	v_fmac_f32_e32 v30, v10, v10
	v_fmac_f32_e32 v31, v12, v12
	v_add_f32_e32 v28, v28, v29
	v_add_f32_e32 v30, v30, v31
	v_add_f32_e32 v151, v28, v30
	v_add_u32_e32 v28, 0x80, v14
	v_add_u32_e32 v29, 0x80, v15
	v_add_u32_e32 v30, 0x80, v16
	v_add_u32_e32 v31, 0x80, v17
	v_perm_b32 v32, v29, v28, s78
	v_perm_b32 v33, v31, v30, s78
	v_perm_b32 v26, v29, v28, s79
	v_perm_b32 v27, v31, v30, s79
	v_perm_b32 v40, v27, v26, s60
	v_add_u32_e32 v28, 0x80, v10
	v_add_u32_e32 v29, 0x80, v11
	v_add_u32_e32 v30, 0x80, v12
	v_add_u32_e32 v31, 0x80, v13
	v_perm_b32 v34, v29, v28, s78
	v_perm_b32 v35, v31, v30, s78
	v_perm_b32 v26, v29, v28, s79
	v_perm_b32 v27, v31, v30, s79
	v_perm_b32 v41, v27, v26, s60
	v_mul_f32_e32 v28, v7, v7
	v_mul_f32_e32 v29, v9, v9
	v_mul_f32_e32 v30, v3, v3
	v_mul_f32_e32 v31, v5, v5
	v_fmac_f32_e32 v28, v6, v6
	v_fmac_f32_e32 v29, v8, v8
	v_fmac_f32_e32 v30, v2, v2
	v_fmac_f32_e32 v31, v4, v4
	v_add_f32_e32 v28, v28, v29
	v_add_f32_e32 v30, v30, v31
	v_add_f32_e32 v28, v28, v30
	v_add_f32_e32 v151, v151, v28
	v_add_u32_e32 v28, 0x80, v6
	v_add_u32_e32 v29, 0x80, v7
	v_add_u32_e32 v30, 0x80, v8
	v_add_u32_e32 v31, 0x80, v9
	v_perm_b32 v36, v29, v28, s78
	v_perm_b32 v37, v31, v30, s78
	v_perm_b32 v26, v29, v28, s79
	v_perm_b32 v27, v31, v30, s79
	v_perm_b32 v146, v27, v26, s60
	v_add_u32_e32 v28, 0x80, v2
	v_add_u32_e32 v29, 0x80, v3
	v_add_u32_e32 v30, 0x80, v4
	v_add_u32_e32 v31, 0x80, v5
	v_perm_b32 v38, v29, v28, s78
	v_perm_b32 v39, v31, v30, s78
	v_perm_b32 v26, v29, v28, s79
	v_perm_b32 v27, v31, v30, s79
	v_perm_b32 v147, v27, v26, s60
	v_mov_b32_dpp v52, v32 quad_perm:[1,0,3,2] row_mask:0xf bank_mask:0xf
	v_mov_b32_dpp v53, v33 quad_perm:[1,0,3,2] row_mask:0xf bank_mask:0xf
	v_mov_b32_dpp v54, v34 quad_perm:[1,0,3,2] row_mask:0xf bank_mask:0xf
	v_mov_b32_dpp v55, v35 quad_perm:[1,0,3,2] row_mask:0xf bank_mask:0xf
	v_mov_b32_dpp v58, v36 quad_perm:[1,0,3,2] row_mask:0xf bank_mask:0xf
	v_mov_b32_dpp v59, v37 quad_perm:[1,0,3,2] row_mask:0xf bank_mask:0xf
	v_mov_b32_dpp v60, v38 quad_perm:[1,0,3,2] row_mask:0xf bank_mask:0xf
	v_mov_b32_dpp v61, v39 quad_perm:[1,0,3,2] row_mask:0xf bank_mask:0xf
	s_mov_b64 exec, s[62:63]
	v_mov_b32_e32 v32, v58
	v_mov_b32_e32 v33, v59
	v_mov_b32_e32 v34, v60
	v_mov_b32_e32 v35, v61
	s_mov_b64 exec, s[66:67]
	v_mov_b32_e32 v36, v52
	v_mov_b32_e32 v37, v53
	v_mov_b32_e32 v38, v54
	v_mov_b32_e32 v39, v55
	s_mov_b64 exec, -1
	v_mov_b32_dpp v52, v40 quad_perm:[1,0,3,2] row_mask:0xf bank_mask:0xf
	v_mov_b32_dpp v53, v41 quad_perm:[1,0,3,2] row_mask:0xf bank_mask:0xf
	v_mov_b32_dpp v58, v146 quad_perm:[1,0,3,2] row_mask:0xf bank_mask:0xf
	v_mov_b32_dpp v59, v147 quad_perm:[1,0,3,2] row_mask:0xf bank_mask:0xf
	s_mov_b64 exec, s[62:63]
	v_mov_b32_e32 v40, v58
	v_mov_b32_e32 v41, v59
	s_mov_b64 exec, s[66:67]
	v_mov_b32_e32 v146, v52
	v_mov_b32_e32 v147, v53
	s_mov_b64 exec, -1
	s_add_u32 s88, s58, 0x58000
	s_addc_u32 s89, s59, 0
	s_add_u32 s90, s74, 0x2c000
	s_addc_u32 s91, s75, 0
	global_store_dwordx4 v149, v[32:35], s[88:89]
	global_store_dwordx4 v149, v[36:39], s[88:89] offset:2048
	global_store_dwordx2 v148, v[40:41], s[90:91]
	global_store_dwordx2 v148, v[146:147], s[90:91] offset:1024
	s_add_u32 s92, s96, 0x58000
	s_addc_u32 s93, s97, 0
	v_pk_mul_f32 v[14:15], v[210:211], v[14:15]
	v_pk_mul_f32 v[16:17], v[212:213], v[16:17]
	v_pk_mul_f32 v[10:11], v[214:215], v[10:11]
	v_pk_mul_f32 v[12:13], v[216:217], v[12:13]
	v_cvt_pk_bf16_f32 v32, v14, v15
	v_cvt_pk_bf16_f32 v33, v16, v17
	v_cvt_pk_bf16_f32 v34, v10, v11
	v_cvt_pk_bf16_f32 v35, v12, v13
	v_pk_mul_f32 v[6:7], v[218:219], v[6:7]
	v_pk_mul_f32 v[8:9], v[220:221], v[8:9]
	v_pk_mul_f32 v[2:3], v[222:223], v[2:3]
	v_pk_mul_f32 v[4:5], v[224:225], v[4:5]
	v_cvt_pk_bf16_f32 v36, v6, v7
	v_cvt_pk_bf16_f32 v37, v8, v9
	v_cvt_pk_bf16_f32 v38, v2, v3
	v_cvt_pk_bf16_f32 v39, v4, v5
	v_mov_b32_dpp v52, v32 quad_perm:[1,0,3,2] row_mask:0xf bank_mask:0xf
	v_mov_b32_dpp v53, v33 quad_perm:[1,0,3,2] row_mask:0xf bank_mask:0xf
	v_mov_b32_dpp v54, v34 quad_perm:[1,0,3,2] row_mask:0xf bank_mask:0xf
	v_mov_b32_dpp v55, v35 quad_perm:[1,0,3,2] row_mask:0xf bank_mask:0xf
	v_mov_b32_dpp v58, v36 quad_perm:[1,0,3,2] row_mask:0xf bank_mask:0xf
	v_mov_b32_dpp v59, v37 quad_perm:[1,0,3,2] row_mask:0xf bank_mask:0xf
	v_mov_b32_dpp v60, v38 quad_perm:[1,0,3,2] row_mask:0xf bank_mask:0xf
	v_mov_b32_dpp v61, v39 quad_perm:[1,0,3,2] row_mask:0xf bank_mask:0xf
	s_mov_b64 exec, s[62:63]
	v_mov_b32_e32 v32, v58
	v_mov_b32_e32 v33, v59
	v_mov_b32_e32 v34, v60
	v_mov_b32_e32 v35, v61
	s_mov_b64 exec, s[66:67]
	v_mov_b32_e32 v36, v52
	v_mov_b32_e32 v37, v53
	v_mov_b32_e32 v38, v54
	v_mov_b32_e32 v39, v55
	s_mov_b64 exec, -1
	global_store_dwordx4 v149, v[32:35], s[92:93]
	global_store_dwordx4 v149, v[36:39], s[92:93] offset:2048
	v_mov_b32_e32 v2, v151
	v_mbcnt_lo_u32_b32 v3, -1, 0
	v_mbcnt_hi_u32_b32 v3, -1, v3
	v_xor_b32_e32 v4, 16, v3
	v_xor_b32_e32 v5, 32, v3
	v_lshlrev_b32_e32 v4, 2, v4
	v_lshlrev_b32_e32 v5, 2, v5
	v_cmp_gt_u32_e64 s[34:35], 16, v3
	ds_bpermute_b32 v6, v4, v130
	ds_bpermute_b32 v7, v4, v114
	ds_bpermute_b32 v8, v4, v98
	ds_bpermute_b32 v9, v4, v82
	ds_bpermute_b32 v10, v4, v66
	ds_bpermute_b32 v11, v4, v50
	ds_bpermute_b32 v12, v4, v18
	ds_bpermute_b32 v13, v4, v2
	s_waitcnt lgkmcnt(0)
	v_add_f32_e32 v130, v130, v6
	v_add_f32_e32 v114, v114, v7
	v_add_f32_e32 v98, v98, v8
	v_add_f32_e32 v82, v82, v9
	v_add_f32_e32 v66, v66, v10
	v_add_f32_e32 v50, v50, v11
	v_add_f32_e32 v18, v18, v12
	v_add_f32_e32 v2, v2, v13
	ds_bpermute_b32 v6, v5, v130
	ds_bpermute_b32 v7, v5, v114
	ds_bpermute_b32 v8, v5, v98
	ds_bpermute_b32 v9, v5, v82
	ds_bpermute_b32 v10, v5, v66
	ds_bpermute_b32 v11, v5, v50
	ds_bpermute_b32 v12, v5, v18
	ds_bpermute_b32 v13, v5, v2
	s_waitcnt lgkmcnt(0)
	v_add_f32_e32 v130, v130, v6
	v_add_f32_e32 v114, v114, v7
	v_add_f32_e32 v98, v98, v8
	v_add_f32_e32 v82, v82, v9
	v_add_f32_e32 v66, v66, v10
	v_add_f32_e32 v50, v50, v11
	v_add_f32_e32 v18, v18, v12
	v_add_f32_e32 v2, v2, v13
	v_readlane_b32 s70, v244, 53
	v_readlane_b32 s71, v244, 54
	v_lshlrev_b32_e32 v3, 6, v192
	s_lshl_b32 s94, s55, 14
	s_lshl_b32 s95, s4, 4
	s_add_u32 s94, s94, s95
	s_lshl_b32 s95, s49, 2
	s_add_u32 s94, s94, s95
	s_add_u32 s94, s70, s94
	s_addc_u32 s95, s71, 0
	s_and_saveexec_b64 s[36:37], s[34:35]
	global_store_dword v3, v130, s[94:95]
	s_add_u32 s84, s94, 0x400
	s_addc_u32 s85, s95, 0
	global_store_dword v3, v114, s[84:85]
	s_add_u32 s84, s94, 0x800
	s_addc_u32 s85, s95, 0
	global_store_dword v3, v98, s[84:85]
	s_add_u32 s84, s94, 0xc00
	s_addc_u32 s85, s95, 0
	global_store_dword v3, v82, s[84:85]
	s_add_u32 s84, s94, 0x2000
	s_addc_u32 s85, s95, 0
	global_store_dword v3, v66, s[84:85]
	s_add_u32 s84, s94, 0x2400
	s_addc_u32 s85, s95, 0
	global_store_dword v3, v50, s[84:85]
	s_add_u32 s84, s94, 0x2800
	s_addc_u32 s85, s95, 0
	global_store_dword v3, v18, s[84:85]
	s_add_u32 s84, s94, 0x2c00
	s_addc_u32 s85, s95, 0
	global_store_dword v3, v2, s[84:85]
	s_or_b64 exec, exec, s[36:37]
	v_readlane_b32 s56, v246, 3
	v_readlane_b32 s57, v246, 4
	s_andn2_b64 vcc, exec, s[18:19]
	s_mov_b64 s[12:13], -1
	s_cbranch_vccnz .LBB0_1180
	s_andn2_b64 vcc, exec, s[0:1]
	s_cbranch_vccnz .LBB0_1179
	s_barrier
	s_branch .LBB0_1179

.LBB0_1381:
	v_lshrrev_b32_e32 v9, 1, v8
	v_and_b32_e32 v182, 24, v9
	s_lshl_b32 s13, s13, 5
	v_and_b32_e32 v180, 15, v8
	v_lshlrev_b32_e32 v9, 1, v182
	v_lshlrev_b32_e32 v8, 2, v8
	s_and_b32 s41, s13, 0x60
	v_lshl_add_u64 v[10:11], s[28:29], 0, v[0:1]
	v_mov_b32_e32 v147, v1
	v_readlane_b32 s26, v245, 37
	s_lshl_b32 s40, s16, 6
	v_lshl_or_b32 v9, v180, 6, v9
	s_lshl_b32 s16, s16, 13
	v_and_b32_e32 v8, 32, v8
	s_lshl_b32 s13, s41, 7
	v_lshl_add_u64 v[12:13], s[28:29], 0, v[146:147]
	v_mov_b32_e32 v151, v1
	v_readlane_b32 s27, v245, 38
	v_bitop3_b32 v18, v9, s16, v8 bitop3:0xde
	v_bitop3_b32 v183, v9, s13, v8 bitop3:0xde
	s_add_i32 m0, s36, 0x18000
	v_lshl_add_u64 v[8:9], v[10:11], 0, s[6:7]
	v_lshl_add_u64 v[14:15], s[26:27], 0, v[150:151]
	v_mov_b32_e32 v149, v1
	s_waitcnt vmcnt(2)
	s_barrier
	global_load_lds_dwordx4 v[8:9], off
	v_lshl_add_u64 v[8:9], v[12:13], 0, s[6:7]
	s_add_i32 m0, s36, 0x1a000
	s_add_i32 s42, s36, 0x8000
	s_add_i32 s43, s36, 0xa000
	v_lshl_add_u64 v[16:17], s[26:27], 0, v[148:149]
	global_load_lds_dwordx4 v[8:9], off
	v_lshl_add_u64 v[8:9], v[14:15], 0, s[6:7]
	s_mov_b32 m0, s42
	s_add_u32 s16, s28, 0x40080
	global_load_lds_dwordx4 v[8:9], off
	v_lshl_add_u64 v[8:9], v[16:17], 0, s[6:7]
	s_mov_b32 m0, s43
	s_addc_u32 s17, s29, 0
	global_load_lds_dwordx4 v[8:9], off
	s_add_i32 m0, s36, 0x1c000
	v_lshl_add_u64 v[8:9], s[16:17], 0, v[0:1]
	global_load_lds_dwordx4 v[8:9], off
	v_lshl_add_u64 v[8:9], s[16:17], 0, v[146:147]
	s_add_i32 m0, s36, 0x1e000
	s_cmpk_lt_u32 s12, 0x100
	global_load_lds_dwordx4 v[8:9], off
	v_lshlrev_b32_e32 v8, 14, v6
	v_and_b32_e32 v8, 0xffff8000, v8
	v_lshl_add_u32 v5, v5, 11, v8
	v_and_b32_e32 v6, 1, v6
	v_lshl_or_b32 v5, v6, 6, v5
	v_lshl_add_u32 v152, v7, 1, v5
	v_lshlrev_b32_e32 v5, 14, v2
	v_and_b32_e32 v5, 0xffff8000, v5
	v_readlane_b32 s12, v245, 18
	s_waitcnt vmcnt(6)
	v_lshl_add_u32 v3, v3, 11, v5
	v_and_b32_e32 v2, 1, v2
	v_readlane_b32 s13, v245, 19
	v_lshl_or_b32 v2, v2, 6, v3
	s_mov_b32 s48, s12
	v_readlane_b32 s12, v245, 35
	v_or_b32_e32 v181, s40, v180
	s_cselect_b64 s[16:17], -1, 0
	v_lshl_or_b32 v184, s41, 1, v182
	v_mov_b32_e32 v153, v1
	v_lshl_add_u32 v166, v4, 1, v2
	v_mov_b32_e32 v167, v1
	s_mov_b32 s52, 0
	v_add_u32_e32 v185, 0, v18
	s_mov_b32 s49, s12
	s_mov_b32 s46, 0
	s_barrier
	v_readlane_b32 s13, v245, 36
	s_branch .LBB0_1384

.LBB0_1394:
	s_lshl_b32 s19, s52, 11
	s_add_i32 s19, s19, 0
	s_add_i32 s19, s19, 0x20400
	s_lshl_b32 s21, s40, 2
	s_add_i32 s21, s19, s21
	v_lshl_add_u32 v130, v180, 2, s21
	s_lshl_b32 s21, s41, 2
	s_add_i32 s19, s19, s21
	ds_read2_b32 v[186:187], v130 offset1:16
	ds_read2_b32 v[174:175], v130 offset0:32 offset1:48
	ds_read2_b32 v[172:173], v130 offset0:128 offset1:144
	ds_read2_b32 v[170:171], v130 offset0:160 offset1:176
	v_lshl_add_u32 v130, v182, 2, s19
	ds_read_b128 v[142:145], v130 offset:1024
	ds_read_b128 v[138:141], v130 offset:1040
	ds_read_b128 v[134:137], v130 offset:1536
	ds_read_b128 v[130:133], v130 offset:1552
	v_lshl_add_u32 v176, s49, 8, v181
	v_lshl_or_b32 v168, s48, 8, v184
	v_ashrrev_i32_e32 v177, 31, v176
	v_ashrrev_i32_e32 v169, 31, v168
	v_lshlrev_b64 v[178:179], 13, v[176:177]
	s_waitcnt lgkmcnt(0)
	v_pk_fma_f32 v[122:123], v[122:123], v[186:187], v[138:139] op_sel_hi:[1,0,1]
	v_lshl_add_u64 v[188:189], s[10:11], 0, v[178:179]
	v_lshlrev_b64 v[178:179], 1, v[168:169]
	v_pk_fma_f32 v[128:129], v[128:129], v[186:187], v[144:145] op_sel_hi:[1,0,1]
	v_pk_fma_f32 v[126:127], v[126:127], v[186:187], v[142:143] op_sel_hi:[1,0,1]
	v_pk_fma_f32 v[124:125], v[124:125], v[186:187], v[140:141] op_sel_hi:[1,0,1]
	v_max_f32_e32 v122, 0, v122
	v_max_f32_e32 v123, 0, v123
	v_lshl_add_u64 v[168:169], v[188:189], 0, v[178:179]
	v_max_f32_e32 v126, 0, v126
	v_max_f32_e32 v127, 0, v127
	v_max_f32_e32 v128, 0, v128
	v_max_f32_e32 v129, 0, v129
	v_pk_mul_f32 v[188:189], v[122:123], v[122:123]
	v_max_f32_e32 v122, 0, v124
	v_max_f32_e32 v123, 0, v125
	v_pk_mul_f32 v[126:127], v[126:127], v[126:127]
	v_pk_mul_f32 v[128:129], v[128:129], v[128:129]
	v_pk_mul_f32 v[190:191], v[122:123], v[122:123]
	v_pk_fma_f32 v[114:115], v[114:115], v[186:187], v[130:131] op_sel_hi:[1,0,1]
	v_cvt_pk_bf16_f32 v122, v126, v127
	v_cvt_pk_bf16_f32 v123, v128, v129
	v_cvt_pk_bf16_f32 v124, v188, v189
	v_cvt_pk_bf16_f32 v125, v190, v191
	v_pk_fma_f32 v[120:121], v[120:121], v[186:187], v[136:137] op_sel_hi:[1,0,1]
	v_pk_fma_f32 v[118:119], v[118:119], v[186:187], v[134:135] op_sel_hi:[1,0,1]
	v_pk_fma_f32 v[116:117], v[116:117], v[186:187], v[132:133] op_sel_hi:[1,0,1]
	v_max_f32_e32 v114, 0, v114
	v_max_f32_e32 v115, 0, v115
	global_store_dwordx4 v[168:169], v[122:125], off
	v_max_f32_e32 v118, 0, v118
	v_max_f32_e32 v119, 0, v119
	v_max_f32_e32 v120, 0, v120
	v_max_f32_e32 v121, 0, v121
	v_pk_mul_f32 v[122:123], v[114:115], v[114:115]
	v_max_f32_e32 v114, 0, v116
	v_max_f32_e32 v115, 0, v117
	v_pk_mul_f32 v[118:119], v[118:119], v[118:119]
	v_pk_mul_f32 v[120:121], v[120:121], v[120:121]
	v_pk_mul_f32 v[124:125], v[114:115], v[114:115]
	v_cvt_pk_bf16_f32 v114, v118, v119
	v_cvt_pk_bf16_f32 v115, v120, v121
	v_cvt_pk_bf16_f32 v116, v122, v123
	v_cvt_pk_bf16_f32 v117, v124, v125
	global_store_dwordx4 v[168:169], v[114:117], off offset:64
	v_pk_fma_f32 v[90:91], v[90:91], v[174:175], v[138:139] op_sel_hi:[1,0,1]
	v_pk_fma_f32 v[96:97], v[96:97], v[174:175], v[144:145] op_sel_hi:[1,0,1]
	v_mov_b32_e32 v116, v187
	v_or_b32_e32 v114, 16, v176
	v_pk_fma_f32 v[106:107], v[106:107], v[116:117], v[138:139] op_sel_hi:[1,0,1]
	v_ashrrev_i32_e32 v115, 31, v114
	v_pk_fma_f32 v[112:113], v[112:113], v[116:117], v[144:145] op_sel_hi:[1,0,1]
	v_pk_fma_f32 v[110:111], v[110:111], v[116:117], v[142:143] op_sel_hi:[1,0,1]
	v_pk_fma_f32 v[108:109], v[108:109], v[116:117], v[140:141] op_sel_hi:[1,0,1]
	v_max_f32_e32 v106, 0, v106
	v_max_f32_e32 v107, 0, v107
	v_lshlrev_b64 v[114:115], 13, v[114:115]
	v_max_f32_e32 v110, 0, v110
	v_max_f32_e32 v111, 0, v111
	v_max_f32_e32 v112, 0, v112
	v_max_f32_e32 v113, 0, v113
	v_pk_mul_f32 v[118:119], v[106:107], v[106:107]
	v_max_f32_e32 v106, 0, v108
	v_max_f32_e32 v107, 0, v109
	v_lshl_add_u64 v[114:115], s[10:11], 0, v[114:115]
	v_pk_mul_f32 v[110:111], v[110:111], v[110:111]
	v_pk_mul_f32 v[112:113], v[112:113], v[112:113]
	v_pk_mul_f32 v[120:121], v[106:107], v[106:107]
	v_pk_fma_f32 v[98:99], v[98:99], v[116:117], v[130:131] op_sel_hi:[1,0,1]
	v_lshl_add_u64 v[114:115], v[114:115], 0, v[178:179]
	v_cvt_pk_bf16_f32 v106, v110, v111
	v_cvt_pk_bf16_f32 v107, v112, v113
	v_cvt_pk_bf16_f32 v108, v118, v119
	v_cvt_pk_bf16_f32 v109, v120, v121
	v_pk_fma_f32 v[104:105], v[104:105], v[116:117], v[136:137] op_sel_hi:[1,0,1]
	v_pk_fma_f32 v[102:103], v[102:103], v[116:117], v[134:135] op_sel_hi:[1,0,1]
	v_pk_fma_f32 v[100:101], v[100:101], v[116:117], v[132:133] op_sel_hi:[1,0,1]
	v_max_f32_e32 v98, 0, v98
	v_max_f32_e32 v99, 0, v99
	global_store_dwordx4 v[114:115], v[106:109], off
	v_max_f32_e32 v102, 0, v102
	v_max_f32_e32 v103, 0, v103
	v_max_f32_e32 v104, 0, v104
	v_max_f32_e32 v105, 0, v105
	v_pk_mul_f32 v[106:107], v[98:99], v[98:99]
	v_max_f32_e32 v98, 0, v100
	v_max_f32_e32 v99, 0, v101
	v_pk_mul_f32 v[102:103], v[102:103], v[102:103]
	v_pk_mul_f32 v[104:105], v[104:105], v[104:105]
	v_pk_mul_f32 v[108:109], v[98:99], v[98:99]
	v_cvt_pk_bf16_f32 v98, v102, v103
	v_cvt_pk_bf16_f32 v99, v104, v105
	v_cvt_pk_bf16_f32 v100, v106, v107
	v_cvt_pk_bf16_f32 v101, v108, v109
	global_store_dwordx4 v[114:115], v[98:101], off offset:64
	v_pk_fma_f32 v[94:95], v[94:95], v[174:175], v[142:143] op_sel_hi:[1,0,1]
	v_pk_fma_f32 v[92:93], v[92:93], v[174:175], v[140:141] op_sel_hi:[1,0,1]
	v_or_b32_e32 v98, 32, v176
	v_ashrrev_i32_e32 v99, 31, v98
	v_max_f32_e32 v90, 0, v90
	v_max_f32_e32 v91, 0, v91
	v_lshlrev_b64 v[98:99], 13, v[98:99]
	v_max_f32_e32 v94, 0, v94
	v_max_f32_e32 v95, 0, v95
	v_max_f32_e32 v96, 0, v96
	v_max_f32_e32 v97, 0, v97
	v_pk_mul_f32 v[100:101], v[90:91], v[90:91]
	v_max_f32_e32 v90, 0, v92
	v_max_f32_e32 v91, 0, v93
	v_lshl_add_u64 v[98:99], s[10:11], 0, v[98:99]
	v_pk_mul_f32 v[94:95], v[94:95], v[94:95]
	v_pk_mul_f32 v[96:97], v[96:97], v[96:97]
	v_pk_mul_f32 v[102:103], v[90:91], v[90:91]
	v_pk_fma_f32 v[82:83], v[82:83], v[174:175], v[130:131] op_sel_hi:[1,0,1]
	v_lshl_add_u64 v[98:99], v[98:99], 0, v[178:179]
	v_cvt_pk_bf16_f32 v90, v94, v95
	v_cvt_pk_bf16_f32 v91, v96, v97
	v_cvt_pk_bf16_f32 v92, v100, v101
	v_cvt_pk_bf16_f32 v93, v102, v103
	v_pk_fma_f32 v[88:89], v[88:89], v[174:175], v[136:137] op_sel_hi:[1,0,1]
	v_pk_fma_f32 v[86:87], v[86:87], v[174:175], v[134:135] op_sel_hi:[1,0,1]
	v_pk_fma_f32 v[84:85], v[84:85], v[174:175], v[132:133] op_sel_hi:[1,0,1]
	v_max_f32_e32 v82, 0, v82
	v_max_f32_e32 v83, 0, v83
	global_store_dwordx4 v[98:99], v[90:93], off
	v_max_f32_e32 v86, 0, v86
	v_max_f32_e32 v87, 0, v87
	v_max_f32_e32 v88, 0, v88
	v_max_f32_e32 v89, 0, v89
	v_pk_mul_f32 v[90:91], v[82:83], v[82:83]
	v_max_f32_e32 v82, 0, v84
	v_max_f32_e32 v83, 0, v85
	v_pk_mul_f32 v[86:87], v[86:87], v[86:87]
	v_pk_mul_f32 v[88:89], v[88:89], v[88:89]
	v_pk_mul_f32 v[92:93], v[82:83], v[82:83]
	v_cvt_pk_bf16_f32 v82, v86, v87
	v_cvt_pk_bf16_f32 v83, v88, v89
	v_cvt_pk_bf16_f32 v84, v90, v91
	v_cvt_pk_bf16_f32 v85, v92, v93
	global_store_dwordx4 v[98:99], v[82:85], off offset:64
	v_pk_fma_f32 v[62:63], v[62:63], v[172:173], v[142:143] op_sel_hi:[1,0,1]
	v_pk_fma_f32 v[58:59], v[58:59], v[172:173], v[138:139] op_sel_hi:[1,0,1]
	v_mov_b32_e32 v84, v175
	v_or_b32_e32 v82, 48, v176
	v_pk_fma_f32 v[74:75], v[74:75], v[84:85], v[138:139] op_sel_hi:[1,0,1]
	v_ashrrev_i32_e32 v83, 31, v82
	v_pk_fma_f32 v[80:81], v[80:81], v[84:85], v[144:145] op_sel_hi:[1,0,1]
	v_pk_fma_f32 v[78:79], v[78:79], v[84:85], v[142:143] op_sel_hi:[1,0,1]
	v_pk_fma_f32 v[76:77], v[76:77], v[84:85], v[140:141] op_sel_hi:[1,0,1]
	v_max_f32_e32 v74, 0, v74
	v_max_f32_e32 v75, 0, v75
	v_lshlrev_b64 v[82:83], 13, v[82:83]
	v_max_f32_e32 v78, 0, v78
	v_max_f32_e32 v79, 0, v79
	v_max_f32_e32 v80, 0, v80
	v_max_f32_e32 v81, 0, v81
	v_pk_mul_f32 v[86:87], v[74:75], v[74:75]
	v_max_f32_e32 v74, 0, v76
	v_max_f32_e32 v75, 0, v77
	v_lshl_add_u64 v[82:83], s[10:11], 0, v[82:83]
	v_pk_mul_f32 v[78:79], v[78:79], v[78:79]
	v_pk_mul_f32 v[80:81], v[80:81], v[80:81]
	v_pk_mul_f32 v[88:89], v[74:75], v[74:75]
	v_pk_fma_f32 v[66:67], v[66:67], v[84:85], v[130:131] op_sel_hi:[1,0,1]
	v_lshl_add_u64 v[82:83], v[82:83], 0, v[178:179]
	v_cvt_pk_bf16_f32 v74, v78, v79
	v_cvt_pk_bf16_f32 v75, v80, v81
	v_cvt_pk_bf16_f32 v76, v86, v87
	v_cvt_pk_bf16_f32 v77, v88, v89
	v_pk_fma_f32 v[72:73], v[72:73], v[84:85], v[136:137] op_sel_hi:[1,0,1]
	v_pk_fma_f32 v[70:71], v[70:71], v[84:85], v[134:135] op_sel_hi:[1,0,1]
	v_pk_fma_f32 v[68:69], v[68:69], v[84:85], v[132:133] op_sel_hi:[1,0,1]
	v_max_f32_e32 v66, 0, v66
	v_max_f32_e32 v67, 0, v67
	global_store_dwordx4 v[82:83], v[74:77], off
	v_max_f32_e32 v70, 0, v70
	v_max_f32_e32 v71, 0, v71
	v_max_f32_e32 v72, 0, v72
	v_max_f32_e32 v73, 0, v73
	v_pk_mul_f32 v[74:75], v[66:67], v[66:67]
	v_max_f32_e32 v66, 0, v68
	v_max_f32_e32 v67, 0, v69
	v_pk_mul_f32 v[70:71], v[70:71], v[70:71]
	v_pk_mul_f32 v[72:73], v[72:73], v[72:73]
	v_pk_mul_f32 v[76:77], v[66:67], v[66:67]
	v_cvt_pk_bf16_f32 v66, v70, v71
	v_cvt_pk_bf16_f32 v67, v72, v73
	v_cvt_pk_bf16_f32 v68, v74, v75
	v_cvt_pk_bf16_f32 v69, v76, v77
	v_pk_fma_f32 v[64:65], v[64:65], v[172:173], v[144:145] op_sel_hi:[1,0,1]
	v_pk_fma_f32 v[60:61], v[60:61], v[172:173], v[140:141] op_sel_hi:[1,0,1]
	v_max_f32_e32 v62, 0, v62
	v_max_f32_e32 v63, 0, v63
	v_max_f32_e32 v58, 0, v58
	v_max_f32_e32 v59, 0, v59
	global_store_dwordx4 v[82:83], v[66:69], off offset:64
	v_pk_mul_f32 v[62:63], v[62:63], v[62:63]
	v_max_f32_e32 v64, 0, v64
	v_max_f32_e32 v65, 0, v65
	v_pk_mul_f32 v[68:69], v[58:59], v[58:59]
	v_max_f32_e32 v58, 0, v60
	v_max_f32_e32 v59, 0, v61
	s_mov_b32 s19, 0x100000
	v_pk_mul_f32 v[64:65], v[64:65], v[64:65]
	v_pk_mul_f32 v[70:71], v[58:59], v[58:59]
	v_cvt_pk_bf16_f32 v58, v62, v63
	v_add_co_u32_e32 v62, vcc, s19, v168
	v_pk_fma_f32 v[50:51], v[50:51], v[172:173], v[130:131] op_sel_hi:[1,0,1]
	v_cvt_pk_bf16_f32 v59, v64, v65
	v_cvt_pk_bf16_f32 v60, v68, v69
	v_cvt_pk_bf16_f32 v61, v70, v71
	v_addc_co_u32_e32 v63, vcc, 0, v169, vcc
	v_pk_fma_f32 v[56:57], v[56:57], v[172:173], v[136:137] op_sel_hi:[1,0,1]
	v_pk_fma_f32 v[54:55], v[54:55], v[172:173], v[134:135] op_sel_hi:[1,0,1]
	v_pk_fma_f32 v[52:53], v[52:53], v[172:173], v[132:133] op_sel_hi:[1,0,1]
	v_max_f32_e32 v50, 0, v50
	v_max_f32_e32 v51, 0, v51
	global_store_dwordx4 v[62:63], v[58:61], off
	v_max_f32_e32 v54, 0, v54
	v_max_f32_e32 v55, 0, v55
	v_max_f32_e32 v56, 0, v56
	v_max_f32_e32 v57, 0, v57
	v_pk_mul_f32 v[58:59], v[50:51], v[50:51]
	v_max_f32_e32 v50, 0, v52
	v_max_f32_e32 v51, 0, v53
	s_mov_b64 s[26:27], 0x100000
	v_pk_mul_f32 v[54:55], v[54:55], v[54:55]
	v_pk_mul_f32 v[56:57], v[56:57], v[56:57]
	v_pk_mul_f32 v[60:61], v[50:51], v[50:51]
	v_lshl_add_u64 v[66:67], v[168:169], 0, s[26:27]
	v_cvt_pk_bf16_f32 v50, v54, v55
	v_cvt_pk_bf16_f32 v51, v56, v57
	v_cvt_pk_bf16_f32 v52, v58, v59
	v_cvt_pk_bf16_f32 v53, v60, v61
	global_store_dwordx4 v[66:67], v[50:53], off offset:64
	s_mov_b32 s19, 0x120000
	s_mov_b64 s[26:27], 0x120000
	v_mov_b32_e32 v52, v173
	v_pk_fma_f32 v[46:47], v[46:47], v[52:53], v[142:143] op_sel_hi:[1,0,1]
	v_pk_fma_f32 v[42:43], v[42:43], v[52:53], v[138:139] op_sel_hi:[1,0,1]
	v_pk_fma_f32 v[48:49], v[48:49], v[52:53], v[144:145] op_sel_hi:[1,0,1]
	v_pk_fma_f32 v[44:45], v[44:45], v[52:53], v[140:141] op_sel_hi:[1,0,1]
	v_max_f32_e32 v46, 0, v46
	v_max_f32_e32 v47, 0, v47
	v_max_f32_e32 v42, 0, v42
	v_max_f32_e32 v43, 0, v43
	v_pk_mul_f32 v[46:47], v[46:47], v[46:47]
	v_max_f32_e32 v48, 0, v48
	v_max_f32_e32 v49, 0, v49
	v_pk_mul_f32 v[54:55], v[42:43], v[42:43]
	v_max_f32_e32 v42, 0, v44
	v_max_f32_e32 v43, 0, v45
	v_pk_mul_f32 v[48:49], v[48:49], v[48:49]
	v_pk_mul_f32 v[56:57], v[42:43], v[42:43]
	v_cvt_pk_bf16_f32 v42, v46, v47
	v_add_co_u32_e32 v46, vcc, s19, v168
	v_pk_fma_f32 v[34:35], v[34:35], v[52:53], v[130:131] op_sel_hi:[1,0,1]
	v_cvt_pk_bf16_f32 v43, v48, v49
	v_cvt_pk_bf16_f32 v44, v54, v55
	v_cvt_pk_bf16_f32 v45, v56, v57
	v_addc_co_u32_e32 v47, vcc, 0, v169, vcc
	v_pk_fma_f32 v[40:41], v[40:41], v[52:53], v[136:137] op_sel_hi:[1,0,1]
	v_pk_fma_f32 v[38:39], v[38:39], v[52:53], v[134:135] op_sel_hi:[1,0,1]
	v_pk_fma_f32 v[36:37], v[36:37], v[52:53], v[132:133] op_sel_hi:[1,0,1]
	v_max_f32_e32 v34, 0, v34
	v_max_f32_e32 v35, 0, v35
	global_store_dwordx4 v[46:47], v[42:45], off
	v_max_f32_e32 v38, 0, v38
	v_max_f32_e32 v39, 0, v39
	v_max_f32_e32 v40, 0, v40
	v_max_f32_e32 v41, 0, v41
	v_pk_mul_f32 v[42:43], v[34:35], v[34:35]
	v_max_f32_e32 v34, 0, v36
	v_max_f32_e32 v35, 0, v37
	v_pk_mul_f32 v[38:39], v[38:39], v[38:39]
	v_pk_mul_f32 v[40:41], v[40:41], v[40:41]
	v_pk_mul_f32 v[44:45], v[34:35], v[34:35]
	v_pk_fma_f32 v[30:31], v[30:31], v[170:171], v[142:143] op_sel_hi:[1,0,1]
	v_pk_fma_f32 v[26:27], v[26:27], v[170:171], v[138:139] op_sel_hi:[1,0,1]
	v_lshl_add_u64 v[50:51], v[168:169], 0, s[26:27]
	v_cvt_pk_bf16_f32 v34, v38, v39
	v_cvt_pk_bf16_f32 v35, v40, v41
	v_cvt_pk_bf16_f32 v36, v42, v43
	v_cvt_pk_bf16_f32 v37, v44, v45
	v_pk_fma_f32 v[32:33], v[32:33], v[170:171], v[144:145] op_sel_hi:[1,0,1]
	v_pk_fma_f32 v[28:29], v[28:29], v[170:171], v[140:141] op_sel_hi:[1,0,1]
	v_max_f32_e32 v30, 0, v30
	v_max_f32_e32 v31, 0, v31
	v_max_f32_e32 v26, 0, v26
	v_max_f32_e32 v27, 0, v27
	global_store_dwordx4 v[50:51], v[34:37], off offset:64
	v_pk_mul_f32 v[30:31], v[30:31], v[30:31]
	v_max_f32_e32 v32, 0, v32
	v_max_f32_e32 v33, 0, v33
	v_pk_mul_f32 v[36:37], v[26:27], v[26:27]
	v_max_f32_e32 v26, 0, v28
	v_max_f32_e32 v27, 0, v29
	s_mov_b32 s19, 0x140000
	v_pk_mul_f32 v[32:33], v[32:33], v[32:33]
	v_pk_mul_f32 v[38:39], v[26:27], v[26:27]
	v_cvt_pk_bf16_f32 v26, v30, v31
	v_add_co_u32_e32 v30, vcc, s19, v168
	v_pk_fma_f32 v[18:19], v[18:19], v[170:171], v[130:131] op_sel_hi:[1,0,1]
	v_cvt_pk_bf16_f32 v27, v32, v33
	v_cvt_pk_bf16_f32 v28, v36, v37
	v_cvt_pk_bf16_f32 v29, v38, v39
	v_addc_co_u32_e32 v31, vcc, 0, v169, vcc
	v_pk_fma_f32 v[24:25], v[24:25], v[170:171], v[136:137] op_sel_hi:[1,0,1]
	v_pk_fma_f32 v[22:23], v[22:23], v[170:171], v[134:135] op_sel_hi:[1,0,1]
	v_pk_fma_f32 v[20:21], v[20:21], v[170:171], v[132:133] op_sel_hi:[1,0,1]
	v_max_f32_e32 v18, 0, v18
	v_max_f32_e32 v19, 0, v19
	global_store_dwordx4 v[30:31], v[26:29], off
	v_max_f32_e32 v22, 0, v22
	v_max_f32_e32 v23, 0, v23
	v_max_f32_e32 v24, 0, v24
	v_max_f32_e32 v25, 0, v25
	v_pk_mul_f32 v[26:27], v[18:19], v[18:19]
	v_max_f32_e32 v18, 0, v20
	v_max_f32_e32 v19, 0, v21
	s_mov_b64 s[26:27], 0x140000
	v_pk_mul_f32 v[22:23], v[22:23], v[22:23]
	v_pk_mul_f32 v[24:25], v[24:25], v[24:25]
	v_pk_mul_f32 v[28:29], v[18:19], v[18:19]
	v_lshl_add_u64 v[34:35], v[168:169], 0, s[26:27]
	v_cvt_pk_bf16_f32 v18, v22, v23
	v_cvt_pk_bf16_f32 v19, v24, v25
	v_cvt_pk_bf16_f32 v20, v26, v27
	v_cvt_pk_bf16_f32 v21, v28, v29
	global_store_dwordx4 v[34:35], v[18:21], off offset:64
	s_mov_b32 s19, 0x160000
	s_mov_b64 s[26:27], 0x160000
	v_mov_b32_e32 v20, v171
	v_pk_fma_f32 v[14:15], v[14:15], v[20:21], v[142:143] op_sel_hi:[1,0,1]
	v_pk_fma_f32 v[10:11], v[10:11], v[20:21], v[138:139] op_sel_hi:[1,0,1]
	v_pk_fma_f32 v[16:17], v[16:17], v[20:21], v[144:145] op_sel_hi:[1,0,1]
	v_pk_fma_f32 v[12:13], v[12:13], v[20:21], v[140:141] op_sel_hi:[1,0,1]
	v_max_f32_e32 v14, 0, v14
	v_max_f32_e32 v15, 0, v15
	v_max_f32_e32 v10, 0, v10
	v_max_f32_e32 v11, 0, v11
	v_pk_mul_f32 v[14:15], v[14:15], v[14:15]
	v_max_f32_e32 v16, 0, v16
	v_max_f32_e32 v17, 0, v17
	v_pk_mul_f32 v[22:23], v[10:11], v[10:11]
	v_max_f32_e32 v10, 0, v12
	v_max_f32_e32 v11, 0, v13
	v_pk_mul_f32 v[16:17], v[16:17], v[16:17]
	v_pk_mul_f32 v[24:25], v[10:11], v[10:11]
	v_cvt_pk_bf16_f32 v10, v14, v15
	v_add_co_u32_e32 v14, vcc, s19, v168
	v_pk_fma_f32 v[2:3], v[2:3], v[20:21], v[130:131] op_sel_hi:[1,0,1]
	v_cvt_pk_bf16_f32 v11, v16, v17
	v_cvt_pk_bf16_f32 v12, v22, v23
	v_cvt_pk_bf16_f32 v13, v24, v25
	v_addc_co_u32_e32 v15, vcc, 0, v169, vcc
	v_pk_fma_f32 v[8:9], v[8:9], v[20:21], v[136:137] op_sel_hi:[1,0,1]
	v_pk_fma_f32 v[6:7], v[6:7], v[20:21], v[134:135] op_sel_hi:[1,0,1]
	v_pk_fma_f32 v[4:5], v[4:5], v[20:21], v[132:133] op_sel_hi:[1,0,1]
	v_max_f32_e32 v2, 0, v2
	v_max_f32_e32 v3, 0, v3
	global_store_dwordx4 v[14:15], v[10:13], off
	v_max_f32_e32 v6, 0, v6
	v_max_f32_e32 v7, 0, v7
	v_max_f32_e32 v8, 0, v8
	v_max_f32_e32 v9, 0, v9
	v_pk_mul_f32 v[10:11], v[2:3], v[2:3]
	v_max_f32_e32 v2, 0, v4
	v_max_f32_e32 v3, 0, v5
	v_pk_mul_f32 v[6:7], v[6:7], v[6:7]
	v_pk_mul_f32 v[8:9], v[8:9], v[8:9]
	v_pk_mul_f32 v[12:13], v[2:3], v[2:3]
	v_lshl_add_u64 v[18:19], v[168:169], 0, s[26:27]
	v_cvt_pk_bf16_f32 v2, v6, v7
	v_cvt_pk_bf16_f32 v3, v8, v9
	v_cvt_pk_bf16_f32 v4, v10, v11
	v_cvt_pk_bf16_f32 v5, v12, v13
	s_andn2_b64 vcc, exec, s[12:13]
	s_mov_b64 s[12:13], -1
	global_store_dwordx4 v[18:19], v[2:5], off offset:64
	s_cbranch_vccnz .LBB0_1383
	s_andn2_b64 vcc, exec, s[0:1]
	s_cbranch_vccnz .LBB0_1382
	s_barrier
	s_branch .LBB0_1382

.LBB0_1512:
	s_and_b64 vcc, exec, s[18:19]
	s_cbranch_vccz .Lepi3_nulla1
	s_ashr_i32 s16, s54, 31
	s_lshr_b32 s16, s16, 29
	s_add_i32 s16, s54, s16
	s_ashr_i32 s16, s16, 3
	s_mul_i32 s27, s16, 0x6000
	s_mul_hi_i32 s25, s16, 0x6000
	s_add_u32 s80, s45, s27
	s_addc_u32 s81, s47, s25
	s_add_u32 s82, s49, s27
	s_addc_u32 s83, s50, s25
	s_mov_b32 s62, 0xaaaaaaaa
	s_mov_b32 s63, 0xaaaaaaaa
	s_mov_b32 s66, 0x55555555
	s_mov_b32 s67, 0x55555555
	v_mbcnt_lo_u32_b32 v172, -1, 0
	v_mbcnt_hi_u32_b32 v172, -1, v172
	v_and_b32_e32 v172, 1, v172
	v_and_b32_e32 v171, 0x60, v196
	v_add_u32_e32 v171, v171, v196
	v_lshl_or_b32 v171, s4, 8, v171
	v_lshlrev_b32_e32 v44, 2, v171
	v_lshl_add_u32 v171, v172, 5, v171
	v_lshl_add_u32 v170, s54, 8, v194
	v_sub_u32_e32 v170, v170, v172
	v_lshl_add_u32 v170, v170, 10, v171
	v_lshlrev_b32_e32 v171, 1, v170
	global_load_dwordx4 v[174:177], v44, s[80:81] offset:0
	global_load_dwordx4 v[178:181], v44, s[80:81] offset:16
	global_load_dwordx4 v[190:193], v44, s[20:21] offset:0
	global_load_dwordx4 v[210:213], v44, s[20:21] offset:16
	global_load_dwordx4 v[182:185], v44, s[80:81] offset:128
	global_load_dwordx4 v[186:189], v44, s[80:81] offset:144
	global_load_dwordx4 v[214:217], v44, s[20:21] offset:128
	global_load_dwordx4 v[218:221], v44, s[20:21] offset:144
	global_load_dwordx4 v[222:225], v44, s[82:83] offset:0
	global_load_dwordx4 v[226:229], v44, s[82:83] offset:16
	s_waitcnt vmcnt(0)
	v_pk_add_f32 v[222:223], v[222:223], 1.0 op_sel_hi:[1,0]
	v_pk_add_f32 v[224:225], v[224:225], 1.0 op_sel_hi:[1,0]
	v_pk_add_f32 v[226:227], v[226:227], 1.0 op_sel_hi:[1,0]
	v_pk_add_f32 v[228:229], v[228:229], 1.0 op_sel_hi:[1,0]
	v_pk_mul_f32 v[190:191], v[190:191], v[222:223]
	v_pk_mul_f32 v[192:193], v[192:193], v[224:225]
	v_pk_mul_f32 v[210:211], v[210:211], v[226:227]
	v_pk_mul_f32 v[212:213], v[212:213], v[228:229]
	s_nop 1
	global_load_dwordx4 v[222:225], v44, s[82:83] offset:128
	global_load_dwordx4 v[226:229], v44, s[82:83] offset:144
	s_waitcnt vmcnt(0)
	v_pk_add_f32 v[222:223], v[222:223], 1.0 op_sel_hi:[1,0]
	v_pk_add_f32 v[224:225], v[224:225], 1.0 op_sel_hi:[1,0]
	v_pk_add_f32 v[226:227], v[226:227], 1.0 op_sel_hi:[1,0]
	v_pk_add_f32 v[228:229], v[228:229], 1.0 op_sel_hi:[1,0]
	v_pk_mul_f32 v[214:215], v[214:215], v[222:223]
	v_pk_mul_f32 v[216:217], v[216:217], v[224:225]
	v_pk_mul_f32 v[218:219], v[218:219], v[226:227]
	v_pk_mul_f32 v[220:221], v[220:221], v[228:229]
	s_add_u32 s84, s58, 0x0
	s_addc_u32 s85, s59, 0
	s_add_u32 s86, s74, 0x0
	s_addc_u32 s87, s75, 0
	global_load_dwordx4 v[222:225], v171, s[84:85]
	global_load_dwordx2 v[226:227], v170, s[86:87]
	global_load_dwordx4 v[228:231], v171, s[84:85] offset:2048
	global_load_dwordx2 v[232:233], v170, s[86:87] offset:1024
	s_waitcnt vmcnt(0)
	v_mov_b32_dpp v48, v222 quad_perm:[1,0,3,2] row_mask:0xf bank_mask:0xf
	v_mov_b32_dpp v49, v223 quad_perm:[1,0,3,2] row_mask:0xf bank_mask:0xf
	v_mov_b32_dpp v50, v224 quad_perm:[1,0,3,2] row_mask:0xf bank_mask:0xf
	v_mov_b32_dpp v51, v225 quad_perm:[1,0,3,2] row_mask:0xf bank_mask:0xf
	v_mov_b32_dpp v52, v228 quad_perm:[1,0,3,2] row_mask:0xf bank_mask:0xf
	v_mov_b32_dpp v53, v229 quad_perm:[1,0,3,2] row_mask:0xf bank_mask:0xf
	v_mov_b32_dpp v54, v230 quad_perm:[1,0,3,2] row_mask:0xf bank_mask:0xf
	v_mov_b32_dpp v55, v231 quad_perm:[1,0,3,2] row_mask:0xf bank_mask:0xf
	s_mov_b64 exec, s[62:63]
	v_mov_b32_e32 v222, v52
	v_mov_b32_e32 v223, v53
	v_mov_b32_e32 v224, v54
	v_mov_b32_e32 v225, v55
	s_mov_b64 exec, s[66:67]
	v_mov_b32_e32 v228, v48
	v_mov_b32_e32 v229, v49
	v_mov_b32_e32 v230, v50
	v_mov_b32_e32 v231, v51
	s_mov_b64 exec, -1
	v_mov_b32_dpp v48, v226 quad_perm:[1,0,3,2] row_mask:0xf bank_mask:0xf
	v_mov_b32_dpp v49, v227 quad_perm:[1,0,3,2] row_mask:0xf bank_mask:0xf
	v_mov_b32_dpp v52, v232 quad_perm:[1,0,3,2] row_mask:0xf bank_mask:0xf
	v_mov_b32_dpp v53, v233 quad_perm:[1,0,3,2] row_mask:0xf bank_mask:0xf
	s_mov_b64 exec, s[62:63]
	v_mov_b32_e32 v226, v52
	v_mov_b32_e32 v227, v53
	s_mov_b64 exec, s[66:67]
	v_mov_b32_e32 v232, v48
	v_mov_b32_e32 v233, v49
	s_mov_b64 exec, -1
	v_lshlrev_b32_e32 v44, 8, v226
	v_perm_b32 v45, v222, v226, s8
	v_lshrrev_b32_e32 v46, 8, v226
	v_lshrrev_b32_e32 v47, 16, v226
	v_perm_b32 v44, v222, v44, s33
	v_perm_b32 v46, v223, v46, s33
	v_perm_b32 v47, v223, v47, s8
	v_pk_fma_f32 v[142:143], v[142:143], v[174:175], v[44:45]
	v_pk_fma_f32 v[144:145], v[144:145], v[176:177], v[46:47]
	v_lshlrev_b32_e32 v44, 8, v227
	v_perm_b32 v45, v224, v227, s8
	v_lshrrev_b32_e32 v46, 8, v227
	v_lshrrev_b32_e32 v47, 16, v227
	v_perm_b32 v44, v224, v44, s33
	v_perm_b32 v46, v225, v46, s33
	v_perm_b32 v47, v225, v47, s8
	v_pk_fma_f32 v[138:139], v[138:139], v[178:179], v[44:45]
	v_pk_fma_f32 v[140:141], v[140:141], v[180:181], v[46:47]
	v_lshlrev_b32_e32 v44, 8, v232
	v_perm_b32 v45, v228, v232, s8
	v_lshrrev_b32_e32 v46, 8, v232
	v_lshrrev_b32_e32 v47, 16, v232
	v_perm_b32 v44, v228, v44, s33
	v_perm_b32 v46, v229, v46, s33
	v_perm_b32 v47, v229, v47, s8
	v_pk_fma_f32 v[134:135], v[134:135], v[182:183], v[44:45]
	v_pk_fma_f32 v[136:137], v[136:137], v[184:185], v[46:47]
	v_lshlrev_b32_e32 v44, 8, v233
	v_perm_b32 v45, v230, v233, s8
	v_lshrrev_b32_e32 v46, 8, v233
	v_lshrrev_b32_e32 v47, 16, v233
	v_perm_b32 v44, v230, v44, s33
	v_perm_b32 v46, v231, v46, s33
	v_perm_b32 v47, v231, v47, s8
	v_pk_fma_f32 v[130:131], v[130:131], v[186:187], v[44:45]
	v_pk_fma_f32 v[132:133], v[132:133], v[188:189], v[46:47]
	v_mul_f32_e32 v44, v143, v143
	v_mul_f32_e32 v45, v145, v145
	v_mul_f32_e32 v46, v139, v139
	v_mul_f32_e32 v47, v141, v141
	v_fmac_f32_e32 v44, v142, v142
	v_fmac_f32_e32 v45, v144, v144
	v_fmac_f32_e32 v46, v138, v138
	v_fmac_f32_e32 v47, v140, v140
	v_add_f32_e32 v44, v44, v45
	v_add_f32_e32 v46, v46, v47
	v_add_f32_e32 v173, v44, v46
	v_add_u32_e32 v44, 0x80, v142
	v_add_u32_e32 v45, 0x80, v143
	v_add_u32_e32 v46, 0x80, v144
	v_add_u32_e32 v47, 0x80, v145
	v_perm_b32 v48, v45, v44, s78
	v_perm_b32 v49, v47, v46, s78
	v_perm_b32 v42, v45, v44, s79
	v_perm_b32 v43, v47, v46, s79
	v_perm_b32 v56, v43, v42, s60
	v_add_u32_e32 v44, 0x80, v138
	v_add_u32_e32 v45, 0x80, v139
	v_add_u32_e32 v46, 0x80, v140
	v_add_u32_e32 v47, 0x80, v141
	v_perm_b32 v50, v45, v44, s78
	v_perm_b32 v51, v47, v46, s78
	v_perm_b32 v42, v45, v44, s79
	v_perm_b32 v43, v47, v46, s79
	v_perm_b32 v57, v43, v42, s60
	v_mul_f32_e32 v44, v135, v135
	v_mul_f32_e32 v45, v137, v137
	v_mul_f32_e32 v46, v131, v131
	v_mul_f32_e32 v47, v133, v133
	v_fmac_f32_e32 v44, v134, v134
	v_fmac_f32_e32 v45, v136, v136
	v_fmac_f32_e32 v46, v130, v130
	v_fmac_f32_e32 v47, v132, v132
	v_add_f32_e32 v44, v44, v45
	v_add_f32_e32 v46, v46, v47
	v_add_f32_e32 v44, v44, v46
	v_add_f32_e32 v173, v173, v44
	v_add_u32_e32 v44, 0x80, v134
	v_add_u32_e32 v45, 0x80, v135
	v_add_u32_e32 v46, 0x80, v136
	v_add_u32_e32 v47, 0x80, v137
	v_perm_b32 v52, v45, v44, s78
	v_perm_b32 v53, v47, v46, s78
	v_perm_b32 v42, v45, v44, s79
	v_perm_b32 v43, v47, v46, s79
	v_perm_b32 v168, v43, v42, s60
	v_add_u32_e32 v44, 0x80, v130
	v_add_u32_e32 v45, 0x80, v131
	v_add_u32_e32 v46, 0x80, v132
	v_add_u32_e32 v47, 0x80, v133
	v_perm_b32 v54, v45, v44, s78
	v_perm_b32 v55, v47, v46, s78
	v_perm_b32 v42, v45, v44, s79
	v_perm_b32 v43, v47, v46, s79
	v_perm_b32 v169, v43, v42, s60
	v_mov_b32_dpp v222, v48 quad_perm:[1,0,3,2] row_mask:0xf bank_mask:0xf
	v_mov_b32_dpp v223, v49 quad_perm:[1,0,3,2] row_mask:0xf bank_mask:0xf
	v_mov_b32_dpp v224, v50 quad_perm:[1,0,3,2] row_mask:0xf bank_mask:0xf
	v_mov_b32_dpp v225, v51 quad_perm:[1,0,3,2] row_mask:0xf bank_mask:0xf
	v_mov_b32_dpp v228, v52 quad_perm:[1,0,3,2] row_mask:0xf bank_mask:0xf
	v_mov_b32_dpp v229, v53 quad_perm:[1,0,3,2] row_mask:0xf bank_mask:0xf
	v_mov_b32_dpp v230, v54 quad_perm:[1,0,3,2] row_mask:0xf bank_mask:0xf
	v_mov_b32_dpp v231, v55 quad_perm:[1,0,3,2] row_mask:0xf bank_mask:0xf
	s_mov_b64 exec, s[62:63]
	v_mov_b32_e32 v48, v228
	v_mov_b32_e32 v49, v229
	v_mov_b32_e32 v50, v230
	v_mov_b32_e32 v51, v231
	s_mov_b64 exec, s[66:67]
	v_mov_b32_e32 v52, v222
	v_mov_b32_e32 v53, v223
	v_mov_b32_e32 v54, v224
	v_mov_b32_e32 v55, v225
	s_mov_b64 exec, -1
	v_mov_b32_dpp v222, v56 quad_perm:[1,0,3,2] row_mask:0xf bank_mask:0xf
	v_mov_b32_dpp v223, v57 quad_perm:[1,0,3,2] row_mask:0xf bank_mask:0xf
	v_mov_b32_dpp v228, v168 quad_perm:[1,0,3,2] row_mask:0xf bank_mask:0xf
	v_mov_b32_dpp v229, v169 quad_perm:[1,0,3,2] row_mask:0xf bank_mask:0xf
	s_mov_b64 exec, s[62:63]
	v_mov_b32_e32 v56, v228
	v_mov_b32_e32 v57, v229
	s_mov_b64 exec, s[66:67]
	v_mov_b32_e32 v168, v222
	v_mov_b32_e32 v169, v223
	s_mov_b64 exec, -1
	s_add_u32 s88, s58, 0x0
	s_addc_u32 s89, s59, 0
	s_add_u32 s90, s74, 0x0
	s_addc_u32 s91, s75, 0
	global_store_dwordx4 v171, v[48:51], s[88:89]
	global_store_dwordx4 v171, v[52:55], s[88:89] offset:2048
	global_store_dwordx2 v170, v[56:57], s[90:91]
	global_store_dwordx2 v170, v[168:169], s[90:91] offset:1024
	s_add_u32 s92, s96, 0x0
	s_addc_u32 s93, s97, 0
	v_pk_mul_f32 v[142:143], v[190:191], v[142:143]
	v_pk_mul_f32 v[144:145], v[192:193], v[144:145]
	v_pk_mul_f32 v[138:139], v[210:211], v[138:139]
	v_pk_mul_f32 v[140:141], v[212:213], v[140:141]
	v_cvt_pk_bf16_f32 v48, v142, v143
	v_cvt_pk_bf16_f32 v49, v144, v145
	v_cvt_pk_bf16_f32 v50, v138, v139
	v_cvt_pk_bf16_f32 v51, v140, v141
	v_pk_mul_f32 v[134:135], v[214:215], v[134:135]
	v_pk_mul_f32 v[136:137], v[216:217], v[136:137]
	v_pk_mul_f32 v[130:131], v[218:219], v[130:131]
	v_pk_mul_f32 v[132:133], v[220:221], v[132:133]
	v_cvt_pk_bf16_f32 v52, v134, v135
	v_cvt_pk_bf16_f32 v53, v136, v137
	v_cvt_pk_bf16_f32 v54, v130, v131
	v_cvt_pk_bf16_f32 v55, v132, v133
	v_mov_b32_dpp v222, v48 quad_perm:[1,0,3,2] row_mask:0xf bank_mask:0xf
	v_mov_b32_dpp v223, v49 quad_perm:[1,0,3,2] row_mask:0xf bank_mask:0xf
	v_mov_b32_dpp v224, v50 quad_perm:[1,0,3,2] row_mask:0xf bank_mask:0xf
	v_mov_b32_dpp v225, v51 quad_perm:[1,0,3,2] row_mask:0xf bank_mask:0xf
	v_mov_b32_dpp v228, v52 quad_perm:[1,0,3,2] row_mask:0xf bank_mask:0xf
	v_mov_b32_dpp v229, v53 quad_perm:[1,0,3,2] row_mask:0xf bank_mask:0xf
	v_mov_b32_dpp v230, v54 quad_perm:[1,0,3,2] row_mask:0xf bank_mask:0xf
	v_mov_b32_dpp v231, v55 quad_perm:[1,0,3,2] row_mask:0xf bank_mask:0xf
	s_mov_b64 exec, s[62:63]
	v_mov_b32_e32 v48, v228
	v_mov_b32_e32 v49, v229
	v_mov_b32_e32 v50, v230
	v_mov_b32_e32 v51, v231
	s_mov_b64 exec, s[66:67]
	v_mov_b32_e32 v52, v222
	v_mov_b32_e32 v53, v223
	v_mov_b32_e32 v54, v224
	v_mov_b32_e32 v55, v225
	s_mov_b64 exec, -1
	global_store_dwordx4 v171, v[48:51], s[92:93]
	global_store_dwordx4 v171, v[52:55], s[92:93] offset:2048
	v_mov_b32_e32 v130, v173
	s_add_u32 s84, s58, 0x8000
	s_addc_u32 s85, s59, 0
	s_add_u32 s86, s74, 0x4000
	s_addc_u32 s87, s75, 0
	global_load_dwordx4 v[132:135], v171, s[84:85]
	global_load_dwordx2 v[136:137], v170, s[86:87]
	global_load_dwordx4 v[138:141], v171, s[84:85] offset:2048
	global_load_dwordx2 v[142:143], v170, s[86:87] offset:1024
	s_add_u32 s84, s58, 0x10000
	s_addc_u32 s85, s59, 0
	s_add_u32 s86, s74, 0x8000
	s_addc_u32 s87, s75, 0
	global_load_dwordx4 v[222:225], v171, s[84:85]
	global_load_dwordx2 v[144:145], v170, s[86:87]
	global_load_dwordx4 v[226:229], v171, s[84:85] offset:2048
	global_load_dwordx2 v[230:231], v170, s[86:87] offset:1024
	s_waitcnt vmcnt(4)
	v_mov_b32_dpp v48, v132 quad_perm:[1,0,3,2] row_mask:0xf bank_mask:0xf
	v_mov_b32_dpp v49, v133 quad_perm:[1,0,3,2] row_mask:0xf bank_mask:0xf
	v_mov_b32_dpp v50, v134 quad_perm:[1,0,3,2] row_mask:0xf bank_mask:0xf
	v_mov_b32_dpp v51, v135 quad_perm:[1,0,3,2] row_mask:0xf bank_mask:0xf
	v_mov_b32_dpp v52, v138 quad_perm:[1,0,3,2] row_mask:0xf bank_mask:0xf
	v_mov_b32_dpp v53, v139 quad_perm:[1,0,3,2] row_mask:0xf bank_mask:0xf
	v_mov_b32_dpp v54, v140 quad_perm:[1,0,3,2] row_mask:0xf bank_mask:0xf
	v_mov_b32_dpp v55, v141 quad_perm:[1,0,3,2] row_mask:0xf bank_mask:0xf
	s_mov_b64 exec, s[62:63]
	v_mov_b32_e32 v132, v52
	v_mov_b32_e32 v133, v53
	v_mov_b32_e32 v134, v54
	v_mov_b32_e32 v135, v55
	s_mov_b64 exec, s[66:67]
	v_mov_b32_e32 v138, v48
	v_mov_b32_e32 v139, v49
	v_mov_b32_e32 v140, v50
	v_mov_b32_e32 v141, v51
	s_mov_b64 exec, -1
	v_mov_b32_dpp v48, v136 quad_perm:[1,0,3,2] row_mask:0xf bank_mask:0xf
	v_mov_b32_dpp v49, v137 quad_perm:[1,0,3,2] row_mask:0xf bank_mask:0xf
	v_mov_b32_dpp v52, v142 quad_perm:[1,0,3,2] row_mask:0xf bank_mask:0xf
	v_mov_b32_dpp v53, v143 quad_perm:[1,0,3,2] row_mask:0xf bank_mask:0xf
	s_mov_b64 exec, s[62:63]
	v_mov_b32_e32 v136, v52
	v_mov_b32_e32 v137, v53
	s_mov_b64 exec, s[66:67]
	v_mov_b32_e32 v142, v48
	v_mov_b32_e32 v143, v49
	s_mov_b64 exec, -1
	v_lshlrev_b32_e32 v44, 8, v136
	v_perm_b32 v45, v132, v136, s8
	v_lshrrev_b32_e32 v46, 8, v136
	v_lshrrev_b32_e32 v47, 16, v136
	v_perm_b32 v44, v132, v44, s33
	v_perm_b32 v46, v133, v46, s33
	v_perm_b32 v47, v133, v47, s8
	v_pk_fma_f32 v[126:127], v[126:127], v[174:175], v[44:45]
	v_pk_fma_f32 v[128:129], v[128:129], v[176:177], v[46:47]
	v_lshlrev_b32_e32 v44, 8, v137
	v_perm_b32 v45, v134, v137, s8
	v_lshrrev_b32_e32 v46, 8, v137
	v_lshrrev_b32_e32 v47, 16, v137
	v_perm_b32 v44, v134, v44, s33
	v_perm_b32 v46, v135, v46, s33
	v_perm_b32 v47, v135, v47, s8
	v_pk_fma_f32 v[122:123], v[122:123], v[178:179], v[44:45]
	v_pk_fma_f32 v[124:125], v[124:125], v[180:181], v[46:47]
	v_lshlrev_b32_e32 v44, 8, v142
	v_perm_b32 v45, v138, v142, s8
	v_lshrrev_b32_e32 v46, 8, v142
	v_lshrrev_b32_e32 v47, 16, v142
	v_perm_b32 v44, v138, v44, s33
	v_perm_b32 v46, v139, v46, s33
	v_perm_b32 v47, v139, v47, s8
	v_pk_fma_f32 v[118:119], v[118:119], v[182:183], v[44:45]
	v_pk_fma_f32 v[120:121], v[120:121], v[184:185], v[46:47]
	v_lshlrev_b32_e32 v44, 8, v143
	v_perm_b32 v45, v140, v143, s8
	v_lshrrev_b32_e32 v46, 8, v143
	v_lshrrev_b32_e32 v47, 16, v143
	v_perm_b32 v44, v140, v44, s33
	v_perm_b32 v46, v141, v46, s33
	v_perm_b32 v47, v141, v47, s8
	v_pk_fma_f32 v[114:115], v[114:115], v[186:187], v[44:45]
	v_pk_fma_f32 v[116:117], v[116:117], v[188:189], v[46:47]
	v_mul_f32_e32 v44, v127, v127
	v_mul_f32_e32 v45, v129, v129
	v_mul_f32_e32 v46, v123, v123
	v_mul_f32_e32 v47, v125, v125
	v_fmac_f32_e32 v44, v126, v126
	v_fmac_f32_e32 v45, v128, v128
	v_fmac_f32_e32 v46, v122, v122
	v_fmac_f32_e32 v47, v124, v124
	v_add_f32_e32 v44, v44, v45
	v_add_f32_e32 v46, v46, v47
	v_add_f32_e32 v173, v44, v46
	v_add_u32_e32 v44, 0x80, v126
	v_add_u32_e32 v45, 0x80, v127
	v_add_u32_e32 v46, 0x80, v128
	v_add_u32_e32 v47, 0x80, v129
	v_perm_b32 v48, v45, v44, s78
	v_perm_b32 v49, v47, v46, s78
	v_perm_b32 v42, v45, v44, s79
	v_perm_b32 v43, v47, v46, s79
	v_perm_b32 v56, v43, v42, s60
	v_add_u32_e32 v44, 0x80, v122
	v_add_u32_e32 v45, 0x80, v123
	v_add_u32_e32 v46, 0x80, v124
	v_add_u32_e32 v47, 0x80, v125
	v_perm_b32 v50, v45, v44, s78
	v_perm_b32 v51, v47, v46, s78
	v_perm_b32 v42, v45, v44, s79
	v_perm_b32 v43, v47, v46, s79
	v_perm_b32 v57, v43, v42, s60
	v_mul_f32_e32 v44, v119, v119
	v_mul_f32_e32 v45, v121, v121
	v_mul_f32_e32 v46, v115, v115
	v_mul_f32_e32 v47, v117, v117
	v_fmac_f32_e32 v44, v118, v118
	v_fmac_f32_e32 v45, v120, v120
	v_fmac_f32_e32 v46, v114, v114
	v_fmac_f32_e32 v47, v116, v116
	v_add_f32_e32 v44, v44, v45
	v_add_f32_e32 v46, v46, v47
	v_add_f32_e32 v44, v44, v46
	v_add_f32_e32 v173, v173, v44
	v_add_u32_e32 v44, 0x80, v118
	v_add_u32_e32 v45, 0x80, v119
	v_add_u32_e32 v46, 0x80, v120
	v_add_u32_e32 v47, 0x80, v121
	v_perm_b32 v52, v45, v44, s78
	v_perm_b32 v53, v47, v46, s78
	v_perm_b32 v42, v45, v44, s79
	v_perm_b32 v43, v47, v46, s79
	v_perm_b32 v168, v43, v42, s60
	v_add_u32_e32 v44, 0x80, v114
	v_add_u32_e32 v45, 0x80, v115
	v_add_u32_e32 v46, 0x80, v116
	v_add_u32_e32 v47, 0x80, v117
	v_perm_b32 v54, v45, v44, s78
	v_perm_b32 v55, v47, v46, s78
	v_perm_b32 v42, v45, v44, s79
	v_perm_b32 v43, v47, v46, s79
	v_perm_b32 v169, v43, v42, s60
	v_mov_b32_dpp v132, v48 quad_perm:[1,0,3,2] row_mask:0xf bank_mask:0xf
	v_mov_b32_dpp v133, v49 quad_perm:[1,0,3,2] row_mask:0xf bank_mask:0xf
	v_mov_b32_dpp v134, v50 quad_perm:[1,0,3,2] row_mask:0xf bank_mask:0xf
	v_mov_b32_dpp v135, v51 quad_perm:[1,0,3,2] row_mask:0xf bank_mask:0xf
	v_mov_b32_dpp v138, v52 quad_perm:[1,0,3,2] row_mask:0xf bank_mask:0xf
	v_mov_b32_dpp v139, v53 quad_perm:[1,0,3,2] row_mask:0xf bank_mask:0xf
	v_mov_b32_dpp v140, v54 quad_perm:[1,0,3,2] row_mask:0xf bank_mask:0xf
	v_mov_b32_dpp v141, v55 quad_perm:[1,0,3,2] row_mask:0xf bank_mask:0xf
	s_mov_b64 exec, s[62:63]
	v_mov_b32_e32 v48, v138
	v_mov_b32_e32 v49, v139
	v_mov_b32_e32 v50, v140
	v_mov_b32_e32 v51, v141
	s_mov_b64 exec, s[66:67]
	v_mov_b32_e32 v52, v132
	v_mov_b32_e32 v53, v133
	v_mov_b32_e32 v54, v134
	v_mov_b32_e32 v55, v135
	s_mov_b64 exec, -1
	v_mov_b32_dpp v132, v56 quad_perm:[1,0,3,2] row_mask:0xf bank_mask:0xf
	v_mov_b32_dpp v133, v57 quad_perm:[1,0,3,2] row_mask:0xf bank_mask:0xf
	v_mov_b32_dpp v138, v168 quad_perm:[1,0,3,2] row_mask:0xf bank_mask:0xf
	v_mov_b32_dpp v139, v169 quad_perm:[1,0,3,2] row_mask:0xf bank_mask:0xf
	s_mov_b64 exec, s[62:63]
	v_mov_b32_e32 v56, v138
	v_mov_b32_e32 v57, v139
	s_mov_b64 exec, s[66:67]
	v_mov_b32_e32 v168, v132
	v_mov_b32_e32 v169, v133
	s_mov_b64 exec, -1
	s_add_u32 s88, s58, 0x8000
	s_addc_u32 s89, s59, 0
	s_add_u32 s90, s74, 0x4000
	s_addc_u32 s91, s75, 0
	global_store_dwordx4 v171, v[48:51], s[88:89]
	global_store_dwordx4 v171, v[52:55], s[88:89] offset:2048
	global_store_dwordx2 v170, v[56:57], s[90:91]
	global_store_dwordx2 v170, v[168:169], s[90:91] offset:1024
	s_add_u32 s92, s96, 0x8000
	s_addc_u32 s93, s97, 0
	v_pk_mul_f32 v[126:127], v[190:191], v[126:127]
	v_pk_mul_f32 v[128:129], v[192:193], v[128:129]
	v_pk_mul_f32 v[122:123], v[210:211], v[122:123]
	v_pk_mul_f32 v[124:125], v[212:213], v[124:125]
	v_cvt_pk_bf16_f32 v48, v126, v127
	v_cvt_pk_bf16_f32 v49, v128, v129
	v_cvt_pk_bf16_f32 v50, v122, v123
	v_cvt_pk_bf16_f32 v51, v124, v125
	v_pk_mul_f32 v[118:119], v[214:215], v[118:119]
	v_pk_mul_f32 v[120:121], v[216:217], v[120:121]
	v_pk_mul_f32 v[114:115], v[218:219], v[114:115]
	v_pk_mul_f32 v[116:117], v[220:221], v[116:117]
	v_cvt_pk_bf16_f32 v52, v118, v119
	v_cvt_pk_bf16_f32 v53, v120, v121
	v_cvt_pk_bf16_f32 v54, v114, v115
	v_cvt_pk_bf16_f32 v55, v116, v117
	v_mov_b32_dpp v132, v48 quad_perm:[1,0,3,2] row_mask:0xf bank_mask:0xf
	v_mov_b32_dpp v133, v49 quad_perm:[1,0,3,2] row_mask:0xf bank_mask:0xf
	v_mov_b32_dpp v134, v50 quad_perm:[1,0,3,2] row_mask:0xf bank_mask:0xf
	v_mov_b32_dpp v135, v51 quad_perm:[1,0,3,2] row_mask:0xf bank_mask:0xf
	v_mov_b32_dpp v138, v52 quad_perm:[1,0,3,2] row_mask:0xf bank_mask:0xf
	v_mov_b32_dpp v139, v53 quad_perm:[1,0,3,2] row_mask:0xf bank_mask:0xf
	v_mov_b32_dpp v140, v54 quad_perm:[1,0,3,2] row_mask:0xf bank_mask:0xf
	v_mov_b32_dpp v141, v55 quad_perm:[1,0,3,2] row_mask:0xf bank_mask:0xf
	s_mov_b64 exec, s[62:63]
	v_mov_b32_e32 v48, v138
	v_mov_b32_e32 v49, v139
	v_mov_b32_e32 v50, v140
	v_mov_b32_e32 v51, v141
	s_mov_b64 exec, s[66:67]
	v_mov_b32_e32 v52, v132
	v_mov_b32_e32 v53, v133
	v_mov_b32_e32 v54, v134
	v_mov_b32_e32 v55, v135
	s_mov_b64 exec, -1
	global_store_dwordx4 v171, v[48:51], s[92:93]
	global_store_dwordx4 v171, v[52:55], s[92:93] offset:2048
	v_mov_b32_e32 v114, v173
	s_add_u32 s84, s58, 0x18000
	s_addc_u32 s85, s59, 0
	s_add_u32 s86, s74, 0xc000
	s_addc_u32 s87, s75, 0
	global_load_dwordx4 v[116:119], v171, s[84:85]
	global_load_dwordx2 v[120:121], v170, s[86:87]
	global_load_dwordx4 v[122:125], v171, s[84:85] offset:2048
	global_load_dwordx2 v[126:127], v170, s[86:87] offset:1024
	s_waitcnt vmcnt(10)
	v_mov_b32_dpp v48, v222 quad_perm:[1,0,3,2] row_mask:0xf bank_mask:0xf
	v_mov_b32_dpp v49, v223 quad_perm:[1,0,3,2] row_mask:0xf bank_mask:0xf
	v_mov_b32_dpp v50, v224 quad_perm:[1,0,3,2] row_mask:0xf bank_mask:0xf
	v_mov_b32_dpp v51, v225 quad_perm:[1,0,3,2] row_mask:0xf bank_mask:0xf
	v_mov_b32_dpp v52, v226 quad_perm:[1,0,3,2] row_mask:0xf bank_mask:0xf
	v_mov_b32_dpp v53, v227 quad_perm:[1,0,3,2] row_mask:0xf bank_mask:0xf
	v_mov_b32_dpp v54, v228 quad_perm:[1,0,3,2] row_mask:0xf bank_mask:0xf
	v_mov_b32_dpp v55, v229 quad_perm:[1,0,3,2] row_mask:0xf bank_mask:0xf
	s_mov_b64 exec, s[62:63]
	v_mov_b32_e32 v222, v52
	v_mov_b32_e32 v223, v53
	v_mov_b32_e32 v224, v54
	v_mov_b32_e32 v225, v55
	s_mov_b64 exec, s[66:67]
	v_mov_b32_e32 v226, v48
	v_mov_b32_e32 v227, v49
	v_mov_b32_e32 v228, v50
	v_mov_b32_e32 v229, v51
	s_mov_b64 exec, -1
	v_mov_b32_dpp v48, v144 quad_perm:[1,0,3,2] row_mask:0xf bank_mask:0xf
	v_mov_b32_dpp v49, v145 quad_perm:[1,0,3,2] row_mask:0xf bank_mask:0xf
	v_mov_b32_dpp v52, v230 quad_perm:[1,0,3,2] row_mask:0xf bank_mask:0xf
	v_mov_b32_dpp v53, v231 quad_perm:[1,0,3,2] row_mask:0xf bank_mask:0xf
	s_mov_b64 exec, s[62:63]
	v_mov_b32_e32 v144, v52
	v_mov_b32_e32 v145, v53
	s_mov_b64 exec, s[66:67]
	v_mov_b32_e32 v230, v48
	v_mov_b32_e32 v231, v49
	s_mov_b64 exec, -1
	v_lshlrev_b32_e32 v44, 8, v144
	v_perm_b32 v45, v222, v144, s8
	v_lshrrev_b32_e32 v46, 8, v144
	v_lshrrev_b32_e32 v47, 16, v144
	v_perm_b32 v44, v222, v44, s33
	v_perm_b32 v46, v223, v46, s33
	v_perm_b32 v47, v223, v47, s8
	v_pk_fma_f32 v[110:111], v[110:111], v[174:175], v[44:45]
	v_pk_fma_f32 v[112:113], v[112:113], v[176:177], v[46:47]
	v_lshlrev_b32_e32 v44, 8, v145
	v_perm_b32 v45, v224, v145, s8
	v_lshrrev_b32_e32 v46, 8, v145
	v_lshrrev_b32_e32 v47, 16, v145
	v_perm_b32 v44, v224, v44, s33
	v_perm_b32 v46, v225, v46, s33
	v_perm_b32 v47, v225, v47, s8
	v_pk_fma_f32 v[106:107], v[106:107], v[178:179], v[44:45]
	v_pk_fma_f32 v[108:109], v[108:109], v[180:181], v[46:47]
	v_lshlrev_b32_e32 v44, 8, v230
	v_perm_b32 v45, v226, v230, s8
	v_lshrrev_b32_e32 v46, 8, v230
	v_lshrrev_b32_e32 v47, 16, v230
	v_perm_b32 v44, v226, v44, s33
	v_perm_b32 v46, v227, v46, s33
	v_perm_b32 v47, v227, v47, s8
	v_pk_fma_f32 v[102:103], v[102:103], v[182:183], v[44:45]
	v_pk_fma_f32 v[104:105], v[104:105], v[184:185], v[46:47]
	v_lshlrev_b32_e32 v44, 8, v231
	v_perm_b32 v45, v228, v231, s8
	v_lshrrev_b32_e32 v46, 8, v231
	v_lshrrev_b32_e32 v47, 16, v231
	v_perm_b32 v44, v228, v44, s33
	v_perm_b32 v46, v229, v46, s33
	v_perm_b32 v47, v229, v47, s8
	v_pk_fma_f32 v[98:99], v[98:99], v[186:187], v[44:45]
	v_pk_fma_f32 v[100:101], v[100:101], v[188:189], v[46:47]
	v_mul_f32_e32 v44, v111, v111
	v_mul_f32_e32 v45, v113, v113
	v_mul_f32_e32 v46, v107, v107
	v_mul_f32_e32 v47, v109, v109
	v_fmac_f32_e32 v44, v110, v110
	v_fmac_f32_e32 v45, v112, v112
	v_fmac_f32_e32 v46, v106, v106
	v_fmac_f32_e32 v47, v108, v108
	v_add_f32_e32 v44, v44, v45
	v_add_f32_e32 v46, v46, v47
	v_add_f32_e32 v173, v44, v46
	v_add_u32_e32 v44, 0x80, v110
	v_add_u32_e32 v45, 0x80, v111
	v_add_u32_e32 v46, 0x80, v112
	v_add_u32_e32 v47, 0x80, v113
	v_perm_b32 v48, v45, v44, s78
	v_perm_b32 v49, v47, v46, s78
	v_perm_b32 v42, v45, v44, s79
	v_perm_b32 v43, v47, v46, s79
	v_perm_b32 v56, v43, v42, s60
	v_add_u32_e32 v44, 0x80, v106
	v_add_u32_e32 v45, 0x80, v107
	v_add_u32_e32 v46, 0x80, v108
	v_add_u32_e32 v47, 0x80, v109
	v_perm_b32 v50, v45, v44, s78
	v_perm_b32 v51, v47, v46, s78
	v_perm_b32 v42, v45, v44, s79
	v_perm_b32 v43, v47, v46, s79
	v_perm_b32 v57, v43, v42, s60
	v_mul_f32_e32 v44, v103, v103
	v_mul_f32_e32 v45, v105, v105
	v_mul_f32_e32 v46, v99, v99
	v_mul_f32_e32 v47, v101, v101
	v_fmac_f32_e32 v44, v102, v102
	v_fmac_f32_e32 v45, v104, v104
	v_fmac_f32_e32 v46, v98, v98
	v_fmac_f32_e32 v47, v100, v100
	v_add_f32_e32 v44, v44, v45
	v_add_f32_e32 v46, v46, v47
	v_add_f32_e32 v44, v44, v46
	v_add_f32_e32 v173, v173, v44
	v_add_u32_e32 v44, 0x80, v102
	v_add_u32_e32 v45, 0x80, v103
	v_add_u32_e32 v46, 0x80, v104
	v_add_u32_e32 v47, 0x80, v105
	v_perm_b32 v52, v45, v44, s78
	v_perm_b32 v53, v47, v46, s78
	v_perm_b32 v42, v45, v44, s79
	v_perm_b32 v43, v47, v46, s79
	v_perm_b32 v168, v43, v42, s60
	v_add_u32_e32 v44, 0x80, v98
	v_add_u32_e32 v45, 0x80, v99
	v_add_u32_e32 v46, 0x80, v100
	v_add_u32_e32 v47, 0x80, v101
	v_perm_b32 v54, v45, v44, s78
	v_perm_b32 v55, v47, v46, s78
	v_perm_b32 v42, v45, v44, s79
	v_perm_b32 v43, v47, v46, s79
	v_perm_b32 v169, v43, v42, s60
	v_mov_b32_dpp v222, v48 quad_perm:[1,0,3,2] row_mask:0xf bank_mask:0xf
	v_mov_b32_dpp v223, v49 quad_perm:[1,0,3,2] row_mask:0xf bank_mask:0xf
	v_mov_b32_dpp v224, v50 quad_perm:[1,0,3,2] row_mask:0xf bank_mask:0xf
	v_mov_b32_dpp v225, v51 quad_perm:[1,0,3,2] row_mask:0xf bank_mask:0xf
	v_mov_b32_dpp v226, v52 quad_perm:[1,0,3,2] row_mask:0xf bank_mask:0xf
	v_mov_b32_dpp v227, v53 quad_perm:[1,0,3,2] row_mask:0xf bank_mask:0xf
	v_mov_b32_dpp v228, v54 quad_perm:[1,0,3,2] row_mask:0xf bank_mask:0xf
	v_mov_b32_dpp v229, v55 quad_perm:[1,0,3,2] row_mask:0xf bank_mask:0xf
	s_mov_b64 exec, s[62:63]
	v_mov_b32_e32 v48, v226
	v_mov_b32_e32 v49, v227
	v_mov_b32_e32 v50, v228
	v_mov_b32_e32 v51, v229
	s_mov_b64 exec, s[66:67]
	v_mov_b32_e32 v52, v222
	v_mov_b32_e32 v53, v223
	v_mov_b32_e32 v54, v224
	v_mov_b32_e32 v55, v225
	s_mov_b64 exec, -1
	v_mov_b32_dpp v222, v56 quad_perm:[1,0,3,2] row_mask:0xf bank_mask:0xf
	v_mov_b32_dpp v223, v57 quad_perm:[1,0,3,2] row_mask:0xf bank_mask:0xf
	v_mov_b32_dpp v226, v168 quad_perm:[1,0,3,2] row_mask:0xf bank_mask:0xf
	v_mov_b32_dpp v227, v169 quad_perm:[1,0,3,2] row_mask:0xf bank_mask:0xf
	s_mov_b64 exec, s[62:63]
	v_mov_b32_e32 v56, v226
	v_mov_b32_e32 v57, v227
	s_mov_b64 exec, s[66:67]
	v_mov_b32_e32 v168, v222
	v_mov_b32_e32 v169, v223
	s_mov_b64 exec, -1
	s_add_u32 s88, s58, 0x10000
	s_addc_u32 s89, s59, 0
	s_add_u32 s90, s74, 0x8000
	s_addc_u32 s91, s75, 0
	global_store_dwordx4 v171, v[48:51], s[88:89]
	global_store_dwordx4 v171, v[52:55], s[88:89] offset:2048
	global_store_dwordx2 v170, v[56:57], s[90:91]
	global_store_dwordx2 v170, v[168:169], s[90:91] offset:1024
	s_add_u32 s92, s96, 0x10000
	s_addc_u32 s93, s97, 0
	v_pk_mul_f32 v[110:111], v[190:191], v[110:111]
	v_pk_mul_f32 v[112:113], v[192:193], v[112:113]
	v_pk_mul_f32 v[106:107], v[210:211], v[106:107]
	v_pk_mul_f32 v[108:109], v[212:213], v[108:109]
	v_cvt_pk_bf16_f32 v48, v110, v111
	v_cvt_pk_bf16_f32 v49, v112, v113
	v_cvt_pk_bf16_f32 v50, v106, v107
	v_cvt_pk_bf16_f32 v51, v108, v109
	v_pk_mul_f32 v[102:103], v[214:215], v[102:103]
	v_pk_mul_f32 v[104:105], v[216:217], v[104:105]
	v_pk_mul_f32 v[98:99], v[218:219], v[98:99]
	v_pk_mul_f32 v[100:101], v[220:221], v[100:101]
	v_cvt_pk_bf16_f32 v52, v102, v103
	v_cvt_pk_bf16_f32 v53, v104, v105
	v_cvt_pk_bf16_f32 v54, v98, v99
	v_cvt_pk_bf16_f32 v55, v100, v101
	v_mov_b32_dpp v222, v48 quad_perm:[1,0,3,2] row_mask:0xf bank_mask:0xf
	v_mov_b32_dpp v223, v49 quad_perm:[1,0,3,2] row_mask:0xf bank_mask:0xf
	v_mov_b32_dpp v224, v50 quad_perm:[1,0,3,2] row_mask:0xf bank_mask:0xf
	v_mov_b32_dpp v225, v51 quad_perm:[1,0,3,2] row_mask:0xf bank_mask:0xf
	v_mov_b32_dpp v226, v52 quad_perm:[1,0,3,2] row_mask:0xf bank_mask:0xf
	v_mov_b32_dpp v227, v53 quad_perm:[1,0,3,2] row_mask:0xf bank_mask:0xf
	v_mov_b32_dpp v228, v54 quad_perm:[1,0,3,2] row_mask:0xf bank_mask:0xf
	v_mov_b32_dpp v229, v55 quad_perm:[1,0,3,2] row_mask:0xf bank_mask:0xf
	s_mov_b64 exec, s[62:63]
	v_mov_b32_e32 v48, v226
	v_mov_b32_e32 v49, v227
	v_mov_b32_e32 v50, v228
	v_mov_b32_e32 v51, v229
	s_mov_b64 exec, s[66:67]
	v_mov_b32_e32 v52, v222
	v_mov_b32_e32 v53, v223
	v_mov_b32_e32 v54, v224
	v_mov_b32_e32 v55, v225
	s_mov_b64 exec, -1
	global_store_dwordx4 v171, v[48:51], s[92:93]
	global_store_dwordx4 v171, v[52:55], s[92:93] offset:2048
	v_mov_b32_e32 v98, v173
	s_add_u32 s84, s58, 0x40000
	s_addc_u32 s85, s59, 0
	s_add_u32 s86, s74, 0x20000
	s_addc_u32 s87, s75, 0
	global_load_dwordx4 v[100:103], v171, s[84:85]
	global_load_dwordx2 v[104:105], v170, s[86:87]
	global_load_dwordx4 v[106:109], v171, s[84:85] offset:2048
	global_load_dwordx2 v[110:111], v170, s[86:87] offset:1024
	s_waitcnt vmcnt(10)
	v_mov_b32_dpp v48, v116 quad_perm:[1,0,3,2] row_mask:0xf bank_mask:0xf
	v_mov_b32_dpp v49, v117 quad_perm:[1,0,3,2] row_mask:0xf bank_mask:0xf
	v_mov_b32_dpp v50, v118 quad_perm:[1,0,3,2] row_mask:0xf bank_mask:0xf
	v_mov_b32_dpp v51, v119 quad_perm:[1,0,3,2] row_mask:0xf bank_mask:0xf
	v_mov_b32_dpp v52, v122 quad_perm:[1,0,3,2] row_mask:0xf bank_mask:0xf
	v_mov_b32_dpp v53, v123 quad_perm:[1,0,3,2] row_mask:0xf bank_mask:0xf
	v_mov_b32_dpp v54, v124 quad_perm:[1,0,3,2] row_mask:0xf bank_mask:0xf
	v_mov_b32_dpp v55, v125 quad_perm:[1,0,3,2] row_mask:0xf bank_mask:0xf
	s_mov_b64 exec, s[62:63]
	v_mov_b32_e32 v116, v52
	v_mov_b32_e32 v117, v53
	v_mov_b32_e32 v118, v54
	v_mov_b32_e32 v119, v55
	s_mov_b64 exec, s[66:67]
	v_mov_b32_e32 v122, v48
	v_mov_b32_e32 v123, v49
	v_mov_b32_e32 v124, v50
	v_mov_b32_e32 v125, v51
	s_mov_b64 exec, -1
	v_mov_b32_dpp v48, v120 quad_perm:[1,0,3,2] row_mask:0xf bank_mask:0xf
	v_mov_b32_dpp v49, v121 quad_perm:[1,0,3,2] row_mask:0xf bank_mask:0xf
	v_mov_b32_dpp v52, v126 quad_perm:[1,0,3,2] row_mask:0xf bank_mask:0xf
	v_mov_b32_dpp v53, v127 quad_perm:[1,0,3,2] row_mask:0xf bank_mask:0xf
	s_mov_b64 exec, s[62:63]
	v_mov_b32_e32 v120, v52
	v_mov_b32_e32 v121, v53
	s_mov_b64 exec, s[66:67]
	v_mov_b32_e32 v126, v48
	v_mov_b32_e32 v127, v49
	s_mov_b64 exec, -1
	v_lshlrev_b32_e32 v44, 8, v120
	v_perm_b32 v45, v116, v120, s8
	v_lshrrev_b32_e32 v46, 8, v120
	v_lshrrev_b32_e32 v47, 16, v120
	v_perm_b32 v44, v116, v44, s33
	v_perm_b32 v46, v117, v46, s33
	v_perm_b32 v47, v117, v47, s8
	v_pk_fma_f32 v[94:95], v[94:95], v[174:175], v[44:45]
	v_pk_fma_f32 v[96:97], v[96:97], v[176:177], v[46:47]
	v_lshlrev_b32_e32 v44, 8, v121
	v_perm_b32 v45, v118, v121, s8
	v_lshrrev_b32_e32 v46, 8, v121
	v_lshrrev_b32_e32 v47, 16, v121
	v_perm_b32 v44, v118, v44, s33
	v_perm_b32 v46, v119, v46, s33
	v_perm_b32 v47, v119, v47, s8
	v_pk_fma_f32 v[90:91], v[90:91], v[178:179], v[44:45]
	v_pk_fma_f32 v[92:93], v[92:93], v[180:181], v[46:47]
	v_lshlrev_b32_e32 v44, 8, v126
	v_perm_b32 v45, v122, v126, s8
	v_lshrrev_b32_e32 v46, 8, v126
	v_lshrrev_b32_e32 v47, 16, v126
	v_perm_b32 v44, v122, v44, s33
	v_perm_b32 v46, v123, v46, s33
	v_perm_b32 v47, v123, v47, s8
	v_pk_fma_f32 v[86:87], v[86:87], v[182:183], v[44:45]
	v_pk_fma_f32 v[88:89], v[88:89], v[184:185], v[46:47]
	v_lshlrev_b32_e32 v44, 8, v127
	v_perm_b32 v45, v124, v127, s8
	v_lshrrev_b32_e32 v46, 8, v127
	v_lshrrev_b32_e32 v47, 16, v127
	v_perm_b32 v44, v124, v44, s33
	v_perm_b32 v46, v125, v46, s33
	v_perm_b32 v47, v125, v47, s8
	v_pk_fma_f32 v[82:83], v[82:83], v[186:187], v[44:45]
	v_pk_fma_f32 v[84:85], v[84:85], v[188:189], v[46:47]
	v_mul_f32_e32 v44, v95, v95
	v_mul_f32_e32 v45, v97, v97
	v_mul_f32_e32 v46, v91, v91
	v_mul_f32_e32 v47, v93, v93
	v_fmac_f32_e32 v44, v94, v94
	v_fmac_f32_e32 v45, v96, v96
	v_fmac_f32_e32 v46, v90, v90
	v_fmac_f32_e32 v47, v92, v92
	v_add_f32_e32 v44, v44, v45
	v_add_f32_e32 v46, v46, v47
	v_add_f32_e32 v173, v44, v46
	v_add_u32_e32 v44, 0x80, v94
	v_add_u32_e32 v45, 0x80, v95
	v_add_u32_e32 v46, 0x80, v96
	v_add_u32_e32 v47, 0x80, v97
	v_perm_b32 v48, v45, v44, s78
	v_perm_b32 v49, v47, v46, s78
	v_perm_b32 v42, v45, v44, s79
	v_perm_b32 v43, v47, v46, s79
	v_perm_b32 v56, v43, v42, s60
	v_add_u32_e32 v44, 0x80, v90
	v_add_u32_e32 v45, 0x80, v91
	v_add_u32_e32 v46, 0x80, v92
	v_add_u32_e32 v47, 0x80, v93
	v_perm_b32 v50, v45, v44, s78
	v_perm_b32 v51, v47, v46, s78
	v_perm_b32 v42, v45, v44, s79
	v_perm_b32 v43, v47, v46, s79
	v_perm_b32 v57, v43, v42, s60
	v_mul_f32_e32 v44, v87, v87
	v_mul_f32_e32 v45, v89, v89
	v_mul_f32_e32 v46, v83, v83
	v_mul_f32_e32 v47, v85, v85
	v_fmac_f32_e32 v44, v86, v86
	v_fmac_f32_e32 v45, v88, v88
	v_fmac_f32_e32 v46, v82, v82
	v_fmac_f32_e32 v47, v84, v84
	v_add_f32_e32 v44, v44, v45
	v_add_f32_e32 v46, v46, v47
	v_add_f32_e32 v44, v44, v46
	v_add_f32_e32 v173, v173, v44
	v_add_u32_e32 v44, 0x80, v86
	v_add_u32_e32 v45, 0x80, v87
	v_add_u32_e32 v46, 0x80, v88
	v_add_u32_e32 v47, 0x80, v89
	v_perm_b32 v52, v45, v44, s78
	v_perm_b32 v53, v47, v46, s78
	v_perm_b32 v42, v45, v44, s79
	v_perm_b32 v43, v47, v46, s79
	v_perm_b32 v168, v43, v42, s60
	v_add_u32_e32 v44, 0x80, v82
	v_add_u32_e32 v45, 0x80, v83
	v_add_u32_e32 v46, 0x80, v84
	v_add_u32_e32 v47, 0x80, v85
	v_perm_b32 v54, v45, v44, s78
	v_perm_b32 v55, v47, v46, s78
	v_perm_b32 v42, v45, v44, s79
	v_perm_b32 v43, v47, v46, s79
	v_perm_b32 v169, v43, v42, s60
	v_mov_b32_dpp v116, v48 quad_perm:[1,0,3,2] row_mask:0xf bank_mask:0xf
	v_mov_b32_dpp v117, v49 quad_perm:[1,0,3,2] row_mask:0xf bank_mask:0xf
	v_mov_b32_dpp v118, v50 quad_perm:[1,0,3,2] row_mask:0xf bank_mask:0xf
	v_mov_b32_dpp v119, v51 quad_perm:[1,0,3,2] row_mask:0xf bank_mask:0xf
	v_mov_b32_dpp v122, v52 quad_perm:[1,0,3,2] row_mask:0xf bank_mask:0xf
	v_mov_b32_dpp v123, v53 quad_perm:[1,0,3,2] row_mask:0xf bank_mask:0xf
	v_mov_b32_dpp v124, v54 quad_perm:[1,0,3,2] row_mask:0xf bank_mask:0xf
	v_mov_b32_dpp v125, v55 quad_perm:[1,0,3,2] row_mask:0xf bank_mask:0xf
	s_mov_b64 exec, s[62:63]
	v_mov_b32_e32 v48, v122
	v_mov_b32_e32 v49, v123
	v_mov_b32_e32 v50, v124
	v_mov_b32_e32 v51, v125
	s_mov_b64 exec, s[66:67]
	v_mov_b32_e32 v52, v116
	v_mov_b32_e32 v53, v117
	v_mov_b32_e32 v54, v118
	v_mov_b32_e32 v55, v119
	s_mov_b64 exec, -1
	v_mov_b32_dpp v116, v56 quad_perm:[1,0,3,2] row_mask:0xf bank_mask:0xf
	v_mov_b32_dpp v117, v57 quad_perm:[1,0,3,2] row_mask:0xf bank_mask:0xf
	v_mov_b32_dpp v122, v168 quad_perm:[1,0,3,2] row_mask:0xf bank_mask:0xf
	v_mov_b32_dpp v123, v169 quad_perm:[1,0,3,2] row_mask:0xf bank_mask:0xf
	s_mov_b64 exec, s[62:63]
	v_mov_b32_e32 v56, v122
	v_mov_b32_e32 v57, v123
	s_mov_b64 exec, s[66:67]
	v_mov_b32_e32 v168, v116
	v_mov_b32_e32 v169, v117
	s_mov_b64 exec, -1
	s_add_u32 s88, s58, 0x18000
	s_addc_u32 s89, s59, 0
	s_add_u32 s90, s74, 0xc000
	s_addc_u32 s91, s75, 0
	global_store_dwordx4 v171, v[48:51], s[88:89]
	global_store_dwordx4 v171, v[52:55], s[88:89] offset:2048
	global_store_dwordx2 v170, v[56:57], s[90:91]
	global_store_dwordx2 v170, v[168:169], s[90:91] offset:1024
	s_add_u32 s92, s96, 0x18000
	s_addc_u32 s93, s97, 0
	v_pk_mul_f32 v[94:95], v[190:191], v[94:95]
	v_pk_mul_f32 v[96:97], v[192:193], v[96:97]
	v_pk_mul_f32 v[90:91], v[210:211], v[90:91]
	v_pk_mul_f32 v[92:93], v[212:213], v[92:93]
	v_cvt_pk_bf16_f32 v48, v94, v95
	v_cvt_pk_bf16_f32 v49, v96, v97
	v_cvt_pk_bf16_f32 v50, v90, v91
	v_cvt_pk_bf16_f32 v51, v92, v93
	v_pk_mul_f32 v[86:87], v[214:215], v[86:87]
	v_pk_mul_f32 v[88:89], v[216:217], v[88:89]
	v_pk_mul_f32 v[82:83], v[218:219], v[82:83]
	v_pk_mul_f32 v[84:85], v[220:221], v[84:85]
	v_cvt_pk_bf16_f32 v52, v86, v87
	v_cvt_pk_bf16_f32 v53, v88, v89
	v_cvt_pk_bf16_f32 v54, v82, v83
	v_cvt_pk_bf16_f32 v55, v84, v85
	v_mov_b32_dpp v116, v48 quad_perm:[1,0,3,2] row_mask:0xf bank_mask:0xf
	v_mov_b32_dpp v117, v49 quad_perm:[1,0,3,2] row_mask:0xf bank_mask:0xf
	v_mov_b32_dpp v118, v50 quad_perm:[1,0,3,2] row_mask:0xf bank_mask:0xf
	v_mov_b32_dpp v119, v51 quad_perm:[1,0,3,2] row_mask:0xf bank_mask:0xf
	v_mov_b32_dpp v122, v52 quad_perm:[1,0,3,2] row_mask:0xf bank_mask:0xf
	v_mov_b32_dpp v123, v53 quad_perm:[1,0,3,2] row_mask:0xf bank_mask:0xf
	v_mov_b32_dpp v124, v54 quad_perm:[1,0,3,2] row_mask:0xf bank_mask:0xf
	v_mov_b32_dpp v125, v55 quad_perm:[1,0,3,2] row_mask:0xf bank_mask:0xf
	s_mov_b64 exec, s[62:63]
	v_mov_b32_e32 v48, v122
	v_mov_b32_e32 v49, v123
	v_mov_b32_e32 v50, v124
	v_mov_b32_e32 v51, v125
	s_mov_b64 exec, s[66:67]
	v_mov_b32_e32 v52, v116
	v_mov_b32_e32 v53, v117
	v_mov_b32_e32 v54, v118
	v_mov_b32_e32 v55, v119
	s_mov_b64 exec, -1
	global_store_dwordx4 v171, v[48:51], s[92:93]
	global_store_dwordx4 v171, v[52:55], s[92:93] offset:2048
	v_mov_b32_e32 v82, v173
	s_add_u32 s84, s58, 0x48000
	s_addc_u32 s85, s59, 0
	s_add_u32 s86, s74, 0x24000
	s_addc_u32 s87, s75, 0
	global_load_dwordx4 v[84:87], v171, s[84:85]
	global_load_dwordx2 v[88:89], v170, s[86:87]
	global_load_dwordx4 v[90:93], v171, s[84:85] offset:2048
	global_load_dwordx2 v[94:95], v170, s[86:87] offset:1024
	s_waitcnt vmcnt(10)
	v_mov_b32_dpp v48, v100 quad_perm:[1,0,3,2] row_mask:0xf bank_mask:0xf
	v_mov_b32_dpp v49, v101 quad_perm:[1,0,3,2] row_mask:0xf bank_mask:0xf
	v_mov_b32_dpp v50, v102 quad_perm:[1,0,3,2] row_mask:0xf bank_mask:0xf
	v_mov_b32_dpp v51, v103 quad_perm:[1,0,3,2] row_mask:0xf bank_mask:0xf
	v_mov_b32_dpp v52, v106 quad_perm:[1,0,3,2] row_mask:0xf bank_mask:0xf
	v_mov_b32_dpp v53, v107 quad_perm:[1,0,3,2] row_mask:0xf bank_mask:0xf
	v_mov_b32_dpp v54, v108 quad_perm:[1,0,3,2] row_mask:0xf bank_mask:0xf
	v_mov_b32_dpp v55, v109 quad_perm:[1,0,3,2] row_mask:0xf bank_mask:0xf
	s_mov_b64 exec, s[62:63]
	v_mov_b32_e32 v100, v52
	v_mov_b32_e32 v101, v53
	v_mov_b32_e32 v102, v54
	v_mov_b32_e32 v103, v55
	s_mov_b64 exec, s[66:67]
	v_mov_b32_e32 v106, v48
	v_mov_b32_e32 v107, v49
	v_mov_b32_e32 v108, v50
	v_mov_b32_e32 v109, v51
	s_mov_b64 exec, -1
	v_mov_b32_dpp v48, v104 quad_perm:[1,0,3,2] row_mask:0xf bank_mask:0xf
	v_mov_b32_dpp v49, v105 quad_perm:[1,0,3,2] row_mask:0xf bank_mask:0xf
	v_mov_b32_dpp v52, v110 quad_perm:[1,0,3,2] row_mask:0xf bank_mask:0xf
	v_mov_b32_dpp v53, v111 quad_perm:[1,0,3,2] row_mask:0xf bank_mask:0xf
	s_mov_b64 exec, s[62:63]
	v_mov_b32_e32 v104, v52
	v_mov_b32_e32 v105, v53
	s_mov_b64 exec, s[66:67]
	v_mov_b32_e32 v110, v48
	v_mov_b32_e32 v111, v49
	s_mov_b64 exec, -1
	v_lshlrev_b32_e32 v44, 8, v104
	v_perm_b32 v45, v100, v104, s8
	v_lshrrev_b32_e32 v46, 8, v104
	v_lshrrev_b32_e32 v47, 16, v104
	v_perm_b32 v44, v100, v44, s33
	v_perm_b32 v46, v101, v46, s33
	v_perm_b32 v47, v101, v47, s8
	v_pk_fma_f32 v[78:79], v[78:79], v[174:175], v[44:45]
	v_pk_fma_f32 v[80:81], v[80:81], v[176:177], v[46:47]
	v_lshlrev_b32_e32 v44, 8, v105
	v_perm_b32 v45, v102, v105, s8
	v_lshrrev_b32_e32 v46, 8, v105
	v_lshrrev_b32_e32 v47, 16, v105
	v_perm_b32 v44, v102, v44, s33
	v_perm_b32 v46, v103, v46, s33
	v_perm_b32 v47, v103, v47, s8
	v_pk_fma_f32 v[74:75], v[74:75], v[178:179], v[44:45]
	v_pk_fma_f32 v[76:77], v[76:77], v[180:181], v[46:47]
	v_lshlrev_b32_e32 v44, 8, v110
	v_perm_b32 v45, v106, v110, s8
	v_lshrrev_b32_e32 v46, 8, v110
	v_lshrrev_b32_e32 v47, 16, v110
	v_perm_b32 v44, v106, v44, s33
	v_perm_b32 v46, v107, v46, s33
	v_perm_b32 v47, v107, v47, s8
	v_pk_fma_f32 v[70:71], v[70:71], v[182:183], v[44:45]
	v_pk_fma_f32 v[72:73], v[72:73], v[184:185], v[46:47]
	v_lshlrev_b32_e32 v44, 8, v111
	v_perm_b32 v45, v108, v111, s8
	v_lshrrev_b32_e32 v46, 8, v111
	v_lshrrev_b32_e32 v47, 16, v111
	v_perm_b32 v44, v108, v44, s33
	v_perm_b32 v46, v109, v46, s33
	v_perm_b32 v47, v109, v47, s8
	v_pk_fma_f32 v[66:67], v[66:67], v[186:187], v[44:45]
	v_pk_fma_f32 v[68:69], v[68:69], v[188:189], v[46:47]
	v_mul_f32_e32 v44, v79, v79
	v_mul_f32_e32 v45, v81, v81
	v_mul_f32_e32 v46, v75, v75
	v_mul_f32_e32 v47, v77, v77
	v_fmac_f32_e32 v44, v78, v78
	v_fmac_f32_e32 v45, v80, v80
	v_fmac_f32_e32 v46, v74, v74
	v_fmac_f32_e32 v47, v76, v76
	v_add_f32_e32 v44, v44, v45
	v_add_f32_e32 v46, v46, v47
	v_add_f32_e32 v173, v44, v46
	v_add_u32_e32 v44, 0x80, v78
	v_add_u32_e32 v45, 0x80, v79
	v_add_u32_e32 v46, 0x80, v80
	v_add_u32_e32 v47, 0x80, v81
	v_perm_b32 v48, v45, v44, s78
	v_perm_b32 v49, v47, v46, s78
	v_perm_b32 v42, v45, v44, s79
	v_perm_b32 v43, v47, v46, s79
	v_perm_b32 v56, v43, v42, s60
	v_add_u32_e32 v44, 0x80, v74
	v_add_u32_e32 v45, 0x80, v75
	v_add_u32_e32 v46, 0x80, v76
	v_add_u32_e32 v47, 0x80, v77
	v_perm_b32 v50, v45, v44, s78
	v_perm_b32 v51, v47, v46, s78
	v_perm_b32 v42, v45, v44, s79
	v_perm_b32 v43, v47, v46, s79
	v_perm_b32 v57, v43, v42, s60
	v_mul_f32_e32 v44, v71, v71
	v_mul_f32_e32 v45, v73, v73
	v_mul_f32_e32 v46, v67, v67
	v_mul_f32_e32 v47, v69, v69
	v_fmac_f32_e32 v44, v70, v70
	v_fmac_f32_e32 v45, v72, v72
	v_fmac_f32_e32 v46, v66, v66
	v_fmac_f32_e32 v47, v68, v68
	v_add_f32_e32 v44, v44, v45
	v_add_f32_e32 v46, v46, v47
	v_add_f32_e32 v44, v44, v46
	v_add_f32_e32 v173, v173, v44
	v_add_u32_e32 v44, 0x80, v70
	v_add_u32_e32 v45, 0x80, v71
	v_add_u32_e32 v46, 0x80, v72
	v_add_u32_e32 v47, 0x80, v73
	v_perm_b32 v52, v45, v44, s78
	v_perm_b32 v53, v47, v46, s78
	v_perm_b32 v42, v45, v44, s79
	v_perm_b32 v43, v47, v46, s79
	v_perm_b32 v168, v43, v42, s60
	v_add_u32_e32 v44, 0x80, v66
	v_add_u32_e32 v45, 0x80, v67
	v_add_u32_e32 v46, 0x80, v68
	v_add_u32_e32 v47, 0x80, v69
	v_perm_b32 v54, v45, v44, s78
	v_perm_b32 v55, v47, v46, s78
	v_perm_b32 v42, v45, v44, s79
	v_perm_b32 v43, v47, v46, s79
	v_perm_b32 v169, v43, v42, s60
	v_mov_b32_dpp v100, v48 quad_perm:[1,0,3,2] row_mask:0xf bank_mask:0xf
	v_mov_b32_dpp v101, v49 quad_perm:[1,0,3,2] row_mask:0xf bank_mask:0xf
	v_mov_b32_dpp v102, v50 quad_perm:[1,0,3,2] row_mask:0xf bank_mask:0xf
	v_mov_b32_dpp v103, v51 quad_perm:[1,0,3,2] row_mask:0xf bank_mask:0xf
	v_mov_b32_dpp v106, v52 quad_perm:[1,0,3,2] row_mask:0xf bank_mask:0xf
	v_mov_b32_dpp v107, v53 quad_perm:[1,0,3,2] row_mask:0xf bank_mask:0xf
	v_mov_b32_dpp v108, v54 quad_perm:[1,0,3,2] row_mask:0xf bank_mask:0xf
	v_mov_b32_dpp v109, v55 quad_perm:[1,0,3,2] row_mask:0xf bank_mask:0xf
	s_mov_b64 exec, s[62:63]
	v_mov_b32_e32 v48, v106
	v_mov_b32_e32 v49, v107
	v_mov_b32_e32 v50, v108
	v_mov_b32_e32 v51, v109
	s_mov_b64 exec, s[66:67]
	v_mov_b32_e32 v52, v100
	v_mov_b32_e32 v53, v101
	v_mov_b32_e32 v54, v102
	v_mov_b32_e32 v55, v103
	s_mov_b64 exec, -1
	v_mov_b32_dpp v100, v56 quad_perm:[1,0,3,2] row_mask:0xf bank_mask:0xf
	v_mov_b32_dpp v101, v57 quad_perm:[1,0,3,2] row_mask:0xf bank_mask:0xf
	v_mov_b32_dpp v106, v168 quad_perm:[1,0,3,2] row_mask:0xf bank_mask:0xf
	v_mov_b32_dpp v107, v169 quad_perm:[1,0,3,2] row_mask:0xf bank_mask:0xf
	s_mov_b64 exec, s[62:63]
	v_mov_b32_e32 v56, v106
	v_mov_b32_e32 v57, v107
	s_mov_b64 exec, s[66:67]
	v_mov_b32_e32 v168, v100
	v_mov_b32_e32 v169, v101
	s_mov_b64 exec, -1
	s_add_u32 s88, s58, 0x40000
	s_addc_u32 s89, s59, 0
	s_add_u32 s90, s74, 0x20000
	s_addc_u32 s91, s75, 0
	global_store_dwordx4 v171, v[48:51], s[88:89]
	global_store_dwordx4 v171, v[52:55], s[88:89] offset:2048
	global_store_dwordx2 v170, v[56:57], s[90:91]
	global_store_dwordx2 v170, v[168:169], s[90:91] offset:1024
	s_add_u32 s92, s96, 0x40000
	s_addc_u32 s93, s97, 0
	v_pk_mul_f32 v[78:79], v[190:191], v[78:79]
	v_pk_mul_f32 v[80:81], v[192:193], v[80:81]
	v_pk_mul_f32 v[74:75], v[210:211], v[74:75]
	v_pk_mul_f32 v[76:77], v[212:213], v[76:77]
	v_cvt_pk_bf16_f32 v48, v78, v79
	v_cvt_pk_bf16_f32 v49, v80, v81
	v_cvt_pk_bf16_f32 v50, v74, v75
	v_cvt_pk_bf16_f32 v51, v76, v77
	v_pk_mul_f32 v[70:71], v[214:215], v[70:71]
	v_pk_mul_f32 v[72:73], v[216:217], v[72:73]
	v_pk_mul_f32 v[66:67], v[218:219], v[66:67]
	v_pk_mul_f32 v[68:69], v[220:221], v[68:69]
	v_cvt_pk_bf16_f32 v52, v70, v71
	v_cvt_pk_bf16_f32 v53, v72, v73
	v_cvt_pk_bf16_f32 v54, v66, v67
	v_cvt_pk_bf16_f32 v55, v68, v69
	v_mov_b32_dpp v100, v48 quad_perm:[1,0,3,2] row_mask:0xf bank_mask:0xf
	v_mov_b32_dpp v101, v49 quad_perm:[1,0,3,2] row_mask:0xf bank_mask:0xf
	v_mov_b32_dpp v102, v50 quad_perm:[1,0,3,2] row_mask:0xf bank_mask:0xf
	v_mov_b32_dpp v103, v51 quad_perm:[1,0,3,2] row_mask:0xf bank_mask:0xf
	v_mov_b32_dpp v106, v52 quad_perm:[1,0,3,2] row_mask:0xf bank_mask:0xf
	v_mov_b32_dpp v107, v53 quad_perm:[1,0,3,2] row_mask:0xf bank_mask:0xf
	v_mov_b32_dpp v108, v54 quad_perm:[1,0,3,2] row_mask:0xf bank_mask:0xf
	v_mov_b32_dpp v109, v55 quad_perm:[1,0,3,2] row_mask:0xf bank_mask:0xf
	s_mov_b64 exec, s[62:63]
	v_mov_b32_e32 v48, v106
	v_mov_b32_e32 v49, v107
	v_mov_b32_e32 v50, v108
	v_mov_b32_e32 v51, v109
	s_mov_b64 exec, s[66:67]
	v_mov_b32_e32 v52, v100
	v_mov_b32_e32 v53, v101
	v_mov_b32_e32 v54, v102
	v_mov_b32_e32 v55, v103
	s_mov_b64 exec, -1
	global_store_dwordx4 v171, v[48:51], s[92:93]
	global_store_dwordx4 v171, v[52:55], s[92:93] offset:2048
	v_mov_b32_e32 v66, v173
	s_add_u32 s84, s58, 0x50000
	s_addc_u32 s85, s59, 0
	s_add_u32 s86, s74, 0x28000
	s_addc_u32 s87, s75, 0
	global_load_dwordx4 v[68:71], v171, s[84:85]
	global_load_dwordx2 v[72:73], v170, s[86:87]
	global_load_dwordx4 v[74:77], v171, s[84:85] offset:2048
	global_load_dwordx2 v[78:79], v170, s[86:87] offset:1024
	s_waitcnt vmcnt(10)
	v_mov_b32_dpp v48, v84 quad_perm:[1,0,3,2] row_mask:0xf bank_mask:0xf
	v_mov_b32_dpp v49, v85 quad_perm:[1,0,3,2] row_mask:0xf bank_mask:0xf
	v_mov_b32_dpp v50, v86 quad_perm:[1,0,3,2] row_mask:0xf bank_mask:0xf
	v_mov_b32_dpp v51, v87 quad_perm:[1,0,3,2] row_mask:0xf bank_mask:0xf
	v_mov_b32_dpp v52, v90 quad_perm:[1,0,3,2] row_mask:0xf bank_mask:0xf
	v_mov_b32_dpp v53, v91 quad_perm:[1,0,3,2] row_mask:0xf bank_mask:0xf
	v_mov_b32_dpp v54, v92 quad_perm:[1,0,3,2] row_mask:0xf bank_mask:0xf
	v_mov_b32_dpp v55, v93 quad_perm:[1,0,3,2] row_mask:0xf bank_mask:0xf
	s_mov_b64 exec, s[62:63]
	v_mov_b32_e32 v84, v52
	v_mov_b32_e32 v85, v53
	v_mov_b32_e32 v86, v54
	v_mov_b32_e32 v87, v55
	s_mov_b64 exec, s[66:67]
	v_mov_b32_e32 v90, v48
	v_mov_b32_e32 v91, v49
	v_mov_b32_e32 v92, v50
	v_mov_b32_e32 v93, v51
	s_mov_b64 exec, -1
	v_mov_b32_dpp v48, v88 quad_perm:[1,0,3,2] row_mask:0xf bank_mask:0xf
	v_mov_b32_dpp v49, v89 quad_perm:[1,0,3,2] row_mask:0xf bank_mask:0xf
	v_mov_b32_dpp v52, v94 quad_perm:[1,0,3,2] row_mask:0xf bank_mask:0xf
	v_mov_b32_dpp v53, v95 quad_perm:[1,0,3,2] row_mask:0xf bank_mask:0xf
	s_mov_b64 exec, s[62:63]
	v_mov_b32_e32 v88, v52
	v_mov_b32_e32 v89, v53
	s_mov_b64 exec, s[66:67]
	v_mov_b32_e32 v94, v48
	v_mov_b32_e32 v95, v49
	s_mov_b64 exec, -1
	v_lshlrev_b32_e32 v44, 8, v88
	v_perm_b32 v45, v84, v88, s8
	v_lshrrev_b32_e32 v46, 8, v88
	v_lshrrev_b32_e32 v47, 16, v88
	v_perm_b32 v44, v84, v44, s33
	v_perm_b32 v46, v85, v46, s33
	v_perm_b32 v47, v85, v47, s8
	v_pk_fma_f32 v[62:63], v[62:63], v[174:175], v[44:45]
	v_pk_fma_f32 v[64:65], v[64:65], v[176:177], v[46:47]
	v_lshlrev_b32_e32 v44, 8, v89
	v_perm_b32 v45, v86, v89, s8
	v_lshrrev_b32_e32 v46, 8, v89
	v_lshrrev_b32_e32 v47, 16, v89
	v_perm_b32 v44, v86, v44, s33
	v_perm_b32 v46, v87, v46, s33
	v_perm_b32 v47, v87, v47, s8
	v_pk_fma_f32 v[58:59], v[58:59], v[178:179], v[44:45]
	v_pk_fma_f32 v[60:61], v[60:61], v[180:181], v[46:47]
	v_lshlrev_b32_e32 v44, 8, v94
	v_perm_b32 v45, v90, v94, s8
	v_lshrrev_b32_e32 v46, 8, v94
	v_lshrrev_b32_e32 v47, 16, v94
	v_perm_b32 v44, v90, v44, s33
	v_perm_b32 v46, v91, v46, s33
	v_perm_b32 v47, v91, v47, s8
	v_pk_fma_f32 v[38:39], v[38:39], v[182:183], v[44:45]
	v_pk_fma_f32 v[40:41], v[40:41], v[184:185], v[46:47]
	v_lshlrev_b32_e32 v44, 8, v95
	v_perm_b32 v45, v92, v95, s8
	v_lshrrev_b32_e32 v46, 8, v95
	v_lshrrev_b32_e32 v47, 16, v95
	v_perm_b32 v44, v92, v44, s33
	v_perm_b32 v46, v93, v46, s33
	v_perm_b32 v47, v93, v47, s8
	v_pk_fma_f32 v[34:35], v[34:35], v[186:187], v[44:45]
	v_pk_fma_f32 v[36:37], v[36:37], v[188:189], v[46:47]
	v_mul_f32_e32 v44, v63, v63
	v_mul_f32_e32 v45, v65, v65
	v_mul_f32_e32 v46, v59, v59
	v_mul_f32_e32 v47, v61, v61
	v_fmac_f32_e32 v44, v62, v62
	v_fmac_f32_e32 v45, v64, v64
	v_fmac_f32_e32 v46, v58, v58
	v_fmac_f32_e32 v47, v60, v60
	v_add_f32_e32 v44, v44, v45
	v_add_f32_e32 v46, v46, v47
	v_add_f32_e32 v173, v44, v46
	v_add_u32_e32 v44, 0x80, v62
	v_add_u32_e32 v45, 0x80, v63
	v_add_u32_e32 v46, 0x80, v64
	v_add_u32_e32 v47, 0x80, v65
	v_perm_b32 v48, v45, v44, s78
	v_perm_b32 v49, v47, v46, s78
	v_perm_b32 v42, v45, v44, s79
	v_perm_b32 v43, v47, v46, s79
	v_perm_b32 v56, v43, v42, s60
	v_add_u32_e32 v44, 0x80, v58
	v_add_u32_e32 v45, 0x80, v59
	v_add_u32_e32 v46, 0x80, v60
	v_add_u32_e32 v47, 0x80, v61
	v_perm_b32 v50, v45, v44, s78
	v_perm_b32 v51, v47, v46, s78
	v_perm_b32 v42, v45, v44, s79
	v_perm_b32 v43, v47, v46, s79
	v_perm_b32 v57, v43, v42, s60
	v_mul_f32_e32 v44, v39, v39
	v_mul_f32_e32 v45, v41, v41
	v_mul_f32_e32 v46, v35, v35
	v_mul_f32_e32 v47, v37, v37
	v_fmac_f32_e32 v44, v38, v38
	v_fmac_f32_e32 v45, v40, v40
	v_fmac_f32_e32 v46, v34, v34
	v_fmac_f32_e32 v47, v36, v36
	v_add_f32_e32 v44, v44, v45
	v_add_f32_e32 v46, v46, v47
	v_add_f32_e32 v44, v44, v46
	v_add_f32_e32 v173, v173, v44
	v_add_u32_e32 v44, 0x80, v38
	v_add_u32_e32 v45, 0x80, v39
	v_add_u32_e32 v46, 0x80, v40
	v_add_u32_e32 v47, 0x80, v41
	v_perm_b32 v52, v45, v44, s78
	v_perm_b32 v53, v47, v46, s78
	v_perm_b32 v42, v45, v44, s79
	v_perm_b32 v43, v47, v46, s79
	v_perm_b32 v168, v43, v42, s60
	v_add_u32_e32 v44, 0x80, v34
	v_add_u32_e32 v45, 0x80, v35
	v_add_u32_e32 v46, 0x80, v36
	v_add_u32_e32 v47, 0x80, v37
	v_perm_b32 v54, v45, v44, s78
	v_perm_b32 v55, v47, v46, s78
	v_perm_b32 v42, v45, v44, s79
	v_perm_b32 v43, v47, v46, s79
	v_perm_b32 v169, v43, v42, s60
	v_mov_b32_dpp v84, v48 quad_perm:[1,0,3,2] row_mask:0xf bank_mask:0xf
	v_mov_b32_dpp v85, v49 quad_perm:[1,0,3,2] row_mask:0xf bank_mask:0xf
	v_mov_b32_dpp v86, v50 quad_perm:[1,0,3,2] row_mask:0xf bank_mask:0xf
	v_mov_b32_dpp v87, v51 quad_perm:[1,0,3,2] row_mask:0xf bank_mask:0xf
	v_mov_b32_dpp v90, v52 quad_perm:[1,0,3,2] row_mask:0xf bank_mask:0xf
	v_mov_b32_dpp v91, v53 quad_perm:[1,0,3,2] row_mask:0xf bank_mask:0xf
	v_mov_b32_dpp v92, v54 quad_perm:[1,0,3,2] row_mask:0xf bank_mask:0xf
	v_mov_b32_dpp v93, v55 quad_perm:[1,0,3,2] row_mask:0xf bank_mask:0xf
	s_mov_b64 exec, s[62:63]
	v_mov_b32_e32 v48, v90
	v_mov_b32_e32 v49, v91
	v_mov_b32_e32 v50, v92
	v_mov_b32_e32 v51, v93
	s_mov_b64 exec, s[66:67]
	v_mov_b32_e32 v52, v84
	v_mov_b32_e32 v53, v85
	v_mov_b32_e32 v54, v86
	v_mov_b32_e32 v55, v87
	s_mov_b64 exec, -1
	v_mov_b32_dpp v84, v56 quad_perm:[1,0,3,2] row_mask:0xf bank_mask:0xf
	v_mov_b32_dpp v85, v57 quad_perm:[1,0,3,2] row_mask:0xf bank_mask:0xf
	v_mov_b32_dpp v90, v168 quad_perm:[1,0,3,2] row_mask:0xf bank_mask:0xf
	v_mov_b32_dpp v91, v169 quad_perm:[1,0,3,2] row_mask:0xf bank_mask:0xf
	s_mov_b64 exec, s[62:63]
	v_mov_b32_e32 v56, v90
	v_mov_b32_e32 v57, v91
	s_mov_b64 exec, s[66:67]
	v_mov_b32_e32 v168, v84
	v_mov_b32_e32 v169, v85
	s_mov_b64 exec, -1
	s_add_u32 s88, s58, 0x48000
	s_addc_u32 s89, s59, 0
	s_add_u32 s90, s74, 0x24000
	s_addc_u32 s91, s75, 0
	global_store_dwordx4 v171, v[48:51], s[88:89]
	global_store_dwordx4 v171, v[52:55], s[88:89] offset:2048
	global_store_dwordx2 v170, v[56:57], s[90:91]
	global_store_dwordx2 v170, v[168:169], s[90:91] offset:1024
	s_add_u32 s92, s96, 0x48000
	s_addc_u32 s93, s97, 0
	v_pk_mul_f32 v[62:63], v[190:191], v[62:63]
	v_pk_mul_f32 v[64:65], v[192:193], v[64:65]
	v_pk_mul_f32 v[58:59], v[210:211], v[58:59]
	v_pk_mul_f32 v[60:61], v[212:213], v[60:61]
	v_cvt_pk_bf16_f32 v48, v62, v63
	v_cvt_pk_bf16_f32 v49, v64, v65
	v_cvt_pk_bf16_f32 v50, v58, v59
	v_cvt_pk_bf16_f32 v51, v60, v61
	v_pk_mul_f32 v[38:39], v[214:215], v[38:39]
	v_pk_mul_f32 v[40:41], v[216:217], v[40:41]
	v_pk_mul_f32 v[34:35], v[218:219], v[34:35]
	v_pk_mul_f32 v[36:37], v[220:221], v[36:37]
	v_cvt_pk_bf16_f32 v52, v38, v39
	v_cvt_pk_bf16_f32 v53, v40, v41
	v_cvt_pk_bf16_f32 v54, v34, v35
	v_cvt_pk_bf16_f32 v55, v36, v37
	v_mov_b32_dpp v84, v48 quad_perm:[1,0,3,2] row_mask:0xf bank_mask:0xf
	v_mov_b32_dpp v85, v49 quad_perm:[1,0,3,2] row_mask:0xf bank_mask:0xf
	v_mov_b32_dpp v86, v50 quad_perm:[1,0,3,2] row_mask:0xf bank_mask:0xf
	v_mov_b32_dpp v87, v51 quad_perm:[1,0,3,2] row_mask:0xf bank_mask:0xf
	v_mov_b32_dpp v90, v52 quad_perm:[1,0,3,2] row_mask:0xf bank_mask:0xf
	v_mov_b32_dpp v91, v53 quad_perm:[1,0,3,2] row_mask:0xf bank_mask:0xf
	v_mov_b32_dpp v92, v54 quad_perm:[1,0,3,2] row_mask:0xf bank_mask:0xf
	v_mov_b32_dpp v93, v55 quad_perm:[1,0,3,2] row_mask:0xf bank_mask:0xf
	s_mov_b64 exec, s[62:63]
	v_mov_b32_e32 v48, v90
	v_mov_b32_e32 v49, v91
	v_mov_b32_e32 v50, v92
	v_mov_b32_e32 v51, v93
	s_mov_b64 exec, s[66:67]
	v_mov_b32_e32 v52, v84
	v_mov_b32_e32 v53, v85
	v_mov_b32_e32 v54, v86
	v_mov_b32_e32 v55, v87
	s_mov_b64 exec, -1
	global_store_dwordx4 v171, v[48:51], s[92:93]
	global_store_dwordx4 v171, v[52:55], s[92:93] offset:2048
	v_mov_b32_e32 v34, v173
	s_add_u32 s84, s58, 0x58000
	s_addc_u32 s85, s59, 0
	s_add_u32 s86, s74, 0x2c000
	s_addc_u32 s87, s75, 0
	global_load_dwordx4 v[36:39], v171, s[84:85]
	global_load_dwordx2 v[40:41], v170, s[86:87]
	global_load_dwordx4 v[58:61], v171, s[84:85] offset:2048
	global_load_dwordx2 v[62:63], v170, s[86:87] offset:1024
	s_waitcnt vmcnt(10)
	v_mov_b32_dpp v48, v68 quad_perm:[1,0,3,2] row_mask:0xf bank_mask:0xf
	v_mov_b32_dpp v49, v69 quad_perm:[1,0,3,2] row_mask:0xf bank_mask:0xf
	v_mov_b32_dpp v50, v70 quad_perm:[1,0,3,2] row_mask:0xf bank_mask:0xf
	v_mov_b32_dpp v51, v71 quad_perm:[1,0,3,2] row_mask:0xf bank_mask:0xf
	v_mov_b32_dpp v52, v74 quad_perm:[1,0,3,2] row_mask:0xf bank_mask:0xf
	v_mov_b32_dpp v53, v75 quad_perm:[1,0,3,2] row_mask:0xf bank_mask:0xf
	v_mov_b32_dpp v54, v76 quad_perm:[1,0,3,2] row_mask:0xf bank_mask:0xf
	v_mov_b32_dpp v55, v77 quad_perm:[1,0,3,2] row_mask:0xf bank_mask:0xf
	s_mov_b64 exec, s[62:63]
	v_mov_b32_e32 v68, v52
	v_mov_b32_e32 v69, v53
	v_mov_b32_e32 v70, v54
	v_mov_b32_e32 v71, v55
	s_mov_b64 exec, s[66:67]
	v_mov_b32_e32 v74, v48
	v_mov_b32_e32 v75, v49
	v_mov_b32_e32 v76, v50
	v_mov_b32_e32 v77, v51
	s_mov_b64 exec, -1
	v_mov_b32_dpp v48, v72 quad_perm:[1,0,3,2] row_mask:0xf bank_mask:0xf
	v_mov_b32_dpp v49, v73 quad_perm:[1,0,3,2] row_mask:0xf bank_mask:0xf
	v_mov_b32_dpp v52, v78 quad_perm:[1,0,3,2] row_mask:0xf bank_mask:0xf
	v_mov_b32_dpp v53, v79 quad_perm:[1,0,3,2] row_mask:0xf bank_mask:0xf
	s_mov_b64 exec, s[62:63]
	v_mov_b32_e32 v72, v52
	v_mov_b32_e32 v73, v53
	s_mov_b64 exec, s[66:67]
	v_mov_b32_e32 v78, v48
	v_mov_b32_e32 v79, v49
	s_mov_b64 exec, -1
	v_lshlrev_b32_e32 v44, 8, v72
	v_perm_b32 v45, v68, v72, s8
	v_lshrrev_b32_e32 v46, 8, v72
	v_lshrrev_b32_e32 v47, 16, v72
	v_perm_b32 v44, v68, v44, s33
	v_perm_b32 v46, v69, v46, s33
	v_perm_b32 v47, v69, v47, s8
	v_pk_fma_f32 v[30:31], v[30:31], v[174:175], v[44:45]
	v_pk_fma_f32 v[32:33], v[32:33], v[176:177], v[46:47]
	v_lshlrev_b32_e32 v44, 8, v73
	v_perm_b32 v45, v70, v73, s8
	v_lshrrev_b32_e32 v46, 8, v73
	v_lshrrev_b32_e32 v47, 16, v73
	v_perm_b32 v44, v70, v44, s33
	v_perm_b32 v46, v71, v46, s33
	v_perm_b32 v47, v71, v47, s8
	v_pk_fma_f32 v[26:27], v[26:27], v[178:179], v[44:45]
	v_pk_fma_f32 v[28:29], v[28:29], v[180:181], v[46:47]
	v_lshlrev_b32_e32 v44, 8, v78
	v_perm_b32 v45, v74, v78, s8
	v_lshrrev_b32_e32 v46, 8, v78
	v_lshrrev_b32_e32 v47, 16, v78
	v_perm_b32 v44, v74, v44, s33
	v_perm_b32 v46, v75, v46, s33
	v_perm_b32 v47, v75, v47, s8
	v_pk_fma_f32 v[22:23], v[22:23], v[182:183], v[44:45]
	v_pk_fma_f32 v[24:25], v[24:25], v[184:185], v[46:47]
	v_lshlrev_b32_e32 v44, 8, v79
	v_perm_b32 v45, v76, v79, s8
	v_lshrrev_b32_e32 v46, 8, v79
	v_lshrrev_b32_e32 v47, 16, v79
	v_perm_b32 v44, v76, v44, s33
	v_perm_b32 v46, v77, v46, s33
	v_perm_b32 v47, v77, v47, s8
	v_pk_fma_f32 v[18:19], v[18:19], v[186:187], v[44:45]
	v_pk_fma_f32 v[20:21], v[20:21], v[188:189], v[46:47]
	v_mul_f32_e32 v44, v31, v31
	v_mul_f32_e32 v45, v33, v33
	v_mul_f32_e32 v46, v27, v27
	v_mul_f32_e32 v47, v29, v29
	v_fmac_f32_e32 v44, v30, v30
	v_fmac_f32_e32 v45, v32, v32
	v_fmac_f32_e32 v46, v26, v26
	v_fmac_f32_e32 v47, v28, v28
	v_add_f32_e32 v44, v44, v45
	v_add_f32_e32 v46, v46, v47
	v_add_f32_e32 v173, v44, v46
	v_add_u32_e32 v44, 0x80, v30
	v_add_u32_e32 v45, 0x80, v31
	v_add_u32_e32 v46, 0x80, v32
	v_add_u32_e32 v47, 0x80, v33
	v_perm_b32 v48, v45, v44, s78
	v_perm_b32 v49, v47, v46, s78
	v_perm_b32 v42, v45, v44, s79
	v_perm_b32 v43, v47, v46, s79
	v_perm_b32 v56, v43, v42, s60
	v_add_u32_e32 v44, 0x80, v26
	v_add_u32_e32 v45, 0x80, v27
	v_add_u32_e32 v46, 0x80, v28
	v_add_u32_e32 v47, 0x80, v29
	v_perm_b32 v50, v45, v44, s78
	v_perm_b32 v51, v47, v46, s78
	v_perm_b32 v42, v45, v44, s79
	v_perm_b32 v43, v47, v46, s79
	v_perm_b32 v57, v43, v42, s60
	v_mul_f32_e32 v44, v23, v23
	v_mul_f32_e32 v45, v25, v25
	v_mul_f32_e32 v46, v19, v19
	v_mul_f32_e32 v47, v21, v21
	v_fmac_f32_e32 v44, v22, v22
	v_fmac_f32_e32 v45, v24, v24
	v_fmac_f32_e32 v46, v18, v18
	v_fmac_f32_e32 v47, v20, v20
	v_add_f32_e32 v44, v44, v45
	v_add_f32_e32 v46, v46, v47
	v_add_f32_e32 v44, v44, v46
	v_add_f32_e32 v173, v173, v44
	v_add_u32_e32 v44, 0x80, v22
	v_add_u32_e32 v45, 0x80, v23
	v_add_u32_e32 v46, 0x80, v24
	v_add_u32_e32 v47, 0x80, v25
	v_perm_b32 v52, v45, v44, s78
	v_perm_b32 v53, v47, v46, s78
	v_perm_b32 v42, v45, v44, s79
	v_perm_b32 v43, v47, v46, s79
	v_perm_b32 v168, v43, v42, s60
	v_add_u32_e32 v44, 0x80, v18
	v_add_u32_e32 v45, 0x80, v19
	v_add_u32_e32 v46, 0x80, v20
	v_add_u32_e32 v47, 0x80, v21
	v_perm_b32 v54, v45, v44, s78
	v_perm_b32 v55, v47, v46, s78
	v_perm_b32 v42, v45, v44, s79
	v_perm_b32 v43, v47, v46, s79
	v_perm_b32 v169, v43, v42, s60
	v_mov_b32_dpp v68, v48 quad_perm:[1,0,3,2] row_mask:0xf bank_mask:0xf
	v_mov_b32_dpp v69, v49 quad_perm:[1,0,3,2] row_mask:0xf bank_mask:0xf
	v_mov_b32_dpp v70, v50 quad_perm:[1,0,3,2] row_mask:0xf bank_mask:0xf
	v_mov_b32_dpp v71, v51 quad_perm:[1,0,3,2] row_mask:0xf bank_mask:0xf
	v_mov_b32_dpp v74, v52 quad_perm:[1,0,3,2] row_mask:0xf bank_mask:0xf
	v_mov_b32_dpp v75, v53 quad_perm:[1,0,3,2] row_mask:0xf bank_mask:0xf
	v_mov_b32_dpp v76, v54 quad_perm:[1,0,3,2] row_mask:0xf bank_mask:0xf
	v_mov_b32_dpp v77, v55 quad_perm:[1,0,3,2] row_mask:0xf bank_mask:0xf
	s_mov_b64 exec, s[62:63]
	v_mov_b32_e32 v48, v74
	v_mov_b32_e32 v49, v75
	v_mov_b32_e32 v50, v76
	v_mov_b32_e32 v51, v77
	s_mov_b64 exec, s[66:67]
	v_mov_b32_e32 v52, v68
	v_mov_b32_e32 v53, v69
	v_mov_b32_e32 v54, v70
	v_mov_b32_e32 v55, v71
	s_mov_b64 exec, -1
	v_mov_b32_dpp v68, v56 quad_perm:[1,0,3,2] row_mask:0xf bank_mask:0xf
	v_mov_b32_dpp v69, v57 quad_perm:[1,0,3,2] row_mask:0xf bank_mask:0xf
	v_mov_b32_dpp v74, v168 quad_perm:[1,0,3,2] row_mask:0xf bank_mask:0xf
	v_mov_b32_dpp v75, v169 quad_perm:[1,0,3,2] row_mask:0xf bank_mask:0xf
	s_mov_b64 exec, s[62:63]
	v_mov_b32_e32 v56, v74
	v_mov_b32_e32 v57, v75
	s_mov_b64 exec, s[66:67]
	v_mov_b32_e32 v168, v68
	v_mov_b32_e32 v169, v69
	s_mov_b64 exec, -1
	s_add_u32 s88, s58, 0x50000
	s_addc_u32 s89, s59, 0
	s_add_u32 s90, s74, 0x28000
	s_addc_u32 s91, s75, 0
	global_store_dwordx4 v171, v[48:51], s[88:89]
	global_store_dwordx4 v171, v[52:55], s[88:89] offset:2048
	global_store_dwordx2 v170, v[56:57], s[90:91]
	global_store_dwordx2 v170, v[168:169], s[90:91] offset:1024
	s_add_u32 s92, s96, 0x50000
	s_addc_u32 s93, s97, 0
	v_pk_mul_f32 v[30:31], v[190:191], v[30:31]
	v_pk_mul_f32 v[32:33], v[192:193], v[32:33]
	v_pk_mul_f32 v[26:27], v[210:211], v[26:27]
	v_pk_mul_f32 v[28:29], v[212:213], v[28:29]
	v_cvt_pk_bf16_f32 v48, v30, v31
	v_cvt_pk_bf16_f32 v49, v32, v33
	v_cvt_pk_bf16_f32 v50, v26, v27
	v_cvt_pk_bf16_f32 v51, v28, v29
	v_pk_mul_f32 v[22:23], v[214:215], v[22:23]
	v_pk_mul_f32 v[24:25], v[216:217], v[24:25]
	v_pk_mul_f32 v[18:19], v[218:219], v[18:19]
	v_pk_mul_f32 v[20:21], v[220:221], v[20:21]
	v_cvt_pk_bf16_f32 v52, v22, v23
	v_cvt_pk_bf16_f32 v53, v24, v25
	v_cvt_pk_bf16_f32 v54, v18, v19
	v_cvt_pk_bf16_f32 v55, v20, v21
	v_mov_b32_dpp v68, v48 quad_perm:[1,0,3,2] row_mask:0xf bank_mask:0xf
	v_mov_b32_dpp v69, v49 quad_perm:[1,0,3,2] row_mask:0xf bank_mask:0xf
	v_mov_b32_dpp v70, v50 quad_perm:[1,0,3,2] row_mask:0xf bank_mask:0xf
	v_mov_b32_dpp v71, v51 quad_perm:[1,0,3,2] row_mask:0xf bank_mask:0xf
	v_mov_b32_dpp v74, v52 quad_perm:[1,0,3,2] row_mask:0xf bank_mask:0xf
	v_mov_b32_dpp v75, v53 quad_perm:[1,0,3,2] row_mask:0xf bank_mask:0xf
	v_mov_b32_dpp v76, v54 quad_perm:[1,0,3,2] row_mask:0xf bank_mask:0xf
	v_mov_b32_dpp v77, v55 quad_perm:[1,0,3,2] row_mask:0xf bank_mask:0xf
	s_mov_b64 exec, s[62:63]
	v_mov_b32_e32 v48, v74
	v_mov_b32_e32 v49, v75
	v_mov_b32_e32 v50, v76
	v_mov_b32_e32 v51, v77
	s_mov_b64 exec, s[66:67]
	v_mov_b32_e32 v52, v68
	v_mov_b32_e32 v53, v69
	v_mov_b32_e32 v54, v70
	v_mov_b32_e32 v55, v71
	s_mov_b64 exec, -1
	global_store_dwordx4 v171, v[48:51], s[92:93]
	global_store_dwordx4 v171, v[52:55], s[92:93] offset:2048
	v_mov_b32_e32 v18, v173
	s_waitcnt vmcnt(6)
	v_mov_b32_dpp v48, v36 quad_perm:[1,0,3,2] row_mask:0xf bank_mask:0xf
	v_mov_b32_dpp v49, v37 quad_perm:[1,0,3,2] row_mask:0xf bank_mask:0xf
	v_mov_b32_dpp v50, v38 quad_perm:[1,0,3,2] row_mask:0xf bank_mask:0xf
	v_mov_b32_dpp v51, v39 quad_perm:[1,0,3,2] row_mask:0xf bank_mask:0xf
	v_mov_b32_dpp v52, v58 quad_perm:[1,0,3,2] row_mask:0xf bank_mask:0xf
	v_mov_b32_dpp v53, v59 quad_perm:[1,0,3,2] row_mask:0xf bank_mask:0xf
	v_mov_b32_dpp v54, v60 quad_perm:[1,0,3,2] row_mask:0xf bank_mask:0xf
	v_mov_b32_dpp v55, v61 quad_perm:[1,0,3,2] row_mask:0xf bank_mask:0xf
	s_mov_b64 exec, s[62:63]
	v_mov_b32_e32 v36, v52
	v_mov_b32_e32 v37, v53
	v_mov_b32_e32 v38, v54
	v_mov_b32_e32 v39, v55
	s_mov_b64 exec, s[66:67]
	v_mov_b32_e32 v58, v48
	v_mov_b32_e32 v59, v49
	v_mov_b32_e32 v60, v50
	v_mov_b32_e32 v61, v51
	s_mov_b64 exec, -1
	v_mov_b32_dpp v48, v40 quad_perm:[1,0,3,2] row_mask:0xf bank_mask:0xf
	v_mov_b32_dpp v49, v41 quad_perm:[1,0,3,2] row_mask:0xf bank_mask:0xf
	v_mov_b32_dpp v52, v62 quad_perm:[1,0,3,2] row_mask:0xf bank_mask:0xf
	v_mov_b32_dpp v53, v63 quad_perm:[1,0,3,2] row_mask:0xf bank_mask:0xf
	s_mov_b64 exec, s[62:63]
	v_mov_b32_e32 v40, v52
	v_mov_b32_e32 v41, v53
	s_mov_b64 exec, s[66:67]
	v_mov_b32_e32 v62, v48
	v_mov_b32_e32 v63, v49
	s_mov_b64 exec, -1
	v_lshlrev_b32_e32 v44, 8, v40
	v_perm_b32 v45, v36, v40, s8
	v_lshrrev_b32_e32 v46, 8, v40
	v_lshrrev_b32_e32 v47, 16, v40
	v_perm_b32 v44, v36, v44, s33
	v_perm_b32 v46, v37, v46, s33
	v_perm_b32 v47, v37, v47, s8
	v_pk_fma_f32 v[14:15], v[14:15], v[174:175], v[44:45]
	v_pk_fma_f32 v[16:17], v[16:17], v[176:177], v[46:47]
	v_lshlrev_b32_e32 v44, 8, v41
	v_perm_b32 v45, v38, v41, s8
	v_lshrrev_b32_e32 v46, 8, v41
	v_lshrrev_b32_e32 v47, 16, v41
	v_perm_b32 v44, v38, v44, s33
	v_perm_b32 v46, v39, v46, s33
	v_perm_b32 v47, v39, v47, s8
	v_pk_fma_f32 v[10:11], v[10:11], v[178:179], v[44:45]
	v_pk_fma_f32 v[12:13], v[12:13], v[180:181], v[46:47]
	v_lshlrev_b32_e32 v44, 8, v62
	v_perm_b32 v45, v58, v62, s8
	v_lshrrev_b32_e32 v46, 8, v62
	v_lshrrev_b32_e32 v47, 16, v62
	v_perm_b32 v44, v58, v44, s33
	v_perm_b32 v46, v59, v46, s33
	v_perm_b32 v47, v59, v47, s8
	v_pk_fma_f32 v[6:7], v[6:7], v[182:183], v[44:45]
	v_pk_fma_f32 v[8:9], v[8:9], v[184:185], v[46:47]
	v_lshlrev_b32_e32 v44, 8, v63
	v_perm_b32 v45, v60, v63, s8
	v_lshrrev_b32_e32 v46, 8, v63
	v_lshrrev_b32_e32 v47, 16, v63
	v_perm_b32 v44, v60, v44, s33
	v_perm_b32 v46, v61, v46, s33
	v_perm_b32 v47, v61, v47, s8
	v_pk_fma_f32 v[2:3], v[2:3], v[186:187], v[44:45]
	v_pk_fma_f32 v[4:5], v[4:5], v[188:189], v[46:47]
	v_mul_f32_e32 v44, v15, v15
	v_mul_f32_e32 v45, v17, v17
	v_mul_f32_e32 v46, v11, v11
	v_mul_f32_e32 v47, v13, v13
	v_fmac_f32_e32 v44, v14, v14
	v_fmac_f32_e32 v45, v16, v16
	v_fmac_f32_e32 v46, v10, v10
	v_fmac_f32_e32 v47, v12, v12
	v_add_f32_e32 v44, v44, v45
	v_add_f32_e32 v46, v46, v47
	v_add_f32_e32 v173, v44, v46
	v_add_u32_e32 v44, 0x80, v14
	v_add_u32_e32 v45, 0x80, v15
	v_add_u32_e32 v46, 0x80, v16
	v_add_u32_e32 v47, 0x80, v17
	v_perm_b32 v48, v45, v44, s78
	v_perm_b32 v49, v47, v46, s78
	v_perm_b32 v42, v45, v44, s79
	v_perm_b32 v43, v47, v46, s79
	v_perm_b32 v56, v43, v42, s60
	v_add_u32_e32 v44, 0x80, v10
	v_add_u32_e32 v45, 0x80, v11
	v_add_u32_e32 v46, 0x80, v12
	v_add_u32_e32 v47, 0x80, v13
	v_perm_b32 v50, v45, v44, s78
	v_perm_b32 v51, v47, v46, s78
	v_perm_b32 v42, v45, v44, s79
	v_perm_b32 v43, v47, v46, s79
	v_perm_b32 v57, v43, v42, s60
	v_mul_f32_e32 v44, v7, v7
	v_mul_f32_e32 v45, v9, v9
	v_mul_f32_e32 v46, v3, v3
	v_mul_f32_e32 v47, v5, v5
	v_fmac_f32_e32 v44, v6, v6
	v_fmac_f32_e32 v45, v8, v8
	v_fmac_f32_e32 v46, v2, v2
	v_fmac_f32_e32 v47, v4, v4
	v_add_f32_e32 v44, v44, v45
	v_add_f32_e32 v46, v46, v47
	v_add_f32_e32 v44, v44, v46
	v_add_f32_e32 v173, v173, v44
	v_add_u32_e32 v44, 0x80, v6
	v_add_u32_e32 v45, 0x80, v7
	v_add_u32_e32 v46, 0x80, v8
	v_add_u32_e32 v47, 0x80, v9
	v_perm_b32 v52, v45, v44, s78
	v_perm_b32 v53, v47, v46, s78
	v_perm_b32 v42, v45, v44, s79
	v_perm_b32 v43, v47, v46, s79
	v_perm_b32 v168, v43, v42, s60
	v_add_u32_e32 v44, 0x80, v2
	v_add_u32_e32 v45, 0x80, v3
	v_add_u32_e32 v46, 0x80, v4
	v_add_u32_e32 v47, 0x80, v5
	v_perm_b32 v54, v45, v44, s78
	v_perm_b32 v55, v47, v46, s78
	v_perm_b32 v42, v45, v44, s79
	v_perm_b32 v43, v47, v46, s79
	v_perm_b32 v169, v43, v42, s60
	v_mov_b32_dpp v36, v48 quad_perm:[1,0,3,2] row_mask:0xf bank_mask:0xf
	v_mov_b32_dpp v37, v49 quad_perm:[1,0,3,2] row_mask:0xf bank_mask:0xf
	v_mov_b32_dpp v38, v50 quad_perm:[1,0,3,2] row_mask:0xf bank_mask:0xf
	v_mov_b32_dpp v39, v51 quad_perm:[1,0,3,2] row_mask:0xf bank_mask:0xf
	v_mov_b32_dpp v58, v52 quad_perm:[1,0,3,2] row_mask:0xf bank_mask:0xf
	v_mov_b32_dpp v59, v53 quad_perm:[1,0,3,2] row_mask:0xf bank_mask:0xf
	v_mov_b32_dpp v60, v54 quad_perm:[1,0,3,2] row_mask:0xf bank_mask:0xf
	v_mov_b32_dpp v61, v55 quad_perm:[1,0,3,2] row_mask:0xf bank_mask:0xf
	s_mov_b64 exec, s[62:63]
	v_mov_b32_e32 v48, v58
	v_mov_b32_e32 v49, v59
	v_mov_b32_e32 v50, v60
	v_mov_b32_e32 v51, v61
	s_mov_b64 exec, s[66:67]
	v_mov_b32_e32 v52, v36
	v_mov_b32_e32 v53, v37
	v_mov_b32_e32 v54, v38
	v_mov_b32_e32 v55, v39
	s_mov_b64 exec, -1
	v_mov_b32_dpp v36, v56 quad_perm:[1,0,3,2] row_mask:0xf bank_mask:0xf
	v_mov_b32_dpp v37, v57 quad_perm:[1,0,3,2] row_mask:0xf bank_mask:0xf
	v_mov_b32_dpp v58, v168 quad_perm:[1,0,3,2] row_mask:0xf bank_mask:0xf
	v_mov_b32_dpp v59, v169 quad_perm:[1,0,3,2] row_mask:0xf bank_mask:0xf
	s_mov_b64 exec, s[62:63]
	v_mov_b32_e32 v56, v58
	v_mov_b32_e32 v57, v59
	s_mov_b64 exec, s[66:67]
	v_mov_b32_e32 v168, v36
	v_mov_b32_e32 v169, v37
	s_mov_b64 exec, -1
	s_add_u32 s88, s58, 0x58000
	s_addc_u32 s89, s59, 0
	s_add_u32 s90, s74, 0x2c000
	s_addc_u32 s91, s75, 0
	global_store_dwordx4 v171, v[48:51], s[88:89]
	global_store_dwordx4 v171, v[52:55], s[88:89] offset:2048
	global_store_dwordx2 v170, v[56:57], s[90:91]
	global_store_dwordx2 v170, v[168:169], s[90:91] offset:1024
	s_add_u32 s92, s96, 0x58000
	s_addc_u32 s93, s97, 0
	v_pk_mul_f32 v[14:15], v[190:191], v[14:15]
	v_pk_mul_f32 v[16:17], v[192:193], v[16:17]
	v_pk_mul_f32 v[10:11], v[210:211], v[10:11]
	v_pk_mul_f32 v[12:13], v[212:213], v[12:13]
	v_cvt_pk_bf16_f32 v48, v14, v15
	v_cvt_pk_bf16_f32 v49, v16, v17
	v_cvt_pk_bf16_f32 v50, v10, v11
	v_cvt_pk_bf16_f32 v51, v12, v13
	v_pk_mul_f32 v[6:7], v[214:215], v[6:7]
	v_pk_mul_f32 v[8:9], v[216:217], v[8:9]
	v_pk_mul_f32 v[2:3], v[218:219], v[2:3]
	v_pk_mul_f32 v[4:5], v[220:221], v[4:5]
	v_cvt_pk_bf16_f32 v52, v6, v7
	v_cvt_pk_bf16_f32 v53, v8, v9
	v_cvt_pk_bf16_f32 v54, v2, v3
	v_cvt_pk_bf16_f32 v55, v4, v5
	v_mov_b32_dpp v36, v48 quad_perm:[1,0,3,2] row_mask:0xf bank_mask:0xf
	v_mov_b32_dpp v37, v49 quad_perm:[1,0,3,2] row_mask:0xf bank_mask:0xf
	v_mov_b32_dpp v38, v50 quad_perm:[1,0,3,2] row_mask:0xf bank_mask:0xf
	v_mov_b32_dpp v39, v51 quad_perm:[1,0,3,2] row_mask:0xf bank_mask:0xf
	v_mov_b32_dpp v58, v52 quad_perm:[1,0,3,2] row_mask:0xf bank_mask:0xf
	v_mov_b32_dpp v59, v53 quad_perm:[1,0,3,2] row_mask:0xf bank_mask:0xf
	v_mov_b32_dpp v60, v54 quad_perm:[1,0,3,2] row_mask:0xf bank_mask:0xf
	v_mov_b32_dpp v61, v55 quad_perm:[1,0,3,2] row_mask:0xf bank_mask:0xf
	s_mov_b64 exec, s[62:63]
	v_mov_b32_e32 v48, v58
	v_mov_b32_e32 v49, v59
	v_mov_b32_e32 v50, v60
	v_mov_b32_e32 v51, v61
	s_mov_b64 exec, s[66:67]
	v_mov_b32_e32 v52, v36
	v_mov_b32_e32 v53, v37
	v_mov_b32_e32 v54, v38
	v_mov_b32_e32 v55, v39
	s_mov_b64 exec, -1
	global_store_dwordx4 v171, v[48:51], s[92:93]
	global_store_dwordx4 v171, v[52:55], s[92:93] offset:2048
	v_mov_b32_e32 v2, v173
	v_mbcnt_lo_u32_b32 v3, -1, 0
	v_mbcnt_hi_u32_b32 v3, -1, v3
	v_xor_b32_e32 v4, 16, v3
	v_xor_b32_e32 v5, 32, v3
	v_lshlrev_b32_e32 v4, 2, v4
	v_lshlrev_b32_e32 v5, 2, v5
	v_cmp_gt_u32_e64 s[34:35], 16, v3
	ds_bpermute_b32 v6, v4, v130
	ds_bpermute_b32 v7, v4, v114
	ds_bpermute_b32 v8, v4, v98
	ds_bpermute_b32 v9, v4, v82
	ds_bpermute_b32 v10, v4, v66
	ds_bpermute_b32 v11, v4, v34
	ds_bpermute_b32 v12, v4, v18
	ds_bpermute_b32 v13, v4, v2
	s_waitcnt lgkmcnt(0)
	v_add_f32_e32 v130, v130, v6
	v_add_f32_e32 v114, v114, v7
	v_add_f32_e32 v98, v98, v8
	v_add_f32_e32 v82, v82, v9
	v_add_f32_e32 v66, v66, v10
	v_add_f32_e32 v34, v34, v11
	v_add_f32_e32 v18, v18, v12
	v_add_f32_e32 v2, v2, v13
	ds_bpermute_b32 v6, v5, v130
	ds_bpermute_b32 v7, v5, v114
	ds_bpermute_b32 v8, v5, v98
	ds_bpermute_b32 v9, v5, v82
	ds_bpermute_b32 v10, v5, v66
	ds_bpermute_b32 v11, v5, v34
	ds_bpermute_b32 v12, v5, v18
	ds_bpermute_b32 v13, v5, v2
	s_waitcnt lgkmcnt(0)
	v_add_f32_e32 v130, v130, v6
	v_add_f32_e32 v114, v114, v7
	v_add_f32_e32 v98, v98, v8
	v_add_f32_e32 v82, v82, v9
	v_add_f32_e32 v66, v66, v10
	v_add_f32_e32 v34, v34, v11
	v_add_f32_e32 v18, v18, v12
	v_add_f32_e32 v2, v2, v13
	v_readlane_b32 s70, v244, 53
	v_readlane_b32 s71, v244, 54
	v_lshlrev_b32_e32 v3, 6, v194
	s_lshl_b32 s94, s54, 14
	s_lshl_b32 s95, s4, 4
	s_add_u32 s94, s94, s95
	s_lshl_b32 s95, s51, 2
	s_add_u32 s94, s94, s95
	s_add_u32 s94, s70, s94
	s_addc_u32 s95, s71, 0
	s_and_saveexec_b64 s[36:37], s[34:35]
	global_store_dword v3, v130, s[94:95]
	s_add_u32 s84, s94, 0x400
	s_addc_u32 s85, s95, 0
	global_store_dword v3, v114, s[84:85]
	s_add_u32 s84, s94, 0x800
	s_addc_u32 s85, s95, 0
	global_store_dword v3, v98, s[84:85]
	s_add_u32 s84, s94, 0xc00
	s_addc_u32 s85, s95, 0
	global_store_dword v3, v82, s[84:85]
	s_add_u32 s84, s94, 0x2000
	s_addc_u32 s85, s95, 0
	global_store_dword v3, v66, s[84:85]
	s_add_u32 s84, s94, 0x2400
	s_addc_u32 s85, s95, 0
	global_store_dword v3, v34, s[84:85]
	s_add_u32 s84, s94, 0x2800
	s_addc_u32 s85, s95, 0
	global_store_dword v3, v18, s[84:85]
	s_add_u32 s84, s94, 0x2c00
	s_addc_u32 s85, s95, 0
	global_store_dword v3, v2, s[84:85]
	s_or_b64 exec, exec, s[36:37]
	v_readlane_b32 s56, v246, 3
	v_readlane_b32 s57, v246, 4
	s_branch .LBB0_1568
.Lepi3_nulla1:
	s_ashr_i32 s16, s54, 31
	s_lshr_b32 s16, s16, 29
	s_add_i32 s16, s54, s16
	s_ashr_i32 s16, s16, 3
	s_mul_i32 s27, s16, 0x6000
	s_mul_hi_i32 s25, s16, 0x6000
	s_add_u32 s80, s45, s27
	s_addc_u32 s81, s47, s25
	s_mov_b32 s62, 0xaaaaaaaa
	s_mov_b32 s63, 0xaaaaaaaa
	s_mov_b32 s66, 0x55555555
	s_mov_b32 s67, 0x55555555
	v_mbcnt_lo_u32_b32 v172, -1, 0
	v_mbcnt_hi_u32_b32 v172, -1, v172
	v_and_b32_e32 v172, 1, v172
	v_and_b32_e32 v171, 0x60, v196
	v_add_u32_e32 v171, v171, v196
	v_lshl_or_b32 v171, s4, 8, v171
	v_lshlrev_b32_e32 v44, 2, v171
	v_lshl_add_u32 v171, v172, 5, v171
	v_lshl_add_u32 v170, s54, 8, v194
	v_sub_u32_e32 v170, v170, v172
	v_lshl_add_u32 v170, v170, 10, v171
	v_lshlrev_b32_e32 v171, 1, v170
	global_load_dwordx4 v[174:177], v44, s[80:81] offset:0
	global_load_dwordx4 v[178:181], v44, s[80:81] offset:16
	global_load_dwordx4 v[182:185], v44, s[80:81] offset:128
	global_load_dwordx4 v[186:189], v44, s[80:81] offset:144
	s_waitcnt vmcnt(0)
	s_add_u32 s84, s58, 0x0
	s_addc_u32 s85, s59, 0
	s_add_u32 s86, s74, 0x0
	s_addc_u32 s87, s75, 0
	global_load_dwordx4 v[190:193], v171, s[84:85]
	global_load_dwordx2 v[210:211], v170, s[86:87]
	global_load_dwordx4 v[212:215], v171, s[84:85] offset:2048
	global_load_dwordx2 v[216:217], v170, s[86:87] offset:1024
	s_add_u32 s84, s58, 0x8000
	s_addc_u32 s85, s59, 0
	s_add_u32 s86, s74, 0x4000
	s_addc_u32 s87, s75, 0
	global_load_dwordx4 v[218:221], v171, s[84:85]
	global_load_dwordx2 v[222:223], v170, s[86:87]
	global_load_dwordx4 v[224:227], v171, s[84:85] offset:2048
	global_load_dwordx2 v[228:229], v170, s[86:87] offset:1024
	s_waitcnt vmcnt(4)
	v_mov_b32_dpp v48, v190 quad_perm:[1,0,3,2] row_mask:0xf bank_mask:0xf
	v_mov_b32_dpp v49, v191 quad_perm:[1,0,3,2] row_mask:0xf bank_mask:0xf
	v_mov_b32_dpp v50, v192 quad_perm:[1,0,3,2] row_mask:0xf bank_mask:0xf
	v_mov_b32_dpp v51, v193 quad_perm:[1,0,3,2] row_mask:0xf bank_mask:0xf
	v_mov_b32_dpp v52, v212 quad_perm:[1,0,3,2] row_mask:0xf bank_mask:0xf
	v_mov_b32_dpp v53, v213 quad_perm:[1,0,3,2] row_mask:0xf bank_mask:0xf
	v_mov_b32_dpp v54, v214 quad_perm:[1,0,3,2] row_mask:0xf bank_mask:0xf
	v_mov_b32_dpp v55, v215 quad_perm:[1,0,3,2] row_mask:0xf bank_mask:0xf
	s_mov_b64 exec, s[62:63]
	v_mov_b32_e32 v190, v52
	v_mov_b32_e32 v191, v53
	v_mov_b32_e32 v192, v54
	v_mov_b32_e32 v193, v55
	s_mov_b64 exec, s[66:67]
	v_mov_b32_e32 v212, v48
	v_mov_b32_e32 v213, v49
	v_mov_b32_e32 v214, v50
	v_mov_b32_e32 v215, v51
	s_mov_b64 exec, -1
	v_mov_b32_dpp v48, v210 quad_perm:[1,0,3,2] row_mask:0xf bank_mask:0xf
	v_mov_b32_dpp v49, v211 quad_perm:[1,0,3,2] row_mask:0xf bank_mask:0xf
	v_mov_b32_dpp v52, v216 quad_perm:[1,0,3,2] row_mask:0xf bank_mask:0xf
	v_mov_b32_dpp v53, v217 quad_perm:[1,0,3,2] row_mask:0xf bank_mask:0xf
	s_mov_b64 exec, s[62:63]
	v_mov_b32_e32 v210, v52
	v_mov_b32_e32 v211, v53
	s_mov_b64 exec, s[66:67]
	v_mov_b32_e32 v216, v48
	v_mov_b32_e32 v217, v49
	s_mov_b64 exec, -1
	v_lshlrev_b32_e32 v44, 8, v210
	v_perm_b32 v45, v190, v210, s8
	v_lshrrev_b32_e32 v46, 8, v210
	v_lshrrev_b32_e32 v47, 16, v210
	v_perm_b32 v44, v190, v44, s33
	v_perm_b32 v46, v191, v46, s33
	v_perm_b32 v47, v191, v47, s8
	v_pk_fma_f32 v[142:143], v[142:143], v[174:175], v[44:45]
	v_pk_fma_f32 v[144:145], v[144:145], v[176:177], v[46:47]
	v_lshlrev_b32_e32 v44, 8, v211
	v_perm_b32 v45, v192, v211, s8
	v_lshrrev_b32_e32 v46, 8, v211
	v_lshrrev_b32_e32 v47, 16, v211
	v_perm_b32 v44, v192, v44, s33
	v_perm_b32 v46, v193, v46, s33
	v_perm_b32 v47, v193, v47, s8
	v_pk_fma_f32 v[138:139], v[138:139], v[178:179], v[44:45]
	v_pk_fma_f32 v[140:141], v[140:141], v[180:181], v[46:47]
	v_lshlrev_b32_e32 v44, 8, v216
	v_perm_b32 v45, v212, v216, s8
	v_lshrrev_b32_e32 v46, 8, v216
	v_lshrrev_b32_e32 v47, 16, v216
	v_perm_b32 v44, v212, v44, s33
	v_perm_b32 v46, v213, v46, s33
	v_perm_b32 v47, v213, v47, s8
	v_pk_fma_f32 v[134:135], v[134:135], v[182:183], v[44:45]
	v_pk_fma_f32 v[136:137], v[136:137], v[184:185], v[46:47]
	v_lshlrev_b32_e32 v44, 8, v217
	v_perm_b32 v45, v214, v217, s8
	v_lshrrev_b32_e32 v46, 8, v217
	v_lshrrev_b32_e32 v47, 16, v217
	v_perm_b32 v44, v214, v44, s33
	v_perm_b32 v46, v215, v46, s33
	v_perm_b32 v47, v215, v47, s8
	v_pk_fma_f32 v[130:131], v[130:131], v[186:187], v[44:45]
	v_pk_fma_f32 v[132:133], v[132:133], v[188:189], v[46:47]
	v_add_u32_e32 v44, 0x80, v142
	v_add_u32_e32 v45, 0x80, v143
	v_add_u32_e32 v46, 0x80, v144
	v_add_u32_e32 v47, 0x80, v145
	v_perm_b32 v48, v45, v44, s78
	v_perm_b32 v49, v47, v46, s78
	v_perm_b32 v42, v45, v44, s79
	v_perm_b32 v43, v47, v46, s79
	v_perm_b32 v56, v43, v42, s60
	v_add_u32_e32 v44, 0x80, v138
	v_add_u32_e32 v45, 0x80, v139
	v_add_u32_e32 v46, 0x80, v140
	v_add_u32_e32 v47, 0x80, v141
	v_perm_b32 v50, v45, v44, s78
	v_perm_b32 v51, v47, v46, s78
	v_perm_b32 v42, v45, v44, s79
	v_perm_b32 v43, v47, v46, s79
	v_perm_b32 v57, v43, v42, s60
	v_add_u32_e32 v44, 0x80, v134
	v_add_u32_e32 v45, 0x80, v135
	v_add_u32_e32 v46, 0x80, v136
	v_add_u32_e32 v47, 0x80, v137
	v_perm_b32 v52, v45, v44, s78
	v_perm_b32 v53, v47, v46, s78
	v_perm_b32 v42, v45, v44, s79
	v_perm_b32 v43, v47, v46, s79
	v_perm_b32 v168, v43, v42, s60
	v_add_u32_e32 v44, 0x80, v130
	v_add_u32_e32 v45, 0x80, v131
	v_add_u32_e32 v46, 0x80, v132
	v_add_u32_e32 v47, 0x80, v133
	v_perm_b32 v54, v45, v44, s78
	v_perm_b32 v55, v47, v46, s78
	v_perm_b32 v42, v45, v44, s79
	v_perm_b32 v43, v47, v46, s79
	v_perm_b32 v169, v43, v42, s60
	v_mov_b32_dpp v190, v48 quad_perm:[1,0,3,2] row_mask:0xf bank_mask:0xf
	v_mov_b32_dpp v191, v49 quad_perm:[1,0,3,2] row_mask:0xf bank_mask:0xf
	v_mov_b32_dpp v192, v50 quad_perm:[1,0,3,2] row_mask:0xf bank_mask:0xf
	v_mov_b32_dpp v193, v51 quad_perm:[1,0,3,2] row_mask:0xf bank_mask:0xf
	v_mov_b32_dpp v212, v52 quad_perm:[1,0,3,2] row_mask:0xf bank_mask:0xf
	v_mov_b32_dpp v213, v53 quad_perm:[1,0,3,2] row_mask:0xf bank_mask:0xf
	v_mov_b32_dpp v214, v54 quad_perm:[1,0,3,2] row_mask:0xf bank_mask:0xf
	v_mov_b32_dpp v215, v55 quad_perm:[1,0,3,2] row_mask:0xf bank_mask:0xf
	s_mov_b64 exec, s[62:63]
	v_mov_b32_e32 v48, v212
	v_mov_b32_e32 v49, v213
	v_mov_b32_e32 v50, v214
	v_mov_b32_e32 v51, v215
	s_mov_b64 exec, s[66:67]
	v_mov_b32_e32 v52, v190
	v_mov_b32_e32 v53, v191
	v_mov_b32_e32 v54, v192
	v_mov_b32_e32 v55, v193
	s_mov_b64 exec, -1
	v_mov_b32_dpp v190, v56 quad_perm:[1,0,3,2] row_mask:0xf bank_mask:0xf
	v_mov_b32_dpp v191, v57 quad_perm:[1,0,3,2] row_mask:0xf bank_mask:0xf
	v_mov_b32_dpp v212, v168 quad_perm:[1,0,3,2] row_mask:0xf bank_mask:0xf
	v_mov_b32_dpp v213, v169 quad_perm:[1,0,3,2] row_mask:0xf bank_mask:0xf
	s_mov_b64 exec, s[62:63]
	v_mov_b32_e32 v56, v212
	v_mov_b32_e32 v57, v213
	s_mov_b64 exec, s[66:67]
	v_mov_b32_e32 v168, v190
	v_mov_b32_e32 v169, v191
	s_mov_b64 exec, -1
	s_add_u32 s88, s58, 0x0
	s_addc_u32 s89, s59, 0
	s_add_u32 s90, s74, 0x0
	s_addc_u32 s91, s75, 0
	global_store_dwordx4 v171, v[48:51], s[88:89]
	global_store_dwordx4 v171, v[52:55], s[88:89] offset:2048
	global_store_dwordx2 v170, v[56:57], s[90:91]
	global_store_dwordx2 v170, v[168:169], s[90:91] offset:1024
	s_add_u32 s84, s58, 0x10000
	s_addc_u32 s85, s59, 0
	s_add_u32 s86, s74, 0x8000
	s_addc_u32 s87, s75, 0
	global_load_dwordx4 v[130:133], v171, s[84:85]
	global_load_dwordx2 v[134:135], v170, s[86:87]
	global_load_dwordx4 v[136:139], v171, s[84:85] offset:2048
	global_load_dwordx2 v[140:141], v170, s[86:87] offset:1024
	s_waitcnt vmcnt(8)
	v_mov_b32_dpp v48, v218 quad_perm:[1,0,3,2] row_mask:0xf bank_mask:0xf
	v_mov_b32_dpp v49, v219 quad_perm:[1,0,3,2] row_mask:0xf bank_mask:0xf
	v_mov_b32_dpp v50, v220 quad_perm:[1,0,3,2] row_mask:0xf bank_mask:0xf
	v_mov_b32_dpp v51, v221 quad_perm:[1,0,3,2] row_mask:0xf bank_mask:0xf
	v_mov_b32_dpp v52, v224 quad_perm:[1,0,3,2] row_mask:0xf bank_mask:0xf
	v_mov_b32_dpp v53, v225 quad_perm:[1,0,3,2] row_mask:0xf bank_mask:0xf
	v_mov_b32_dpp v54, v226 quad_perm:[1,0,3,2] row_mask:0xf bank_mask:0xf
	v_mov_b32_dpp v55, v227 quad_perm:[1,0,3,2] row_mask:0xf bank_mask:0xf
	s_mov_b64 exec, s[62:63]
	v_mov_b32_e32 v218, v52
	v_mov_b32_e32 v219, v53
	v_mov_b32_e32 v220, v54
	v_mov_b32_e32 v221, v55
	s_mov_b64 exec, s[66:67]
	v_mov_b32_e32 v224, v48
	v_mov_b32_e32 v225, v49
	v_mov_b32_e32 v226, v50
	v_mov_b32_e32 v227, v51
	s_mov_b64 exec, -1
	v_mov_b32_dpp v48, v222 quad_perm:[1,0,3,2] row_mask:0xf bank_mask:0xf
	v_mov_b32_dpp v49, v223 quad_perm:[1,0,3,2] row_mask:0xf bank_mask:0xf
	v_mov_b32_dpp v52, v228 quad_perm:[1,0,3,2] row_mask:0xf bank_mask:0xf
	v_mov_b32_dpp v53, v229 quad_perm:[1,0,3,2] row_mask:0xf bank_mask:0xf
	s_mov_b64 exec, s[62:63]
	v_mov_b32_e32 v222, v52
	v_mov_b32_e32 v223, v53
	s_mov_b64 exec, s[66:67]
	v_mov_b32_e32 v228, v48
	v_mov_b32_e32 v229, v49
	s_mov_b64 exec, -1
	v_lshlrev_b32_e32 v44, 8, v222
	v_perm_b32 v45, v218, v222, s8
	v_lshrrev_b32_e32 v46, 8, v222
	v_lshrrev_b32_e32 v47, 16, v222
	v_perm_b32 v44, v218, v44, s33
	v_perm_b32 v46, v219, v46, s33
	v_perm_b32 v47, v219, v47, s8
	v_pk_fma_f32 v[126:127], v[126:127], v[174:175], v[44:45]
	v_pk_fma_f32 v[128:129], v[128:129], v[176:177], v[46:47]
	v_lshlrev_b32_e32 v44, 8, v223
	v_perm_b32 v45, v220, v223, s8
	v_lshrrev_b32_e32 v46, 8, v223
	v_lshrrev_b32_e32 v47, 16, v223
	v_perm_b32 v44, v220, v44, s33
	v_perm_b32 v46, v221, v46, s33
	v_perm_b32 v47, v221, v47, s8
	v_pk_fma_f32 v[122:123], v[122:123], v[178:179], v[44:45]
	v_pk_fma_f32 v[124:125], v[124:125], v[180:181], v[46:47]
	v_lshlrev_b32_e32 v44, 8, v228
	v_perm_b32 v45, v224, v228, s8
	v_lshrrev_b32_e32 v46, 8, v228
	v_lshrrev_b32_e32 v47, 16, v228
	v_perm_b32 v44, v224, v44, s33
	v_perm_b32 v46, v225, v46, s33
	v_perm_b32 v47, v225, v47, s8
	v_pk_fma_f32 v[118:119], v[118:119], v[182:183], v[44:45]
	v_pk_fma_f32 v[120:121], v[120:121], v[184:185], v[46:47]
	v_lshlrev_b32_e32 v44, 8, v229
	v_perm_b32 v45, v226, v229, s8
	v_lshrrev_b32_e32 v46, 8, v229
	v_lshrrev_b32_e32 v47, 16, v229
	v_perm_b32 v44, v226, v44, s33
	v_perm_b32 v46, v227, v46, s33
	v_perm_b32 v47, v227, v47, s8
	v_pk_fma_f32 v[114:115], v[114:115], v[186:187], v[44:45]
	v_pk_fma_f32 v[116:117], v[116:117], v[188:189], v[46:47]
	v_add_u32_e32 v44, 0x80, v126
	v_add_u32_e32 v45, 0x80, v127
	v_add_u32_e32 v46, 0x80, v128
	v_add_u32_e32 v47, 0x80, v129
	v_perm_b32 v48, v45, v44, s78
	v_perm_b32 v49, v47, v46, s78
	v_perm_b32 v42, v45, v44, s79
	v_perm_b32 v43, v47, v46, s79
	v_perm_b32 v56, v43, v42, s60
	v_add_u32_e32 v44, 0x80, v122
	v_add_u32_e32 v45, 0x80, v123
	v_add_u32_e32 v46, 0x80, v124
	v_add_u32_e32 v47, 0x80, v125
	v_perm_b32 v50, v45, v44, s78
	v_perm_b32 v51, v47, v46, s78
	v_perm_b32 v42, v45, v44, s79
	v_perm_b32 v43, v47, v46, s79
	v_perm_b32 v57, v43, v42, s60
	v_add_u32_e32 v44, 0x80, v118
	v_add_u32_e32 v45, 0x80, v119
	v_add_u32_e32 v46, 0x80, v120
	v_add_u32_e32 v47, 0x80, v121
	v_perm_b32 v52, v45, v44, s78
	v_perm_b32 v53, v47, v46, s78
	v_perm_b32 v42, v45, v44, s79
	v_perm_b32 v43, v47, v46, s79
	v_perm_b32 v168, v43, v42, s60
	v_add_u32_e32 v44, 0x80, v114
	v_add_u32_e32 v45, 0x80, v115
	v_add_u32_e32 v46, 0x80, v116
	v_add_u32_e32 v47, 0x80, v117
	v_perm_b32 v54, v45, v44, s78
	v_perm_b32 v55, v47, v46, s78
	v_perm_b32 v42, v45, v44, s79
	v_perm_b32 v43, v47, v46, s79
	v_perm_b32 v169, v43, v42, s60
	v_mov_b32_dpp v218, v48 quad_perm:[1,0,3,2] row_mask:0xf bank_mask:0xf
	v_mov_b32_dpp v219, v49 quad_perm:[1,0,3,2] row_mask:0xf bank_mask:0xf
	v_mov_b32_dpp v220, v50 quad_perm:[1,0,3,2] row_mask:0xf bank_mask:0xf
	v_mov_b32_dpp v221, v51 quad_perm:[1,0,3,2] row_mask:0xf bank_mask:0xf
	v_mov_b32_dpp v224, v52 quad_perm:[1,0,3,2] row_mask:0xf bank_mask:0xf
	v_mov_b32_dpp v225, v53 quad_perm:[1,0,3,2] row_mask:0xf bank_mask:0xf
	v_mov_b32_dpp v226, v54 quad_perm:[1,0,3,2] row_mask:0xf bank_mask:0xf
	v_mov_b32_dpp v227, v55 quad_perm:[1,0,3,2] row_mask:0xf bank_mask:0xf
	s_mov_b64 exec, s[62:63]
	v_mov_b32_e32 v48, v224
	v_mov_b32_e32 v49, v225
	v_mov_b32_e32 v50, v226
	v_mov_b32_e32 v51, v227
	s_mov_b64 exec, s[66:67]
	v_mov_b32_e32 v52, v218
	v_mov_b32_e32 v53, v219
	v_mov_b32_e32 v54, v220
	v_mov_b32_e32 v55, v221
	s_mov_b64 exec, -1
	v_mov_b32_dpp v218, v56 quad_perm:[1,0,3,2] row_mask:0xf bank_mask:0xf
	v_mov_b32_dpp v219, v57 quad_perm:[1,0,3,2] row_mask:0xf bank_mask:0xf
	v_mov_b32_dpp v224, v168 quad_perm:[1,0,3,2] row_mask:0xf bank_mask:0xf
	v_mov_b32_dpp v225, v169 quad_perm:[1,0,3,2] row_mask:0xf bank_mask:0xf
	s_mov_b64 exec, s[62:63]
	v_mov_b32_e32 v56, v224
	v_mov_b32_e32 v57, v225
	s_mov_b64 exec, s[66:67]
	v_mov_b32_e32 v168, v218
	v_mov_b32_e32 v169, v219
	s_mov_b64 exec, -1
	s_add_u32 s88, s58, 0x8000
	s_addc_u32 s89, s59, 0
	s_add_u32 s90, s74, 0x4000
	s_addc_u32 s91, s75, 0
	global_store_dwordx4 v171, v[48:51], s[88:89]
	global_store_dwordx4 v171, v[52:55], s[88:89] offset:2048
	global_store_dwordx2 v170, v[56:57], s[90:91]
	global_store_dwordx2 v170, v[168:169], s[90:91] offset:1024
	s_add_u32 s84, s58, 0x18000
	s_addc_u32 s85, s59, 0
	s_add_u32 s86, s74, 0xc000
	s_addc_u32 s87, s75, 0
	global_load_dwordx4 v[114:117], v171, s[84:85]
	global_load_dwordx2 v[118:119], v170, s[86:87]
	global_load_dwordx4 v[120:123], v171, s[84:85] offset:2048
	global_load_dwordx2 v[124:125], v170, s[86:87] offset:1024
	s_waitcnt vmcnt(8)
	v_mov_b32_dpp v48, v130 quad_perm:[1,0,3,2] row_mask:0xf bank_mask:0xf
	v_mov_b32_dpp v49, v131 quad_perm:[1,0,3,2] row_mask:0xf bank_mask:0xf
	v_mov_b32_dpp v50, v132 quad_perm:[1,0,3,2] row_mask:0xf bank_mask:0xf
	v_mov_b32_dpp v51, v133 quad_perm:[1,0,3,2] row_mask:0xf bank_mask:0xf
	v_mov_b32_dpp v52, v136 quad_perm:[1,0,3,2] row_mask:0xf bank_mask:0xf
	v_mov_b32_dpp v53, v137 quad_perm:[1,0,3,2] row_mask:0xf bank_mask:0xf
	v_mov_b32_dpp v54, v138 quad_perm:[1,0,3,2] row_mask:0xf bank_mask:0xf
	v_mov_b32_dpp v55, v139 quad_perm:[1,0,3,2] row_mask:0xf bank_mask:0xf
	s_mov_b64 exec, s[62:63]
	v_mov_b32_e32 v130, v52
	v_mov_b32_e32 v131, v53
	v_mov_b32_e32 v132, v54
	v_mov_b32_e32 v133, v55
	s_mov_b64 exec, s[66:67]
	v_mov_b32_e32 v136, v48
	v_mov_b32_e32 v137, v49
	v_mov_b32_e32 v138, v50
	v_mov_b32_e32 v139, v51
	s_mov_b64 exec, -1
	v_mov_b32_dpp v48, v134 quad_perm:[1,0,3,2] row_mask:0xf bank_mask:0xf
	v_mov_b32_dpp v49, v135 quad_perm:[1,0,3,2] row_mask:0xf bank_mask:0xf
	v_mov_b32_dpp v52, v140 quad_perm:[1,0,3,2] row_mask:0xf bank_mask:0xf
	v_mov_b32_dpp v53, v141 quad_perm:[1,0,3,2] row_mask:0xf bank_mask:0xf
	s_mov_b64 exec, s[62:63]
	v_mov_b32_e32 v134, v52
	v_mov_b32_e32 v135, v53
	s_mov_b64 exec, s[66:67]
	v_mov_b32_e32 v140, v48
	v_mov_b32_e32 v141, v49
	s_mov_b64 exec, -1
	v_lshlrev_b32_e32 v44, 8, v134
	v_perm_b32 v45, v130, v134, s8
	v_lshrrev_b32_e32 v46, 8, v134
	v_lshrrev_b32_e32 v47, 16, v134
	v_perm_b32 v44, v130, v44, s33
	v_perm_b32 v46, v131, v46, s33
	v_perm_b32 v47, v131, v47, s8
	v_pk_fma_f32 v[110:111], v[110:111], v[174:175], v[44:45]
	v_pk_fma_f32 v[112:113], v[112:113], v[176:177], v[46:47]
	v_lshlrev_b32_e32 v44, 8, v135
	v_perm_b32 v45, v132, v135, s8
	v_lshrrev_b32_e32 v46, 8, v135
	v_lshrrev_b32_e32 v47, 16, v135
	v_perm_b32 v44, v132, v44, s33
	v_perm_b32 v46, v133, v46, s33
	v_perm_b32 v47, v133, v47, s8
	v_pk_fma_f32 v[106:107], v[106:107], v[178:179], v[44:45]
	v_pk_fma_f32 v[108:109], v[108:109], v[180:181], v[46:47]
	v_lshlrev_b32_e32 v44, 8, v140
	v_perm_b32 v45, v136, v140, s8
	v_lshrrev_b32_e32 v46, 8, v140
	v_lshrrev_b32_e32 v47, 16, v140
	v_perm_b32 v44, v136, v44, s33
	v_perm_b32 v46, v137, v46, s33
	v_perm_b32 v47, v137, v47, s8
	v_pk_fma_f32 v[102:103], v[102:103], v[182:183], v[44:45]
	v_pk_fma_f32 v[104:105], v[104:105], v[184:185], v[46:47]
	v_lshlrev_b32_e32 v44, 8, v141
	v_perm_b32 v45, v138, v141, s8
	v_lshrrev_b32_e32 v46, 8, v141
	v_lshrrev_b32_e32 v47, 16, v141
	v_perm_b32 v44, v138, v44, s33
	v_perm_b32 v46, v139, v46, s33
	v_perm_b32 v47, v139, v47, s8
	v_pk_fma_f32 v[98:99], v[98:99], v[186:187], v[44:45]
	v_pk_fma_f32 v[100:101], v[100:101], v[188:189], v[46:47]
	v_add_u32_e32 v44, 0x80, v110
	v_add_u32_e32 v45, 0x80, v111
	v_add_u32_e32 v46, 0x80, v112
	v_add_u32_e32 v47, 0x80, v113
	v_perm_b32 v48, v45, v44, s78
	v_perm_b32 v49, v47, v46, s78
	v_perm_b32 v42, v45, v44, s79
	v_perm_b32 v43, v47, v46, s79
	v_perm_b32 v56, v43, v42, s60
	v_add_u32_e32 v44, 0x80, v106
	v_add_u32_e32 v45, 0x80, v107
	v_add_u32_e32 v46, 0x80, v108
	v_add_u32_e32 v47, 0x80, v109
	v_perm_b32 v50, v45, v44, s78
	v_perm_b32 v51, v47, v46, s78
	v_perm_b32 v42, v45, v44, s79
	v_perm_b32 v43, v47, v46, s79
	v_perm_b32 v57, v43, v42, s60
	v_add_u32_e32 v44, 0x80, v102
	v_add_u32_e32 v45, 0x80, v103
	v_add_u32_e32 v46, 0x80, v104
	v_add_u32_e32 v47, 0x80, v105
	v_perm_b32 v52, v45, v44, s78
	v_perm_b32 v53, v47, v46, s78
	v_perm_b32 v42, v45, v44, s79
	v_perm_b32 v43, v47, v46, s79
	v_perm_b32 v168, v43, v42, s60
	v_add_u32_e32 v44, 0x80, v98
	v_add_u32_e32 v45, 0x80, v99
	v_add_u32_e32 v46, 0x80, v100
	v_add_u32_e32 v47, 0x80, v101
	v_perm_b32 v54, v45, v44, s78
	v_perm_b32 v55, v47, v46, s78
	v_perm_b32 v42, v45, v44, s79
	v_perm_b32 v43, v47, v46, s79
	v_perm_b32 v169, v43, v42, s60
	v_mov_b32_dpp v130, v48 quad_perm:[1,0,3,2] row_mask:0xf bank_mask:0xf
	v_mov_b32_dpp v131, v49 quad_perm:[1,0,3,2] row_mask:0xf bank_mask:0xf
	v_mov_b32_dpp v132, v50 quad_perm:[1,0,3,2] row_mask:0xf bank_mask:0xf
	v_mov_b32_dpp v133, v51 quad_perm:[1,0,3,2] row_mask:0xf bank_mask:0xf
	v_mov_b32_dpp v136, v52 quad_perm:[1,0,3,2] row_mask:0xf bank_mask:0xf
	v_mov_b32_dpp v137, v53 quad_perm:[1,0,3,2] row_mask:0xf bank_mask:0xf
	v_mov_b32_dpp v138, v54 quad_perm:[1,0,3,2] row_mask:0xf bank_mask:0xf
	v_mov_b32_dpp v139, v55 quad_perm:[1,0,3,2] row_mask:0xf bank_mask:0xf
	s_mov_b64 exec, s[62:63]
	v_mov_b32_e32 v48, v136
	v_mov_b32_e32 v49, v137
	v_mov_b32_e32 v50, v138
	v_mov_b32_e32 v51, v139
	s_mov_b64 exec, s[66:67]
	v_mov_b32_e32 v52, v130
	v_mov_b32_e32 v53, v131
	v_mov_b32_e32 v54, v132
	v_mov_b32_e32 v55, v133
	s_mov_b64 exec, -1
	v_mov_b32_dpp v130, v56 quad_perm:[1,0,3,2] row_mask:0xf bank_mask:0xf
	v_mov_b32_dpp v131, v57 quad_perm:[1,0,3,2] row_mask:0xf bank_mask:0xf
	v_mov_b32_dpp v136, v168 quad_perm:[1,0,3,2] row_mask:0xf bank_mask:0xf
	v_mov_b32_dpp v137, v169 quad_perm:[1,0,3,2] row_mask:0xf bank_mask:0xf
	s_mov_b64 exec, s[62:63]
	v_mov_b32_e32 v56, v136
	v_mov_b32_e32 v57, v137
	s_mov_b64 exec, s[66:67]
	v_mov_b32_e32 v168, v130
	v_mov_b32_e32 v169, v131
	s_mov_b64 exec, -1
	s_add_u32 s88, s58, 0x10000
	s_addc_u32 s89, s59, 0
	s_add_u32 s90, s74, 0x8000
	s_addc_u32 s91, s75, 0
	global_store_dwordx4 v171, v[48:51], s[88:89]
	global_store_dwordx4 v171, v[52:55], s[88:89] offset:2048
	global_store_dwordx2 v170, v[56:57], s[90:91]
	global_store_dwordx2 v170, v[168:169], s[90:91] offset:1024
	s_add_u32 s84, s58, 0x40000
	s_addc_u32 s85, s59, 0
	s_add_u32 s86, s74, 0x20000
	s_addc_u32 s87, s75, 0
	global_load_dwordx4 v[98:101], v171, s[84:85]
	global_load_dwordx2 v[102:103], v170, s[86:87]
	global_load_dwordx4 v[104:107], v171, s[84:85] offset:2048
	global_load_dwordx2 v[108:109], v170, s[86:87] offset:1024
	s_waitcnt vmcnt(8)
	v_mov_b32_dpp v48, v114 quad_perm:[1,0,3,2] row_mask:0xf bank_mask:0xf
	v_mov_b32_dpp v49, v115 quad_perm:[1,0,3,2] row_mask:0xf bank_mask:0xf
	v_mov_b32_dpp v50, v116 quad_perm:[1,0,3,2] row_mask:0xf bank_mask:0xf
	v_mov_b32_dpp v51, v117 quad_perm:[1,0,3,2] row_mask:0xf bank_mask:0xf
	v_mov_b32_dpp v52, v120 quad_perm:[1,0,3,2] row_mask:0xf bank_mask:0xf
	v_mov_b32_dpp v53, v121 quad_perm:[1,0,3,2] row_mask:0xf bank_mask:0xf
	v_mov_b32_dpp v54, v122 quad_perm:[1,0,3,2] row_mask:0xf bank_mask:0xf
	v_mov_b32_dpp v55, v123 quad_perm:[1,0,3,2] row_mask:0xf bank_mask:0xf
	s_mov_b64 exec, s[62:63]
	v_mov_b32_e32 v114, v52
	v_mov_b32_e32 v115, v53
	v_mov_b32_e32 v116, v54
	v_mov_b32_e32 v117, v55
	s_mov_b64 exec, s[66:67]
	v_mov_b32_e32 v120, v48
	v_mov_b32_e32 v121, v49
	v_mov_b32_e32 v122, v50
	v_mov_b32_e32 v123, v51
	s_mov_b64 exec, -1
	v_mov_b32_dpp v48, v118 quad_perm:[1,0,3,2] row_mask:0xf bank_mask:0xf
	v_mov_b32_dpp v49, v119 quad_perm:[1,0,3,2] row_mask:0xf bank_mask:0xf
	v_mov_b32_dpp v52, v124 quad_perm:[1,0,3,2] row_mask:0xf bank_mask:0xf
	v_mov_b32_dpp v53, v125 quad_perm:[1,0,3,2] row_mask:0xf bank_mask:0xf
	s_mov_b64 exec, s[62:63]
	v_mov_b32_e32 v118, v52
	v_mov_b32_e32 v119, v53
	s_mov_b64 exec, s[66:67]
	v_mov_b32_e32 v124, v48
	v_mov_b32_e32 v125, v49
	s_mov_b64 exec, -1
	v_lshlrev_b32_e32 v44, 8, v118
	v_perm_b32 v45, v114, v118, s8
	v_lshrrev_b32_e32 v46, 8, v118
	v_lshrrev_b32_e32 v47, 16, v118
	v_perm_b32 v44, v114, v44, s33
	v_perm_b32 v46, v115, v46, s33
	v_perm_b32 v47, v115, v47, s8
	v_pk_fma_f32 v[94:95], v[94:95], v[174:175], v[44:45]
	v_pk_fma_f32 v[96:97], v[96:97], v[176:177], v[46:47]
	v_lshlrev_b32_e32 v44, 8, v119
	v_perm_b32 v45, v116, v119, s8
	v_lshrrev_b32_e32 v46, 8, v119
	v_lshrrev_b32_e32 v47, 16, v119
	v_perm_b32 v44, v116, v44, s33
	v_perm_b32 v46, v117, v46, s33
	v_perm_b32 v47, v117, v47, s8
	v_pk_fma_f32 v[90:91], v[90:91], v[178:179], v[44:45]
	v_pk_fma_f32 v[92:93], v[92:93], v[180:181], v[46:47]
	v_lshlrev_b32_e32 v44, 8, v124
	v_perm_b32 v45, v120, v124, s8
	v_lshrrev_b32_e32 v46, 8, v124
	v_lshrrev_b32_e32 v47, 16, v124
	v_perm_b32 v44, v120, v44, s33
	v_perm_b32 v46, v121, v46, s33
	v_perm_b32 v47, v121, v47, s8
	v_pk_fma_f32 v[86:87], v[86:87], v[182:183], v[44:45]
	v_pk_fma_f32 v[88:89], v[88:89], v[184:185], v[46:47]
	v_lshlrev_b32_e32 v44, 8, v125
	v_perm_b32 v45, v122, v125, s8
	v_lshrrev_b32_e32 v46, 8, v125
	v_lshrrev_b32_e32 v47, 16, v125
	v_perm_b32 v44, v122, v44, s33
	v_perm_b32 v46, v123, v46, s33
	v_perm_b32 v47, v123, v47, s8
	v_pk_fma_f32 v[82:83], v[82:83], v[186:187], v[44:45]
	v_pk_fma_f32 v[84:85], v[84:85], v[188:189], v[46:47]
	v_add_u32_e32 v44, 0x80, v94
	v_add_u32_e32 v45, 0x80, v95
	v_add_u32_e32 v46, 0x80, v96
	v_add_u32_e32 v47, 0x80, v97
	v_perm_b32 v48, v45, v44, s78
	v_perm_b32 v49, v47, v46, s78
	v_perm_b32 v42, v45, v44, s79
	v_perm_b32 v43, v47, v46, s79
	v_perm_b32 v56, v43, v42, s60
	v_add_u32_e32 v44, 0x80, v90
	v_add_u32_e32 v45, 0x80, v91
	v_add_u32_e32 v46, 0x80, v92
	v_add_u32_e32 v47, 0x80, v93
	v_perm_b32 v50, v45, v44, s78
	v_perm_b32 v51, v47, v46, s78
	v_perm_b32 v42, v45, v44, s79
	v_perm_b32 v43, v47, v46, s79
	v_perm_b32 v57, v43, v42, s60
	v_add_u32_e32 v44, 0x80, v86
	v_add_u32_e32 v45, 0x80, v87
	v_add_u32_e32 v46, 0x80, v88
	v_add_u32_e32 v47, 0x80, v89
	v_perm_b32 v52, v45, v44, s78
	v_perm_b32 v53, v47, v46, s78
	v_perm_b32 v42, v45, v44, s79
	v_perm_b32 v43, v47, v46, s79
	v_perm_b32 v168, v43, v42, s60
	v_add_u32_e32 v44, 0x80, v82
	v_add_u32_e32 v45, 0x80, v83
	v_add_u32_e32 v46, 0x80, v84
	v_add_u32_e32 v47, 0x80, v85
	v_perm_b32 v54, v45, v44, s78
	v_perm_b32 v55, v47, v46, s78
	v_perm_b32 v42, v45, v44, s79
	v_perm_b32 v43, v47, v46, s79
	v_perm_b32 v169, v43, v42, s60
	v_mov_b32_dpp v114, v48 quad_perm:[1,0,3,2] row_mask:0xf bank_mask:0xf
	v_mov_b32_dpp v115, v49 quad_perm:[1,0,3,2] row_mask:0xf bank_mask:0xf
	v_mov_b32_dpp v116, v50 quad_perm:[1,0,3,2] row_mask:0xf bank_mask:0xf
	v_mov_b32_dpp v117, v51 quad_perm:[1,0,3,2] row_mask:0xf bank_mask:0xf
	v_mov_b32_dpp v120, v52 quad_perm:[1,0,3,2] row_mask:0xf bank_mask:0xf
	v_mov_b32_dpp v121, v53 quad_perm:[1,0,3,2] row_mask:0xf bank_mask:0xf
	v_mov_b32_dpp v122, v54 quad_perm:[1,0,3,2] row_mask:0xf bank_mask:0xf
	v_mov_b32_dpp v123, v55 quad_perm:[1,0,3,2] row_mask:0xf bank_mask:0xf
	s_mov_b64 exec, s[62:63]
	v_mov_b32_e32 v48, v120
	v_mov_b32_e32 v49, v121
	v_mov_b32_e32 v50, v122
	v_mov_b32_e32 v51, v123
	s_mov_b64 exec, s[66:67]
	v_mov_b32_e32 v52, v114
	v_mov_b32_e32 v53, v115
	v_mov_b32_e32 v54, v116
	v_mov_b32_e32 v55, v117
	s_mov_b64 exec, -1
	v_mov_b32_dpp v114, v56 quad_perm:[1,0,3,2] row_mask:0xf bank_mask:0xf
	v_mov_b32_dpp v115, v57 quad_perm:[1,0,3,2] row_mask:0xf bank_mask:0xf
	v_mov_b32_dpp v120, v168 quad_perm:[1,0,3,2] row_mask:0xf bank_mask:0xf
	v_mov_b32_dpp v121, v169 quad_perm:[1,0,3,2] row_mask:0xf bank_mask:0xf
	s_mov_b64 exec, s[62:63]
	v_mov_b32_e32 v56, v120
	v_mov_b32_e32 v57, v121
	s_mov_b64 exec, s[66:67]
	v_mov_b32_e32 v168, v114
	v_mov_b32_e32 v169, v115
	s_mov_b64 exec, -1
	s_add_u32 s88, s58, 0x18000
	s_addc_u32 s89, s59, 0
	s_add_u32 s90, s74, 0xc000
	s_addc_u32 s91, s75, 0
	global_store_dwordx4 v171, v[48:51], s[88:89]
	global_store_dwordx4 v171, v[52:55], s[88:89] offset:2048
	global_store_dwordx2 v170, v[56:57], s[90:91]
	global_store_dwordx2 v170, v[168:169], s[90:91] offset:1024
	s_add_u32 s84, s58, 0x48000
	s_addc_u32 s85, s59, 0
	s_add_u32 s86, s74, 0x24000
	s_addc_u32 s87, s75, 0
	global_load_dwordx4 v[82:85], v171, s[84:85]
	global_load_dwordx2 v[86:87], v170, s[86:87]
	global_load_dwordx4 v[88:91], v171, s[84:85] offset:2048
	global_load_dwordx2 v[92:93], v170, s[86:87] offset:1024
	s_waitcnt vmcnt(8)
	v_mov_b32_dpp v48, v98 quad_perm:[1,0,3,2] row_mask:0xf bank_mask:0xf
	v_mov_b32_dpp v49, v99 quad_perm:[1,0,3,2] row_mask:0xf bank_mask:0xf
	v_mov_b32_dpp v50, v100 quad_perm:[1,0,3,2] row_mask:0xf bank_mask:0xf
	v_mov_b32_dpp v51, v101 quad_perm:[1,0,3,2] row_mask:0xf bank_mask:0xf
	v_mov_b32_dpp v52, v104 quad_perm:[1,0,3,2] row_mask:0xf bank_mask:0xf
	v_mov_b32_dpp v53, v105 quad_perm:[1,0,3,2] row_mask:0xf bank_mask:0xf
	v_mov_b32_dpp v54, v106 quad_perm:[1,0,3,2] row_mask:0xf bank_mask:0xf
	v_mov_b32_dpp v55, v107 quad_perm:[1,0,3,2] row_mask:0xf bank_mask:0xf
	s_mov_b64 exec, s[62:63]
	v_mov_b32_e32 v98, v52
	v_mov_b32_e32 v99, v53
	v_mov_b32_e32 v100, v54
	v_mov_b32_e32 v101, v55
	s_mov_b64 exec, s[66:67]
	v_mov_b32_e32 v104, v48
	v_mov_b32_e32 v105, v49
	v_mov_b32_e32 v106, v50
	v_mov_b32_e32 v107, v51
	s_mov_b64 exec, -1
	v_mov_b32_dpp v48, v102 quad_perm:[1,0,3,2] row_mask:0xf bank_mask:0xf
	v_mov_b32_dpp v49, v103 quad_perm:[1,0,3,2] row_mask:0xf bank_mask:0xf
	v_mov_b32_dpp v52, v108 quad_perm:[1,0,3,2] row_mask:0xf bank_mask:0xf
	v_mov_b32_dpp v53, v109 quad_perm:[1,0,3,2] row_mask:0xf bank_mask:0xf
	s_mov_b64 exec, s[62:63]
	v_mov_b32_e32 v102, v52
	v_mov_b32_e32 v103, v53
	s_mov_b64 exec, s[66:67]
	v_mov_b32_e32 v108, v48
	v_mov_b32_e32 v109, v49
	s_mov_b64 exec, -1
	v_lshlrev_b32_e32 v44, 8, v102
	v_perm_b32 v45, v98, v102, s8
	v_lshrrev_b32_e32 v46, 8, v102
	v_lshrrev_b32_e32 v47, 16, v102
	v_perm_b32 v44, v98, v44, s33
	v_perm_b32 v46, v99, v46, s33
	v_perm_b32 v47, v99, v47, s8
	v_pk_fma_f32 v[78:79], v[78:79], v[174:175], v[44:45]
	v_pk_fma_f32 v[80:81], v[80:81], v[176:177], v[46:47]
	v_lshlrev_b32_e32 v44, 8, v103
	v_perm_b32 v45, v100, v103, s8
	v_lshrrev_b32_e32 v46, 8, v103
	v_lshrrev_b32_e32 v47, 16, v103
	v_perm_b32 v44, v100, v44, s33
	v_perm_b32 v46, v101, v46, s33
	v_perm_b32 v47, v101, v47, s8
	v_pk_fma_f32 v[74:75], v[74:75], v[178:179], v[44:45]
	v_pk_fma_f32 v[76:77], v[76:77], v[180:181], v[46:47]
	v_lshlrev_b32_e32 v44, 8, v108
	v_perm_b32 v45, v104, v108, s8
	v_lshrrev_b32_e32 v46, 8, v108
	v_lshrrev_b32_e32 v47, 16, v108
	v_perm_b32 v44, v104, v44, s33
	v_perm_b32 v46, v105, v46, s33
	v_perm_b32 v47, v105, v47, s8
	v_pk_fma_f32 v[70:71], v[70:71], v[182:183], v[44:45]
	v_pk_fma_f32 v[72:73], v[72:73], v[184:185], v[46:47]
	v_lshlrev_b32_e32 v44, 8, v109
	v_perm_b32 v45, v106, v109, s8
	v_lshrrev_b32_e32 v46, 8, v109
	v_lshrrev_b32_e32 v47, 16, v109
	v_perm_b32 v44, v106, v44, s33
	v_perm_b32 v46, v107, v46, s33
	v_perm_b32 v47, v107, v47, s8
	v_pk_fma_f32 v[66:67], v[66:67], v[186:187], v[44:45]
	v_pk_fma_f32 v[68:69], v[68:69], v[188:189], v[46:47]
	v_add_u32_e32 v44, 0x80, v78
	v_add_u32_e32 v45, 0x80, v79
	v_add_u32_e32 v46, 0x80, v80
	v_add_u32_e32 v47, 0x80, v81
	v_perm_b32 v48, v45, v44, s78
	v_perm_b32 v49, v47, v46, s78
	v_perm_b32 v42, v45, v44, s79
	v_perm_b32 v43, v47, v46, s79
	v_perm_b32 v56, v43, v42, s60
	v_add_u32_e32 v44, 0x80, v74
	v_add_u32_e32 v45, 0x80, v75
	v_add_u32_e32 v46, 0x80, v76
	v_add_u32_e32 v47, 0x80, v77
	v_perm_b32 v50, v45, v44, s78
	v_perm_b32 v51, v47, v46, s78
	v_perm_b32 v42, v45, v44, s79
	v_perm_b32 v43, v47, v46, s79
	v_perm_b32 v57, v43, v42, s60
	v_add_u32_e32 v44, 0x80, v70
	v_add_u32_e32 v45, 0x80, v71
	v_add_u32_e32 v46, 0x80, v72
	v_add_u32_e32 v47, 0x80, v73
	v_perm_b32 v52, v45, v44, s78
	v_perm_b32 v53, v47, v46, s78
	v_perm_b32 v42, v45, v44, s79
	v_perm_b32 v43, v47, v46, s79
	v_perm_b32 v168, v43, v42, s60
	v_add_u32_e32 v44, 0x80, v66
	v_add_u32_e32 v45, 0x80, v67
	v_add_u32_e32 v46, 0x80, v68
	v_add_u32_e32 v47, 0x80, v69
	v_perm_b32 v54, v45, v44, s78
	v_perm_b32 v55, v47, v46, s78
	v_perm_b32 v42, v45, v44, s79
	v_perm_b32 v43, v47, v46, s79
	v_perm_b32 v169, v43, v42, s60
	v_mov_b32_dpp v98, v48 quad_perm:[1,0,3,2] row_mask:0xf bank_mask:0xf
	v_mov_b32_dpp v99, v49 quad_perm:[1,0,3,2] row_mask:0xf bank_mask:0xf
	v_mov_b32_dpp v100, v50 quad_perm:[1,0,3,2] row_mask:0xf bank_mask:0xf
	v_mov_b32_dpp v101, v51 quad_perm:[1,0,3,2] row_mask:0xf bank_mask:0xf
	v_mov_b32_dpp v104, v52 quad_perm:[1,0,3,2] row_mask:0xf bank_mask:0xf
	v_mov_b32_dpp v105, v53 quad_perm:[1,0,3,2] row_mask:0xf bank_mask:0xf
	v_mov_b32_dpp v106, v54 quad_perm:[1,0,3,2] row_mask:0xf bank_mask:0xf
	v_mov_b32_dpp v107, v55 quad_perm:[1,0,3,2] row_mask:0xf bank_mask:0xf
	s_mov_b64 exec, s[62:63]
	v_mov_b32_e32 v48, v104
	v_mov_b32_e32 v49, v105
	v_mov_b32_e32 v50, v106
	v_mov_b32_e32 v51, v107
	s_mov_b64 exec, s[66:67]
	v_mov_b32_e32 v52, v98
	v_mov_b32_e32 v53, v99
	v_mov_b32_e32 v54, v100
	v_mov_b32_e32 v55, v101
	s_mov_b64 exec, -1
	v_mov_b32_dpp v98, v56 quad_perm:[1,0,3,2] row_mask:0xf bank_mask:0xf
	v_mov_b32_dpp v99, v57 quad_perm:[1,0,3,2] row_mask:0xf bank_mask:0xf
	v_mov_b32_dpp v104, v168 quad_perm:[1,0,3,2] row_mask:0xf bank_mask:0xf
	v_mov_b32_dpp v105, v169 quad_perm:[1,0,3,2] row_mask:0xf bank_mask:0xf
	s_mov_b64 exec, s[62:63]
	v_mov_b32_e32 v56, v104
	v_mov_b32_e32 v57, v105
	s_mov_b64 exec, s[66:67]
	v_mov_b32_e32 v168, v98
	v_mov_b32_e32 v169, v99
	s_mov_b64 exec, -1
	s_add_u32 s88, s58, 0x40000
	s_addc_u32 s89, s59, 0
	s_add_u32 s90, s74, 0x20000
	s_addc_u32 s91, s75, 0
	global_store_dwordx4 v171, v[48:51], s[88:89]
	global_store_dwordx4 v171, v[52:55], s[88:89] offset:2048
	global_store_dwordx2 v170, v[56:57], s[90:91]
	global_store_dwordx2 v170, v[168:169], s[90:91] offset:1024
	s_add_u32 s84, s58, 0x50000
	s_addc_u32 s85, s59, 0
	s_add_u32 s86, s74, 0x28000
	s_addc_u32 s87, s75, 0
	global_load_dwordx4 v[66:69], v171, s[84:85]
	global_load_dwordx2 v[70:71], v170, s[86:87]
	global_load_dwordx4 v[72:75], v171, s[84:85] offset:2048
	global_load_dwordx2 v[76:77], v170, s[86:87] offset:1024
	s_waitcnt vmcnt(8)
	v_mov_b32_dpp v48, v82 quad_perm:[1,0,3,2] row_mask:0xf bank_mask:0xf
	v_mov_b32_dpp v49, v83 quad_perm:[1,0,3,2] row_mask:0xf bank_mask:0xf
	v_mov_b32_dpp v50, v84 quad_perm:[1,0,3,2] row_mask:0xf bank_mask:0xf
	v_mov_b32_dpp v51, v85 quad_perm:[1,0,3,2] row_mask:0xf bank_mask:0xf
	v_mov_b32_dpp v52, v88 quad_perm:[1,0,3,2] row_mask:0xf bank_mask:0xf
	v_mov_b32_dpp v53, v89 quad_perm:[1,0,3,2] row_mask:0xf bank_mask:0xf
	v_mov_b32_dpp v54, v90 quad_perm:[1,0,3,2] row_mask:0xf bank_mask:0xf
	v_mov_b32_dpp v55, v91 quad_perm:[1,0,3,2] row_mask:0xf bank_mask:0xf
	s_mov_b64 exec, s[62:63]
	v_mov_b32_e32 v82, v52
	v_mov_b32_e32 v83, v53
	v_mov_b32_e32 v84, v54
	v_mov_b32_e32 v85, v55
	s_mov_b64 exec, s[66:67]
	v_mov_b32_e32 v88, v48
	v_mov_b32_e32 v89, v49
	v_mov_b32_e32 v90, v50
	v_mov_b32_e32 v91, v51
	s_mov_b64 exec, -1
	v_mov_b32_dpp v48, v86 quad_perm:[1,0,3,2] row_mask:0xf bank_mask:0xf
	v_mov_b32_dpp v49, v87 quad_perm:[1,0,3,2] row_mask:0xf bank_mask:0xf
	v_mov_b32_dpp v52, v92 quad_perm:[1,0,3,2] row_mask:0xf bank_mask:0xf
	v_mov_b32_dpp v53, v93 quad_perm:[1,0,3,2] row_mask:0xf bank_mask:0xf
	s_mov_b64 exec, s[62:63]
	v_mov_b32_e32 v86, v52
	v_mov_b32_e32 v87, v53
	s_mov_b64 exec, s[66:67]
	v_mov_b32_e32 v92, v48
	v_mov_b32_e32 v93, v49
	s_mov_b64 exec, -1
	v_lshlrev_b32_e32 v44, 8, v86
	v_perm_b32 v45, v82, v86, s8
	v_lshrrev_b32_e32 v46, 8, v86
	v_lshrrev_b32_e32 v47, 16, v86
	v_perm_b32 v44, v82, v44, s33
	v_perm_b32 v46, v83, v46, s33
	v_perm_b32 v47, v83, v47, s8
	v_pk_fma_f32 v[62:63], v[62:63], v[174:175], v[44:45]
	v_pk_fma_f32 v[64:65], v[64:65], v[176:177], v[46:47]
	v_lshlrev_b32_e32 v44, 8, v87
	v_perm_b32 v45, v84, v87, s8
	v_lshrrev_b32_e32 v46, 8, v87
	v_lshrrev_b32_e32 v47, 16, v87
	v_perm_b32 v44, v84, v44, s33
	v_perm_b32 v46, v85, v46, s33
	v_perm_b32 v47, v85, v47, s8
	v_pk_fma_f32 v[58:59], v[58:59], v[178:179], v[44:45]
	v_pk_fma_f32 v[60:61], v[60:61], v[180:181], v[46:47]
	v_lshlrev_b32_e32 v44, 8, v92
	v_perm_b32 v45, v88, v92, s8
	v_lshrrev_b32_e32 v46, 8, v92
	v_lshrrev_b32_e32 v47, 16, v92
	v_perm_b32 v44, v88, v44, s33
	v_perm_b32 v46, v89, v46, s33
	v_perm_b32 v47, v89, v47, s8
	v_pk_fma_f32 v[38:39], v[38:39], v[182:183], v[44:45]
	v_pk_fma_f32 v[40:41], v[40:41], v[184:185], v[46:47]
	v_lshlrev_b32_e32 v44, 8, v93
	v_perm_b32 v45, v90, v93, s8
	v_lshrrev_b32_e32 v46, 8, v93
	v_lshrrev_b32_e32 v47, 16, v93
	v_perm_b32 v44, v90, v44, s33
	v_perm_b32 v46, v91, v46, s33
	v_perm_b32 v47, v91, v47, s8
	v_pk_fma_f32 v[34:35], v[34:35], v[186:187], v[44:45]
	v_pk_fma_f32 v[36:37], v[36:37], v[188:189], v[46:47]
	v_add_u32_e32 v44, 0x80, v62
	v_add_u32_e32 v45, 0x80, v63
	v_add_u32_e32 v46, 0x80, v64
	v_add_u32_e32 v47, 0x80, v65
	v_perm_b32 v48, v45, v44, s78
	v_perm_b32 v49, v47, v46, s78
	v_perm_b32 v42, v45, v44, s79
	v_perm_b32 v43, v47, v46, s79
	v_perm_b32 v56, v43, v42, s60
	v_add_u32_e32 v44, 0x80, v58
	v_add_u32_e32 v45, 0x80, v59
	v_add_u32_e32 v46, 0x80, v60
	v_add_u32_e32 v47, 0x80, v61
	v_perm_b32 v50, v45, v44, s78
	v_perm_b32 v51, v47, v46, s78
	v_perm_b32 v42, v45, v44, s79
	v_perm_b32 v43, v47, v46, s79
	v_perm_b32 v57, v43, v42, s60
	v_add_u32_e32 v44, 0x80, v38
	v_add_u32_e32 v45, 0x80, v39
	v_add_u32_e32 v46, 0x80, v40
	v_add_u32_e32 v47, 0x80, v41
	v_perm_b32 v52, v45, v44, s78
	v_perm_b32 v53, v47, v46, s78
	v_perm_b32 v42, v45, v44, s79
	v_perm_b32 v43, v47, v46, s79
	v_perm_b32 v168, v43, v42, s60
	v_add_u32_e32 v44, 0x80, v34
	v_add_u32_e32 v45, 0x80, v35
	v_add_u32_e32 v46, 0x80, v36
	v_add_u32_e32 v47, 0x80, v37
	v_perm_b32 v54, v45, v44, s78
	v_perm_b32 v55, v47, v46, s78
	v_perm_b32 v42, v45, v44, s79
	v_perm_b32 v43, v47, v46, s79
	v_perm_b32 v169, v43, v42, s60
	v_mov_b32_dpp v82, v48 quad_perm:[1,0,3,2] row_mask:0xf bank_mask:0xf
	v_mov_b32_dpp v83, v49 quad_perm:[1,0,3,2] row_mask:0xf bank_mask:0xf
	v_mov_b32_dpp v84, v50 quad_perm:[1,0,3,2] row_mask:0xf bank_mask:0xf
	v_mov_b32_dpp v85, v51 quad_perm:[1,0,3,2] row_mask:0xf bank_mask:0xf
	v_mov_b32_dpp v88, v52 quad_perm:[1,0,3,2] row_mask:0xf bank_mask:0xf
	v_mov_b32_dpp v89, v53 quad_perm:[1,0,3,2] row_mask:0xf bank_mask:0xf
	v_mov_b32_dpp v90, v54 quad_perm:[1,0,3,2] row_mask:0xf bank_mask:0xf
	v_mov_b32_dpp v91, v55 quad_perm:[1,0,3,2] row_mask:0xf bank_mask:0xf
	s_mov_b64 exec, s[62:63]
	v_mov_b32_e32 v48, v88
	v_mov_b32_e32 v49, v89
	v_mov_b32_e32 v50, v90
	v_mov_b32_e32 v51, v91
	s_mov_b64 exec, s[66:67]
	v_mov_b32_e32 v52, v82
	v_mov_b32_e32 v53, v83
	v_mov_b32_e32 v54, v84
	v_mov_b32_e32 v55, v85
	s_mov_b64 exec, -1
	v_mov_b32_dpp v82, v56 quad_perm:[1,0,3,2] row_mask:0xf bank_mask:0xf
	v_mov_b32_dpp v83, v57 quad_perm:[1,0,3,2] row_mask:0xf bank_mask:0xf
	v_mov_b32_dpp v88, v168 quad_perm:[1,0,3,2] row_mask:0xf bank_mask:0xf
	v_mov_b32_dpp v89, v169 quad_perm:[1,0,3,2] row_mask:0xf bank_mask:0xf
	s_mov_b64 exec, s[62:63]
	v_mov_b32_e32 v56, v88
	v_mov_b32_e32 v57, v89
	s_mov_b64 exec, s[66:67]
	v_mov_b32_e32 v168, v82
	v_mov_b32_e32 v169, v83
	s_mov_b64 exec, -1
	s_add_u32 s88, s58, 0x48000
	s_addc_u32 s89, s59, 0
	s_add_u32 s90, s74, 0x24000
	s_addc_u32 s91, s75, 0
	global_store_dwordx4 v171, v[48:51], s[88:89]
	global_store_dwordx4 v171, v[52:55], s[88:89] offset:2048
	global_store_dwordx2 v170, v[56:57], s[90:91]
	global_store_dwordx2 v170, v[168:169], s[90:91] offset:1024
	s_add_u32 s84, s58, 0x58000
	s_addc_u32 s85, s59, 0
	s_add_u32 s86, s74, 0x2c000
	s_addc_u32 s87, s75, 0
	global_load_dwordx4 v[34:37], v171, s[84:85]
	global_load_dwordx2 v[38:39], v170, s[86:87]
	global_load_dwordx4 v[58:61], v171, s[84:85] offset:2048
	global_load_dwordx2 v[40:41], v170, s[86:87] offset:1024
	s_waitcnt vmcnt(8)
	v_mov_b32_dpp v48, v66 quad_perm:[1,0,3,2] row_mask:0xf bank_mask:0xf
	v_mov_b32_dpp v49, v67 quad_perm:[1,0,3,2] row_mask:0xf bank_mask:0xf
	v_mov_b32_dpp v50, v68 quad_perm:[1,0,3,2] row_mask:0xf bank_mask:0xf
	v_mov_b32_dpp v51, v69 quad_perm:[1,0,3,2] row_mask:0xf bank_mask:0xf
	v_mov_b32_dpp v52, v72 quad_perm:[1,0,3,2] row_mask:0xf bank_mask:0xf
	v_mov_b32_dpp v53, v73 quad_perm:[1,0,3,2] row_mask:0xf bank_mask:0xf
	v_mov_b32_dpp v54, v74 quad_perm:[1,0,3,2] row_mask:0xf bank_mask:0xf
	v_mov_b32_dpp v55, v75 quad_perm:[1,0,3,2] row_mask:0xf bank_mask:0xf
	s_mov_b64 exec, s[62:63]
	v_mov_b32_e32 v66, v52
	v_mov_b32_e32 v67, v53
	v_mov_b32_e32 v68, v54
	v_mov_b32_e32 v69, v55
	s_mov_b64 exec, s[66:67]
	v_mov_b32_e32 v72, v48
	v_mov_b32_e32 v73, v49
	v_mov_b32_e32 v74, v50
	v_mov_b32_e32 v75, v51
	s_mov_b64 exec, -1
	v_mov_b32_dpp v48, v70 quad_perm:[1,0,3,2] row_mask:0xf bank_mask:0xf
	v_mov_b32_dpp v49, v71 quad_perm:[1,0,3,2] row_mask:0xf bank_mask:0xf
	v_mov_b32_dpp v52, v76 quad_perm:[1,0,3,2] row_mask:0xf bank_mask:0xf
	v_mov_b32_dpp v53, v77 quad_perm:[1,0,3,2] row_mask:0xf bank_mask:0xf
	s_mov_b64 exec, s[62:63]
	v_mov_b32_e32 v70, v52
	v_mov_b32_e32 v71, v53
	s_mov_b64 exec, s[66:67]
	v_mov_b32_e32 v76, v48
	v_mov_b32_e32 v77, v49
	s_mov_b64 exec, -1
	v_lshlrev_b32_e32 v44, 8, v70
	v_perm_b32 v45, v66, v70, s8
	v_lshrrev_b32_e32 v46, 8, v70
	v_lshrrev_b32_e32 v47, 16, v70
	v_perm_b32 v44, v66, v44, s33
	v_perm_b32 v46, v67, v46, s33
	v_perm_b32 v47, v67, v47, s8
	v_pk_fma_f32 v[30:31], v[30:31], v[174:175], v[44:45]
	v_pk_fma_f32 v[32:33], v[32:33], v[176:177], v[46:47]
	v_lshlrev_b32_e32 v44, 8, v71
	v_perm_b32 v45, v68, v71, s8
	v_lshrrev_b32_e32 v46, 8, v71
	v_lshrrev_b32_e32 v47, 16, v71
	v_perm_b32 v44, v68, v44, s33
	v_perm_b32 v46, v69, v46, s33
	v_perm_b32 v47, v69, v47, s8
	v_pk_fma_f32 v[26:27], v[26:27], v[178:179], v[44:45]
	v_pk_fma_f32 v[28:29], v[28:29], v[180:181], v[46:47]
	v_lshlrev_b32_e32 v44, 8, v76
	v_perm_b32 v45, v72, v76, s8
	v_lshrrev_b32_e32 v46, 8, v76
	v_lshrrev_b32_e32 v47, 16, v76
	v_perm_b32 v44, v72, v44, s33
	v_perm_b32 v46, v73, v46, s33
	v_perm_b32 v47, v73, v47, s8
	v_pk_fma_f32 v[22:23], v[22:23], v[182:183], v[44:45]
	v_pk_fma_f32 v[24:25], v[24:25], v[184:185], v[46:47]
	v_lshlrev_b32_e32 v44, 8, v77
	v_perm_b32 v45, v74, v77, s8
	v_lshrrev_b32_e32 v46, 8, v77
	v_lshrrev_b32_e32 v47, 16, v77
	v_perm_b32 v44, v74, v44, s33
	v_perm_b32 v46, v75, v46, s33
	v_perm_b32 v47, v75, v47, s8
	v_pk_fma_f32 v[18:19], v[18:19], v[186:187], v[44:45]
	v_pk_fma_f32 v[20:21], v[20:21], v[188:189], v[46:47]
	v_add_u32_e32 v44, 0x80, v30
	v_add_u32_e32 v45, 0x80, v31
	v_add_u32_e32 v46, 0x80, v32
	v_add_u32_e32 v47, 0x80, v33
	v_perm_b32 v48, v45, v44, s78
	v_perm_b32 v49, v47, v46, s78
	v_perm_b32 v42, v45, v44, s79
	v_perm_b32 v43, v47, v46, s79
	v_perm_b32 v56, v43, v42, s60
	v_add_u32_e32 v44, 0x80, v26
	v_add_u32_e32 v45, 0x80, v27
	v_add_u32_e32 v46, 0x80, v28
	v_add_u32_e32 v47, 0x80, v29
	v_perm_b32 v50, v45, v44, s78
	v_perm_b32 v51, v47, v46, s78
	v_perm_b32 v42, v45, v44, s79
	v_perm_b32 v43, v47, v46, s79
	v_perm_b32 v57, v43, v42, s60
	v_add_u32_e32 v44, 0x80, v22
	v_add_u32_e32 v45, 0x80, v23
	v_add_u32_e32 v46, 0x80, v24
	v_add_u32_e32 v47, 0x80, v25
	v_perm_b32 v52, v45, v44, s78
	v_perm_b32 v53, v47, v46, s78
	v_perm_b32 v42, v45, v44, s79
	v_perm_b32 v43, v47, v46, s79
	v_perm_b32 v168, v43, v42, s60
	v_add_u32_e32 v44, 0x80, v18
	v_add_u32_e32 v45, 0x80, v19
	v_add_u32_e32 v46, 0x80, v20
	v_add_u32_e32 v47, 0x80, v21
	v_perm_b32 v54, v45, v44, s78
	v_perm_b32 v55, v47, v46, s78
	v_perm_b32 v42, v45, v44, s79
	v_perm_b32 v43, v47, v46, s79
	v_perm_b32 v169, v43, v42, s60
	v_mov_b32_dpp v66, v48 quad_perm:[1,0,3,2] row_mask:0xf bank_mask:0xf
	v_mov_b32_dpp v67, v49 quad_perm:[1,0,3,2] row_mask:0xf bank_mask:0xf
	v_mov_b32_dpp v68, v50 quad_perm:[1,0,3,2] row_mask:0xf bank_mask:0xf
	v_mov_b32_dpp v69, v51 quad_perm:[1,0,3,2] row_mask:0xf bank_mask:0xf
	v_mov_b32_dpp v72, v52 quad_perm:[1,0,3,2] row_mask:0xf bank_mask:0xf
	v_mov_b32_dpp v73, v53 quad_perm:[1,0,3,2] row_mask:0xf bank_mask:0xf
	v_mov_b32_dpp v74, v54 quad_perm:[1,0,3,2] row_mask:0xf bank_mask:0xf
	v_mov_b32_dpp v75, v55 quad_perm:[1,0,3,2] row_mask:0xf bank_mask:0xf
	s_mov_b64 exec, s[62:63]
	v_mov_b32_e32 v48, v72
	v_mov_b32_e32 v49, v73
	v_mov_b32_e32 v50, v74
	v_mov_b32_e32 v51, v75
	s_mov_b64 exec, s[66:67]
	v_mov_b32_e32 v52, v66
	v_mov_b32_e32 v53, v67
	v_mov_b32_e32 v54, v68
	v_mov_b32_e32 v55, v69
	s_mov_b64 exec, -1
	v_mov_b32_dpp v66, v56 quad_perm:[1,0,3,2] row_mask:0xf bank_mask:0xf
	v_mov_b32_dpp v67, v57 quad_perm:[1,0,3,2] row_mask:0xf bank_mask:0xf
	v_mov_b32_dpp v72, v168 quad_perm:[1,0,3,2] row_mask:0xf bank_mask:0xf
	v_mov_b32_dpp v73, v169 quad_perm:[1,0,3,2] row_mask:0xf bank_mask:0xf
	s_mov_b64 exec, s[62:63]
	v_mov_b32_e32 v56, v72
	v_mov_b32_e32 v57, v73
	s_mov_b64 exec, s[66:67]
	v_mov_b32_e32 v168, v66
	v_mov_b32_e32 v169, v67
	s_mov_b64 exec, -1
	s_add_u32 s88, s58, 0x50000
	s_addc_u32 s89, s59, 0
	s_add_u32 s90, s74, 0x28000
	s_addc_u32 s91, s75, 0
	global_store_dwordx4 v171, v[48:51], s[88:89]
	global_store_dwordx4 v171, v[52:55], s[88:89] offset:2048
	global_store_dwordx2 v170, v[56:57], s[90:91]
	global_store_dwordx2 v170, v[168:169], s[90:91] offset:1024
	s_waitcnt vmcnt(4)
	v_mov_b32_dpp v48, v34 quad_perm:[1,0,3,2] row_mask:0xf bank_mask:0xf
	v_mov_b32_dpp v49, v35 quad_perm:[1,0,3,2] row_mask:0xf bank_mask:0xf
	v_mov_b32_dpp v50, v36 quad_perm:[1,0,3,2] row_mask:0xf bank_mask:0xf
	v_mov_b32_dpp v51, v37 quad_perm:[1,0,3,2] row_mask:0xf bank_mask:0xf
	v_mov_b32_dpp v52, v58 quad_perm:[1,0,3,2] row_mask:0xf bank_mask:0xf
	v_mov_b32_dpp v53, v59 quad_perm:[1,0,3,2] row_mask:0xf bank_mask:0xf
	v_mov_b32_dpp v54, v60 quad_perm:[1,0,3,2] row_mask:0xf bank_mask:0xf
	v_mov_b32_dpp v55, v61 quad_perm:[1,0,3,2] row_mask:0xf bank_mask:0xf
	s_mov_b64 exec, s[62:63]
	v_mov_b32_e32 v34, v52
	v_mov_b32_e32 v35, v53
	v_mov_b32_e32 v36, v54
	v_mov_b32_e32 v37, v55
	s_mov_b64 exec, s[66:67]
	v_mov_b32_e32 v58, v48
	v_mov_b32_e32 v59, v49
	v_mov_b32_e32 v60, v50
	v_mov_b32_e32 v61, v51
	s_mov_b64 exec, -1
	v_mov_b32_dpp v48, v38 quad_perm:[1,0,3,2] row_mask:0xf bank_mask:0xf
	v_mov_b32_dpp v49, v39 quad_perm:[1,0,3,2] row_mask:0xf bank_mask:0xf
	v_mov_b32_dpp v52, v40 quad_perm:[1,0,3,2] row_mask:0xf bank_mask:0xf
	v_mov_b32_dpp v53, v41 quad_perm:[1,0,3,2] row_mask:0xf bank_mask:0xf
	s_mov_b64 exec, s[62:63]
	v_mov_b32_e32 v38, v52
	v_mov_b32_e32 v39, v53
	s_mov_b64 exec, s[66:67]
	v_mov_b32_e32 v40, v48
	v_mov_b32_e32 v41, v49
	s_mov_b64 exec, -1
	v_lshlrev_b32_e32 v44, 8, v38
	v_perm_b32 v45, v34, v38, s8
	v_lshrrev_b32_e32 v46, 8, v38
	v_lshrrev_b32_e32 v47, 16, v38
	v_perm_b32 v44, v34, v44, s33
	v_perm_b32 v46, v35, v46, s33
	v_perm_b32 v47, v35, v47, s8
	v_pk_fma_f32 v[14:15], v[14:15], v[174:175], v[44:45]
	v_pk_fma_f32 v[16:17], v[16:17], v[176:177], v[46:47]
	v_lshlrev_b32_e32 v44, 8, v39
	v_perm_b32 v45, v36, v39, s8
	v_lshrrev_b32_e32 v46, 8, v39
	v_lshrrev_b32_e32 v47, 16, v39
	v_perm_b32 v44, v36, v44, s33
	v_perm_b32 v46, v37, v46, s33
	v_perm_b32 v47, v37, v47, s8
	v_pk_fma_f32 v[10:11], v[10:11], v[178:179], v[44:45]
	v_pk_fma_f32 v[12:13], v[12:13], v[180:181], v[46:47]
	v_lshlrev_b32_e32 v44, 8, v40
	v_perm_b32 v45, v58, v40, s8
	v_lshrrev_b32_e32 v46, 8, v40
	v_lshrrev_b32_e32 v47, 16, v40
	v_perm_b32 v44, v58, v44, s33
	v_perm_b32 v46, v59, v46, s33
	v_perm_b32 v47, v59, v47, s8
	v_pk_fma_f32 v[6:7], v[6:7], v[182:183], v[44:45]
	v_pk_fma_f32 v[8:9], v[8:9], v[184:185], v[46:47]
	v_lshlrev_b32_e32 v44, 8, v41
	v_perm_b32 v45, v60, v41, s8
	v_lshrrev_b32_e32 v46, 8, v41
	v_lshrrev_b32_e32 v47, 16, v41
	v_perm_b32 v44, v60, v44, s33
	v_perm_b32 v46, v61, v46, s33
	v_perm_b32 v47, v61, v47, s8
	v_pk_fma_f32 v[2:3], v[2:3], v[186:187], v[44:45]
	v_pk_fma_f32 v[4:5], v[4:5], v[188:189], v[46:47]
	v_add_u32_e32 v44, 0x80, v14
	v_add_u32_e32 v45, 0x80, v15
	v_add_u32_e32 v46, 0x80, v16
	v_add_u32_e32 v47, 0x80, v17
	v_perm_b32 v48, v45, v44, s78
	v_perm_b32 v49, v47, v46, s78
	v_perm_b32 v42, v45, v44, s79
	v_perm_b32 v43, v47, v46, s79
	v_perm_b32 v56, v43, v42, s60
	v_add_u32_e32 v44, 0x80, v10
	v_add_u32_e32 v45, 0x80, v11
	v_add_u32_e32 v46, 0x80, v12
	v_add_u32_e32 v47, 0x80, v13
	v_perm_b32 v50, v45, v44, s78
	v_perm_b32 v51, v47, v46, s78
	v_perm_b32 v42, v45, v44, s79
	v_perm_b32 v43, v47, v46, s79
	v_perm_b32 v57, v43, v42, s60
	v_add_u32_e32 v44, 0x80, v6
	v_add_u32_e32 v45, 0x80, v7
	v_add_u32_e32 v46, 0x80, v8
	v_add_u32_e32 v47, 0x80, v9
	v_perm_b32 v52, v45, v44, s78
	v_perm_b32 v53, v47, v46, s78
	v_perm_b32 v42, v45, v44, s79
	v_perm_b32 v43, v47, v46, s79
	v_perm_b32 v168, v43, v42, s60
	v_add_u32_e32 v44, 0x80, v2
	v_add_u32_e32 v45, 0x80, v3
	v_add_u32_e32 v46, 0x80, v4
	v_add_u32_e32 v47, 0x80, v5
	v_perm_b32 v54, v45, v44, s78
	v_perm_b32 v55, v47, v46, s78
	v_perm_b32 v42, v45, v44, s79
	v_perm_b32 v43, v47, v46, s79
	v_perm_b32 v169, v43, v42, s60
	v_mov_b32_dpp v34, v48 quad_perm:[1,0,3,2] row_mask:0xf bank_mask:0xf
	v_mov_b32_dpp v35, v49 quad_perm:[1,0,3,2] row_mask:0xf bank_mask:0xf
	v_mov_b32_dpp v36, v50 quad_perm:[1,0,3,2] row_mask:0xf bank_mask:0xf
	v_mov_b32_dpp v37, v51 quad_perm:[1,0,3,2] row_mask:0xf bank_mask:0xf
	v_mov_b32_dpp v58, v52 quad_perm:[1,0,3,2] row_mask:0xf bank_mask:0xf
	v_mov_b32_dpp v59, v53 quad_perm:[1,0,3,2] row_mask:0xf bank_mask:0xf
	v_mov_b32_dpp v60, v54 quad_perm:[1,0,3,2] row_mask:0xf bank_mask:0xf
	v_mov_b32_dpp v61, v55 quad_perm:[1,0,3,2] row_mask:0xf bank_mask:0xf
	s_mov_b64 exec, s[62:63]
	v_mov_b32_e32 v48, v58
	v_mov_b32_e32 v49, v59
	v_mov_b32_e32 v50, v60
	v_mov_b32_e32 v51, v61
	s_mov_b64 exec, s[66:67]
	v_mov_b32_e32 v52, v34
	v_mov_b32_e32 v53, v35
	v_mov_b32_e32 v54, v36
	v_mov_b32_e32 v55, v37
	s_mov_b64 exec, -1
	v_mov_b32_dpp v34, v56 quad_perm:[1,0,3,2] row_mask:0xf bank_mask:0xf
	v_mov_b32_dpp v35, v57 quad_perm:[1,0,3,2] row_mask:0xf bank_mask:0xf
	v_mov_b32_dpp v58, v168 quad_perm:[1,0,3,2] row_mask:0xf bank_mask:0xf
	v_mov_b32_dpp v59, v169 quad_perm:[1,0,3,2] row_mask:0xf bank_mask:0xf
	s_mov_b64 exec, s[62:63]
	v_mov_b32_e32 v56, v58
	v_mov_b32_e32 v57, v59
	s_mov_b64 exec, s[66:67]
	v_mov_b32_e32 v168, v34
	v_mov_b32_e32 v169, v35
	s_mov_b64 exec, -1
	s_add_u32 s88, s58, 0x58000
	s_addc_u32 s89, s59, 0
	s_add_u32 s90, s74, 0x2c000
	s_addc_u32 s91, s75, 0
	global_store_dwordx4 v171, v[48:51], s[88:89]
	global_store_dwordx4 v171, v[52:55], s[88:89] offset:2048
	global_store_dwordx2 v170, v[56:57], s[90:91]
	global_store_dwordx2 v170, v[168:169], s[90:91] offset:1024
	v_readlane_b32 s70, v244, 53
	v_readlane_b32 s71, v244, 54
	v_readlane_b32 s56, v246, 3
	v_readlane_b32 s57, v246, 4
